# late_convert/P0 transposes: LDS readout batched, gain loads hoisted/batched; on top of 9 earlier load-batching fixes
# speedup vs baseline: 1.0047x; 1.0010x over previous
; #define LAS __attribute__((address_space(3)))
; #define LDS_WAIT() asm volatile("s_waitcnt lgkmcnt(0)" ::: "memory")
; __device__ __forceinline__ unsigned cvtpk(float lo, float hi) { unsigned r; asm volatile("v_cvt_pk_bf16_f32 %0, %1, %2" : "=v"(r) : "v"(lo), "v"(hi)); return r; }
; __device__ __forceinline__ void tr_item(const float* W, int ldw, bf16* WT, int ldt, const float* gain, int dst_row0, int k0, int n0, LAS float* scr, int lane) {
;     ...
;     for (int i = 0; i < 16; ++i) { const int k = kr + 4 * i; const float g = gain ? gain[k0 + k] : 1.0f; LAS float* d = scr + k * 65 + n4;
;         d[0] = v[i][0] * g; d[1] = v[i][1] * g; d[2] = v[i][2] * g; d[3] = v[i][3] * g; }
;     LDS_WAIT(); asm volatile("" ::: "memory");
;     const int c = lane & 7;
; #pragma unroll
;     for (int j = 0; j < 8; ++j) { const int n = (lane >> 3) + 8 * j; const LAS float* s = scr + (8 * c) * 65 + n;
;         u32x4 o; o.x = cvtpk(s[0 * 65], s[1 * 65]); o.y = cvtpk(s[2 * 65], s[3 * 65]); o.z = cvtpk(s[4 * 65], s[5 * 65]); o.w = cvtpk(s[6 * 65], s[7 * 65]);
;         *(u32x4*)(WT + (size_t)(dst_row0 + n) * ldt + k0 + 8 * c) = o; }
;     LDS_WAIT(); asm volatile("" ::: "memory");
.LBB0_21:
	s_waitcnt vmcnt(0)
	v_pk_mul_f32 v[0:1], v[0:1], v[8:9] op_sel_hi:[1,0]
	v_add_u32_e32 v4, 0x1040, v17
	ds_write2_b32 v4, v0, v1 offset1:1
	v_pk_mul_f32 v[0:1], v[2:3], v[8:9] op_sel_hi:[1,0]
	v_add_u32_e32 v2, 0x1048, v17
	ds_write2_b32 v2, v0, v1 offset1:1
	s_ashr_i32 s8, s46, 1
	s_waitcnt lgkmcnt(0)
	s_mul_hi_i32 s9, s8, 0x2c00000
	s_mul_i32 s8, s8, 0x2c00000
	s_add_u32 s41, s14, s8
	ds_read2_b32 v[252:253], v91 offset1:65
	s_addc_u32 s9, s15, s9
	s_and_b32 s8, s70, 0x1fffffe
	ds_read2_b32 v[250:251], v91 offset0:130 offset1:195
	s_or_b32 s8, s8, s16
	v_add_u32_e32 v10, 0x400, v91
	ds_read2_b32 v[248:249], v10 offset0:4 offset1:69
	s_lshl_b32 s8, s8, 7
	s_and_b32 s16, s40, 64
	s_or_b32 s8, s8, s16
	s_lshl_b64 s[10:11], s[10:11], 1
	ds_read2_b32 v[246:247], v10 offset0:134 offset1:199
	s_add_u32 s10, s41, s10
	v_or_b32_e32 v4, s8, v89
	s_addc_u32 s11, s9, s11
	v_lshlrev_b32_e32 v66, 1, v76
	v_ashrrev_i32_e32 v5, 31, v4
	v_lshl_add_u64 v[6:7], s[10:11], 0, v[66:67]
	v_lshlrev_b64 v[4:5], 12, v[4:5]
	v_lshl_add_u64 v[4:5], v[6:7], 0, v[4:5]
	ds_read2_b32 v[244:245], v91 offset0:8 offset1:73
	v_mov_b32_e32 v204, v4
	v_mov_b32_e32 v205, v5
	s_nop 0
	ds_read2_b32 v[242:243], v91 offset0:138 offset1:203
	ds_read2_b32 v[240:241], v10 offset0:12 offset1:77
	ds_read2_b32 v[238:239], v10 offset0:142 offset1:207
	v_or_b32_e32 v4, s8, v94
	v_ashrrev_i32_e32 v5, 31, v4
	v_lshlrev_b64 v[4:5], 12, v[4:5]
	ds_read2_b32 v[236:237], v91 offset0:16 offset1:81
	v_lshl_add_u64 v[4:5], v[6:7], 0, v[4:5]
	v_mov_b32_e32 v202, v4
	v_mov_b32_e32 v203, v5
	s_nop 0
	v_or_b32_e32 v8, s8, v95
	v_ashrrev_i32_e32 v9, 31, v8
	ds_read2_b32 v[234:235], v91 offset0:146 offset1:211
	v_lshlrev_b64 v[8:9], 12, v[8:9]
	ds_read2_b32 v[232:233], v10 offset0:20 offset1:85
	v_lshl_add_u64 v[8:9], v[6:7], 0, v[8:9]
	ds_read2_b32 v[216:217], v10 offset0:150 offset1:215
	v_mov_b32_e32 v200, v8
	v_mov_b32_e32 v201, v9
	v_or_b32_e32 v8, s8, v96
	v_ashrrev_i32_e32 v9, 31, v8
	ds_read2_b32 v[214:215], v91 offset0:24 offset1:89
	ds_read2_b32 v[212:213], v91 offset0:154 offset1:219
	v_lshlrev_b64 v[8:9], 12, v[8:9]
	ds_read2_b32 v[210:211], v10 offset0:28 offset1:93
	v_lshl_add_u64 v[8:9], v[6:7], 0, v[8:9]
	ds_read2_b32 v[208:209], v10 offset0:158 offset1:223
	v_mov_b32_e32 v198, v8
	v_mov_b32_e32 v199, v9
	s_waitcnt lgkmcnt(0)
	v_cvt_pk_bf16_f32 v207, v252, v253
	v_cvt_pk_bf16_f32 v253, v250, v251
	v_cvt_pk_bf16_f32 v252, v248, v249
	v_cvt_pk_bf16_f32 v251, v246, v247
	v_mov_b32_e32 v154, v207
	v_mov_b32_e32 v155, v253
	v_mov_b32_e32 v156, v252
	v_mov_b32_e32 v157, v251
	global_store_dwordx4 v[204:205], v[154:157], off
	v_cvt_pk_bf16_f32 v250, v244, v245
	v_cvt_pk_bf16_f32 v253, v242, v243
	v_cvt_pk_bf16_f32 v252, v240, v241
	v_cvt_pk_bf16_f32 v251, v238, v239
	v_mov_b32_e32 v158, v250
	v_mov_b32_e32 v159, v253
	v_mov_b32_e32 v160, v252
	v_mov_b32_e32 v161, v251
	global_store_dwordx4 v[202:203], v[158:161], off
	v_cvt_pk_bf16_f32 v249, v236, v237
	v_cvt_pk_bf16_f32 v253, v234, v235
	v_cvt_pk_bf16_f32 v252, v232, v233
	v_cvt_pk_bf16_f32 v251, v216, v217
	v_mov_b32_e32 v154, v249
	v_mov_b32_e32 v155, v253
	v_mov_b32_e32 v156, v252
	v_mov_b32_e32 v157, v251
	global_store_dwordx4 v[200:201], v[154:157], off
	v_cvt_pk_bf16_f32 v250, v214, v215
	v_cvt_pk_bf16_f32 v253, v212, v213
	v_cvt_pk_bf16_f32 v252, v210, v211
	v_cvt_pk_bf16_f32 v251, v208, v209
	v_mov_b32_e32 v158, v250
	v_mov_b32_e32 v159, v253
	v_mov_b32_e32 v160, v252
	v_mov_b32_e32 v161, v251
	global_store_dwordx4 v[198:199], v[158:161], off
	v_mov_b32_e32 v0, v250
	v_mov_b32_e32 v1, v253
	v_mov_b32_e32 v2, v252
	v_mov_b32_e32 v3, v251
	v_mov_b32_e32 v4, v208
	v_mov_b32_e32 v5, v209
	v_or_b32_e32 v8, s8, v97
	v_ashrrev_i32_e32 v9, 31, v8
	ds_read2_b32 v[252:253], v91 offset0:32 offset1:97
	ds_read2_b32 v[250:251], v91 offset0:162 offset1:227
	v_lshlrev_b64 v[8:9], 12, v[8:9]
	ds_read2_b32 v[248:249], v10 offset0:36 offset1:101
	v_lshl_add_u64 v[8:9], v[6:7], 0, v[8:9]
	ds_read2_b32 v[246:247], v10 offset0:166 offset1:231
	v_mov_b32_e32 v204, v8
	v_mov_b32_e32 v205, v9
	v_or_b32_e32 v8, s8, v98
	v_ashrrev_i32_e32 v9, 31, v8
	ds_read2_b32 v[244:245], v91 offset0:40 offset1:105
	ds_read2_b32 v[242:243], v91 offset0:170 offset1:235
	v_lshlrev_b64 v[8:9], 12, v[8:9]
	ds_read2_b32 v[240:241], v10 offset0:44 offset1:109
	v_lshl_add_u64 v[8:9], v[6:7], 0, v[8:9]
	ds_read2_b32 v[238:239], v10 offset0:174 offset1:239
	v_mov_b32_e32 v202, v8
	v_mov_b32_e32 v203, v9
	v_or_b32_e32 v8, s8, v99
	ds_read2_b32 v[236:237], v91 offset0:48 offset1:113
	ds_read2_b32 v[234:235], v91 offset0:178 offset1:243
	v_ashrrev_i32_e32 v9, 31, v8
	ds_read2_b32 v[232:233], v10 offset0:52 offset1:117
	v_lshlrev_b64 v[8:9], 12, v[8:9]
	ds_read2_b32 v[216:217], v10 offset0:182 offset1:247
	v_lshl_add_u64 v[8:9], v[6:7], 0, v[8:9]
	ds_read2_b32 v[214:215], v91 offset0:56 offset1:121
	v_mov_b32_e32 v200, v8
	v_mov_b32_e32 v201, v9
	v_or_b32_e32 v8, s8, v100
	v_ashrrev_i32_e32 v9, 31, v8
	ds_read2_b32 v[212:213], v91 offset0:186 offset1:251
	ds_read2_b32 v[210:211], v10 offset0:60 offset1:125
	ds_read2_b32 v[208:209], v10 offset0:190 offset1:255
	v_lshlrev_b64 v[8:9], 12, v[8:9]
	v_lshl_add_u64 v[4:5], v[6:7], 0, v[8:9]
	v_mov_b32_e32 v198, v4
	v_mov_b32_e32 v199, v5
	s_waitcnt lgkmcnt(0)
	v_cvt_pk_bf16_f32 v207, v252, v253
	v_cvt_pk_bf16_f32 v253, v250, v251
	v_cvt_pk_bf16_f32 v252, v248, v249
	v_cvt_pk_bf16_f32 v251, v246, v247
	v_mov_b32_e32 v154, v207
	v_mov_b32_e32 v155, v253
	v_mov_b32_e32 v156, v252
	v_mov_b32_e32 v157, v251
	global_store_dwordx4 v[204:205], v[154:157], off
	v_cvt_pk_bf16_f32 v250, v244, v245
	v_cvt_pk_bf16_f32 v253, v242, v243
	v_cvt_pk_bf16_f32 v252, v240, v241
	v_cvt_pk_bf16_f32 v251, v238, v239
	v_mov_b32_e32 v158, v250
	v_mov_b32_e32 v159, v253
	v_mov_b32_e32 v160, v252
	v_mov_b32_e32 v161, v251
	global_store_dwordx4 v[202:203], v[158:161], off
	v_cvt_pk_bf16_f32 v249, v236, v237
	v_cvt_pk_bf16_f32 v253, v234, v235
	v_cvt_pk_bf16_f32 v252, v232, v233
	v_cvt_pk_bf16_f32 v251, v216, v217
	v_mov_b32_e32 v154, v249
	v_mov_b32_e32 v155, v253
	v_mov_b32_e32 v156, v252
	v_mov_b32_e32 v157, v251
	global_store_dwordx4 v[200:201], v[154:157], off
	v_cvt_pk_bf16_f32 v250, v214, v215
	v_cvt_pk_bf16_f32 v253, v212, v213
	v_cvt_pk_bf16_f32 v252, v210, v211
	v_cvt_pk_bf16_f32 v251, v208, v209
	v_mov_b32_e32 v158, v250
	v_mov_b32_e32 v159, v253
	v_mov_b32_e32 v160, v252
	v_mov_b32_e32 v161, v251
	global_store_dwordx4 v[198:199], v[158:161], off
	s_waitcnt lgkmcnt(0)

; #define LAS __attribute__((address_space(3)))
; __device__ __forceinline__ void tr_item(const float* W, int ldw, bf16* WT, int ldt, const float* gain, int dst_row0, int k0, int n0, LAS float* scr, int lane) {
;     const int n4 = (lane & 15) * 4, kr = lane >> 4;
;     f32x4 v[16];
; #pragma unroll
;     for (int i = 0; i < 16; ++i) v[i] = __builtin_nontemporal_load((const f32x4*)(W + (size_t)(k0 + kr + 4 * i) * ldw + n0 + n4));
; #pragma unroll
;     for (int i = 0; i < 16; ++i) { const int k = kr + 4 * i; const float g = gain ? gain[k0 + k] : 1.0f; LAS float* d = scr + k * 65 + n4;
;         d[0] = v[i][0] * g; d[1] = v[i][1] * g; d[2] = v[i][2] * g; d[3] = v[i][3] * g; }
; __device__ __forceinline__ void phase0(KArgs a, LAS unsigned char* lds, int gw, int NGW, int wave, int lane) {
;     ...
;         if (r < N_E) { const int m = r / IT_BD, item = r - m * IT_BD, z = m >> 1, which = m & 1;
;             tr_job((which ? a->in[I_WI] : a->in[I_WA]) + (size_t)z * 65536, 256, 256, (bf16*)(ws + WS_WAI), nullptr, 1, z * 512 + 128 * which, item, scr, lane); continue; }
.LBB0_57:
	s_andn2_b64 vcc, exec, s[8:9]
	s_cbranch_vccnz .LBB0_59
	s_ashr_i32 s8, s74, 31
	s_lshr_b32 s8, s8, 28
	s_add_i32 s9, s74, s8
	s_and_b32 s16, s9, -16
	s_sub_i32 s42, s74, s16
	s_ashr_i32 s8, s9, 5
	s_bfe_u32 s43, s9, 0x10004
	s_cmp_eq_u32 s43, 0
	s_cselect_b32 s9, s65, 0xa0
	s_add_u32 s10, s12, s9
	s_addc_u32 s11, s13, 0
	s_load_dwordx2 s[10:11], s[10:11], 0x0
	s_ashr_i32 s9, s8, 31
	s_lshl_b64 s[40:41], s[8:9], 18
	v_lshlrev_b32_e32 v66, 2, v72
	s_waitcnt lgkmcnt(0)
	s_add_u32 s9, s10, s40
	s_addc_u32 s11, s11, s41
	s_lshl_b32 s8, s8, 9
	s_lshl_b32 s10, s43, 7
	s_or_b32 s8, s8, s10
	s_ashr_i32 s10, s42, 31
	s_lshr_b32 s10, s10, 30
	s_add_i32 s42, s42, s10
	s_and_b32 s10, s42, -4
	s_add_i32 s10, s10, s16
	s_sub_i32 s10, s74, s10
	s_lshl_b32 s40, s10, 6
	s_lshl_b32 s10, s10, 7
	s_and_b32 s10, s10, 0xffffff00
	s_add_i32 s8, s8, s10
	s_and_b32 s10, s40, 64
	s_or_b32 s10, s8, s10
	s_lshl_b32 s8, s42, 4
	s_andn2_b32 s8, s8, 63
	s_ashr_i32 s41, s40, 31
	v_or_b32_e32 v60, s8, v74
	s_lshl_b64 s[40:41], s[40:41], 2
	s_add_u32 s40, s9, s40
	v_or_b32_e32 v2, 4, v60
	s_addc_u32 s41, s11, s41
	v_ashrrev_i32_e32 v61, 31, v60
	v_ashrrev_i32_e32 v3, 31, v2
	v_lshl_add_u64 v[62:63], s[40:41], 0, v[66:67]
	v_lshlrev_b64 v[0:1], 10, v[60:61]
	v_lshlrev_b64 v[2:3], 10, v[2:3]
	v_lshl_add_u64 v[0:1], v[62:63], 0, v[0:1]
	v_lshl_add_u64 v[4:5], v[62:63], 0, v[2:3]
	v_or_b32_e32 v8, 8, v60
	v_or_b32_e32 v10, 12, v60
	global_load_dwordx4 v[0:3], v[0:1], off nt
	s_nop 0
	global_load_dwordx4 v[4:7], v[4:5], off nt
	v_ashrrev_i32_e32 v9, 31, v8
	v_ashrrev_i32_e32 v11, 31, v10
	v_lshlrev_b64 v[8:9], 10, v[8:9]
	v_lshlrev_b64 v[10:11], 10, v[10:11]
	v_lshl_add_u64 v[8:9], v[62:63], 0, v[8:9]
	v_lshl_add_u64 v[12:13], v[62:63], 0, v[10:11]
	global_load_dwordx4 v[8:11], v[8:9], off nt
	s_nop 0
	global_load_dwordx4 v[12:15], v[12:13], off nt
	v_or_b32_e32 v16, 16, v60
	v_or_b32_e32 v18, 20, v60
	v_ashrrev_i32_e32 v17, 31, v16
	v_ashrrev_i32_e32 v19, 31, v18
	v_lshlrev_b64 v[16:17], 10, v[16:17]
	v_lshlrev_b64 v[18:19], 10, v[18:19]
	v_lshl_add_u64 v[16:17], v[62:63], 0, v[16:17]
	v_lshl_add_u64 v[20:21], v[62:63], 0, v[18:19]
	global_load_dwordx4 v[16:19], v[16:17], off nt
	s_nop 0
	global_load_dwordx4 v[20:23], v[20:21], off nt
	v_or_b32_e32 v24, 24, v60
	v_or_b32_e32 v26, 28, v60
	v_ashrrev_i32_e32 v25, 31, v24
	v_ashrrev_i32_e32 v27, 31, v26
	v_lshlrev_b64 v[24:25], 10, v[24:25]
	v_lshlrev_b64 v[26:27], 10, v[26:27]
	v_lshl_add_u64 v[24:25], v[62:63], 0, v[24:25]
	v_lshl_add_u64 v[28:29], v[62:63], 0, v[26:27]
	global_load_dwordx4 v[24:27], v[24:25], off nt
	s_nop 0
	global_load_dwordx4 v[28:31], v[28:29], off nt
	v_or_b32_e32 v32, 32, v60
	v_or_b32_e32 v34, 36, v60
	v_ashrrev_i32_e32 v33, 31, v32
	v_ashrrev_i32_e32 v35, 31, v34
	v_lshlrev_b64 v[32:33], 10, v[32:33]
	v_lshlrev_b64 v[34:35], 10, v[34:35]
	v_lshl_add_u64 v[32:33], v[62:63], 0, v[32:33]
	v_lshl_add_u64 v[36:37], v[62:63], 0, v[34:35]
	global_load_dwordx4 v[32:35], v[32:33], off nt
	s_nop 0
	global_load_dwordx4 v[36:39], v[36:37], off nt
	v_or_b32_e32 v40, 40, v60
	v_or_b32_e32 v42, 44, v60
	v_ashrrev_i32_e32 v41, 31, v40
	v_ashrrev_i32_e32 v43, 31, v42
	v_lshlrev_b64 v[40:41], 10, v[40:41]
	v_lshlrev_b64 v[42:43], 10, v[42:43]
	v_lshl_add_u64 v[40:41], v[62:63], 0, v[40:41]
	v_lshl_add_u64 v[44:45], v[62:63], 0, v[42:43]
	v_or_b32_e32 v48, 48, v60
	global_load_dwordx4 v[40:43], v[40:41], off nt
	s_nop 0
	global_load_dwordx4 v[44:47], v[44:45], off nt
	v_ashrrev_i32_e32 v49, 31, v48
	v_lshlrev_b64 v[48:49], 10, v[48:49]
	v_or_b32_e32 v52, 52, v60
	v_lshl_add_u64 v[48:49], v[62:63], 0, v[48:49]
	v_ashrrev_i32_e32 v53, 31, v52
	global_load_dwordx4 v[48:51], v[48:49], off nt
	v_lshlrev_b64 v[52:53], 10, v[52:53]
	v_or_b32_e32 v56, 56, v60
	v_lshl_add_u64 v[52:53], v[62:63], 0, v[52:53]
	v_ashrrev_i32_e32 v57, 31, v56
	global_load_dwordx4 v[52:55], v[52:53], off nt
	v_lshlrev_b64 v[56:57], 10, v[56:57]
	v_or_b32_e32 v60, 60, v60
	v_lshl_add_u64 v[56:57], v[62:63], 0, v[56:57]
	v_ashrrev_i32_e32 v61, 31, v60
	global_load_dwordx4 v[56:59], v[56:57], off nt
	v_lshlrev_b64 v[60:61], 10, v[60:61]
	v_lshl_add_u64 v[60:61], v[62:63], 0, v[60:61]
	global_load_dwordx4 v[60:63], v[60:61], off nt
	s_waitcnt vmcnt(15)
	ds_write2_b32 v77, v0, v1 offset1:1
	ds_write2_b32 v77, v2, v3 offset0:2 offset1:3
	v_add_u32_e32 v0, 0x410, v77
	s_waitcnt vmcnt(14)
	ds_write2_b32 v0, v4, v5 offset1:1
	v_add_u32_e32 v0, 0x418, v77
	ds_write2_b32 v0, v6, v7 offset1:1
	v_add_u32_e32 v0, 0x820, v77
	s_ashr_i32 s9, s8, 31
	s_waitcnt vmcnt(13)
	ds_write2_b32 v0, v8, v9 offset1:1
	v_add_u32_e32 v0, 0x828, v77
	ds_write2_b32 v0, v10, v11 offset1:1
	v_add_u32_e32 v0, 0xc30, v77
	s_waitcnt vmcnt(12)
	ds_write2_b32 v0, v12, v13 offset1:1
	v_add_u32_e32 v0, 0xc38, v77
	ds_write2_b32 v0, v14, v15 offset1:1
	v_add_u32_e32 v0, 0x1040, v77
	v_add_u32_e32 v10, 0x400, v91
	s_waitcnt vmcnt(11)
	ds_write2_b32 v0, v16, v17 offset1:1
	v_add_u32_e32 v0, 0x1048, v77
	ds_write2_b32 v0, v18, v19 offset1:1
	v_add_u32_e32 v0, 0x1450, v77
	s_waitcnt vmcnt(10)
	ds_write2_b32 v0, v20, v21 offset1:1
	v_add_u32_e32 v0, 0x1458, v77
	ds_write2_b32 v0, v22, v23 offset1:1
	v_add_u32_e32 v0, 0x1860, v77
	v_lshl_add_u64 v[6:7], s[8:9], 1, v[78:79]
	s_waitcnt vmcnt(9)
	ds_write2_b32 v0, v24, v25 offset1:1
	v_add_u32_e32 v0, 0x1868, v77
	ds_write2_b32 v0, v26, v27 offset1:1
	v_add_u32_e32 v0, 0x1c70, v77
	s_waitcnt vmcnt(8)
	ds_write2_b32 v0, v28, v29 offset1:1
	v_add_u32_e32 v0, 0x1c78, v77
	ds_write2_b32 v0, v30, v31 offset1:1
	v_add_u32_e32 v0, 0x2080, v77
	s_waitcnt vmcnt(7)
	ds_write2_b32 v0, v32, v33 offset1:1
	v_add_u32_e32 v0, 0x2088, v77
	ds_write2_b32 v0, v34, v35 offset1:1
	v_add_u32_e32 v0, 0x2490, v77
	s_waitcnt vmcnt(6)
; #define LAS __attribute__((address_space(3)))
; #define LDS_WAIT() asm volatile("s_waitcnt lgkmcnt(0)" ::: "memory")
; __device__ __forceinline__ unsigned cvtpk(float lo, float hi) { unsigned r; asm volatile("v_cvt_pk_bf16_f32 %0, %1, %2" : "=v"(r) : "v"(lo), "v"(hi)); return r; }
; __device__ __forceinline__ void tr_item(const float* W, int ldw, bf16* WT, int ldt, const float* gain, int dst_row0, int k0, int n0, LAS float* scr, int lane) {
;     ...
;     for (int i = 0; i < 16; ++i) { const int k = kr + 4 * i; const float g = gain ? gain[k0 + k] : 1.0f; LAS float* d = scr + k * 65 + n4;
;         d[0] = v[i][0] * g; d[1] = v[i][1] * g; d[2] = v[i][2] * g; d[3] = v[i][3] * g; }
;     LDS_WAIT(); asm volatile("" ::: "memory");
;     const int c = lane & 7;
; #pragma unroll
;     for (int j = 0; j < 8; ++j) { const int n = (lane >> 3) + 8 * j; const LAS float* s = scr + (8 * c) * 65 + n;
;         u32x4 o; o.x = cvtpk(s[0 * 65], s[1 * 65]); o.y = cvtpk(s[2 * 65], s[3 * 65]); o.z = cvtpk(s[4 * 65], s[5 * 65]); o.w = cvtpk(s[6 * 65], s[7 * 65]);
;         *(u32x4*)(WT + (size_t)(dst_row0 + n) * ldt + k0 + 8 * c) = o; }
;     LDS_WAIT(); asm volatile("" ::: "memory");
	ds_write2_b32 v0, v36, v37 offset1:1
	v_add_u32_e32 v0, 0x2498, v77
	ds_write2_b32 v0, v38, v39 offset1:1
	v_add_u32_e32 v0, 0x28a0, v77
	s_waitcnt vmcnt(5)
	ds_write2_b32 v0, v40, v41 offset1:1
	v_add_u32_e32 v0, 0x28a8, v77
	ds_write2_b32 v0, v42, v43 offset1:1
	v_add_u32_e32 v0, 0x2cb0, v77
	s_waitcnt vmcnt(4)
	ds_write2_b32 v0, v44, v45 offset1:1
	v_add_u32_e32 v0, 0x2cb8, v77
	ds_write2_b32 v0, v46, v47 offset1:1
	v_add_u32_e32 v0, 0x30c0, v77
	s_waitcnt vmcnt(3)
	ds_write2_b32 v0, v48, v49 offset1:1
	v_add_u32_e32 v0, 0x30c8, v77
	ds_write2_b32 v0, v50, v51 offset1:1
	v_add_u32_e32 v0, 0x34d0, v77
	s_waitcnt vmcnt(2)
	ds_write2_b32 v0, v52, v53 offset1:1
	v_add_u32_e32 v0, 0x34d8, v77
	ds_write2_b32 v0, v54, v55 offset1:1
	v_add_u32_e32 v0, 0x38e0, v77
	s_waitcnt vmcnt(1)
	ds_write2_b32 v0, v56, v57 offset1:1
	v_add_u32_e32 v0, 0x38e8, v77
	ds_write2_b32 v0, v58, v59 offset1:1
	v_add_u32_e32 v0, 0x3cf0, v77
	s_waitcnt vmcnt(0)
	ds_write2_b32 v0, v60, v61 offset1:1
	v_add_u32_e32 v0, 0x3cf8, v77
	ds_write2_b32 v0, v62, v63 offset1:1
	s_waitcnt lgkmcnt(0)
	ds_read2_b32 v[252:253], v91 offset1:65
	ds_read2_b32 v[250:251], v91 offset0:130 offset1:195
	ds_read2_b32 v[248:249], v10 offset0:4 offset1:69
	ds_read2_b32 v[246:247], v10 offset0:134 offset1:199
	v_or_b32_e32 v4, s10, v89
	v_ashrrev_i32_e32 v5, 31, v4
	v_lshlrev_b64 v[4:5], 9, v[4:5]
	v_lshl_add_u64 v[4:5], v[6:7], 0, v[4:5]
	ds_read2_b32 v[244:245], v91 offset0:8 offset1:73
	v_mov_b32_e32 v202, v4
	v_mov_b32_e32 v203, v5
	s_nop 0
	ds_read2_b32 v[242:243], v91 offset0:138 offset1:203
	ds_read2_b32 v[240:241], v10 offset0:12 offset1:77
	ds_read2_b32 v[238:239], v10 offset0:142 offset1:207
	v_or_b32_e32 v4, s10, v94
	v_ashrrev_i32_e32 v5, 31, v4
	v_lshlrev_b64 v[4:5], 9, v[4:5]
	v_lshl_add_u64 v[4:5], v[6:7], 0, v[4:5]
	ds_read2_b32 v[236:237], v91 offset0:16 offset1:81
	v_mov_b32_e32 v200, v4
	v_mov_b32_e32 v201, v5
	s_nop 0
	ds_read2_b32 v[234:235], v91 offset0:146 offset1:211
	ds_read2_b32 v[232:233], v10 offset0:20 offset1:85
	ds_read2_b32 v[216:217], v10 offset0:150 offset1:215
	v_or_b32_e32 v4, s10, v95
	v_ashrrev_i32_e32 v5, 31, v4
	v_lshlrev_b64 v[4:5], 9, v[4:5]
	v_lshl_add_u64 v[4:5], v[6:7], 0, v[4:5]
	ds_read2_b32 v[214:215], v91 offset0:24 offset1:89
	v_mov_b32_e32 v198, v4
	v_mov_b32_e32 v199, v5
	s_nop 0
	ds_read2_b32 v[212:213], v91 offset0:154 offset1:219
	ds_read2_b32 v[210:211], v10 offset0:28 offset1:93
	ds_read2_b32 v[208:209], v10 offset0:158 offset1:223
	v_or_b32_e32 v4, s10, v96
	v_ashrrev_i32_e32 v5, 31, v4
	v_lshlrev_b64 v[4:5], 9, v[4:5]
	v_lshl_add_u64 v[4:5], v[6:7], 0, v[4:5]
	ds_read2_b32 v[206:207], v91 offset0:32 offset1:97
	v_mov_b32_e32 v196, v4
	v_mov_b32_e32 v197, v5
	s_waitcnt lgkmcnt(0)
	v_cvt_pk_bf16_f32 v205, v252, v253
	v_cvt_pk_bf16_f32 v253, v250, v251
	v_cvt_pk_bf16_f32 v252, v248, v249
	v_cvt_pk_bf16_f32 v251, v246, v247
	v_mov_b32_e32 v154, v205
	v_mov_b32_e32 v155, v253
	v_mov_b32_e32 v156, v252
	v_mov_b32_e32 v157, v251
	global_store_dwordx4 v[202:203], v[154:157], off
	v_cvt_pk_bf16_f32 v250, v244, v245
	v_cvt_pk_bf16_f32 v253, v242, v243
	v_cvt_pk_bf16_f32 v252, v240, v241
	v_cvt_pk_bf16_f32 v251, v238, v239
	v_mov_b32_e32 v158, v250
	v_mov_b32_e32 v159, v253
	v_mov_b32_e32 v160, v252
	v_mov_b32_e32 v161, v251
	global_store_dwordx4 v[200:201], v[158:161], off
	v_cvt_pk_bf16_f32 v249, v236, v237
	v_cvt_pk_bf16_f32 v253, v234, v235
	v_cvt_pk_bf16_f32 v252, v232, v233
	v_cvt_pk_bf16_f32 v251, v216, v217
	v_mov_b32_e32 v154, v249
	v_mov_b32_e32 v155, v253
	v_mov_b32_e32 v156, v252
	v_mov_b32_e32 v157, v251
	global_store_dwordx4 v[198:199], v[154:157], off
	v_cvt_pk_bf16_f32 v250, v214, v215
	v_cvt_pk_bf16_f32 v253, v212, v213
	v_cvt_pk_bf16_f32 v252, v210, v211
	v_cvt_pk_bf16_f32 v251, v208, v209
	v_mov_b32_e32 v158, v250
	v_mov_b32_e32 v159, v253
	v_mov_b32_e32 v160, v252
	v_mov_b32_e32 v161, v251
	global_store_dwordx4 v[196:197], v[158:161], off
	v_mov_b32_e32 v0, v250
	v_mov_b32_e32 v1, v253
	v_mov_b32_e32 v2, v252
	v_mov_b32_e32 v3, v251
	v_mov_b32_e32 v8, v206
	v_mov_b32_e32 v9, v207
	s_nop 0
	v_cvt_pk_bf16_f32 v0, v8, v9
	ds_read2_b32 v[252:253], v91 offset0:162 offset1:227
	ds_read2_b32 v[250:251], v10 offset0:36 offset1:101
	ds_read2_b32 v[248:249], v10 offset0:166 offset1:231
	v_or_b32_e32 v4, s10, v97
	v_ashrrev_i32_e32 v5, 31, v4
	v_lshlrev_b64 v[4:5], 9, v[4:5]
	v_lshl_add_u64 v[4:5], v[6:7], 0, v[4:5]
	ds_read2_b32 v[246:247], v91 offset0:40 offset1:105
	v_mov_b32_e32 v206, v4
	v_mov_b32_e32 v207, v5
	v_mov_b32_e32 v208, v0
	s_nop 0
	ds_read2_b32 v[244:245], v91 offset0:170 offset1:235
	ds_read2_b32 v[242:243], v10 offset0:44 offset1:109
	ds_read2_b32 v[240:241], v10 offset0:174 offset1:239
	v_or_b32_e32 v4, s10, v98
	v_ashrrev_i32_e32 v5, 31, v4
	v_lshlrev_b64 v[4:5], 9, v[4:5]
	v_lshl_add_u64 v[4:5], v[6:7], 0, v[4:5]
	ds_read2_b32 v[238:239], v91 offset0:48 offset1:113
	v_mov_b32_e32 v204, v4
	v_mov_b32_e32 v205, v5
	s_nop 0
	ds_read2_b32 v[236:237], v91 offset0:178 offset1:243
	ds_read2_b32 v[234:235], v10 offset0:52 offset1:117
	ds_read2_b32 v[232:233], v10 offset0:182 offset1:247
	v_or_b32_e32 v4, s10, v99
	v_ashrrev_i32_e32 v5, 31, v4
	v_lshlrev_b64 v[4:5], 9, v[4:5]
	v_lshl_add_u64 v[4:5], v[6:7], 0, v[4:5]
	ds_read2_b32 v[216:217], v91 offset0:56 offset1:121
	v_mov_b32_e32 v202, v4
	v_mov_b32_e32 v203, v5
	s_nop 0
	ds_read2_b32 v[214:215], v91 offset0:186 offset1:251
	ds_read2_b32 v[212:213], v10 offset0:60 offset1:125
	ds_read2_b32 v[210:211], v10 offset0:190 offset1:255
	v_or_b32_e32 v4, s10, v100
	v_ashrrev_i32_e32 v5, 31, v4
	v_lshlrev_b64 v[4:5], 9, v[4:5]
	v_lshl_add_u64 v[4:5], v[6:7], 0, v[4:5]
	v_mov_b32_e32 v200, v4
	v_mov_b32_e32 v201, v5
	s_waitcnt lgkmcnt(0)
	v_cvt_pk_bf16_f32 v209, v252, v253
	v_cvt_pk_bf16_f32 v253, v250, v251
	v_cvt_pk_bf16_f32 v252, v248, v249
	v_mov_b32_e32 v154, v208
	v_mov_b32_e32 v155, v209
	v_mov_b32_e32 v156, v253
	v_mov_b32_e32 v157, v252
	global_store_dwordx4 v[206:207], v[154:157], off
	v_cvt_pk_bf16_f32 v251, v246, v247
	v_cvt_pk_bf16_f32 v253, v244, v245
	v_cvt_pk_bf16_f32 v252, v242, v243
	v_cvt_pk_bf16_f32 v250, v240, v241
	v_mov_b32_e32 v158, v251
	v_mov_b32_e32 v159, v253
	v_mov_b32_e32 v160, v252
	v_mov_b32_e32 v161, v250
	global_store_dwordx4 v[204:205], v[158:161], off
	v_cvt_pk_bf16_f32 v249, v238, v239
	v_cvt_pk_bf16_f32 v253, v236, v237
	v_cvt_pk_bf16_f32 v252, v234, v235
	v_cvt_pk_bf16_f32 v251, v232, v233
	v_mov_b32_e32 v154, v249
	v_mov_b32_e32 v155, v253
	v_mov_b32_e32 v156, v252
	v_mov_b32_e32 v157, v251
	global_store_dwordx4 v[202:203], v[154:157], off
	v_cvt_pk_bf16_f32 v250, v216, v217
	v_cvt_pk_bf16_f32 v253, v214, v215
	v_cvt_pk_bf16_f32 v252, v212, v213
	v_cvt_pk_bf16_f32 v251, v210, v211
	v_mov_b32_e32 v158, v250
	v_mov_b32_e32 v159, v253
	v_mov_b32_e32 v160, v252
	v_mov_b32_e32 v161, v251
	global_store_dwordx4 v[200:201], v[158:161], off
	s_waitcnt lgkmcnt(0)

; #define LAS __attribute__((address_space(3)))
; __device__ __forceinline__ void tr_item(const float* W, int ldw, bf16* WT, int ldt, const float* gain, int dst_row0, int k0, int n0, LAS float* scr, int lane) {
;     ...
;     for (int i = 0; i < 16; ++i) v[i] = __builtin_nontemporal_load((const f32x4*)(W + (size_t)(k0 + kr + 4 * i) * ldw + n0 + n4));
; #pragma unroll
;     for (int i = 0; i < 16; ++i) { const int k = kr + 4 * i; const float g = gain ? gain[k0 + k] : 1.0f; LAS float* d = scr + k * 65 + n4;
;         d[0] = v[i][0] * g; d[1] = v[i][1] * g; d[2] = v[i][2] * g; d[3] = v[i][3] * g; }
; __device__ __forceinline__ void phase0(KArgs a, LAS unsigned char* lds, int gw, int NGW, int wave, int lane) {
;     ...
;         if (r < N_D) { const int m = r / IT_QK, item = r - m * IT_QK;
;             tr_job(m ? a->in[I_GK] : a->in[I_GQ], DM, 1024, (bf16*)(ws + WS_WQKVR), a->in[I_LNMIX] + DM, 0, m * 1024, item, scr, lane); continue; }
.LBB0_60:
	s_andn2_b64 vcc, exec, s[8:9]
	s_cbranch_vccnz .LBB0_62
	s_ashr_i32 s8, s73, 31
	s_lshr_b32 s8, s8, 23
	s_add_i32 s8, s73, s8
	s_ashr_i32 s16, s8, 9
	s_and_b32 s8, s8, 0xfffffe00
	s_add_i32 s9, s73, 0x1ff
	s_sub_i32 s40, s73, s8
	s_cmpk_lt_u32 s9, 0x3ff
	s_load_dwordx2 s[8:9], s[12:13], 0x48
	s_cselect_b32 s10, s66, 0xc8
	s_add_u32 s10, s12, s10
	s_addc_u32 s11, s13, 0
	s_load_dwordx2 s[42:43], s[10:11], 0x0
	s_waitcnt lgkmcnt(0)
	s_add_u32 s10, s8, 0x2000
	s_addc_u32 s11, s9, 0
	s_ashr_i32 s8, s40, 31
	s_lshr_b32 s8, s8, 28
	s_add_i32 s40, s40, s8
	s_ashr_i32 s8, s40, 4
	s_lshl_b32 s9, s8, 10
	s_sub_i32 s40, 0, s9
	s_lshl_b32 s9, s16, 15
	s_sub_i32 s9, s40, s9
	s_add_i32 s41, s61, s69
	s_add_i32 s44, s41, s9
	s_lshl_b32 s8, s8, 6
	s_ashr_i32 s45, s44, 31
	v_or_b32_e32 v50, s8, v74
	s_lshl_b64 s[44:45], s[44:45], 2
	s_add_u32 s42, s42, s44
	v_or_b32_e32 v2, 4, v50
	s_addc_u32 s43, s43, s45
	v_lshlrev_b32_e32 v66, 2, v72
	v_ashrrev_i32_e32 v51, 31, v50
	v_ashrrev_i32_e32 v3, 31, v2
	v_lshl_add_u64 v[48:49], s[42:43], 0, v[66:67]
	v_lshlrev_b64 v[0:1], 12, v[50:51]
	v_lshlrev_b64 v[2:3], 12, v[2:3]
	v_lshl_add_u64 v[0:1], v[48:49], 0, v[0:1]
	v_lshl_add_u64 v[2:3], v[48:49], 0, v[2:3]
	global_load_dwordx4 v[28:31], v[0:1], off nt
	global_load_dwordx4 v[20:23], v[2:3], off nt
	v_or_b32_e32 v0, 8, v50
	v_or_b32_e32 v2, 12, v50
	v_or_b32_e32 v4, 16, v50
	v_or_b32_e32 v6, 20, v50
	v_or_b32_e32 v12, 24, v50
	v_or_b32_e32 v14, 28, v50
	v_ashrrev_i32_e32 v1, 31, v0
	v_ashrrev_i32_e32 v3, 31, v2
	v_ashrrev_i32_e32 v5, 31, v4
	v_ashrrev_i32_e32 v7, 31, v6
	v_ashrrev_i32_e32 v13, 31, v12
	v_ashrrev_i32_e32 v15, 31, v14
	v_lshlrev_b64 v[0:1], 12, v[0:1]
	v_lshlrev_b64 v[2:3], 12, v[2:3]
	v_lshlrev_b64 v[4:5], 12, v[4:5]
	v_lshlrev_b64 v[6:7], 12, v[6:7]
	v_lshlrev_b64 v[12:13], 12, v[12:13]
	v_lshlrev_b64 v[14:15], 12, v[14:15]
	v_lshl_add_u64 v[0:1], v[48:49], 0, v[0:1]
	v_lshl_add_u64 v[2:3], v[48:49], 0, v[2:3]
	v_lshl_add_u64 v[4:5], v[48:49], 0, v[4:5]
	v_lshl_add_u64 v[6:7], v[48:49], 0, v[6:7]
	v_lshl_add_u64 v[12:13], v[48:49], 0, v[12:13]
	v_lshl_add_u64 v[14:15], v[48:49], 0, v[14:15]
	v_lshl_add_u64 v[36:37], v[50:51], 2, s[10:11]
	global_load_dwordx4 v[8:11], v[0:1], off nt
	s_nop 0
	global_load_dwordx4 v[0:3], v[2:3], off nt
	s_nop 0
	global_load_dwordx4 v[16:19], v[4:5], off nt
	s_nop 0
	global_load_dwordx4 v[4:7], v[6:7], off nt
	s_nop 0
	global_load_dwordx4 v[24:27], v[12:13], off nt
	s_nop 0
	global_load_dwordx4 v[12:15], v[14:15], off nt
	v_or_b32_e32 v32, 32, v50
	global_load_dword v66, v[36:37], off
	v_or_b32_e32 v34, 36, v50
	v_ashrrev_i32_e32 v33, 31, v32
	v_ashrrev_i32_e32 v35, 31, v34
	v_or_b32_e32 v42, s8, v101
	v_lshlrev_b64 v[32:33], 12, v[32:33]
	v_lshlrev_b64 v[34:35], 12, v[34:35]
	v_ashrrev_i32_e32 v43, 31, v42
	v_lshl_add_u64 v[32:33], v[48:49], 0, v[32:33]
	v_lshl_add_u64 v[34:35], v[48:49], 0, v[34:35]
	v_lshl_add_u64 v[42:43], v[42:43], 2, s[10:11]
	global_load_dwordx4 v[36:39], v[32:33], off nt
	s_nop 0
	global_load_dwordx4 v[32:35], v[34:35], off nt
	v_or_b32_e32 v40, 40, v50
	global_load_dword v92, v[42:43], off
	v_or_b32_e32 v42, 44, v50
	v_ashrrev_i32_e32 v41, 31, v40
	v_ashrrev_i32_e32 v43, 31, v42
	v_or_b32_e32 v54, s8, v103
	v_or_b32_e32 v56, s8, v107
	v_lshlrev_b64 v[40:41], 12, v[40:41]
	v_lshlrev_b64 v[42:43], 12, v[42:43]
	v_ashrrev_i32_e32 v55, 31, v54
	v_ashrrev_i32_e32 v57, 31, v56
	v_lshl_add_u64 v[40:41], v[48:49], 0, v[40:41]
	v_lshl_add_u64 v[42:43], v[48:49], 0, v[42:43]
	v_lshl_add_u64 v[54:55], v[54:55], 2, s[10:11]
	v_lshl_add_u64 v[56:57], v[56:57], 2, s[10:11]
	global_load_dwordx4 v[44:47], v[40:41], off nt
	s_nop 0
	global_load_dwordx4 v[40:43], v[42:43], off nt
	v_or_b32_e32 v52, 48, v50
	global_load_dword v132, v[54:55], off
	global_load_dword v136, v[56:57], off
	v_or_b32_e32 v54, s8, v105
	v_ashrrev_i32_e32 v55, 31, v54
	v_lshl_add_u64 v[54:55], v[54:55], 2, s[10:11]
	global_load_dword v134, v[54:55], off
	v_or_b32_e32 v54, 52, v50
	v_ashrrev_i32_e32 v55, 31, v54
	v_lshlrev_b64 v[54:55], 12, v[54:55]
	v_ashrrev_i32_e32 v53, 31, v52
	v_lshl_add_u64 v[56:57], v[48:49], 0, v[54:55]
	v_or_b32_e32 v54, s8, v109
	v_or_b32_e32 v60, s8, v111
	v_or_b32_e32 v62, s8, v113
	v_lshlrev_b64 v[52:53], 12, v[52:53]
	v_ashrrev_i32_e32 v55, 31, v54
	v_ashrrev_i32_e32 v61, 31, v60
	v_ashrrev_i32_e32 v63, 31, v62
	v_lshl_add_u64 v[52:53], v[48:49], 0, v[52:53]
	v_lshl_add_u64 v[54:55], v[54:55], 2, s[10:11]
	v_lshl_add_u64 v[60:61], v[60:61], 2, s[10:11]
	v_lshl_add_u64 v[62:63], v[62:63], 2, s[10:11]
	global_load_dword v138, v[54:55], off
	s_nop 0
	global_load_dwordx4 v[52:55], v[52:53], off nt
	s_nop 0
	global_load_dwordx4 v[56:59], v[56:57], off nt
	v_or_b32_e32 v150, s8, v121
	global_load_dword v140, v[60:61], off
	global_load_dword v142, v[62:63], off
	v_or_b32_e32 v62, s8, v115
	v_ashrrev_i32_e32 v63, 31, v62
	v_lshl_add_u64 v[62:63], v[62:63], 2, s[10:11]
	v_or_b32_e32 v60, 56, v50
	global_load_dword v144, v[62:63], off
	v_or_b32_e32 v50, 60, v50
	v_or_b32_e32 v62, s8, v117
	v_ashrrev_i32_e32 v61, 31, v60
	v_ashrrev_i32_e32 v51, 31, v50
	v_ashrrev_i32_e32 v63, 31, v62
	v_lshlrev_b64 v[60:61], 12, v[60:61]
	v_lshl_add_u64 v[62:63], v[62:63], 2, s[10:11]
	v_lshlrev_b64 v[50:51], 12, v[50:51]
	v_lshl_add_u64 v[60:61], v[48:49], 0, v[60:61]
	global_load_dword v146, v[62:63], off
	v_lshl_add_u64 v[62:63], v[48:49], 0, v[50:51]
	v_or_b32_e32 v48, s8, v119
	v_ashrrev_i32_e32 v49, 31, v48
	v_lshl_add_u64 v[48:49], v[48:49], 2, s[10:11]
	v_ashrrev_i32_e32 v151, 31, v150
	global_load_dword v148, v[48:49], off
	s_nop 0
	global_load_dwordx4 v[48:51], v[60:61], off nt
	s_nop 0
	global_load_dwordx4 v[60:63], v[62:63], off nt
	v_lshl_add_u64 v[150:151], v[150:151], 2, s[10:11]
	global_load_dword v150, v[150:151], off
	v_or_b32_e32 v152, s8, v127
	v_ashrrev_i32_e32 v153, 31, v152
	s_waitcnt vmcnt(19)
; #define LAS __attribute__((address_space(3)))
; #define LDS_WAIT() asm volatile("s_waitcnt lgkmcnt(0)" ::: "memory")
; __device__ __forceinline__ void tr_item(const float* W, int ldw, bf16* WT, int ldt, const float* gain, int dst_row0, int k0, int n0, LAS float* scr, int lane) {
;     ...
;     for (int i = 0; i < 16; ++i) { const int k = kr + 4 * i; const float g = gain ? gain[k0 + k] : 1.0f; LAS float* d = scr + k * 65 + n4;
;         d[0] = v[i][0] * g; d[1] = v[i][1] * g; d[2] = v[i][2] * g; d[3] = v[i][3] * g; }
;     LDS_WAIT(); asm volatile("" ::: "memory");
	v_pk_mul_f32 v[28:29], v[28:29], v[66:67] op_sel_hi:[1,0]
	ds_write2_b32 v77, v28, v29 offset1:1
	v_or_b32_e32 v28, s8, v123
	v_ashrrev_i32_e32 v29, 31, v28
	v_pk_mul_f32 v[30:31], v[30:31], v[66:67] op_sel_hi:[1,0]
	v_lshl_add_u64 v[28:29], v[28:29], 2, s[10:11]
	ds_write2_b32 v77, v30, v31 offset0:2 offset1:3
	v_or_b32_e32 v30, s8, v126
	global_load_dword v28, v[28:29], off
	v_ashrrev_i32_e32 v31, 31, v30
	v_lshl_add_u64 v[30:31], v[30:31], 2, s[10:11]
	global_load_dword v30, v[30:31], off
	v_add_u32_e32 v29, v73, v102
	s_waitcnt vmcnt(18)
	v_pk_mul_f32 v[20:21], v[20:21], v[92:93] op_sel_hi:[1,0]
	v_lshl_add_u64 v[152:153], v[152:153], 2, s[10:11]
	ds_write2_b32 v29, v20, v21 offset1:1
	v_pk_mul_f32 v[20:21], v[22:23], v[92:93] op_sel_hi:[1,0]
	v_or_b32_e32 v22, s8, v128
	global_load_dword v66, v[152:153], off
	v_ashrrev_i32_e32 v23, 31, v22
	v_lshl_add_u64 v[22:23], v[22:23], 2, s[10:11]
	global_load_dword v22, v[22:23], off
	ds_write2_b32 v29, v20, v21 offset0:2 offset1:3
	v_add_u32_e32 v20, 0x410, v29
	s_ashr_i32 s9, s8, 31
	s_mulk_i32 s16, 0x7c00
	s_waitcnt vmcnt(17)
	v_pk_mul_f32 v[8:9], v[8:9], v[132:133] op_sel_hi:[1,0]
	ds_write2_b32 v20, v8, v9 offset1:1
	v_pk_mul_f32 v[8:9], v[10:11], v[132:133] op_sel_hi:[1,0]
	v_add_u32_e32 v10, 0x418, v29
	ds_write2_b32 v10, v8, v9 offset1:1
	s_waitcnt vmcnt(15)
	v_pk_mul_f32 v[0:1], v[0:1], v[134:135] op_sel_hi:[1,0]
	v_add_u32_e32 v8, 0x820, v29
	ds_write2_b32 v8, v0, v1 offset1:1
	v_pk_mul_f32 v[0:1], v[2:3], v[134:135] op_sel_hi:[1,0]
	v_add_u32_e32 v2, 0x828, v29
	ds_write2_b32 v2, v0, v1 offset1:1
	v_pk_mul_f32 v[0:1], v[16:17], v[136:137] op_sel_hi:[1,0]
	v_add_u32_e32 v2, 0xc30, v29
	ds_write2_b32 v2, v0, v1 offset1:1
	v_pk_mul_f32 v[0:1], v[18:19], v[136:137] op_sel_hi:[1,0]
	v_add_u32_e32 v2, 0xc38, v29
	ds_write2_b32 v2, v0, v1 offset1:1
	v_add_u32_e32 v2, 0x1040, v29
	s_waitcnt vmcnt(14)
	v_pk_mul_f32 v[0:1], v[4:5], v[138:139] op_sel_hi:[1,0]
	ds_write2_b32 v2, v0, v1 offset1:1
	v_pk_mul_f32 v[0:1], v[6:7], v[138:139] op_sel_hi:[1,0]
	v_add_u32_e32 v2, 0x1048, v29
	ds_write2_b32 v2, v0, v1 offset1:1
	s_waitcnt vmcnt(11)
	v_pk_mul_f32 v[0:1], v[24:25], v[140:141] op_sel_hi:[1,0]
	v_add_u32_e32 v2, 0x1450, v29
	ds_write2_b32 v2, v0, v1 offset1:1
	v_pk_mul_f32 v[0:1], v[26:27], v[140:141] op_sel_hi:[1,0]
	v_add_u32_e32 v2, v73, v112
	ds_write2_b32 v2, v0, v1 offset0:2 offset1:3
	s_waitcnt vmcnt(10)
	v_pk_mul_f32 v[0:1], v[12:13], v[142:143] op_sel_hi:[1,0]
	v_add_u32_e32 v3, 0x410, v2
	ds_write2_b32 v3, v0, v1 offset1:1
	v_pk_mul_f32 v[0:1], v[14:15], v[142:143] op_sel_hi:[1,0]
	v_add_u32_e32 v3, 0x418, v2
	ds_write2_b32 v3, v0, v1 offset1:1
	s_waitcnt vmcnt(9)
	v_pk_mul_f32 v[0:1], v[36:37], v[144:145] op_sel_hi:[1,0]
	v_add_u32_e32 v3, 0x820, v2
	ds_write2_b32 v3, v0, v1 offset1:1
	v_pk_mul_f32 v[0:1], v[38:39], v[144:145] op_sel_hi:[1,0]
	v_add_u32_e32 v3, 0x828, v2
	ds_write2_b32 v3, v0, v1 offset1:1
	s_waitcnt vmcnt(8)
	v_pk_mul_f32 v[0:1], v[32:33], v[146:147] op_sel_hi:[1,0]
	v_add_u32_e32 v3, 0xc30, v2
	ds_write2_b32 v3, v0, v1 offset1:1
	v_pk_mul_f32 v[0:1], v[34:35], v[146:147] op_sel_hi:[1,0]
	v_add_u32_e32 v3, 0xc38, v2
	ds_write2_b32 v3, v0, v1 offset1:1
	s_waitcnt vmcnt(7)
	v_pk_mul_f32 v[0:1], v[44:45], v[148:149] op_sel_hi:[1,0]
	v_add_u32_e32 v3, 0x1040, v2
	ds_write2_b32 v3, v0, v1 offset1:1
	v_pk_mul_f32 v[0:1], v[46:47], v[148:149] op_sel_hi:[1,0]
	v_add_u32_e32 v3, 0x1048, v2
	ds_write2_b32 v3, v0, v1 offset1:1
	s_waitcnt vmcnt(4)
	v_pk_mul_f32 v[0:1], v[40:41], v[150:151] op_sel_hi:[1,0]
	v_add_u32_e32 v2, 0x1450, v2
	ds_write2_b32 v2, v0, v1 offset1:1
	v_pk_mul_f32 v[0:1], v[42:43], v[150:151] op_sel_hi:[1,0]
	v_add_u32_e32 v2, v73, v122
	ds_write2_b32 v2, v0, v1 offset0:2 offset1:3
	s_waitcnt vmcnt(3)
	v_pk_mul_f32 v[0:1], v[52:53], v[28:29] op_sel_hi:[1,0]
	v_add_u32_e32 v3, 0x410, v2
	ds_write2_b32 v3, v0, v1 offset1:1
	v_pk_mul_f32 v[0:1], v[54:55], v[28:29] op_sel_hi:[1,0]
	v_add_u32_e32 v3, 0x418, v2
	ds_write2_b32 v3, v0, v1 offset1:1
	s_waitcnt vmcnt(2)
	v_pk_mul_f32 v[0:1], v[56:57], v[30:31] op_sel_hi:[1,0]
	v_add_u32_e32 v3, 0x820, v2
	ds_write2_b32 v3, v0, v1 offset1:1
	v_pk_mul_f32 v[0:1], v[58:59], v[30:31] op_sel_hi:[1,0]
	v_add_u32_e32 v3, 0x828, v2
	ds_write2_b32 v3, v0, v1 offset1:1
	s_waitcnt vmcnt(1)
	v_pk_mul_f32 v[0:1], v[48:49], v[66:67] op_sel_hi:[1,0]
	v_add_u32_e32 v3, 0xc30, v2
	ds_write2_b32 v3, v0, v1 offset1:1
	v_pk_mul_f32 v[0:1], v[50:51], v[66:67] op_sel_hi:[1,0]
	v_add_u32_e32 v3, 0xc38, v2
	ds_write2_b32 v3, v0, v1 offset1:1
	s_waitcnt vmcnt(0)
	v_pk_mul_f32 v[0:1], v[60:61], v[22:23] op_sel_hi:[1,0]
	v_add_u32_e32 v3, 0x1040, v2
	ds_write2_b32 v3, v0, v1 offset1:1
	v_pk_mul_f32 v[0:1], v[62:63], v[22:23] op_sel_hi:[1,0]
	v_add_u32_e32 v2, 0x1048, v2
	ds_write2_b32 v2, v0, v1 offset1:1
	s_waitcnt lgkmcnt(0)
; #define LAS __attribute__((address_space(3)))
; #define LDS_WAIT() asm volatile("s_waitcnt lgkmcnt(0)" ::: "memory")
; __device__ __forceinline__ unsigned cvtpk(float lo, float hi) { unsigned r; asm volatile("v_cvt_pk_bf16_f32 %0, %1, %2" : "=v"(r) : "v"(lo), "v"(hi)); return r; }
; __device__ __forceinline__ void tr_item(const float* W, int ldw, bf16* WT, int ldt, const float* gain, int dst_row0, int k0, int n0, LAS float* scr, int lane) {
;     ...
;     const int c = lane & 7;
; #pragma unroll
;     for (int j = 0; j < 8; ++j) { const int n = (lane >> 3) + 8 * j; const LAS float* s = scr + (8 * c) * 65 + n;
;         u32x4 o; o.x = cvtpk(s[0 * 65], s[1 * 65]); o.y = cvtpk(s[2 * 65], s[3 * 65]); o.z = cvtpk(s[4 * 65], s[5 * 65]); o.w = cvtpk(s[6 * 65], s[7 * 65]);
;         *(u32x4*)(WT + (size_t)(dst_row0 + n) * ldt + k0 + 8 * c) = o; }
;     LDS_WAIT(); asm volatile("" ::: "memory");
	ds_read2_b32 v[252:253], v91 offset1:65
	ds_read2_b32 v[250:251], v91 offset0:130 offset1:195
	v_add_u32_e32 v12, 0x400, v91
	ds_read2_b32 v[248:249], v12 offset0:4 offset1:69
	v_lshl_add_u64 v[6:7], s[8:9], 1, v[80:81]
	s_sub_i32 s8, s40, s16
	ds_read2_b32 v[246:247], v12 offset0:134 offset1:199
	s_add_i32 s8, s8, s69
	v_add_u32_e32 v4, s8, v124
	v_ashrrev_i32_e32 v5, 31, v4
	v_lshlrev_b64 v[10:11], 12, v[4:5]
	v_lshl_add_u64 v[10:11], v[6:7], 0, v[10:11]
	ds_read2_b32 v[244:245], v91 offset0:8 offset1:73
	v_mov_b32_e32 v202, v10
	v_mov_b32_e32 v203, v11
	s_nop 0
	ds_read2_b32 v[242:243], v91 offset0:138 offset1:203
	ds_read2_b32 v[240:241], v12 offset0:12 offset1:77
	ds_read2_b32 v[238:239], v12 offset0:142 offset1:207
	v_add_u32_e32 v8, 8, v4
	v_ashrrev_i32_e32 v9, 31, v8
	v_lshlrev_b64 v[8:9], 12, v[8:9]
	v_lshl_add_u64 v[8:9], v[6:7], 0, v[8:9]
	ds_read2_b32 v[236:237], v91 offset0:16 offset1:81
	v_mov_b32_e32 v200, v8
	v_mov_b32_e32 v201, v9
	s_nop 0
	ds_read2_b32 v[234:235], v91 offset0:146 offset1:211
	ds_read2_b32 v[232:233], v12 offset0:20 offset1:85
	ds_read2_b32 v[216:217], v12 offset0:150 offset1:215
	v_add_u32_e32 v8, 16, v4
	v_ashrrev_i32_e32 v9, 31, v8
	v_lshlrev_b64 v[8:9], 12, v[8:9]
	v_lshl_add_u64 v[8:9], v[6:7], 0, v[8:9]
	ds_read2_b32 v[214:215], v91 offset0:24 offset1:89
	v_mov_b32_e32 v198, v8
	v_mov_b32_e32 v199, v9
	s_nop 0
	ds_read2_b32 v[212:213], v91 offset0:154 offset1:219
	ds_read2_b32 v[210:211], v12 offset0:28 offset1:93
	ds_read2_b32 v[208:209], v12 offset0:158 offset1:223
	v_add_u32_e32 v8, 24, v4
	v_ashrrev_i32_e32 v9, 31, v8
	v_lshlrev_b64 v[8:9], 12, v[8:9]
	v_lshl_add_u64 v[8:9], v[6:7], 0, v[8:9]
	ds_read2_b32 v[206:207], v91 offset0:32 offset1:97
	v_mov_b32_e32 v196, v8
	v_mov_b32_e32 v197, v9
	s_waitcnt lgkmcnt(0)
	v_cvt_pk_bf16_f32 v205, v252, v253
	v_cvt_pk_bf16_f32 v253, v250, v251
	v_cvt_pk_bf16_f32 v252, v248, v249
	v_cvt_pk_bf16_f32 v251, v246, v247
	v_mov_b32_e32 v154, v205
	v_mov_b32_e32 v155, v253
	v_mov_b32_e32 v156, v252
	v_mov_b32_e32 v157, v251
	global_store_dwordx4 v[202:203], v[154:157], off
	v_cvt_pk_bf16_f32 v250, v244, v245
	v_cvt_pk_bf16_f32 v253, v242, v243
	v_cvt_pk_bf16_f32 v252, v240, v241
	v_cvt_pk_bf16_f32 v251, v238, v239
	v_mov_b32_e32 v158, v250
	v_mov_b32_e32 v159, v253
	v_mov_b32_e32 v160, v252
	v_mov_b32_e32 v161, v251
	global_store_dwordx4 v[200:201], v[158:161], off
	v_cvt_pk_bf16_f32 v249, v236, v237
	v_cvt_pk_bf16_f32 v253, v234, v235
	v_cvt_pk_bf16_f32 v252, v232, v233
	v_cvt_pk_bf16_f32 v251, v216, v217
	v_mov_b32_e32 v154, v249
	v_mov_b32_e32 v155, v253
	v_mov_b32_e32 v156, v252
	v_mov_b32_e32 v157, v251
	global_store_dwordx4 v[198:199], v[154:157], off
	v_cvt_pk_bf16_f32 v250, v214, v215
	v_cvt_pk_bf16_f32 v253, v212, v213
	v_cvt_pk_bf16_f32 v252, v210, v211
	v_cvt_pk_bf16_f32 v251, v208, v209
	v_mov_b32_e32 v158, v250
	v_mov_b32_e32 v159, v253
	v_mov_b32_e32 v160, v252
	v_mov_b32_e32 v161, v251
	global_store_dwordx4 v[196:197], v[158:161], off
	v_mov_b32_e32 v0, v250
	v_mov_b32_e32 v1, v253
	v_mov_b32_e32 v2, v252
	v_mov_b32_e32 v3, v251
	v_mov_b32_e32 v10, v206
	v_mov_b32_e32 v11, v207
	s_nop 0
	v_cvt_pk_bf16_f32 v0, v10, v11
	ds_read2_b32 v[252:253], v91 offset0:162 offset1:227
	ds_read2_b32 v[250:251], v12 offset0:36 offset1:101
	ds_read2_b32 v[248:249], v12 offset0:166 offset1:231
	v_add_u32_e32 v8, 32, v4
	v_ashrrev_i32_e32 v9, 31, v8
	v_lshlrev_b64 v[8:9], 12, v[8:9]
	v_lshl_add_u64 v[8:9], v[6:7], 0, v[8:9]
	ds_read2_b32 v[246:247], v91 offset0:40 offset1:105
	v_mov_b32_e32 v206, v8
	v_mov_b32_e32 v207, v9
	v_mov_b32_e32 v208, v0
	s_nop 0
	ds_read2_b32 v[244:245], v91 offset0:170 offset1:235
	ds_read2_b32 v[242:243], v12 offset0:44 offset1:109
	ds_read2_b32 v[240:241], v12 offset0:174 offset1:239
	v_add_u32_e32 v8, 40, v4
	v_ashrrev_i32_e32 v9, 31, v8
	v_lshlrev_b64 v[8:9], 12, v[8:9]
	v_lshl_add_u64 v[8:9], v[6:7], 0, v[8:9]
	ds_read2_b32 v[238:239], v91 offset0:48 offset1:113
	v_mov_b32_e32 v204, v8
	v_mov_b32_e32 v205, v9
	s_nop 0
	ds_read2_b32 v[236:237], v91 offset0:178 offset1:243
	ds_read2_b32 v[234:235], v12 offset0:52 offset1:117
	ds_read2_b32 v[232:233], v12 offset0:182 offset1:247
	v_add_u32_e32 v8, 48, v4
	v_ashrrev_i32_e32 v9, 31, v8
	v_lshlrev_b64 v[8:9], 12, v[8:9]
	v_add_u32_e32 v4, 56, v4
	v_lshl_add_u64 v[8:9], v[6:7], 0, v[8:9]
	v_ashrrev_i32_e32 v5, 31, v4
	ds_read2_b32 v[216:217], v91 offset0:56 offset1:121
	v_mov_b32_e32 v202, v8
	v_mov_b32_e32 v203, v9
	v_lshlrev_b64 v[4:5], 12, v[4:5]
	v_lshl_add_u64 v[4:5], v[6:7], 0, v[4:5]
	ds_read2_b32 v[214:215], v91 offset0:186 offset1:251
	ds_read2_b32 v[212:213], v12 offset0:60 offset1:125
	ds_read2_b32 v[210:211], v12 offset0:190 offset1:255
	v_mov_b32_e32 v200, v4
	v_mov_b32_e32 v201, v5
	s_waitcnt lgkmcnt(0)
	v_cvt_pk_bf16_f32 v209, v252, v253
	v_cvt_pk_bf16_f32 v253, v250, v251
	v_cvt_pk_bf16_f32 v252, v248, v249
	v_mov_b32_e32 v154, v208
	v_mov_b32_e32 v155, v209
	v_mov_b32_e32 v156, v253
	v_mov_b32_e32 v157, v252
	global_store_dwordx4 v[206:207], v[154:157], off
	v_cvt_pk_bf16_f32 v251, v246, v247
	v_cvt_pk_bf16_f32 v253, v244, v245
	v_cvt_pk_bf16_f32 v252, v242, v243
	v_cvt_pk_bf16_f32 v250, v240, v241
	v_mov_b32_e32 v158, v251
	v_mov_b32_e32 v159, v253
	v_mov_b32_e32 v160, v252
	v_mov_b32_e32 v161, v250
	global_store_dwordx4 v[204:205], v[158:161], off
	v_cvt_pk_bf16_f32 v249, v238, v239
	v_cvt_pk_bf16_f32 v253, v236, v237
	v_cvt_pk_bf16_f32 v252, v234, v235
	v_cvt_pk_bf16_f32 v251, v232, v233
	v_mov_b32_e32 v154, v249
	v_mov_b32_e32 v155, v253
	v_mov_b32_e32 v156, v252
	v_mov_b32_e32 v157, v251
	global_store_dwordx4 v[202:203], v[154:157], off
	v_cvt_pk_bf16_f32 v250, v216, v217
	v_cvt_pk_bf16_f32 v253, v214, v215
	v_cvt_pk_bf16_f32 v252, v212, v213
	v_cvt_pk_bf16_f32 v251, v210, v211
	v_mov_b32_e32 v158, v250
	v_mov_b32_e32 v159, v253
	v_mov_b32_e32 v160, v252
	v_mov_b32_e32 v161, v251
	global_store_dwordx4 v[200:201], v[158:161], off
	s_waitcnt lgkmcnt(0)

; #define LAS __attribute__((address_space(3)))
; #define LDS_WAIT() asm volatile("s_waitcnt lgkmcnt(0)" ::: "memory")
; __device__ __forceinline__ unsigned cvtpk(float lo, float hi) { unsigned r; asm volatile("v_cvt_pk_bf16_f32 %0, %1, %2" : "=v"(r) : "v"(lo), "v"(hi)); return r; }
; __device__ __forceinline__ void tr_item(const float* W, int ldw, bf16* WT, int ldt, const float* gain, int dst_row0, int k0, int n0, LAS float* scr, int lane) {
;     ...
;     for (int i = 0; i < 16; ++i) { const int k = kr + 4 * i; const float g = gain ? gain[k0 + k] : 1.0f; LAS float* d = scr + k * 65 + n4;
;         d[0] = v[i][0] * g; d[1] = v[i][1] * g; d[2] = v[i][2] * g; d[3] = v[i][3] * g; }
;     LDS_WAIT(); asm volatile("" ::: "memory");
;     const int c = lane & 7;
; #pragma unroll
;     for (int j = 0; j < 8; ++j) { const int n = (lane >> 3) + 8 * j; const LAS float* s = scr + (8 * c) * 65 + n;
;         u32x4 o; o.x = cvtpk(s[0 * 65], s[1 * 65]); o.y = cvtpk(s[2 * 65], s[3 * 65]); o.z = cvtpk(s[4 * 65], s[5 * 65]); o.w = cvtpk(s[6 * 65], s[7 * 65]);
;         *(u32x4*)(WT + (size_t)(dst_row0 + n) * ldt + k0 + 8 * c) = o; }
;     LDS_WAIT(); asm volatile("" ::: "memory");
; __device__ __forceinline__ void phase0(KArgs a, LAS unsigned char* lds, int gw, int NGW, int wave, int lane) {
;     ...
;         if (r < N_C) { const int m = r / IT_SQ, item = r - m * IT_SQ;
;             const float* src = m == 0 ? a->in[I_WY] : m == 1 ? a->in[I_WX] : m == 2 ? a->in[I_RWO] : m == 3 ? a->in[I_GV] : m == 4 ? a->in[I_GR] : a->in[I_GWO];
;             const float* gain = (m == 0 || m == 1) ? a->in[I_LNMIX] : (m == 3 || m == 4) ? a->in[I_LNMIX] + DM : nullptr;
;             bf16* dst = (bf16*)(ws + (m <= 1 ? WS_WYX : m == 2 ? WS_WRO : m <= 4 ? WS_WQKVR : WS_WGO));
;             const int base = m == 1 ? 2048 : m == 3 ? 2048 : m == 4 ? 4096 : 0;
;             tr_job(src, DM, DM, dst, gain, 0, base, item, scr, lane); continue; }
.LBB0_107:
	s_and_b32 s8, s72, 0x7ffffc00
	s_cmpk_lt_u32 s72, 0x1400
	s_cselect_b32 s9, s67, 0x13b00000
	s_cmpk_lg_i32 s8, 0x800
	s_waitcnt vmcnt(0)
	v_pk_mul_f32 v[0:1], v[0:1], v[8:9] op_sel_hi:[1,0]
	v_add_u32_e32 v4, 0x1040, v17
	s_cselect_b32 s8, s9, 0x11a00000
	ds_write2_b32 v4, v0, v1 offset1:1
	v_pk_mul_f32 v[0:1], v[2:3], v[8:9] op_sel_hi:[1,0]
	v_add_u32_e32 v2, 0x1048, v17
	s_cmpk_gt_i32 s72, 0x7ff
	ds_write2_b32 v2, v0, v1 offset1:1
	s_cselect_b32 s8, s8, 0x10800000
	s_waitcnt lgkmcnt(0)
	s_add_u32 s9, s14, s8
	s_addc_u32 s16, s15, 0
	s_and_b32 s8, s72, 0xfffff400
	s_and_b32 s11, s72, 0xfffffc00
	ds_read2_b32 v[252:253], v91 offset1:65
	s_cmpk_eq_i32 s11, 0x1000
	ds_read2_b32 v[250:251], v91 offset0:130 offset1:195
	s_cselect_b32 s11, s11, 0
	v_add_u32_e32 v10, 0x400, v91
	s_cmpk_lg_i32 s8, 0x400
	ds_read2_b32 v[248:249], v10 offset0:4 offset1:69
	s_cselect_b32 s8, s11, 0x800
	s_add_i32 s8, s10, s8
	s_lshl_b64 s[10:11], s[40:41], 1
	ds_read2_b32 v[246:247], v10 offset0:134 offset1:199
	s_add_u32 s10, s9, s10
	v_or_b32_e32 v4, s8, v89
	s_addc_u32 s11, s16, s11
	v_lshlrev_b32_e32 v66, 1, v76
	v_ashrrev_i32_e32 v5, 31, v4
	v_lshl_add_u64 v[6:7], s[10:11], 0, v[66:67]
	v_lshlrev_b64 v[4:5], 12, v[4:5]
	v_lshl_add_u64 v[4:5], v[6:7], 0, v[4:5]
	ds_read2_b32 v[244:245], v91 offset0:8 offset1:73
	v_mov_b32_e32 v204, v4
	v_mov_b32_e32 v205, v5
	s_nop 0
	ds_read2_b32 v[242:243], v91 offset0:138 offset1:203
	ds_read2_b32 v[240:241], v10 offset0:12 offset1:77
	ds_read2_b32 v[238:239], v10 offset0:142 offset1:207
	v_or_b32_e32 v4, s8, v94
	v_ashrrev_i32_e32 v5, 31, v4
	v_lshlrev_b64 v[4:5], 12, v[4:5]
	ds_read2_b32 v[236:237], v91 offset0:16 offset1:81
	v_lshl_add_u64 v[4:5], v[6:7], 0, v[4:5]
	v_mov_b32_e32 v202, v4
	v_mov_b32_e32 v203, v5
	s_nop 0
	v_or_b32_e32 v8, s8, v95
	v_ashrrev_i32_e32 v9, 31, v8
	ds_read2_b32 v[234:235], v91 offset0:146 offset1:211
	v_lshlrev_b64 v[8:9], 12, v[8:9]
	ds_read2_b32 v[232:233], v10 offset0:20 offset1:85
	v_lshl_add_u64 v[8:9], v[6:7], 0, v[8:9]
	ds_read2_b32 v[216:217], v10 offset0:150 offset1:215
	v_mov_b32_e32 v200, v8
	v_mov_b32_e32 v201, v9
	v_or_b32_e32 v8, s8, v96
	v_ashrrev_i32_e32 v9, 31, v8
	ds_read2_b32 v[214:215], v91 offset0:24 offset1:89
	ds_read2_b32 v[212:213], v91 offset0:154 offset1:219
	v_lshlrev_b64 v[8:9], 12, v[8:9]
	ds_read2_b32 v[210:211], v10 offset0:28 offset1:93
	v_lshl_add_u64 v[8:9], v[6:7], 0, v[8:9]
	ds_read2_b32 v[208:209], v10 offset0:158 offset1:223
	v_mov_b32_e32 v198, v8
	v_mov_b32_e32 v199, v9
	s_waitcnt lgkmcnt(0)
	v_cvt_pk_bf16_f32 v207, v252, v253
	v_cvt_pk_bf16_f32 v253, v250, v251
	v_cvt_pk_bf16_f32 v252, v248, v249
	v_cvt_pk_bf16_f32 v251, v246, v247
	v_mov_b32_e32 v154, v207
	v_mov_b32_e32 v155, v253
	v_mov_b32_e32 v156, v252
	v_mov_b32_e32 v157, v251
	global_store_dwordx4 v[204:205], v[154:157], off
	v_cvt_pk_bf16_f32 v250, v244, v245
	v_cvt_pk_bf16_f32 v253, v242, v243
	v_cvt_pk_bf16_f32 v252, v240, v241
	v_cvt_pk_bf16_f32 v251, v238, v239
	v_mov_b32_e32 v158, v250
	v_mov_b32_e32 v159, v253
	v_mov_b32_e32 v160, v252
	v_mov_b32_e32 v161, v251
	global_store_dwordx4 v[202:203], v[158:161], off
	v_cvt_pk_bf16_f32 v249, v236, v237
	v_cvt_pk_bf16_f32 v253, v234, v235
	v_cvt_pk_bf16_f32 v252, v232, v233
	v_cvt_pk_bf16_f32 v251, v216, v217
	v_mov_b32_e32 v154, v249
	v_mov_b32_e32 v155, v253
	v_mov_b32_e32 v156, v252
	v_mov_b32_e32 v157, v251
	global_store_dwordx4 v[200:201], v[154:157], off
	v_cvt_pk_bf16_f32 v250, v214, v215
	v_cvt_pk_bf16_f32 v253, v212, v213
	v_cvt_pk_bf16_f32 v252, v210, v211
	v_cvt_pk_bf16_f32 v251, v208, v209
	v_mov_b32_e32 v158, v250
	v_mov_b32_e32 v159, v253
	v_mov_b32_e32 v160, v252
	v_mov_b32_e32 v161, v251
	global_store_dwordx4 v[198:199], v[158:161], off
	v_mov_b32_e32 v0, v250
	v_mov_b32_e32 v1, v253
	v_mov_b32_e32 v2, v252
	v_mov_b32_e32 v3, v251
	v_mov_b32_e32 v4, v208
	v_mov_b32_e32 v5, v209
	v_or_b32_e32 v8, s8, v97
	v_ashrrev_i32_e32 v9, 31, v8
	ds_read2_b32 v[252:253], v91 offset0:32 offset1:97
	ds_read2_b32 v[250:251], v91 offset0:162 offset1:227
	v_lshlrev_b64 v[8:9], 12, v[8:9]
	ds_read2_b32 v[248:249], v10 offset0:36 offset1:101
	v_lshl_add_u64 v[8:9], v[6:7], 0, v[8:9]
	ds_read2_b32 v[246:247], v10 offset0:166 offset1:231
	v_mov_b32_e32 v204, v8
	v_mov_b32_e32 v205, v9
	v_or_b32_e32 v8, s8, v98
	v_ashrrev_i32_e32 v9, 31, v8
	ds_read2_b32 v[244:245], v91 offset0:40 offset1:105
	ds_read2_b32 v[242:243], v91 offset0:170 offset1:235
	v_lshlrev_b64 v[8:9], 12, v[8:9]
	ds_read2_b32 v[240:241], v10 offset0:44 offset1:109
	v_lshl_add_u64 v[8:9], v[6:7], 0, v[8:9]
	ds_read2_b32 v[238:239], v10 offset0:174 offset1:239
	v_mov_b32_e32 v202, v8
	v_mov_b32_e32 v203, v9
	v_or_b32_e32 v8, s8, v99
	ds_read2_b32 v[236:237], v91 offset0:48 offset1:113
	ds_read2_b32 v[234:235], v91 offset0:178 offset1:243
	v_ashrrev_i32_e32 v9, 31, v8
	ds_read2_b32 v[232:233], v10 offset0:52 offset1:117
	v_lshlrev_b64 v[8:9], 12, v[8:9]
	ds_read2_b32 v[216:217], v10 offset0:182 offset1:247
	v_lshl_add_u64 v[8:9], v[6:7], 0, v[8:9]
	ds_read2_b32 v[214:215], v91 offset0:56 offset1:121
	v_mov_b32_e32 v200, v8
	v_mov_b32_e32 v201, v9
	v_or_b32_e32 v8, s8, v100
	v_ashrrev_i32_e32 v9, 31, v8
	ds_read2_b32 v[212:213], v91 offset0:186 offset1:251
	ds_read2_b32 v[210:211], v10 offset0:60 offset1:125
	ds_read2_b32 v[208:209], v10 offset0:190 offset1:255
	v_lshlrev_b64 v[8:9], 12, v[8:9]
	v_lshl_add_u64 v[4:5], v[6:7], 0, v[8:9]
	v_mov_b32_e32 v198, v4
	v_mov_b32_e32 v199, v5
	s_waitcnt lgkmcnt(0)
	v_cvt_pk_bf16_f32 v207, v252, v253
	v_cvt_pk_bf16_f32 v253, v250, v251
	v_cvt_pk_bf16_f32 v252, v248, v249
	v_cvt_pk_bf16_f32 v251, v246, v247
	v_mov_b32_e32 v154, v207
	v_mov_b32_e32 v155, v253
	v_mov_b32_e32 v156, v252
	v_mov_b32_e32 v157, v251
	global_store_dwordx4 v[204:205], v[154:157], off
	v_cvt_pk_bf16_f32 v250, v244, v245
	v_cvt_pk_bf16_f32 v253, v242, v243
	v_cvt_pk_bf16_f32 v252, v240, v241
	v_cvt_pk_bf16_f32 v251, v238, v239
	v_mov_b32_e32 v158, v250
	v_mov_b32_e32 v159, v253
	v_mov_b32_e32 v160, v252
	v_mov_b32_e32 v161, v251
	global_store_dwordx4 v[202:203], v[158:161], off
	v_cvt_pk_bf16_f32 v249, v236, v237
	v_cvt_pk_bf16_f32 v253, v234, v235
	v_cvt_pk_bf16_f32 v252, v232, v233
	v_cvt_pk_bf16_f32 v251, v216, v217
	v_mov_b32_e32 v154, v249
	v_mov_b32_e32 v155, v253
	v_mov_b32_e32 v156, v252
	v_mov_b32_e32 v157, v251
	global_store_dwordx4 v[200:201], v[154:157], off
	v_cvt_pk_bf16_f32 v250, v214, v215
	v_cvt_pk_bf16_f32 v253, v212, v213
	v_cvt_pk_bf16_f32 v252, v210, v211
	v_cvt_pk_bf16_f32 v251, v208, v209
	v_mov_b32_e32 v158, v250
	v_mov_b32_e32 v159, v253
	v_mov_b32_e32 v160, v252
	v_mov_b32_e32 v161, v251
	global_store_dwordx4 v[198:199], v[158:161], off
	s_waitcnt lgkmcnt(0)

; #define LAS __attribute__((address_space(3)))
; __device__ __forceinline__ void tr_item(const float* W, int ldw, bf16* WT, int ldt, const float* gain, int dst_row0, int k0, int n0, LAS float* scr, int lane) {
;     ...
;     for (int i = 0; i < 16; ++i) v[i] = __builtin_nontemporal_load((const f32x4*)(W + (size_t)(k0 + kr + 4 * i) * ldw + n0 + n4));
; #pragma unroll
;     for (int i = 0; i < 16; ++i) { const int k = kr + 4 * i; const float g = gain ? gain[k0 + k] : 1.0f; LAS float* d = scr + k * 65 + n4;
;         d[0] = v[i][0] * g; d[1] = v[i][1] * g; d[2] = v[i][2] * g; d[3] = v[i][3] * g; }
; __device__ __forceinline__ void phase0(KArgs a, LAS unsigned char* lds, int gw, int NGW, int wave, int lane) {
;     ...
;         if (r < N_B) { const int f = r / IT_DN, item = r - f * IT_DN, layer = f >> 1, second = f & 1;
;             const float* src = (second ? a->in[I_F2W2] : a->in[I_F1W2]) + (size_t)layer * DM * FF;
;             tr_job(src, FF, DM, (bf16*)(ws + WS_WDN + (size_t)f * SZ_WDN), nullptr, 0, 0, item, scr, lane); continue; }
.LBB0_109:
	s_andn2_b64 vcc, exec, s[8:9]
	s_cbranch_vccnz .LBB0_111
	s_mul_hi_i32 s8, s71, 0x2e8ba2e9
	s_lshr_b32 s9, s8, 31
	s_ashr_i32 s8, s8, 9
	s_add_i32 s10, s8, s9
	s_mul_i32 s8, s10, 0xfffff500
	s_add_i32 s40, s71, s8
	s_ashr_i32 s11, s10, 1
	s_bitcmp0_b32 s10, 0
	s_cselect_b32 s8, 64, 0x68
	s_add_u32 s8, s12, s8
	s_addc_u32 s9, s13, 0
	s_load_dwordx2 s[8:9], s[8:9], 0x0
	s_mul_hi_i32 s16, s11, 0x2c00000
	s_mul_i32 s11, s11, 0x2c00000
	v_lshlrev_b32_e32 v66, 2, v72
	s_waitcnt lgkmcnt(0)
	s_add_u32 s42, s8, s11
	s_addc_u32 s9, s9, s16
	s_mul_i32 s11, s10, 0x1600000
	s_mul_hi_i32 s8, s10, 0x1600000
	s_add_u32 s11, s53, s11
	s_addc_u32 s16, s54, s8
	s_ashr_i32 s8, s40, 31
	s_lshr_b32 s8, s8, 27
	s_add_i32 s40, s40, s8
	s_ashr_i32 s8, s40, 5
	s_lshl_b32 s40, s8, 11
	s_mul_i32 s10, s10, 0x2c000
	s_add_i32 s10, s40, s10
	s_add_i32 s40, s63, s69
	s_sub_i32 s40, s40, s10
	s_lshl_b32 s8, s8, 6
	s_ashr_i32 s41, s40, 31
	v_or_b32_e32 v60, s8, v74
	s_lshl_b64 s[40:41], s[40:41], 2
	s_add_u32 s40, s42, s40
	v_or_b32_e32 v2, 4, v60
	s_addc_u32 s41, s9, s41
	v_ashrrev_i32_e32 v61, 31, v60
	v_ashrrev_i32_e32 v3, 31, v2
	v_lshl_add_u64 v[62:63], s[40:41], 0, v[66:67]
	v_lshlrev_b64 v[0:1], 13, v[60:61]
	v_lshlrev_b64 v[2:3], 13, v[2:3]
	v_lshl_add_u64 v[0:1], v[62:63], 0, v[0:1]
	v_lshl_add_u64 v[4:5], v[62:63], 0, v[2:3]
	v_or_b32_e32 v8, 8, v60
	v_or_b32_e32 v10, 12, v60
	global_load_dwordx4 v[0:3], v[0:1], off nt
	s_nop 0
	global_load_dwordx4 v[4:7], v[4:5], off nt
	v_ashrrev_i32_e32 v9, 31, v8
	v_ashrrev_i32_e32 v11, 31, v10
	v_lshlrev_b64 v[8:9], 13, v[8:9]
	v_lshlrev_b64 v[10:11], 13, v[10:11]
	v_lshl_add_u64 v[8:9], v[62:63], 0, v[8:9]
	v_lshl_add_u64 v[12:13], v[62:63], 0, v[10:11]
	global_load_dwordx4 v[8:11], v[8:9], off nt
	s_nop 0
	global_load_dwordx4 v[12:15], v[12:13], off nt
	v_or_b32_e32 v16, 16, v60
	v_or_b32_e32 v18, 20, v60
	v_ashrrev_i32_e32 v17, 31, v16
	v_ashrrev_i32_e32 v19, 31, v18
	v_lshlrev_b64 v[16:17], 13, v[16:17]
	v_lshlrev_b64 v[18:19], 13, v[18:19]
	v_lshl_add_u64 v[16:17], v[62:63], 0, v[16:17]
	v_lshl_add_u64 v[20:21], v[62:63], 0, v[18:19]
	global_load_dwordx4 v[16:19], v[16:17], off nt
	s_nop 0
	global_load_dwordx4 v[20:23], v[20:21], off nt
	v_or_b32_e32 v24, 24, v60
	v_or_b32_e32 v26, 28, v60
	v_ashrrev_i32_e32 v25, 31, v24
	v_ashrrev_i32_e32 v27, 31, v26
	v_lshlrev_b64 v[24:25], 13, v[24:25]
	v_lshlrev_b64 v[26:27], 13, v[26:27]
	v_lshl_add_u64 v[24:25], v[62:63], 0, v[24:25]
	v_lshl_add_u64 v[28:29], v[62:63], 0, v[26:27]
	global_load_dwordx4 v[24:27], v[24:25], off nt
	s_nop 0
	global_load_dwordx4 v[28:31], v[28:29], off nt
	v_or_b32_e32 v32, 32, v60
	v_or_b32_e32 v34, 36, v60
	v_ashrrev_i32_e32 v33, 31, v32
	v_ashrrev_i32_e32 v35, 31, v34
	v_lshlrev_b64 v[32:33], 13, v[32:33]
	v_lshlrev_b64 v[34:35], 13, v[34:35]
	v_lshl_add_u64 v[32:33], v[62:63], 0, v[32:33]
	v_lshl_add_u64 v[36:37], v[62:63], 0, v[34:35]
	global_load_dwordx4 v[32:35], v[32:33], off nt
	s_nop 0
	global_load_dwordx4 v[36:39], v[36:37], off nt
	v_or_b32_e32 v40, 40, v60
	v_or_b32_e32 v42, 44, v60
	v_ashrrev_i32_e32 v41, 31, v40
	v_ashrrev_i32_e32 v43, 31, v42
	v_lshlrev_b64 v[40:41], 13, v[40:41]
	v_lshlrev_b64 v[42:43], 13, v[42:43]
	v_lshl_add_u64 v[40:41], v[62:63], 0, v[40:41]
	v_lshl_add_u64 v[44:45], v[62:63], 0, v[42:43]
	v_or_b32_e32 v48, 48, v60
	global_load_dwordx4 v[40:43], v[40:41], off nt
	s_nop 0
	global_load_dwordx4 v[44:47], v[44:45], off nt
	v_ashrrev_i32_e32 v49, 31, v48
	v_lshlrev_b64 v[48:49], 13, v[48:49]
	v_or_b32_e32 v52, 52, v60
	v_lshl_add_u64 v[48:49], v[62:63], 0, v[48:49]
	v_ashrrev_i32_e32 v53, 31, v52
	global_load_dwordx4 v[48:51], v[48:49], off nt
	v_lshlrev_b64 v[52:53], 13, v[52:53]
	v_or_b32_e32 v56, 56, v60
	v_lshl_add_u64 v[52:53], v[62:63], 0, v[52:53]
	v_ashrrev_i32_e32 v57, 31, v56
	global_load_dwordx4 v[52:55], v[52:53], off nt
	v_lshlrev_b64 v[56:57], 13, v[56:57]
	v_or_b32_e32 v60, 60, v60
	v_lshl_add_u64 v[56:57], v[62:63], 0, v[56:57]
	v_ashrrev_i32_e32 v61, 31, v60
	global_load_dwordx4 v[56:59], v[56:57], off nt
	v_lshlrev_b64 v[60:61], 13, v[60:61]
	v_lshl_add_u64 v[60:61], v[62:63], 0, v[60:61]
	global_load_dwordx4 v[60:63], v[60:61], off nt
	s_waitcnt vmcnt(15)
	ds_write2_b32 v77, v0, v1 offset1:1
	ds_write2_b32 v77, v2, v3 offset0:2 offset1:3
	v_add_u32_e32 v0, 0x410, v77
	s_waitcnt vmcnt(14)
	ds_write2_b32 v0, v4, v5 offset1:1
	v_add_u32_e32 v0, 0x418, v77
	ds_write2_b32 v0, v6, v7 offset1:1
	v_add_u32_e32 v0, 0x820, v77
	s_ashr_i32 s9, s8, 31
	s_waitcnt vmcnt(13)
	ds_write2_b32 v0, v8, v9 offset1:1
	v_add_u32_e32 v0, 0x828, v77
	ds_write2_b32 v0, v10, v11 offset1:1
	v_add_u32_e32 v0, 0xc30, v77
	s_waitcnt vmcnt(12)
	ds_write2_b32 v0, v12, v13 offset1:1
	v_add_u32_e32 v0, 0xc38, v77
	ds_write2_b32 v0, v14, v15 offset1:1
	v_add_u32_e32 v0, 0x1040, v77
	s_lshl_b64 s[8:9], s[8:9], 1
	s_waitcnt vmcnt(11)
	ds_write2_b32 v0, v16, v17 offset1:1
	v_add_u32_e32 v0, 0x1048, v77
	ds_write2_b32 v0, v18, v19 offset1:1
	v_add_u32_e32 v0, 0x1450, v77
	s_waitcnt vmcnt(10)
	ds_write2_b32 v0, v20, v21 offset1:1
	v_add_u32_e32 v0, 0x1458, v77
	ds_write2_b32 v0, v22, v23 offset1:1
	v_add_u32_e32 v0, 0x1860, v77
	s_add_u32 s8, s11, s8
	s_waitcnt vmcnt(9)
	ds_write2_b32 v0, v24, v25 offset1:1
	v_add_u32_e32 v0, 0x1868, v77
	ds_write2_b32 v0, v26, v27 offset1:1
	v_add_u32_e32 v0, 0x1c70, v77
	s_waitcnt vmcnt(8)
	ds_write2_b32 v0, v28, v29 offset1:1
	v_add_u32_e32 v0, 0x1c78, v77
	ds_write2_b32 v0, v30, v31 offset1:1
	v_add_u32_e32 v0, 0x2080, v77
	s_addc_u32 s9, s16, s9
	s_waitcnt vmcnt(7)
	ds_write2_b32 v0, v32, v33 offset1:1
	v_add_u32_e32 v0, 0x2088, v77
	ds_write2_b32 v0, v34, v35 offset1:1
	v_add_u32_e32 v0, 0x2490, v77
	s_waitcnt vmcnt(6)
; #define LAS __attribute__((address_space(3)))
; #define LDS_WAIT() asm volatile("s_waitcnt lgkmcnt(0)" ::: "memory")
; __device__ __forceinline__ unsigned cvtpk(float lo, float hi) { unsigned r; asm volatile("v_cvt_pk_bf16_f32 %0, %1, %2" : "=v"(r) : "v"(lo), "v"(hi)); return r; }
; __device__ __forceinline__ void tr_item(const float* W, int ldw, bf16* WT, int ldt, const float* gain, int dst_row0, int k0, int n0, LAS float* scr, int lane) {
;     ...
;     const int c = lane & 7;
; #pragma unroll
;     for (int j = 0; j < 8; ++j) { const int n = (lane >> 3) + 8 * j; const LAS float* s = scr + (8 * c) * 65 + n;
;         u32x4 o; o.x = cvtpk(s[0 * 65], s[1 * 65]); o.y = cvtpk(s[2 * 65], s[3 * 65]); o.z = cvtpk(s[4 * 65], s[5 * 65]); o.w = cvtpk(s[6 * 65], s[7 * 65]);
;         *(u32x4*)(WT + (size_t)(dst_row0 + n) * ldt + k0 + 8 * c) = o; }
;     LDS_WAIT(); asm volatile("" ::: "memory");
	ds_write2_b32 v0, v36, v37 offset1:1
	v_add_u32_e32 v0, 0x2498, v77
	ds_write2_b32 v0, v38, v39 offset1:1
	v_add_u32_e32 v0, 0x28a0, v77
	v_lshlrev_b32_e32 v66, 1, v76
	v_add_u32_e32 v10, 0x400, v91
	s_waitcnt vmcnt(5)
	ds_write2_b32 v0, v40, v41 offset1:1
	v_add_u32_e32 v0, 0x28a8, v77
	ds_write2_b32 v0, v42, v43 offset1:1
	v_add_u32_e32 v0, 0x2cb0, v77
	s_waitcnt vmcnt(4)
	ds_write2_b32 v0, v44, v45 offset1:1
	v_add_u32_e32 v0, 0x2cb8, v77
	ds_write2_b32 v0, v46, v47 offset1:1
	v_add_u32_e32 v0, 0x30c0, v77
	s_waitcnt vmcnt(3)
	ds_write2_b32 v0, v48, v49 offset1:1
	v_add_u32_e32 v0, 0x30c8, v77
	ds_write2_b32 v0, v50, v51 offset1:1
	v_add_u32_e32 v0, 0x34d0, v77
	s_waitcnt vmcnt(2)
	ds_write2_b32 v0, v52, v53 offset1:1
	v_add_u32_e32 v0, 0x34d8, v77
	ds_write2_b32 v0, v54, v55 offset1:1
	v_add_u32_e32 v0, 0x38e0, v77
	v_lshl_add_u64 v[6:7], s[8:9], 0, v[66:67]
	s_waitcnt vmcnt(1)
	ds_write2_b32 v0, v56, v57 offset1:1
	v_add_u32_e32 v0, 0x38e8, v77
	ds_write2_b32 v0, v58, v59 offset1:1
	v_add_u32_e32 v0, 0x3cf0, v77
	s_waitcnt vmcnt(0)
	ds_write2_b32 v0, v60, v61 offset1:1
	v_add_u32_e32 v0, 0x3cf8, v77
	ds_write2_b32 v0, v62, v63 offset1:1
	s_waitcnt lgkmcnt(0)
	ds_read2_b32 v[252:253], v91 offset1:65
	ds_read2_b32 v[250:251], v91 offset0:130 offset1:195
	s_sub_i32 s8, s69, s10
	ds_read2_b32 v[248:249], v10 offset0:4 offset1:69
	v_add_u32_e32 v11, s8, v125
	ds_read2_b32 v[246:247], v10 offset0:134 offset1:199
	v_mad_i64_i32 v[8:9], s[8:9], v11, s25, v[6:7]
	ds_read2_b32 v[244:245], v91 offset0:8 offset1:73
	v_mov_b32_e32 v202, v8
	v_mov_b32_e32 v203, v9
	v_add_u32_e32 v8, 8, v11
	v_mad_i64_i32 v[8:9], s[8:9], v8, s25, v[6:7]
	ds_read2_b32 v[242:243], v91 offset0:138 offset1:203
	ds_read2_b32 v[240:241], v10 offset0:12 offset1:77
	ds_read2_b32 v[238:239], v10 offset0:142 offset1:207
	ds_read2_b32 v[236:237], v91 offset0:16 offset1:81
	v_mov_b32_e32 v200, v8
	v_mov_b32_e32 v201, v9
	v_add_u32_e32 v8, 16, v11
	v_mad_i64_i32 v[8:9], s[8:9], v8, s25, v[6:7]
	ds_read2_b32 v[234:235], v91 offset0:146 offset1:211
	ds_read2_b32 v[232:233], v10 offset0:20 offset1:85
	ds_read2_b32 v[216:217], v10 offset0:150 offset1:215
	ds_read2_b32 v[214:215], v91 offset0:24 offset1:89
	v_mov_b32_e32 v198, v8
	v_mov_b32_e32 v199, v9
	v_add_u32_e32 v8, 24, v11
	v_mad_i64_i32 v[8:9], s[8:9], v8, s25, v[6:7]
	ds_read2_b32 v[212:213], v91 offset0:154 offset1:219
	ds_read2_b32 v[210:211], v10 offset0:28 offset1:93
	ds_read2_b32 v[208:209], v10 offset0:158 offset1:223
	ds_read2_b32 v[206:207], v91 offset0:32 offset1:97
	v_mov_b32_e32 v196, v8
	v_mov_b32_e32 v197, v9
	s_waitcnt lgkmcnt(0)
	v_cvt_pk_bf16_f32 v205, v252, v253
	v_cvt_pk_bf16_f32 v253, v250, v251
	v_cvt_pk_bf16_f32 v252, v248, v249
	v_cvt_pk_bf16_f32 v251, v246, v247
	v_mov_b32_e32 v154, v205
	v_mov_b32_e32 v155, v253
	v_mov_b32_e32 v156, v252
	v_mov_b32_e32 v157, v251
	global_store_dwordx4 v[202:203], v[154:157], off
	v_cvt_pk_bf16_f32 v250, v244, v245
	v_cvt_pk_bf16_f32 v253, v242, v243
	v_cvt_pk_bf16_f32 v252, v240, v241
	v_cvt_pk_bf16_f32 v251, v238, v239
	v_mov_b32_e32 v158, v250
	v_mov_b32_e32 v159, v253
	v_mov_b32_e32 v160, v252
	v_mov_b32_e32 v161, v251
	global_store_dwordx4 v[200:201], v[158:161], off
	v_cvt_pk_bf16_f32 v249, v236, v237
	v_cvt_pk_bf16_f32 v253, v234, v235
	v_cvt_pk_bf16_f32 v252, v232, v233
	v_cvt_pk_bf16_f32 v251, v216, v217
	v_mov_b32_e32 v154, v249
	v_mov_b32_e32 v155, v253
	v_mov_b32_e32 v156, v252
	v_mov_b32_e32 v157, v251
	global_store_dwordx4 v[198:199], v[154:157], off
	v_cvt_pk_bf16_f32 v250, v214, v215
	v_cvt_pk_bf16_f32 v253, v212, v213
	v_cvt_pk_bf16_f32 v252, v210, v211
	v_cvt_pk_bf16_f32 v251, v208, v209
	v_mov_b32_e32 v158, v250
	v_mov_b32_e32 v159, v253
	v_mov_b32_e32 v160, v252
	v_mov_b32_e32 v161, v251
	global_store_dwordx4 v[196:197], v[158:161], off
	v_mov_b32_e32 v0, v250
	v_mov_b32_e32 v1, v253
	v_mov_b32_e32 v2, v252
	v_mov_b32_e32 v3, v251
	v_mov_b32_e32 v4, v206
	v_mov_b32_e32 v5, v207
	v_add_u32_e32 v8, 32, v11
	v_mad_i64_i32 v[8:9], s[8:9], v8, s25, v[6:7]
	v_cvt_pk_bf16_f32 v0, v4, v5
	ds_read2_b32 v[252:253], v91 offset0:162 offset1:227
	ds_read2_b32 v[250:251], v10 offset0:36 offset1:101
	ds_read2_b32 v[248:249], v10 offset0:166 offset1:231
	ds_read2_b32 v[246:247], v91 offset0:40 offset1:105
	v_mov_b32_e32 v206, v8
	v_mov_b32_e32 v207, v9
	v_mov_b32_e32 v208, v0
	v_add_u32_e32 v8, 40, v11
	v_mad_i64_i32 v[8:9], s[8:9], v8, s25, v[6:7]
	ds_read2_b32 v[244:245], v91 offset0:170 offset1:235
	ds_read2_b32 v[242:243], v10 offset0:44 offset1:109
	ds_read2_b32 v[240:241], v10 offset0:174 offset1:239
	ds_read2_b32 v[238:239], v91 offset0:48 offset1:113
	v_mov_b32_e32 v204, v8
	v_mov_b32_e32 v205, v9
	v_add_u32_e32 v8, 48, v11
	v_mad_i64_i32 v[8:9], s[8:9], v8, s25, v[6:7]
	ds_read2_b32 v[236:237], v91 offset0:178 offset1:243
	ds_read2_b32 v[234:235], v10 offset0:52 offset1:117
	ds_read2_b32 v[232:233], v10 offset0:182 offset1:247
	ds_read2_b32 v[216:217], v91 offset0:56 offset1:121
	v_mov_b32_e32 v202, v8
	v_mov_b32_e32 v203, v9
	s_nop 0
	ds_read2_b32 v[214:215], v91 offset0:186 offset1:251
	ds_read2_b32 v[212:213], v10 offset0:60 offset1:125
	ds_read2_b32 v[210:211], v10 offset0:190 offset1:255
	v_add_u32_e32 v4, 56, v11
	v_mad_i64_i32 v[4:5], s[8:9], v4, s25, v[6:7]
	v_mov_b32_e32 v200, v4
	v_mov_b32_e32 v201, v5
	s_waitcnt lgkmcnt(0)
	v_cvt_pk_bf16_f32 v209, v252, v253
	v_cvt_pk_bf16_f32 v253, v250, v251
	v_cvt_pk_bf16_f32 v252, v248, v249
	v_mov_b32_e32 v154, v208
	v_mov_b32_e32 v155, v209
	v_mov_b32_e32 v156, v253
	v_mov_b32_e32 v157, v252
	global_store_dwordx4 v[206:207], v[154:157], off
	v_cvt_pk_bf16_f32 v251, v246, v247
	v_cvt_pk_bf16_f32 v253, v244, v245
	v_cvt_pk_bf16_f32 v252, v242, v243
	v_cvt_pk_bf16_f32 v250, v240, v241
	v_mov_b32_e32 v158, v251
	v_mov_b32_e32 v159, v253
	v_mov_b32_e32 v160, v252
	v_mov_b32_e32 v161, v250
	global_store_dwordx4 v[204:205], v[158:161], off
	v_cvt_pk_bf16_f32 v249, v238, v239
	v_cvt_pk_bf16_f32 v253, v236, v237
	v_cvt_pk_bf16_f32 v252, v234, v235
	v_cvt_pk_bf16_f32 v251, v232, v233
	v_mov_b32_e32 v154, v249
	v_mov_b32_e32 v155, v253
	v_mov_b32_e32 v156, v252
	v_mov_b32_e32 v157, v251
	global_store_dwordx4 v[202:203], v[154:157], off
	v_cvt_pk_bf16_f32 v250, v216, v217
	v_cvt_pk_bf16_f32 v253, v214, v215
	v_cvt_pk_bf16_f32 v252, v212, v213
	v_cvt_pk_bf16_f32 v251, v210, v211
	v_mov_b32_e32 v158, v250
	v_mov_b32_e32 v159, v253
	v_mov_b32_e32 v160, v252
	v_mov_b32_e32 v161, v251
	global_store_dwordx4 v[200:201], v[158:161], off
	s_waitcnt lgkmcnt(0)

; #define LAS __attribute__((address_space(3)))
; __device__ __forceinline__ void tr_item(const float* W, int ldw, bf16* WT, int ldt, const float* gain, int dst_row0, int k0, int n0, LAS float* scr, int lane) {
;     ...
;     for (int i = 0; i < 16; ++i) v[i] = __builtin_nontemporal_load((const f32x4*)(W + (size_t)(k0 + kr + 4 * i) * ldw + n0 + n4));
; #pragma unroll
;     for (int i = 0; i < 16; ++i) { const int k = kr + 4 * i; const float g = gain ? gain[k0 + k] : 1.0f; LAS float* d = scr + k * 65 + n4;
;         d[0] = v[i][0] * g; d[1] = v[i][1] * g; d[2] = v[i][2] * g; d[3] = v[i][3] * g; }
; __device__ __forceinline__ void late_up_items(KArgs a, int f, int first, int last, int wi, int nw, LAS float* scr, int lane) {
;     ...
;     for (int idx = first + wi; idx < last; idx += nw) { const int m = idx >= IT_UP ? 1 : 0, item = idx - m * IT_UP;
;         const float* src = (second ? (m ? a->in[I_F2W3] : a->in[I_F2W1]) : (m ? a->in[I_F1W3] : a->in[I_F1W1])) + (size_t)layer * DM * FF;
;         tr_job(src, DM, FF, (bf16*)(a->ws + WS_WUP + (size_t)f * SZ_WUP), (second ? a->in[I_LNF2] : a->in[I_LNF1]) + layer * DM, 1, 128 * m, item, scr, lane); }
.LBB0_246:
	s_addk_i32 s10, 0x2a0
	s_mul_hi_i32 s8, s10, 0x2e8ba2e9
	s_lshr_b32 s9, s8, 31
	s_ashr_i32 s8, s8, 4
	s_add_i32 s8, s8, s9
	s_mul_i32 s9, s8, 0xffffea00
	s_add_i32 s18, s15, s9
	s_mul_i32 s9, s8, 0xffffd400
	s_lshl_b32 s8, s8, 6
	s_ashr_i32 s19, s18, 31
	v_or_b32_e32 v98, s8, v67
	v_lshl_add_u64 v[2:3], s[18:19], 2, v[64:65]
	s_and_b32 s16, s18, 64
	v_mad_i64_i32 v[4:5], s[18:19], v98, s33, v[2:3]
	v_or_b32_e32 v0, 4, v98
	global_load_dwordx4 v[94:97], v[4:5], off nt
	v_mad_i64_i32 v[4:5], s[18:19], v0, s33, v[2:3]
	v_or_b32_e32 v0, 8, v98
	global_load_dwordx4 v[58:61], v[4:5], off nt
	v_mad_i64_i32 v[4:5], s[18:19], v0, s33, v[2:3]
	v_or_b32_e32 v0, 12, v98
	global_load_dwordx4 v[54:57], v[4:5], off nt
	v_mad_i64_i32 v[4:5], s[18:19], v0, s33, v[2:3]
	v_or_b32_e32 v0, 16, v98
	global_load_dwordx4 v[50:53], v[4:5], off nt
	v_mad_i64_i32 v[4:5], s[18:19], v0, s33, v[2:3]
	v_or_b32_e32 v0, 20, v98
	global_load_dwordx4 v[46:49], v[4:5], off nt
	v_mad_i64_i32 v[4:5], s[18:19], v0, s33, v[2:3]
	v_or_b32_e32 v0, 24, v98
	global_load_dwordx4 v[42:45], v[4:5], off nt
	v_mad_i64_i32 v[4:5], s[18:19], v0, s33, v[2:3]
	v_or_b32_e32 v0, 28, v98
	global_load_dwordx4 v[38:41], v[4:5], off nt
	v_mad_i64_i32 v[4:5], s[18:19], v0, s33, v[2:3]
	v_or_b32_e32 v0, 32, v98
	global_load_dwordx4 v[34:37], v[4:5], off nt
	v_mad_i64_i32 v[4:5], s[18:19], v0, s33, v[2:3]
	v_or_b32_e32 v0, 36, v98
	global_load_dwordx4 v[30:33], v[4:5], off nt
	v_mad_i64_i32 v[4:5], s[18:19], v0, s33, v[2:3]
	v_or_b32_e32 v0, 40, v98
	global_load_dwordx4 v[26:29], v[4:5], off nt
	v_mad_i64_i32 v[4:5], s[18:19], v0, s33, v[2:3]
	v_or_b32_e32 v0, 44, v98
	global_load_dwordx4 v[22:25], v[4:5], off nt
	v_mad_i64_i32 v[4:5], s[18:19], v0, s33, v[2:3]
	v_or_b32_e32 v0, 48, v98
	global_load_dwordx4 v[18:21], v[4:5], off nt
	v_mad_i64_i32 v[4:5], s[18:19], v0, s33, v[2:3]
	v_or_b32_e32 v0, 52, v98
	v_ashrrev_i32_e32 v99, 31, v98
	global_load_dwordx4 v[14:17], v[4:5], off nt
	v_mad_i64_i32 v[4:5], s[18:19], v0, s33, v[2:3]
	v_or_b32_e32 v0, 56, v98
	global_load_dwordx4 v[10:13], v[4:5], off nt
	v_mad_i64_i32 v[4:5], s[18:19], v0, s33, v[2:3]
	v_or_b32_e32 v0, 60, v98
	v_lshl_add_u64 v[98:99], v[98:99], 2, s[6:7]
	v_mad_i64_i32 v[2:3], s[18:19], v0, s33, v[2:3]
	global_load_dword v0, v[98:99], off
	v_or_b32_e32 v156, s8, v68
	v_ashrrev_i32_e32 v157, 31, v156
	v_lshl_add_u64 v[156:157], v[156:157], 2, s[6:7]
	global_load_dword v141, v[156:157], off
	v_or_b32_e32 v156, s8, v69
	v_ashrrev_i32_e32 v157, 31, v156
	v_lshl_add_u64 v[156:157], v[156:157], 2, s[6:7]
	global_load_dword v142, v[156:157], off
	v_or_b32_e32 v156, s8, v70
	v_ashrrev_i32_e32 v157, 31, v156
	v_lshl_add_u64 v[156:157], v[156:157], 2, s[6:7]
	global_load_dword v143, v[156:157], off
	v_or_b32_e32 v156, s8, v71
	v_ashrrev_i32_e32 v157, 31, v156
	v_lshl_add_u64 v[156:157], v[156:157], 2, s[6:7]
	global_load_dword v144, v[156:157], off
	v_or_b32_e32 v156, s8, v72
	v_ashrrev_i32_e32 v157, 31, v156
	v_lshl_add_u64 v[156:157], v[156:157], 2, s[6:7]
	global_load_dword v145, v[156:157], off
	v_or_b32_e32 v156, s8, v73
	v_ashrrev_i32_e32 v157, 31, v156
	v_lshl_add_u64 v[156:157], v[156:157], 2, s[6:7]
	global_load_dword v146, v[156:157], off
	v_or_b32_e32 v156, s8, v74
	v_ashrrev_i32_e32 v157, 31, v156
	v_lshl_add_u64 v[156:157], v[156:157], 2, s[6:7]
	global_load_dword v147, v[156:157], off
	v_or_b32_e32 v156, s8, v75
	v_ashrrev_i32_e32 v157, 31, v156
	v_lshl_add_u64 v[156:157], v[156:157], 2, s[6:7]
	global_load_dword v148, v[156:157], off
	v_or_b32_e32 v156, s8, v76
	v_ashrrev_i32_e32 v157, 31, v156
	v_lshl_add_u64 v[156:157], v[156:157], 2, s[6:7]
	global_load_dword v149, v[156:157], off
	v_or_b32_e32 v156, s8, v77
	v_ashrrev_i32_e32 v157, 31, v156
	v_lshl_add_u64 v[156:157], v[156:157], 2, s[6:7]
	global_load_dword v150, v[156:157], off
	v_or_b32_e32 v156, s8, v78
	v_ashrrev_i32_e32 v157, 31, v156
	v_lshl_add_u64 v[156:157], v[156:157], 2, s[6:7]
	global_load_dword v151, v[156:157], off
	v_or_b32_e32 v156, s8, v79
	v_ashrrev_i32_e32 v157, 31, v156
	v_lshl_add_u64 v[156:157], v[156:157], 2, s[6:7]
	global_load_dword v152, v[156:157], off
	v_or_b32_e32 v156, s8, v80
	v_ashrrev_i32_e32 v157, 31, v156
	v_lshl_add_u64 v[156:157], v[156:157], 2, s[6:7]
	global_load_dword v153, v[156:157], off
	v_or_b32_e32 v156, s8, v81
	v_ashrrev_i32_e32 v157, 31, v156
	v_lshl_add_u64 v[156:157], v[156:157], 2, s[6:7]
	global_load_dword v154, v[156:157], off
	v_or_b32_e32 v156, s8, v82
	v_ashrrev_i32_e32 v157, 31, v156
	v_lshl_add_u64 v[156:157], v[156:157], 2, s[6:7]
	global_load_dword v155, v[156:157], off
	v_add_u32_e32 v93, 0x410, v92
	global_load_dwordx4 v[6:9], v[4:5], off nt
	s_add_i32 s9, s11, s9
	global_load_dwordx4 v[2:5], v[2:3], off nt
	s_and_b32 s9, s9, 0xffffff00
	s_or_b32 s16, s9, s16
	s_ashr_i32 s9, s8, 31
	s_add_i32 s11, s11, 0x15000
	s_add_i32 s15, s15, 0xa800
	s_cmpk_lt_i32 s10, 0x4b6
	s_waitcnt vmcnt(2)
	v_pk_mul_f32 v[94:95], v[94:95], v[0:1] op_sel_hi:[1,0]
	ds_write2_b32 v92, v94, v95 offset1:1
	v_pk_mul_f32 v[94:95], v[96:97], v[0:1] op_sel_hi:[1,0]
	ds_write2_b32 v92, v94, v95 offset0:2 offset1:3
	v_or_b32_e32 v94, s8, v68
	v_ashrrev_i32_e32 v95, 31, v94
	v_lshl_add_u64 v[94:95], v[94:95], 2, s[6:7]
	v_mov_b32_e32 v0, v141
	s_waitcnt vmcnt(0)
	v_pk_mul_f32 v[58:59], v[58:59], v[0:1] op_sel_hi:[1,0]
	ds_write2_b32 v93, v58, v59 offset1:1
	v_pk_mul_f32 v[58:59], v[60:61], v[0:1] op_sel_hi:[1,0]
	v_add_u32_e32 v0, 0x418, v92
	ds_write2_b32 v0, v58, v59 offset1:1
	v_or_b32_e32 v58, s8, v69
	v_ashrrev_i32_e32 v59, 31, v58
	v_lshl_add_u64 v[58:59], v[58:59], 2, s[6:7]
	v_mov_b32_e32 v0, v142
	v_add_u32_e32 v58, 0x820, v92
	s_waitcnt vmcnt(0)
; #define LAS __attribute__((address_space(3)))
; __device__ __forceinline__ void tr_item(const float* W, int ldw, bf16* WT, int ldt, const float* gain, int dst_row0, int k0, int n0, LAS float* scr, int lane) {
;     ...
;     for (int i = 0; i < 16; ++i) { const int k = kr + 4 * i; const float g = gain ? gain[k0 + k] : 1.0f; LAS float* d = scr + k * 65 + n4;
;         d[0] = v[i][0] * g; d[1] = v[i][1] * g; d[2] = v[i][2] * g; d[3] = v[i][3] * g; }
	v_pk_mul_f32 v[54:55], v[54:55], v[0:1] op_sel_hi:[1,0]
	ds_write2_b32 v58, v54, v55 offset1:1
	v_pk_mul_f32 v[54:55], v[56:57], v[0:1] op_sel_hi:[1,0]
	v_add_u32_e32 v0, 0x828, v92
	ds_write2_b32 v0, v54, v55 offset1:1
	v_or_b32_e32 v54, s8, v70
	v_ashrrev_i32_e32 v55, 31, v54
	v_lshl_add_u64 v[54:55], v[54:55], 2, s[6:7]
	v_mov_b32_e32 v0, v143
	v_add_u32_e32 v54, 0xc30, v92
	s_waitcnt vmcnt(0)
	v_pk_mul_f32 v[50:51], v[50:51], v[0:1] op_sel_hi:[1,0]
	ds_write2_b32 v54, v50, v51 offset1:1
	v_pk_mul_f32 v[50:51], v[52:53], v[0:1] op_sel_hi:[1,0]
	v_add_u32_e32 v0, 0xc38, v92
	ds_write2_b32 v0, v50, v51 offset1:1
	v_or_b32_e32 v50, s8, v71
	v_ashrrev_i32_e32 v51, 31, v50
	v_lshl_add_u64 v[50:51], v[50:51], 2, s[6:7]
	v_mov_b32_e32 v0, v144
	v_add_u32_e32 v50, 0x1040, v92
	s_waitcnt vmcnt(0)
	v_pk_mul_f32 v[46:47], v[46:47], v[0:1] op_sel_hi:[1,0]
	ds_write2_b32 v50, v46, v47 offset1:1
	v_pk_mul_f32 v[46:47], v[48:49], v[0:1] op_sel_hi:[1,0]
	v_add_u32_e32 v0, 0x1048, v92
	ds_write2_b32 v0, v46, v47 offset1:1
	v_or_b32_e32 v46, s8, v72
	v_ashrrev_i32_e32 v47, 31, v46
	v_lshl_add_u64 v[46:47], v[46:47], 2, s[6:7]
	v_mov_b32_e32 v0, v145
	v_add_u32_e32 v46, 0x1450, v92
	s_waitcnt vmcnt(0)
	v_pk_mul_f32 v[42:43], v[42:43], v[0:1] op_sel_hi:[1,0]
	ds_write2_b32 v46, v42, v43 offset1:1
	v_pk_mul_f32 v[42:43], v[44:45], v[0:1] op_sel_hi:[1,0]
	v_add_u32_e32 v0, 0x1458, v92
	ds_write2_b32 v0, v42, v43 offset1:1
	v_or_b32_e32 v42, s8, v73
	v_ashrrev_i32_e32 v43, 31, v42
	v_lshl_add_u64 v[42:43], v[42:43], 2, s[6:7]
	v_mov_b32_e32 v0, v146
	v_add_u32_e32 v42, 0x1860, v92
	s_waitcnt vmcnt(0)
	v_pk_mul_f32 v[38:39], v[38:39], v[0:1] op_sel_hi:[1,0]
	ds_write2_b32 v42, v38, v39 offset1:1
	v_pk_mul_f32 v[38:39], v[40:41], v[0:1] op_sel_hi:[1,0]
	v_add_u32_e32 v0, 0x1868, v92
	ds_write2_b32 v0, v38, v39 offset1:1
	v_or_b32_e32 v38, s8, v74
	v_ashrrev_i32_e32 v39, 31, v38
	v_lshl_add_u64 v[38:39], v[38:39], 2, s[6:7]
	v_mov_b32_e32 v0, v147
	v_add_u32_e32 v38, 0x1c70, v92
	s_waitcnt vmcnt(0)
	v_pk_mul_f32 v[34:35], v[34:35], v[0:1] op_sel_hi:[1,0]
	ds_write2_b32 v38, v34, v35 offset1:1
	v_pk_mul_f32 v[34:35], v[36:37], v[0:1] op_sel_hi:[1,0]
	v_add_u32_e32 v0, 0x1c78, v92
	ds_write2_b32 v0, v34, v35 offset1:1
	v_or_b32_e32 v34, s8, v75
	v_ashrrev_i32_e32 v35, 31, v34
	v_lshl_add_u64 v[34:35], v[34:35], 2, s[6:7]
	v_mov_b32_e32 v0, v148
	v_add_u32_e32 v34, 0x2080, v92
	s_waitcnt vmcnt(0)
	v_pk_mul_f32 v[30:31], v[30:31], v[0:1] op_sel_hi:[1,0]
	ds_write2_b32 v34, v30, v31 offset1:1
	v_pk_mul_f32 v[30:31], v[32:33], v[0:1] op_sel_hi:[1,0]
	v_add_u32_e32 v0, 0x2088, v92
	ds_write2_b32 v0, v30, v31 offset1:1
	v_or_b32_e32 v30, s8, v76
	v_ashrrev_i32_e32 v31, 31, v30
	v_lshl_add_u64 v[30:31], v[30:31], 2, s[6:7]
	v_mov_b32_e32 v0, v149
	v_add_u32_e32 v30, 0x2490, v92
	s_waitcnt vmcnt(0)
	v_pk_mul_f32 v[26:27], v[26:27], v[0:1] op_sel_hi:[1,0]
	ds_write2_b32 v30, v26, v27 offset1:1
	v_pk_mul_f32 v[26:27], v[28:29], v[0:1] op_sel_hi:[1,0]
	v_add_u32_e32 v0, 0x2498, v92
	ds_write2_b32 v0, v26, v27 offset1:1
	v_or_b32_e32 v26, s8, v77
	v_ashrrev_i32_e32 v27, 31, v26
	v_lshl_add_u64 v[26:27], v[26:27], 2, s[6:7]
	v_mov_b32_e32 v0, v150
	v_add_u32_e32 v26, 0x28a0, v92
	s_waitcnt vmcnt(0)
	v_pk_mul_f32 v[22:23], v[22:23], v[0:1] op_sel_hi:[1,0]
	ds_write2_b32 v26, v22, v23 offset1:1
	v_pk_mul_f32 v[22:23], v[24:25], v[0:1] op_sel_hi:[1,0]
	v_add_u32_e32 v0, 0x28a8, v92
	ds_write2_b32 v0, v22, v23 offset1:1
	v_or_b32_e32 v22, s8, v78
	v_ashrrev_i32_e32 v23, 31, v22
	v_lshl_add_u64 v[22:23], v[22:23], 2, s[6:7]
	v_mov_b32_e32 v0, v151
	v_add_u32_e32 v22, 0x2cb0, v92
	s_waitcnt vmcnt(0)
	v_pk_mul_f32 v[18:19], v[18:19], v[0:1] op_sel_hi:[1,0]
	ds_write2_b32 v22, v18, v19 offset1:1
	v_pk_mul_f32 v[18:19], v[20:21], v[0:1] op_sel_hi:[1,0]
	v_add_u32_e32 v0, 0x2cb8, v92
	ds_write2_b32 v0, v18, v19 offset1:1
	v_or_b32_e32 v18, s8, v79
	v_ashrrev_i32_e32 v19, 31, v18
	v_lshl_add_u64 v[18:19], v[18:19], 2, s[6:7]
	v_mov_b32_e32 v0, v152
	v_add_u32_e32 v18, 0x30c0, v92
	s_waitcnt vmcnt(0)
	v_pk_mul_f32 v[14:15], v[14:15], v[0:1] op_sel_hi:[1,0]
	ds_write2_b32 v18, v14, v15 offset1:1
	v_pk_mul_f32 v[14:15], v[16:17], v[0:1] op_sel_hi:[1,0]
	v_add_u32_e32 v0, 0x30c8, v92
	ds_write2_b32 v0, v14, v15 offset1:1
	v_or_b32_e32 v14, s8, v80
	v_ashrrev_i32_e32 v15, 31, v14
	v_lshl_add_u64 v[14:15], v[14:15], 2, s[6:7]
	v_mov_b32_e32 v0, v153
	v_add_u32_e32 v14, 0x34d0, v92
	s_waitcnt vmcnt(0)
	v_pk_mul_f32 v[10:11], v[10:11], v[0:1] op_sel_hi:[1,0]
	ds_write2_b32 v14, v10, v11 offset1:1
	v_pk_mul_f32 v[10:11], v[12:13], v[0:1] op_sel_hi:[1,0]
	v_add_u32_e32 v0, 0x34d8, v92
	ds_write2_b32 v0, v10, v11 offset1:1
	v_or_b32_e32 v10, s8, v81
	v_ashrrev_i32_e32 v11, 31, v10
	v_lshl_add_u64 v[10:11], v[10:11], 2, s[6:7]
	v_mov_b32_e32 v0, v154
	v_add_u32_e32 v10, 0x38e0, v92
	s_waitcnt vmcnt(0)
	v_pk_mul_f32 v[6:7], v[6:7], v[0:1] op_sel_hi:[1,0]
	ds_write2_b32 v10, v6, v7 offset1:1
	v_pk_mul_f32 v[6:7], v[8:9], v[0:1] op_sel_hi:[1,0]
	v_add_u32_e32 v0, 0x38e8, v92
	ds_write2_b32 v0, v6, v7 offset1:1
	v_or_b32_e32 v6, s8, v82
	v_ashrrev_i32_e32 v7, 31, v6
	v_lshl_add_u64 v[6:7], v[6:7], 2, s[6:7]
	v_mov_b32_e32 v0, v155
	v_add_u32_e32 v6, 0x3cf0, v92
	s_waitcnt vmcnt(0)
	v_pk_mul_f32 v[2:3], v[2:3], v[0:1] op_sel_hi:[1,0]
	ds_write2_b32 v6, v2, v3 offset1:1
	v_pk_mul_f32 v[2:3], v[4:5], v[0:1] op_sel_hi:[1,0]
	v_add_u32_e32 v0, 0x3cf8, v92
	ds_write2_b32 v0, v2, v3 offset1:1
	s_waitcnt lgkmcnt(0)
; #define LAS __attribute__((address_space(3)))
; #define LDS_WAIT() asm volatile("s_waitcnt lgkmcnt(0)" ::: "memory")
; __device__ __forceinline__ unsigned cvtpk(float lo, float hi) { unsigned r; asm volatile("v_cvt_pk_bf16_f32 %0, %1, %2" : "=v"(r) : "v"(lo), "v"(hi)); return r; }
; __device__ __forceinline__ void tr_item(const float* W, int ldw, bf16* WT, int ldt, const float* gain, int dst_row0, int k0, int n0, LAS float* scr, int lane) {
;     ...
;     const int c = lane & 7;
; #pragma unroll
;     for (int j = 0; j < 8; ++j) { const int n = (lane >> 3) + 8 * j; const LAS float* s = scr + (8 * c) * 65 + n;
;         u32x4 o; o.x = cvtpk(s[0 * 65], s[1 * 65]); o.y = cvtpk(s[2 * 65], s[3 * 65]); o.z = cvtpk(s[4 * 65], s[5 * 65]); o.w = cvtpk(s[6 * 65], s[7 * 65]);
;         *(u32x4*)(WT + (size_t)(dst_row0 + n) * ldt + k0 + 8 * c) = o; }
;     LDS_WAIT(); asm volatile("" ::: "memory");
	ds_read2_b32 v[252:253], v84 offset1:65
	ds_read2_b32 v[250:251], v84 offset0:130 offset1:195
	v_add_u32_e32 v0, 0x400, v84
	ds_read2_b32 v[248:249], v0 offset0:4 offset1:69
	ds_read2_b32 v[246:247], v0 offset0:134 offset1:199
	v_or_b32_e32 v8, s16, v83
	v_ashrrev_i32_e32 v9, 31, v8
	v_lshl_add_u64 v[6:7], s[8:9], 1, v[62:63]
	v_lshlrev_b64 v[8:9], 12, v[8:9]
	v_lshl_add_u64 v[8:9], v[6:7], 0, v[8:9]
	v_mov_b32_e32 v156, v8
	v_mov_b32_e32 v157, v9
	ds_read2_b32 v[244:245], v84 offset0:8 offset1:73
	ds_read2_b32 v[242:243], v84 offset0:138 offset1:203
	ds_read2_b32 v[240:241], v0 offset0:12 offset1:77
	ds_read2_b32 v[238:239], v0 offset0:142 offset1:207
	v_or_b32_e32 v8, s16, v85
	v_ashrrev_i32_e32 v9, 31, v8
	v_lshlrev_b64 v[8:9], 12, v[8:9]
	v_lshl_add_u64 v[8:9], v[6:7], 0, v[8:9]
	v_mov_b32_e32 v154, v8
	v_mov_b32_e32 v155, v9
	ds_read2_b32 v[236:237], v84 offset0:16 offset1:81
	ds_read2_b32 v[234:235], v84 offset0:146 offset1:211
	ds_read2_b32 v[232:233], v0 offset0:20 offset1:85
	ds_read2_b32 v[216:217], v0 offset0:150 offset1:215
	v_or_b32_e32 v8, s16, v86
	v_ashrrev_i32_e32 v9, 31, v8
	v_lshlrev_b64 v[8:9], 12, v[8:9]
	v_lshl_add_u64 v[8:9], v[6:7], 0, v[8:9]
	v_mov_b32_e32 v152, v8
	v_mov_b32_e32 v153, v9
	ds_read2_b32 v[214:215], v84 offset0:24 offset1:89
	ds_read2_b32 v[212:213], v84 offset0:154 offset1:219
	ds_read2_b32 v[210:211], v0 offset0:28 offset1:93
	ds_read2_b32 v[208:209], v0 offset0:158 offset1:223
	v_or_b32_e32 v8, s16, v87
	v_ashrrev_i32_e32 v9, 31, v8
	v_lshlrev_b64 v[8:9], 12, v[8:9]
	v_lshl_add_u64 v[8:9], v[6:7], 0, v[8:9]
	v_mov_b32_e32 v150, v8
	v_mov_b32_e32 v151, v9
	ds_read2_b32 v[206:207], v84 offset0:32 offset1:97
	ds_read2_b32 v[204:205], v84 offset0:162 offset1:227
	ds_read2_b32 v[202:203], v0 offset0:36 offset1:101
	ds_read2_b32 v[200:201], v0 offset0:166 offset1:231
	v_or_b32_e32 v8, s16, v88
	v_ashrrev_i32_e32 v9, 31, v8
	v_lshlrev_b64 v[8:9], 12, v[8:9]
	v_lshl_add_u64 v[8:9], v[6:7], 0, v[8:9]
	v_mov_b32_e32 v148, v8
	v_mov_b32_e32 v149, v9
	ds_read2_b32 v[198:199], v84 offset0:40 offset1:105
	ds_read2_b32 v[196:197], v84 offset0:170 offset1:235
	ds_read2_b32 v[194:195], v0 offset0:44 offset1:109
	ds_read2_b32 v[176:177], v0 offset0:174 offset1:239
	v_or_b32_e32 v8, s16, v89
	v_ashrrev_i32_e32 v9, 31, v8
	v_lshlrev_b64 v[8:9], 12, v[8:9]
	v_lshl_add_u64 v[8:9], v[6:7], 0, v[8:9]
	v_mov_b32_e32 v146, v8
	v_mov_b32_e32 v147, v9
	ds_read2_b32 v[174:175], v84 offset0:48 offset1:113
	ds_read2_b32 v[172:173], v84 offset0:178 offset1:243
	ds_read2_b32 v[170:171], v0 offset0:52 offset1:117
	ds_read2_b32 v[168:169], v0 offset0:182 offset1:247
	v_or_b32_e32 v8, s16, v90
	v_ashrrev_i32_e32 v9, 31, v8
	v_lshlrev_b64 v[8:9], 12, v[8:9]
	v_lshl_add_u64 v[8:9], v[6:7], 0, v[8:9]
	v_mov_b32_e32 v144, v8
	v_mov_b32_e32 v145, v9
	ds_read2_b32 v[166:167], v84 offset0:56 offset1:121
	ds_read2_b32 v[164:165], v84 offset0:186 offset1:251
	ds_read2_b32 v[162:163], v0 offset0:60 offset1:125
	ds_read2_b32 v[160:161], v0 offset0:190 offset1:255
	v_or_b32_e32 v8, s16, v91
	v_ashrrev_i32_e32 v9, 31, v8
	v_lshlrev_b64 v[8:9], 12, v[8:9]
	v_lshl_add_u64 v[6:7], v[6:7], 0, v[8:9]
	v_mov_b32_e32 v142, v6
	v_mov_b32_e32 v143, v7
	s_waitcnt lgkmcnt(0)
	v_cvt_pk_bf16_f32 v159, v252, v253
	v_cvt_pk_bf16_f32 v253, v250, v251
	v_cvt_pk_bf16_f32 v252, v248, v249
	v_cvt_pk_bf16_f32 v251, v246, v247
	v_mov_b32_e32 v132, v159
	v_mov_b32_e32 v133, v253
	v_mov_b32_e32 v134, v252
	v_mov_b32_e32 v135, v251
	global_store_dwordx4 v[156:157], v[132:135], off
	v_cvt_pk_bf16_f32 v253, v244, v245
	v_cvt_pk_bf16_f32 v252, v242, v243
	v_cvt_pk_bf16_f32 v251, v240, v241
	v_cvt_pk_bf16_f32 v250, v238, v239
	v_mov_b32_e32 v136, v253
	v_mov_b32_e32 v137, v252
	v_mov_b32_e32 v138, v251
	v_mov_b32_e32 v139, v250
	global_store_dwordx4 v[154:155], v[136:139], off
	v_cvt_pk_bf16_f32 v253, v236, v237
	v_cvt_pk_bf16_f32 v252, v234, v235
	v_cvt_pk_bf16_f32 v251, v232, v233
	v_cvt_pk_bf16_f32 v250, v216, v217
	v_mov_b32_e32 v132, v253
	v_mov_b32_e32 v133, v252
	v_mov_b32_e32 v134, v251
	v_mov_b32_e32 v135, v250
	global_store_dwordx4 v[152:153], v[132:135], off
	v_cvt_pk_bf16_f32 v253, v214, v215
	v_cvt_pk_bf16_f32 v252, v212, v213
	v_cvt_pk_bf16_f32 v251, v210, v211
	v_cvt_pk_bf16_f32 v250, v208, v209
	v_mov_b32_e32 v136, v253
	v_mov_b32_e32 v137, v252
	v_mov_b32_e32 v138, v251
	v_mov_b32_e32 v139, v250
	global_store_dwordx4 v[150:151], v[136:139], off
	v_cvt_pk_bf16_f32 v253, v206, v207
	v_cvt_pk_bf16_f32 v252, v204, v205
	v_cvt_pk_bf16_f32 v251, v202, v203
	v_cvt_pk_bf16_f32 v250, v200, v201
	v_mov_b32_e32 v132, v253
	v_mov_b32_e32 v133, v252
	v_mov_b32_e32 v134, v251
	v_mov_b32_e32 v135, v250
	global_store_dwordx4 v[148:149], v[132:135], off
	v_cvt_pk_bf16_f32 v253, v198, v199
	v_cvt_pk_bf16_f32 v252, v196, v197
	v_cvt_pk_bf16_f32 v251, v194, v195
	v_cvt_pk_bf16_f32 v250, v176, v177
	v_mov_b32_e32 v136, v253
	v_mov_b32_e32 v137, v252
	v_mov_b32_e32 v138, v251
	v_mov_b32_e32 v139, v250
	global_store_dwordx4 v[146:147], v[136:139], off
	v_cvt_pk_bf16_f32 v253, v174, v175
	v_cvt_pk_bf16_f32 v252, v172, v173
	v_cvt_pk_bf16_f32 v251, v170, v171
	v_cvt_pk_bf16_f32 v250, v168, v169
	v_mov_b32_e32 v132, v253
	v_mov_b32_e32 v133, v252
	v_mov_b32_e32 v134, v251
	v_mov_b32_e32 v135, v250
	global_store_dwordx4 v[144:145], v[132:135], off
	v_cvt_pk_bf16_f32 v253, v166, v167
	v_cvt_pk_bf16_f32 v252, v164, v165
	v_cvt_pk_bf16_f32 v251, v162, v163
	v_cvt_pk_bf16_f32 v250, v160, v161
	v_mov_b32_e32 v136, v253
	v_mov_b32_e32 v137, v252
	v_mov_b32_e32 v138, v251
	v_mov_b32_e32 v139, v250
	global_store_dwordx4 v[142:143], v[136:139], off
	s_waitcnt lgkmcnt(0)
	s_cbranch_scc1 .LBB0_246

; #define LAS __attribute__((address_space(3)))
; __device__ __forceinline__ void tr_item(const float* W, int ldw, bf16* WT, int ldt, const float* gain, int dst_row0, int k0, int n0, LAS float* scr, int lane) {
;     ...
;     for (int i = 0; i < 16; ++i) v[i] = __builtin_nontemporal_load((const f32x4*)(W + (size_t)(k0 + kr + 4 * i) * ldw + n0 + n4));
; #pragma unroll
;     for (int i = 0; i < 16; ++i) { const int k = kr + 4 * i; const float g = gain ? gain[k0 + k] : 1.0f; LAS float* d = scr + k * 65 + n4;
;         d[0] = v[i][0] * g; d[1] = v[i][1] * g; d[2] = v[i][2] * g; d[3] = v[i][3] * g; }
.LBB0_249:
	s_addk_i32 s8, 0x2a0
	s_ashr_i32 s6, s8, 31
	s_lshr_b32 s6, s6, 27
	s_add_i32 s6, s8, s6
	s_ashr_i32 s6, s6, 5
	s_lshl_b32 s11, s6, 11
	s_add_i32 s7, s9, s10
	s_lshl_b32 s6, s6, 6
	s_sub_i32 s16, s7, s11
	v_or_b32_e32 v2, s6, v67
	s_ashr_i32 s17, s16, 31
	v_ashrrev_i32_e32 v3, 31, v2
	v_lshl_add_u64 v[4:5], s[16:17], 2, v[62:63]
	v_lshlrev_b64 v[6:7], 13, v[2:3]
	v_lshl_add_u64 v[6:7], v[4:5], 0, v[6:7]
	global_load_dwordx4 v[70:73], v[6:7], off nt
	v_or_b32_e32 v6, 4, v2
	v_ashrrev_i32_e32 v7, 31, v6
	v_lshlrev_b64 v[6:7], 13, v[6:7]
	v_lshl_add_u64 v[6:7], v[4:5], 0, v[6:7]
	global_load_dwordx4 v[58:61], v[6:7], off nt
	v_or_b32_e32 v6, 8, v2
	v_ashrrev_i32_e32 v7, 31, v6
	v_lshlrev_b64 v[6:7], 13, v[6:7]
	v_lshl_add_u64 v[6:7], v[4:5], 0, v[6:7]
	global_load_dwordx4 v[54:57], v[6:7], off nt
	v_or_b32_e32 v6, 12, v2
	v_ashrrev_i32_e32 v7, 31, v6
	v_lshlrev_b64 v[6:7], 13, v[6:7]
	v_lshl_add_u64 v[6:7], v[4:5], 0, v[6:7]
	global_load_dwordx4 v[50:53], v[6:7], off nt
	v_or_b32_e32 v6, 16, v2
	v_ashrrev_i32_e32 v7, 31, v6
	v_lshlrev_b64 v[6:7], 13, v[6:7]
	v_lshl_add_u64 v[6:7], v[4:5], 0, v[6:7]
	global_load_dwordx4 v[46:49], v[6:7], off nt
	v_or_b32_e32 v6, 20, v2
	v_ashrrev_i32_e32 v7, 31, v6
	v_lshlrev_b64 v[6:7], 13, v[6:7]
	v_lshl_add_u64 v[6:7], v[4:5], 0, v[6:7]
	global_load_dwordx4 v[42:45], v[6:7], off nt
	v_or_b32_e32 v6, 24, v2
	v_ashrrev_i32_e32 v7, 31, v6
	v_lshlrev_b64 v[6:7], 13, v[6:7]
	v_lshl_add_u64 v[6:7], v[4:5], 0, v[6:7]
	global_load_dwordx4 v[38:41], v[6:7], off nt
	v_or_b32_e32 v6, 28, v2
	v_ashrrev_i32_e32 v7, 31, v6
	v_lshlrev_b64 v[6:7], 13, v[6:7]
	v_lshl_add_u64 v[6:7], v[4:5], 0, v[6:7]
	global_load_dwordx4 v[34:37], v[6:7], off nt
	v_or_b32_e32 v6, 32, v2
	v_ashrrev_i32_e32 v7, 31, v6
	v_lshlrev_b64 v[6:7], 13, v[6:7]
	v_lshl_add_u64 v[6:7], v[4:5], 0, v[6:7]
	global_load_dwordx4 v[30:33], v[6:7], off nt
	v_or_b32_e32 v6, 36, v2
	v_ashrrev_i32_e32 v7, 31, v6
	v_lshlrev_b64 v[6:7], 13, v[6:7]
	v_lshl_add_u64 v[6:7], v[4:5], 0, v[6:7]
	global_load_dwordx4 v[26:29], v[6:7], off nt
	v_or_b32_e32 v6, 40, v2
	v_ashrrev_i32_e32 v7, 31, v6
	v_lshlrev_b64 v[6:7], 13, v[6:7]
	v_lshl_add_u64 v[6:7], v[4:5], 0, v[6:7]
	global_load_dwordx4 v[22:25], v[6:7], off nt
	v_or_b32_e32 v6, 44, v2
	v_ashrrev_i32_e32 v7, 31, v6
	v_lshlrev_b64 v[6:7], 13, v[6:7]
	v_lshl_add_u64 v[6:7], v[4:5], 0, v[6:7]
	global_load_dwordx4 v[18:21], v[6:7], off nt
	v_or_b32_e32 v6, 48, v2
	v_ashrrev_i32_e32 v7, 31, v6
	v_lshlrev_b64 v[6:7], 13, v[6:7]
	v_lshl_add_u64 v[6:7], v[4:5], 0, v[6:7]
	global_load_dwordx4 v[14:17], v[6:7], off nt
	v_or_b32_e32 v6, 52, v2
	v_ashrrev_i32_e32 v7, 31, v6
	v_lshlrev_b64 v[6:7], 13, v[6:7]
	v_lshl_add_u64 v[6:7], v[4:5], 0, v[6:7]
	global_load_dwordx4 v[10:13], v[6:7], off nt
	v_or_b32_e32 v6, 56, v2
	v_ashrrev_i32_e32 v7, 31, v6
	v_lshlrev_b64 v[6:7], 13, v[6:7]
	v_or_b32_e32 v2, 60, v2
	v_lshl_add_u64 v[6:7], v[4:5], 0, v[6:7]
	v_ashrrev_i32_e32 v3, 31, v2
	global_load_dwordx4 v[6:9], v[6:7], off nt
	v_lshlrev_b64 v[2:3], 13, v[2:3]
	v_lshl_add_u64 v[2:3], v[4:5], 0, v[2:3]
	global_load_dwordx4 v[2:5], v[2:3], off nt
	s_waitcnt vmcnt(15)
	ds_write2_b32 v69, v70, v71 offset1:1
	ds_write2_b32 v69, v72, v73 offset0:2 offset1:3
	v_add_u32_e32 v70, 0x410, v69
	s_ashr_i32 s7, s6, 31
	s_add_i32 s10, s10, 0xa800
	s_waitcnt vmcnt(14)
	ds_write2_b32 v70, v58, v59 offset1:1
	v_add_u32_e32 v58, 0x418, v69
	ds_write2_b32 v58, v60, v61 offset1:1
	v_add_u32_e32 v58, 0x820, v69
	s_waitcnt vmcnt(13)
	ds_write2_b32 v58, v54, v55 offset1:1
	v_add_u32_e32 v54, 0x828, v69
	ds_write2_b32 v54, v56, v57 offset1:1
	v_add_u32_e32 v54, 0xc30, v69
	s_waitcnt vmcnt(12)
	ds_write2_b32 v54, v50, v51 offset1:1
	v_add_u32_e32 v50, 0xc38, v69
	ds_write2_b32 v50, v52, v53 offset1:1
	v_add_u32_e32 v50, 0x1040, v69
	s_waitcnt vmcnt(11)
	ds_write2_b32 v50, v46, v47 offset1:1
	v_add_u32_e32 v46, 0x1048, v69
	ds_write2_b32 v46, v48, v49 offset1:1
	v_add_u32_e32 v46, 0x1450, v69
	s_waitcnt vmcnt(10)
	ds_write2_b32 v46, v42, v43 offset1:1
	v_add_u32_e32 v42, 0x1458, v69
	ds_write2_b32 v42, v44, v45 offset1:1
	v_add_u32_e32 v42, 0x1860, v69
	s_waitcnt vmcnt(9)
	ds_write2_b32 v42, v38, v39 offset1:1
	v_add_u32_e32 v38, 0x1868, v69
	ds_write2_b32 v38, v40, v41 offset1:1
	v_add_u32_e32 v38, 0x1c70, v69
	s_waitcnt vmcnt(8)
	ds_write2_b32 v38, v34, v35 offset1:1
	v_add_u32_e32 v34, 0x1c78, v69
	ds_write2_b32 v34, v36, v37 offset1:1
	v_add_u32_e32 v34, 0x2080, v69
	s_waitcnt vmcnt(7)
	ds_write2_b32 v34, v30, v31 offset1:1
	v_add_u32_e32 v30, 0x2088, v69
	ds_write2_b32 v30, v32, v33 offset1:1
	v_add_u32_e32 v30, 0x2490, v69
	s_waitcnt vmcnt(6)
	ds_write2_b32 v30, v26, v27 offset1:1
	v_add_u32_e32 v26, 0x2498, v69
	ds_write2_b32 v26, v28, v29 offset1:1
	v_add_u32_e32 v26, 0x28a0, v69
	s_waitcnt vmcnt(5)
	ds_write2_b32 v26, v22, v23 offset1:1
	v_add_u32_e32 v22, 0x28a8, v69
	ds_write2_b32 v22, v24, v25 offset1:1
	v_add_u32_e32 v22, 0x2cb0, v69
	s_waitcnt vmcnt(4)
	ds_write2_b32 v22, v18, v19 offset1:1
	v_add_u32_e32 v18, 0x2cb8, v69
	ds_write2_b32 v18, v20, v21 offset1:1
	v_add_u32_e32 v18, 0x30c0, v69
	s_waitcnt vmcnt(3)
	ds_write2_b32 v18, v14, v15 offset1:1
	v_add_u32_e32 v14, 0x30c8, v69
	ds_write2_b32 v14, v16, v17 offset1:1
	v_add_u32_e32 v14, 0x34d0, v69
	s_waitcnt vmcnt(2)
	ds_write2_b32 v14, v10, v11 offset1:1
	v_add_u32_e32 v10, 0x34d8, v69
	ds_write2_b32 v10, v12, v13 offset1:1
	v_add_u32_e32 v10, 0x38e0, v69
	s_waitcnt vmcnt(1)
	ds_write2_b32 v10, v6, v7 offset1:1
	v_add_u32_e32 v6, 0x38e8, v69
	ds_write2_b32 v6, v8, v9 offset1:1
	v_add_u32_e32 v6, 0x3cf0, v69
	s_waitcnt vmcnt(0)
; #define LAS __attribute__((address_space(3)))
; #define LDS_WAIT() asm volatile("s_waitcnt lgkmcnt(0)" ::: "memory")
; __device__ __forceinline__ unsigned cvtpk(float lo, float hi) { unsigned r; asm volatile("v_cvt_pk_bf16_f32 %0, %1, %2" : "=v"(r) : "v"(lo), "v"(hi)); return r; }
; __device__ __forceinline__ void tr_item(const float* W, int ldw, bf16* WT, int ldt, const float* gain, int dst_row0, int k0, int n0, LAS float* scr, int lane) {
;     ...
;     const int c = lane & 7;
; #pragma unroll
;     for (int j = 0; j < 8; ++j) { const int n = (lane >> 3) + 8 * j; const LAS float* s = scr + (8 * c) * 65 + n;
;         u32x4 o; o.x = cvtpk(s[0 * 65], s[1 * 65]); o.y = cvtpk(s[2 * 65], s[3 * 65]); o.z = cvtpk(s[4 * 65], s[5 * 65]); o.w = cvtpk(s[6 * 65], s[7 * 65]);
;         *(u32x4*)(WT + (size_t)(dst_row0 + n) * ldt + k0 + 8 * c) = o; }
;     LDS_WAIT(); asm volatile("" ::: "memory");
	ds_write2_b32 v6, v2, v3 offset1:1
	v_add_u32_e32 v2, 0x3cf8, v69
	ds_write2_b32 v2, v4, v5 offset1:1
	s_waitcnt lgkmcnt(0)
	ds_read2_b32 v[252:253], v0 offset1:65
	ds_read2_b32 v[250:251], v0 offset0:130 offset1:195
	v_add_u32_e32 v8, 0x400, v0
	v_lshl_add_u64 v[6:7], s[6:7], 1, v[64:65]
	ds_read2_b32 v[248:249], v8 offset0:4 offset1:69
	s_sub_i32 s6, s9, s11
	ds_read2_b32 v[246:247], v8 offset0:134 offset1:199
	v_add_u32_e32 v9, s6, v68
	v_add_u32_e32 v10, 0xfffea800, v9
	v_mad_i64_i32 v[10:11], s[6:7], v10, s61, v[6:7]
	v_mov_b32_e32 v156, v10
	v_mov_b32_e32 v157, v11
	ds_read2_b32 v[244:245], v0 offset0:8 offset1:73
	v_add_u32_e32 v68, 0xa800, v68
	ds_read2_b32 v[242:243], v0 offset0:138 offset1:203
	ds_read2_b32 v[240:241], v8 offset0:12 offset1:77
	ds_read2_b32 v[238:239], v8 offset0:142 offset1:207
	v_add_u32_e32 v10, 0xfffea808, v9
	v_mad_i64_i32 v[10:11], s[6:7], v10, s61, v[6:7]
	v_mov_b32_e32 v154, v10
	v_mov_b32_e32 v155, v11
	ds_read2_b32 v[236:237], v0 offset0:16 offset1:81
	s_cmpk_lt_i32 s8, 0x860
	ds_read2_b32 v[234:235], v0 offset0:146 offset1:211
	ds_read2_b32 v[232:233], v8 offset0:20 offset1:85
	ds_read2_b32 v[216:217], v8 offset0:150 offset1:215
	v_add_u32_e32 v10, 0xfffea810, v9
	v_mad_i64_i32 v[10:11], s[6:7], v10, s61, v[6:7]
	v_mov_b32_e32 v152, v10
	v_mov_b32_e32 v153, v11
	ds_read2_b32 v[214:215], v0 offset0:24 offset1:89
	ds_read2_b32 v[212:213], v0 offset0:154 offset1:219
	ds_read2_b32 v[210:211], v8 offset0:28 offset1:93
	ds_read2_b32 v[208:209], v8 offset0:158 offset1:223
	v_add_u32_e32 v10, 0xfffea818, v9
	v_mad_i64_i32 v[10:11], s[6:7], v10, s61, v[6:7]
	v_mov_b32_e32 v150, v10
	v_mov_b32_e32 v151, v11
	ds_read2_b32 v[206:207], v0 offset0:32 offset1:97
	ds_read2_b32 v[204:205], v0 offset0:162 offset1:227
	ds_read2_b32 v[202:203], v8 offset0:36 offset1:101
	ds_read2_b32 v[200:201], v8 offset0:166 offset1:231
	v_add_u32_e32 v10, 0xfffea820, v9
	v_mad_i64_i32 v[10:11], s[6:7], v10, s61, v[6:7]
	v_mov_b32_e32 v148, v10
	v_mov_b32_e32 v149, v11
	ds_read2_b32 v[198:199], v0 offset0:40 offset1:105
	ds_read2_b32 v[196:197], v0 offset0:170 offset1:235
	ds_read2_b32 v[194:195], v8 offset0:44 offset1:109
	ds_read2_b32 v[176:177], v8 offset0:174 offset1:239
	v_add_u32_e32 v10, 0xfffea828, v9
	v_mad_i64_i32 v[10:11], s[6:7], v10, s61, v[6:7]
	v_mov_b32_e32 v146, v10
	v_mov_b32_e32 v147, v11
	ds_read2_b32 v[174:175], v0 offset0:48 offset1:113
	ds_read2_b32 v[172:173], v0 offset0:178 offset1:243
	ds_read2_b32 v[170:171], v8 offset0:52 offset1:117
	ds_read2_b32 v[168:169], v8 offset0:182 offset1:247
	v_add_u32_e32 v10, 0xfffea830, v9
	v_mad_i64_i32 v[10:11], s[6:7], v10, s61, v[6:7]
	v_mov_b32_e32 v144, v10
	v_mov_b32_e32 v145, v11
	ds_read2_b32 v[166:167], v0 offset0:56 offset1:121
	ds_read2_b32 v[164:165], v0 offset0:186 offset1:251
	ds_read2_b32 v[162:163], v8 offset0:60 offset1:125
	ds_read2_b32 v[160:161], v8 offset0:190 offset1:255
	v_add_u32_e32 v8, 0xfffea838, v9
	v_mad_i64_i32 v[6:7], s[6:7], v8, s61, v[6:7]
	v_mov_b32_e32 v142, v6
	v_mov_b32_e32 v143, v7
	s_waitcnt lgkmcnt(0)
	v_cvt_pk_bf16_f32 v159, v252, v253
	v_cvt_pk_bf16_f32 v253, v250, v251
	v_cvt_pk_bf16_f32 v252, v248, v249
	v_cvt_pk_bf16_f32 v251, v246, v247
	v_mov_b32_e32 v132, v159
	v_mov_b32_e32 v133, v253
	v_mov_b32_e32 v134, v252
	v_mov_b32_e32 v135, v251
	global_store_dwordx4 v[156:157], v[132:135], off
	v_cvt_pk_bf16_f32 v253, v244, v245
	v_cvt_pk_bf16_f32 v252, v242, v243
	v_cvt_pk_bf16_f32 v251, v240, v241
	v_cvt_pk_bf16_f32 v250, v238, v239
	v_mov_b32_e32 v136, v253
	v_mov_b32_e32 v137, v252
	v_mov_b32_e32 v138, v251
	v_mov_b32_e32 v139, v250
	global_store_dwordx4 v[154:155], v[136:139], off
	v_cvt_pk_bf16_f32 v253, v236, v237
	v_cvt_pk_bf16_f32 v252, v234, v235
	v_cvt_pk_bf16_f32 v251, v232, v233
	v_cvt_pk_bf16_f32 v250, v216, v217
	v_mov_b32_e32 v132, v253
	v_mov_b32_e32 v133, v252
	v_mov_b32_e32 v134, v251
	v_mov_b32_e32 v135, v250
	global_store_dwordx4 v[152:153], v[132:135], off
	v_cvt_pk_bf16_f32 v253, v214, v215
	v_cvt_pk_bf16_f32 v252, v212, v213
	v_cvt_pk_bf16_f32 v251, v210, v211
	v_cvt_pk_bf16_f32 v250, v208, v209
	v_mov_b32_e32 v136, v253
	v_mov_b32_e32 v137, v252
	v_mov_b32_e32 v138, v251
	v_mov_b32_e32 v139, v250
	global_store_dwordx4 v[150:151], v[136:139], off
	v_cvt_pk_bf16_f32 v253, v206, v207
	v_cvt_pk_bf16_f32 v252, v204, v205
	v_cvt_pk_bf16_f32 v251, v202, v203
	v_cvt_pk_bf16_f32 v250, v200, v201
	v_mov_b32_e32 v132, v253
	v_mov_b32_e32 v133, v252
	v_mov_b32_e32 v134, v251
	v_mov_b32_e32 v135, v250
	global_store_dwordx4 v[148:149], v[132:135], off
	v_cvt_pk_bf16_f32 v253, v198, v199
	v_cvt_pk_bf16_f32 v252, v196, v197
	v_cvt_pk_bf16_f32 v251, v194, v195
	v_cvt_pk_bf16_f32 v250, v176, v177
	v_mov_b32_e32 v136, v253
	v_mov_b32_e32 v137, v252
	v_mov_b32_e32 v138, v251
	v_mov_b32_e32 v139, v250
	global_store_dwordx4 v[146:147], v[136:139], off
	v_cvt_pk_bf16_f32 v253, v174, v175
	v_cvt_pk_bf16_f32 v252, v172, v173
	v_cvt_pk_bf16_f32 v251, v170, v171
	v_cvt_pk_bf16_f32 v250, v168, v169
	v_mov_b32_e32 v132, v253
	v_mov_b32_e32 v133, v252
	v_mov_b32_e32 v134, v251
	v_mov_b32_e32 v135, v250
	global_store_dwordx4 v[144:145], v[132:135], off
	v_cvt_pk_bf16_f32 v253, v166, v167
	v_cvt_pk_bf16_f32 v252, v164, v165
	v_cvt_pk_bf16_f32 v251, v162, v163
	v_cvt_pk_bf16_f32 v250, v160, v161
	v_mov_b32_e32 v136, v253
	v_mov_b32_e32 v137, v252
	v_mov_b32_e32 v138, v251
	v_mov_b32_e32 v139, v250
	global_store_dwordx4 v[142:143], v[136:139], off
	s_waitcnt lgkmcnt(0)
	s_cbranch_scc1 .LBB0_249

; #define LAS __attribute__((address_space(3)))
; __device__ __forceinline__ void tr_item(const float* W, int ldw, bf16* WT, int ldt, const float* gain, int dst_row0, int k0, int n0, LAS float* scr, int lane) {
;     ...
;     for (int i = 0; i < 16; ++i) v[i] = __builtin_nontemporal_load((const f32x4*)(W + (size_t)(k0 + kr + 4 * i) * ldw + n0 + n4));
; #pragma unroll
;     for (int i = 0; i < 16; ++i) { const int k = kr + 4 * i; const float g = gain ? gain[k0 + k] : 1.0f; LAS float* d = scr + k * 65 + n4;
;         d[0] = v[i][0] * g; d[1] = v[i][1] * g; d[2] = v[i][2] * g; d[3] = v[i][3] * g; }
; __device__ __forceinline__ void late_up_items(KArgs a, int f, int first, int last, int wi, int nw, LAS float* scr, int lane) {
;     ...
;     for (int idx = first + wi; idx < last; idx += nw) { const int m = idx >= IT_UP ? 1 : 0, item = idx - m * IT_UP;
;         const float* src = (second ? (m ? a->in[I_F2W3] : a->in[I_F2W1]) : (m ? a->in[I_F1W3] : a->in[I_F1W1])) + (size_t)layer * DM * FF;
;         tr_job(src, DM, FF, (bf16*)(a->ws + WS_WUP + (size_t)f * SZ_WUP), (second ? a->in[I_LNF2] : a->in[I_LNF1]) + layer * DM, 1, 128 * m, item, scr, lane); }
.LBB0_254:
	s_addk_i32 s15, 0x2a0
	s_mul_hi_i32 s10, s15, 0x2e8ba2e9
	s_lshr_b32 s11, s10, 31
	s_ashr_i32 s10, s10, 4
	s_add_i32 s10, s10, s11
	s_mul_i32 s11, s10, 0xffffea00
	s_add_i32 s20, s17, s11
	s_mul_i32 s11, s10, 0xffffd400
	s_lshl_b32 s10, s10, 6
	s_ashr_i32 s21, s20, 31
	v_or_b32_e32 v100, s10, v67
	v_lshl_add_u64 v[2:3], s[20:21], 2, v[64:65]
	s_and_b32 s18, s20, 64
	v_mad_i64_i32 v[4:5], s[20:21], v100, s33, v[2:3]
	v_or_b32_e32 v0, 4, v100
	global_load_dwordx4 v[96:99], v[4:5], off nt
	v_mad_i64_i32 v[4:5], s[20:21], v0, s33, v[2:3]
	v_or_b32_e32 v0, 8, v100
	global_load_dwordx4 v[58:61], v[4:5], off nt
	v_mad_i64_i32 v[4:5], s[20:21], v0, s33, v[2:3]
	v_or_b32_e32 v0, 12, v100
	global_load_dwordx4 v[54:57], v[4:5], off nt
	v_mad_i64_i32 v[4:5], s[20:21], v0, s33, v[2:3]
	v_or_b32_e32 v0, 16, v100
	global_load_dwordx4 v[50:53], v[4:5], off nt
	v_mad_i64_i32 v[4:5], s[20:21], v0, s33, v[2:3]
	v_or_b32_e32 v0, 20, v100
	global_load_dwordx4 v[46:49], v[4:5], off nt
	v_mad_i64_i32 v[4:5], s[20:21], v0, s33, v[2:3]
	v_or_b32_e32 v0, 24, v100
	global_load_dwordx4 v[42:45], v[4:5], off nt
	v_mad_i64_i32 v[4:5], s[20:21], v0, s33, v[2:3]
	v_or_b32_e32 v0, 28, v100
	global_load_dwordx4 v[38:41], v[4:5], off nt
	v_mad_i64_i32 v[4:5], s[20:21], v0, s33, v[2:3]
	v_or_b32_e32 v0, 32, v100
	global_load_dwordx4 v[34:37], v[4:5], off nt
	v_mad_i64_i32 v[4:5], s[20:21], v0, s33, v[2:3]
	v_or_b32_e32 v0, 36, v100
	global_load_dwordx4 v[30:33], v[4:5], off nt
	v_mad_i64_i32 v[4:5], s[20:21], v0, s33, v[2:3]
	v_or_b32_e32 v0, 40, v100
	global_load_dwordx4 v[26:29], v[4:5], off nt
	v_mad_i64_i32 v[4:5], s[20:21], v0, s33, v[2:3]
	v_or_b32_e32 v0, 44, v100
	global_load_dwordx4 v[22:25], v[4:5], off nt
	v_mad_i64_i32 v[4:5], s[20:21], v0, s33, v[2:3]
	v_or_b32_e32 v0, 48, v100
	global_load_dwordx4 v[18:21], v[4:5], off nt
	v_mad_i64_i32 v[4:5], s[20:21], v0, s33, v[2:3]
	v_or_b32_e32 v0, 52, v100
	v_ashrrev_i32_e32 v101, 31, v100
	global_load_dwordx4 v[14:17], v[4:5], off nt
	v_mad_i64_i32 v[4:5], s[20:21], v0, s33, v[2:3]
	v_or_b32_e32 v0, 56, v100
	global_load_dwordx4 v[10:13], v[4:5], off nt
	v_mad_i64_i32 v[4:5], s[20:21], v0, s33, v[2:3]
	v_or_b32_e32 v0, 60, v100
	v_lshl_add_u64 v[100:101], v[100:101], 2, s[8:9]
	v_mad_i64_i32 v[2:3], s[20:21], v0, s33, v[2:3]
	global_load_dword v0, v[100:101], off
	v_or_b32_e32 v156, s10, v69
	v_ashrrev_i32_e32 v157, 31, v156
	v_lshl_add_u64 v[156:157], v[156:157], 2, s[8:9]
	global_load_dword v141, v[156:157], off
	v_or_b32_e32 v156, s10, v70
	v_ashrrev_i32_e32 v157, 31, v156
	v_lshl_add_u64 v[156:157], v[156:157], 2, s[8:9]
	global_load_dword v142, v[156:157], off
	v_or_b32_e32 v156, s10, v71
	v_ashrrev_i32_e32 v157, 31, v156
	v_lshl_add_u64 v[156:157], v[156:157], 2, s[8:9]
	global_load_dword v143, v[156:157], off
	v_or_b32_e32 v156, s10, v72
	v_ashrrev_i32_e32 v157, 31, v156
	v_lshl_add_u64 v[156:157], v[156:157], 2, s[8:9]
	global_load_dword v144, v[156:157], off
	v_or_b32_e32 v156, s10, v73
	v_ashrrev_i32_e32 v157, 31, v156
	v_lshl_add_u64 v[156:157], v[156:157], 2, s[8:9]
	global_load_dword v145, v[156:157], off
	v_or_b32_e32 v156, s10, v74
	v_ashrrev_i32_e32 v157, 31, v156
	v_lshl_add_u64 v[156:157], v[156:157], 2, s[8:9]
	global_load_dword v146, v[156:157], off
	v_or_b32_e32 v156, s10, v75
	v_ashrrev_i32_e32 v157, 31, v156
	v_lshl_add_u64 v[156:157], v[156:157], 2, s[8:9]
	global_load_dword v147, v[156:157], off
	v_or_b32_e32 v156, s10, v76
	v_ashrrev_i32_e32 v157, 31, v156
	v_lshl_add_u64 v[156:157], v[156:157], 2, s[8:9]
	global_load_dword v148, v[156:157], off
	v_or_b32_e32 v156, s10, v77
	v_ashrrev_i32_e32 v157, 31, v156
	v_lshl_add_u64 v[156:157], v[156:157], 2, s[8:9]
	global_load_dword v149, v[156:157], off
	v_or_b32_e32 v156, s10, v78
	v_ashrrev_i32_e32 v157, 31, v156
	v_lshl_add_u64 v[156:157], v[156:157], 2, s[8:9]
	global_load_dword v150, v[156:157], off
	v_or_b32_e32 v156, s10, v79
	v_ashrrev_i32_e32 v157, 31, v156
	v_lshl_add_u64 v[156:157], v[156:157], 2, s[8:9]
	global_load_dword v151, v[156:157], off
	v_or_b32_e32 v156, s10, v80
	v_ashrrev_i32_e32 v157, 31, v156
	v_lshl_add_u64 v[156:157], v[156:157], 2, s[8:9]
	global_load_dword v152, v[156:157], off
	v_or_b32_e32 v156, s10, v81
	v_ashrrev_i32_e32 v157, 31, v156
	v_lshl_add_u64 v[156:157], v[156:157], 2, s[8:9]
	global_load_dword v153, v[156:157], off
	v_or_b32_e32 v156, s10, v82
	v_ashrrev_i32_e32 v157, 31, v156
	v_lshl_add_u64 v[156:157], v[156:157], 2, s[8:9]
	global_load_dword v154, v[156:157], off
	v_or_b32_e32 v156, s10, v83
	v_ashrrev_i32_e32 v157, 31, v156
	v_lshl_add_u64 v[156:157], v[156:157], 2, s[8:9]
	global_load_dword v155, v[156:157], off
	global_load_dwordx4 v[6:9], v[4:5], off nt
	s_add_i32 s11, s16, s11
	global_load_dwordx4 v[2:5], v[2:3], off nt
	s_and_b32 s11, s11, 0xffffff00
	s_or_b32 s18, s11, s18
	s_ashr_i32 s11, s10, 31
	s_add_i32 s16, s16, 0x15000
	s_add_i32 s17, s17, 0xa800
	s_cmpk_lt_i32 s15, 0x860
	s_waitcnt vmcnt(2)
	v_pk_mul_f32 v[96:97], v[96:97], v[0:1] op_sel_hi:[1,0]
	ds_write2_b32 v95, v96, v97 offset1:1
	v_pk_mul_f32 v[96:97], v[98:99], v[0:1] op_sel_hi:[1,0]
	ds_write2_b32 v95, v96, v97 offset0:2 offset1:3
	v_or_b32_e32 v96, s10, v69
	v_ashrrev_i32_e32 v97, 31, v96
	v_lshl_add_u64 v[96:97], v[96:97], 2, s[8:9]
	v_mov_b32_e32 v0, v141
	v_add_u32_e32 v96, 0x410, v95
	s_waitcnt vmcnt(0)
	v_pk_mul_f32 v[58:59], v[58:59], v[0:1] op_sel_hi:[1,0]
	ds_write2_b32 v96, v58, v59 offset1:1
	v_pk_mul_f32 v[58:59], v[60:61], v[0:1] op_sel_hi:[1,0]
	v_add_u32_e32 v0, 0x418, v95
	ds_write2_b32 v0, v58, v59 offset1:1
	v_or_b32_e32 v58, s10, v70
	v_ashrrev_i32_e32 v59, 31, v58
	v_lshl_add_u64 v[58:59], v[58:59], 2, s[8:9]
	v_mov_b32_e32 v0, v142
	v_add_u32_e32 v58, 0x820, v95
	s_waitcnt vmcnt(0)
; #define LAS __attribute__((address_space(3)))
; __device__ __forceinline__ void tr_item(const float* W, int ldw, bf16* WT, int ldt, const float* gain, int dst_row0, int k0, int n0, LAS float* scr, int lane) {
;     ...
;     for (int i = 0; i < 16; ++i) { const int k = kr + 4 * i; const float g = gain ? gain[k0 + k] : 1.0f; LAS float* d = scr + k * 65 + n4;
;         d[0] = v[i][0] * g; d[1] = v[i][1] * g; d[2] = v[i][2] * g; d[3] = v[i][3] * g; }
	v_pk_mul_f32 v[54:55], v[54:55], v[0:1] op_sel_hi:[1,0]
	ds_write2_b32 v58, v54, v55 offset1:1
	v_pk_mul_f32 v[54:55], v[56:57], v[0:1] op_sel_hi:[1,0]
	v_add_u32_e32 v0, 0x828, v95
	ds_write2_b32 v0, v54, v55 offset1:1
	v_or_b32_e32 v54, s10, v71
	v_ashrrev_i32_e32 v55, 31, v54
	v_lshl_add_u64 v[54:55], v[54:55], 2, s[8:9]
	v_mov_b32_e32 v0, v143
	v_add_u32_e32 v54, 0xc30, v95
	s_waitcnt vmcnt(0)
	v_pk_mul_f32 v[50:51], v[50:51], v[0:1] op_sel_hi:[1,0]
	ds_write2_b32 v54, v50, v51 offset1:1
	v_pk_mul_f32 v[50:51], v[52:53], v[0:1] op_sel_hi:[1,0]
	v_add_u32_e32 v0, 0xc38, v95
	ds_write2_b32 v0, v50, v51 offset1:1
	v_or_b32_e32 v50, s10, v72
	v_ashrrev_i32_e32 v51, 31, v50
	v_lshl_add_u64 v[50:51], v[50:51], 2, s[8:9]
	v_mov_b32_e32 v0, v144
	v_add_u32_e32 v50, 0x1040, v95
	s_waitcnt vmcnt(0)
	v_pk_mul_f32 v[46:47], v[46:47], v[0:1] op_sel_hi:[1,0]
	ds_write2_b32 v50, v46, v47 offset1:1
	v_pk_mul_f32 v[46:47], v[48:49], v[0:1] op_sel_hi:[1,0]
	v_add_u32_e32 v0, 0x1048, v95
	ds_write2_b32 v0, v46, v47 offset1:1
	v_or_b32_e32 v46, s10, v73
	v_ashrrev_i32_e32 v47, 31, v46
	v_lshl_add_u64 v[46:47], v[46:47], 2, s[8:9]
	v_mov_b32_e32 v0, v145
	v_add_u32_e32 v46, 0x1450, v95
	s_waitcnt vmcnt(0)
	v_pk_mul_f32 v[42:43], v[42:43], v[0:1] op_sel_hi:[1,0]
	ds_write2_b32 v46, v42, v43 offset1:1
	v_pk_mul_f32 v[42:43], v[44:45], v[0:1] op_sel_hi:[1,0]
	v_add_u32_e32 v0, 0x1458, v95
	ds_write2_b32 v0, v42, v43 offset1:1
	v_or_b32_e32 v42, s10, v74
	v_ashrrev_i32_e32 v43, 31, v42
	v_lshl_add_u64 v[42:43], v[42:43], 2, s[8:9]
	v_mov_b32_e32 v0, v146
	v_add_u32_e32 v42, 0x1860, v95
	s_waitcnt vmcnt(0)
	v_pk_mul_f32 v[38:39], v[38:39], v[0:1] op_sel_hi:[1,0]
	ds_write2_b32 v42, v38, v39 offset1:1
	v_pk_mul_f32 v[38:39], v[40:41], v[0:1] op_sel_hi:[1,0]
	v_add_u32_e32 v0, 0x1868, v95
	ds_write2_b32 v0, v38, v39 offset1:1
	v_or_b32_e32 v38, s10, v75
	v_ashrrev_i32_e32 v39, 31, v38
	v_lshl_add_u64 v[38:39], v[38:39], 2, s[8:9]
	v_mov_b32_e32 v0, v147
	v_add_u32_e32 v38, 0x1c70, v95
	s_waitcnt vmcnt(0)
	v_pk_mul_f32 v[34:35], v[34:35], v[0:1] op_sel_hi:[1,0]
	ds_write2_b32 v38, v34, v35 offset1:1
	v_pk_mul_f32 v[34:35], v[36:37], v[0:1] op_sel_hi:[1,0]
	v_add_u32_e32 v0, 0x1c78, v95
	ds_write2_b32 v0, v34, v35 offset1:1
	v_or_b32_e32 v34, s10, v76
	v_ashrrev_i32_e32 v35, 31, v34
	v_lshl_add_u64 v[34:35], v[34:35], 2, s[8:9]
	v_mov_b32_e32 v0, v148
	v_add_u32_e32 v34, 0x2080, v95
	s_waitcnt vmcnt(0)
	v_pk_mul_f32 v[30:31], v[30:31], v[0:1] op_sel_hi:[1,0]
	ds_write2_b32 v34, v30, v31 offset1:1
	v_pk_mul_f32 v[30:31], v[32:33], v[0:1] op_sel_hi:[1,0]
	v_add_u32_e32 v0, 0x2088, v95
	ds_write2_b32 v0, v30, v31 offset1:1
	v_or_b32_e32 v30, s10, v77
	v_ashrrev_i32_e32 v31, 31, v30
	v_lshl_add_u64 v[30:31], v[30:31], 2, s[8:9]
	v_mov_b32_e32 v0, v149
	v_add_u32_e32 v30, 0x2490, v95
	s_waitcnt vmcnt(0)
	v_pk_mul_f32 v[26:27], v[26:27], v[0:1] op_sel_hi:[1,0]
	ds_write2_b32 v30, v26, v27 offset1:1
	v_pk_mul_f32 v[26:27], v[28:29], v[0:1] op_sel_hi:[1,0]
	v_add_u32_e32 v0, 0x2498, v95
	ds_write2_b32 v0, v26, v27 offset1:1
	v_or_b32_e32 v26, s10, v78
	v_ashrrev_i32_e32 v27, 31, v26
	v_lshl_add_u64 v[26:27], v[26:27], 2, s[8:9]
	v_mov_b32_e32 v0, v150
	v_add_u32_e32 v26, 0x28a0, v95
	s_waitcnt vmcnt(0)
	v_pk_mul_f32 v[22:23], v[22:23], v[0:1] op_sel_hi:[1,0]
	ds_write2_b32 v26, v22, v23 offset1:1
	v_pk_mul_f32 v[22:23], v[24:25], v[0:1] op_sel_hi:[1,0]
	v_add_u32_e32 v0, 0x28a8, v95
	ds_write2_b32 v0, v22, v23 offset1:1
	v_or_b32_e32 v22, s10, v79
	v_ashrrev_i32_e32 v23, 31, v22
	v_lshl_add_u64 v[22:23], v[22:23], 2, s[8:9]
	v_mov_b32_e32 v0, v151
	v_add_u32_e32 v22, 0x2cb0, v95
	s_waitcnt vmcnt(0)
	v_pk_mul_f32 v[18:19], v[18:19], v[0:1] op_sel_hi:[1,0]
	ds_write2_b32 v22, v18, v19 offset1:1
	v_pk_mul_f32 v[18:19], v[20:21], v[0:1] op_sel_hi:[1,0]
	v_add_u32_e32 v0, 0x2cb8, v95
	ds_write2_b32 v0, v18, v19 offset1:1
	v_or_b32_e32 v18, s10, v80
	v_ashrrev_i32_e32 v19, 31, v18
	v_lshl_add_u64 v[18:19], v[18:19], 2, s[8:9]
	v_mov_b32_e32 v0, v152
	v_add_u32_e32 v18, 0x30c0, v95
	s_waitcnt vmcnt(0)
	v_pk_mul_f32 v[14:15], v[14:15], v[0:1] op_sel_hi:[1,0]
	ds_write2_b32 v18, v14, v15 offset1:1
	v_pk_mul_f32 v[14:15], v[16:17], v[0:1] op_sel_hi:[1,0]
	v_add_u32_e32 v0, 0x30c8, v95
	ds_write2_b32 v0, v14, v15 offset1:1
	v_or_b32_e32 v14, s10, v81
	v_ashrrev_i32_e32 v15, 31, v14
	v_lshl_add_u64 v[14:15], v[14:15], 2, s[8:9]
	v_mov_b32_e32 v0, v153
	v_add_u32_e32 v14, 0x34d0, v95
	s_waitcnt vmcnt(0)
	v_pk_mul_f32 v[10:11], v[10:11], v[0:1] op_sel_hi:[1,0]
	ds_write2_b32 v14, v10, v11 offset1:1
	v_pk_mul_f32 v[10:11], v[12:13], v[0:1] op_sel_hi:[1,0]
	v_add_u32_e32 v0, 0x34d8, v95
	ds_write2_b32 v0, v10, v11 offset1:1
	v_or_b32_e32 v10, s10, v82
	v_ashrrev_i32_e32 v11, 31, v10
	v_lshl_add_u64 v[10:11], v[10:11], 2, s[8:9]
	v_mov_b32_e32 v0, v154
	v_add_u32_e32 v10, 0x38e0, v95
	s_waitcnt vmcnt(0)
	v_pk_mul_f32 v[6:7], v[6:7], v[0:1] op_sel_hi:[1,0]
	ds_write2_b32 v10, v6, v7 offset1:1
	v_pk_mul_f32 v[6:7], v[8:9], v[0:1] op_sel_hi:[1,0]
	v_add_u32_e32 v0, 0x38e8, v95
	ds_write2_b32 v0, v6, v7 offset1:1
	v_or_b32_e32 v6, s10, v83
	v_ashrrev_i32_e32 v7, 31, v6
	v_lshl_add_u64 v[6:7], v[6:7], 2, s[8:9]
	v_mov_b32_e32 v0, v155
	v_add_u32_e32 v6, 0x3cf0, v95
	s_waitcnt vmcnt(0)
	v_pk_mul_f32 v[2:3], v[2:3], v[0:1] op_sel_hi:[1,0]
	ds_write2_b32 v6, v2, v3 offset1:1
	v_pk_mul_f32 v[2:3], v[4:5], v[0:1] op_sel_hi:[1,0]
	v_add_u32_e32 v0, 0x3cf8, v95
	ds_write2_b32 v0, v2, v3 offset1:1
	s_waitcnt lgkmcnt(0)
; #define LAS __attribute__((address_space(3)))
; #define LDS_WAIT() asm volatile("s_waitcnt lgkmcnt(0)" ::: "memory")
; __device__ __forceinline__ unsigned cvtpk(float lo, float hi) { unsigned r; asm volatile("v_cvt_pk_bf16_f32 %0, %1, %2" : "=v"(r) : "v"(lo), "v"(hi)); return r; }
; __device__ __forceinline__ void tr_item(const float* W, int ldw, bf16* WT, int ldt, const float* gain, int dst_row0, int k0, int n0, LAS float* scr, int lane) {
;     ...
;     const int c = lane & 7;
; #pragma unroll
;     for (int j = 0; j < 8; ++j) { const int n = (lane >> 3) + 8 * j; const LAS float* s = scr + (8 * c) * 65 + n;
;         u32x4 o; o.x = cvtpk(s[0 * 65], s[1 * 65]); o.y = cvtpk(s[2 * 65], s[3 * 65]); o.z = cvtpk(s[4 * 65], s[5 * 65]); o.w = cvtpk(s[6 * 65], s[7 * 65]);
;         *(u32x4*)(WT + (size_t)(dst_row0 + n) * ldt + k0 + 8 * c) = o; }
;     LDS_WAIT(); asm volatile("" ::: "memory");
	ds_read2_b32 v[252:253], v87 offset1:65
	ds_read2_b32 v[250:251], v87 offset0:130 offset1:195
	v_add_u32_e32 v0, 0x400, v87
	ds_read2_b32 v[248:249], v0 offset0:4 offset1:69
	ds_read2_b32 v[246:247], v0 offset0:134 offset1:199
	v_or_b32_e32 v8, s18, v68
	v_ashrrev_i32_e32 v9, 31, v8
	v_lshl_add_u64 v[6:7], s[10:11], 1, v[62:63]
	v_lshlrev_b64 v[8:9], 12, v[8:9]
	v_lshl_add_u64 v[8:9], v[6:7], 0, v[8:9]
	v_mov_b32_e32 v156, v8
	v_mov_b32_e32 v157, v9
	ds_read2_b32 v[244:245], v87 offset0:8 offset1:73
	ds_read2_b32 v[242:243], v87 offset0:138 offset1:203
	ds_read2_b32 v[240:241], v0 offset0:12 offset1:77
	ds_read2_b32 v[238:239], v0 offset0:142 offset1:207
	v_or_b32_e32 v8, s18, v88
	v_ashrrev_i32_e32 v9, 31, v8
	v_lshlrev_b64 v[8:9], 12, v[8:9]
	v_lshl_add_u64 v[8:9], v[6:7], 0, v[8:9]
	v_mov_b32_e32 v154, v8
	v_mov_b32_e32 v155, v9
	ds_read2_b32 v[236:237], v87 offset0:16 offset1:81
	ds_read2_b32 v[234:235], v87 offset0:146 offset1:211
	ds_read2_b32 v[232:233], v0 offset0:20 offset1:85
	ds_read2_b32 v[216:217], v0 offset0:150 offset1:215
	v_or_b32_e32 v8, s18, v89
	v_ashrrev_i32_e32 v9, 31, v8
	v_lshlrev_b64 v[8:9], 12, v[8:9]
	v_lshl_add_u64 v[8:9], v[6:7], 0, v[8:9]
	v_mov_b32_e32 v152, v8
	v_mov_b32_e32 v153, v9
	ds_read2_b32 v[214:215], v87 offset0:24 offset1:89
	ds_read2_b32 v[212:213], v87 offset0:154 offset1:219
	ds_read2_b32 v[210:211], v0 offset0:28 offset1:93
	ds_read2_b32 v[208:209], v0 offset0:158 offset1:223
	v_or_b32_e32 v8, s18, v90
	v_ashrrev_i32_e32 v9, 31, v8
	v_lshlrev_b64 v[8:9], 12, v[8:9]
	v_lshl_add_u64 v[8:9], v[6:7], 0, v[8:9]
	v_mov_b32_e32 v150, v8
	v_mov_b32_e32 v151, v9
	ds_read2_b32 v[206:207], v87 offset0:32 offset1:97
	ds_read2_b32 v[204:205], v87 offset0:162 offset1:227
	ds_read2_b32 v[202:203], v0 offset0:36 offset1:101
	ds_read2_b32 v[200:201], v0 offset0:166 offset1:231
	v_or_b32_e32 v8, s18, v91
	v_ashrrev_i32_e32 v9, 31, v8
	v_lshlrev_b64 v[8:9], 12, v[8:9]
	v_lshl_add_u64 v[8:9], v[6:7], 0, v[8:9]
	v_mov_b32_e32 v148, v8
	v_mov_b32_e32 v149, v9
	ds_read2_b32 v[198:199], v87 offset0:40 offset1:105
	ds_read2_b32 v[196:197], v87 offset0:170 offset1:235
	ds_read2_b32 v[194:195], v0 offset0:44 offset1:109
	ds_read2_b32 v[176:177], v0 offset0:174 offset1:239
	v_or_b32_e32 v8, s18, v92
	v_ashrrev_i32_e32 v9, 31, v8
	v_lshlrev_b64 v[8:9], 12, v[8:9]
	v_lshl_add_u64 v[8:9], v[6:7], 0, v[8:9]
	v_mov_b32_e32 v146, v8
	v_mov_b32_e32 v147, v9
	ds_read2_b32 v[174:175], v87 offset0:48 offset1:113
	ds_read2_b32 v[172:173], v87 offset0:178 offset1:243
	ds_read2_b32 v[170:171], v0 offset0:52 offset1:117
	ds_read2_b32 v[168:169], v0 offset0:182 offset1:247
	v_or_b32_e32 v8, s18, v93
	v_ashrrev_i32_e32 v9, 31, v8
	v_lshlrev_b64 v[8:9], 12, v[8:9]
	v_lshl_add_u64 v[8:9], v[6:7], 0, v[8:9]
	v_mov_b32_e32 v144, v8
	v_mov_b32_e32 v145, v9
	ds_read2_b32 v[166:167], v87 offset0:56 offset1:121
	ds_read2_b32 v[164:165], v87 offset0:186 offset1:251
	ds_read2_b32 v[162:163], v0 offset0:60 offset1:125
	ds_read2_b32 v[160:161], v0 offset0:190 offset1:255
	v_or_b32_e32 v8, s18, v94
	v_ashrrev_i32_e32 v9, 31, v8
	v_lshlrev_b64 v[8:9], 12, v[8:9]
	v_lshl_add_u64 v[6:7], v[6:7], 0, v[8:9]
	v_mov_b32_e32 v142, v6
	v_mov_b32_e32 v143, v7
	s_waitcnt lgkmcnt(0)
	v_cvt_pk_bf16_f32 v159, v252, v253
	v_cvt_pk_bf16_f32 v253, v250, v251
	v_cvt_pk_bf16_f32 v252, v248, v249
	v_cvt_pk_bf16_f32 v251, v246, v247
	v_mov_b32_e32 v132, v159
	v_mov_b32_e32 v133, v253
	v_mov_b32_e32 v134, v252
	v_mov_b32_e32 v135, v251
	global_store_dwordx4 v[156:157], v[132:135], off
	v_cvt_pk_bf16_f32 v253, v244, v245
	v_cvt_pk_bf16_f32 v252, v242, v243
	v_cvt_pk_bf16_f32 v251, v240, v241
	v_cvt_pk_bf16_f32 v250, v238, v239
	v_mov_b32_e32 v136, v253
	v_mov_b32_e32 v137, v252
	v_mov_b32_e32 v138, v251
	v_mov_b32_e32 v139, v250
	global_store_dwordx4 v[154:155], v[136:139], off
	v_cvt_pk_bf16_f32 v253, v236, v237
	v_cvt_pk_bf16_f32 v252, v234, v235
	v_cvt_pk_bf16_f32 v251, v232, v233
	v_cvt_pk_bf16_f32 v250, v216, v217
	v_mov_b32_e32 v132, v253
	v_mov_b32_e32 v133, v252
	v_mov_b32_e32 v134, v251
	v_mov_b32_e32 v135, v250
	global_store_dwordx4 v[152:153], v[132:135], off
	v_cvt_pk_bf16_f32 v253, v214, v215
	v_cvt_pk_bf16_f32 v252, v212, v213
	v_cvt_pk_bf16_f32 v251, v210, v211
	v_cvt_pk_bf16_f32 v250, v208, v209
	v_mov_b32_e32 v136, v253
	v_mov_b32_e32 v137, v252
	v_mov_b32_e32 v138, v251
	v_mov_b32_e32 v139, v250
	global_store_dwordx4 v[150:151], v[136:139], off
	v_cvt_pk_bf16_f32 v253, v206, v207
	v_cvt_pk_bf16_f32 v252, v204, v205
	v_cvt_pk_bf16_f32 v251, v202, v203
	v_cvt_pk_bf16_f32 v250, v200, v201
	v_mov_b32_e32 v132, v253
	v_mov_b32_e32 v133, v252
	v_mov_b32_e32 v134, v251
	v_mov_b32_e32 v135, v250
	global_store_dwordx4 v[148:149], v[132:135], off
	v_cvt_pk_bf16_f32 v253, v198, v199
	v_cvt_pk_bf16_f32 v252, v196, v197
	v_cvt_pk_bf16_f32 v251, v194, v195
	v_cvt_pk_bf16_f32 v250, v176, v177
	v_mov_b32_e32 v136, v253
	v_mov_b32_e32 v137, v252
	v_mov_b32_e32 v138, v251
	v_mov_b32_e32 v139, v250
	global_store_dwordx4 v[146:147], v[136:139], off
	v_cvt_pk_bf16_f32 v253, v174, v175
	v_cvt_pk_bf16_f32 v252, v172, v173
	v_cvt_pk_bf16_f32 v251, v170, v171
	v_cvt_pk_bf16_f32 v250, v168, v169
	v_mov_b32_e32 v132, v253
	v_mov_b32_e32 v133, v252
	v_mov_b32_e32 v134, v251
	v_mov_b32_e32 v135, v250
	global_store_dwordx4 v[144:145], v[132:135], off
	v_cvt_pk_bf16_f32 v253, v166, v167
	v_cvt_pk_bf16_f32 v252, v164, v165
	v_cvt_pk_bf16_f32 v251, v162, v163
	v_cvt_pk_bf16_f32 v250, v160, v161
	v_mov_b32_e32 v136, v253
	v_mov_b32_e32 v137, v252
	v_mov_b32_e32 v138, v251
	v_mov_b32_e32 v139, v250
	global_store_dwordx4 v[142:143], v[136:139], off
	s_waitcnt lgkmcnt(0)
	s_cbranch_scc1 .LBB0_254

; #define LAS __attribute__((address_space(3)))
; __device__ __forceinline__ void tr_item(const float* W, int ldw, bf16* WT, int ldt, const float* gain, int dst_row0, int k0, int n0, LAS float* scr, int lane) {
;     ...
;     for (int i = 0; i < 16; ++i) v[i] = __builtin_nontemporal_load((const f32x4*)(W + (size_t)(k0 + kr + 4 * i) * ldw + n0 + n4));
; #pragma unroll
;     for (int i = 0; i < 16; ++i) { const int k = kr + 4 * i; const float g = gain ? gain[k0 + k] : 1.0f; LAS float* d = scr + k * 65 + n4;
;         d[0] = v[i][0] * g; d[1] = v[i][1] * g; d[2] = v[i][2] * g; d[3] = v[i][3] * g; }
; __device__ __forceinline__ void late_convert(KArgs a, LAS unsigned char* lds, int set, int wi, int nw, int wave, int lane) {
;     ...
;             else tr_job(a->in[I_GV], DM, DM, (bf16*)(a->ws + WS_WQKVR), gm, 0, 2048, idx - IT_SQ, scr, lane); }
.LBB0_260:
	s_lshr_b32 s12, s10, 5
	s_lshl_b32 s8, s12, 11
	s_load_dwordx2 s[14:15], s[4:5], 0xd0
	s_sub_i32 s8, s2, s8
	s_add_i32 s8, s8, 0xfffda800
	s_ashr_i32 s9, s8, 31
	s_lshl_b32 s13, s12, 6
	s_lshl_b64 s[16:17], s[8:9], 2
	s_waitcnt lgkmcnt(0)
	s_add_u32 s14, s14, s16
	v_or_b32_e32 v130, s13, v67
	s_addc_u32 s15, s15, s17
	v_mov_b32_e32 v131, v1
	v_lshl_add_u64 v[2:3], s[14:15], 0, v[0:1]
	v_lshlrev_b64 v[4:5], 13, v[130:131]
	v_lshl_add_u64 v[4:5], v[2:3], 0, v[4:5]
	global_load_dwordx4 v[132:135], v[4:5], off nt
	v_lshlrev_b32_e32 v4, 11, v130
	v_lshl_add_u64 v[130:131], v[130:131], 2, s[6:7]
	global_load_dword v253, v[130:131], off
	v_mov_b32_e32 v5, v1
	v_lshl_add_u64 v[2:3], v[4:5], 2, v[2:3]
	s_mov_b32 s9, 0x8000
	v_add_co_u32_e32 v4, vcc, s9, v2
	s_mov_b32 s9, 0x10000
	s_nop 0
	v_addc_co_u32_e32 v5, vcc, 0, v3, vcc
	global_load_dwordx4 v[136:139], v[4:5], off nt
	v_add_co_u32_e32 v4, vcc, s9, v2
	s_lshl_b32 s48, s12, 7
	s_nop 0
	v_addc_co_u32_e32 v5, vcc, 0, v3, vcc
	global_load_dwordx4 v[140:143], v[4:5], off nt
	v_add_co_u32_e32 v4, vcc, s18, v2
	v_mov_b32_e32 v246, v131
	v_or_b32_e32 v102, s13, v69
	v_mov_b32_e32 v103, v1
	v_lshl_add_u64 v[102:103], v[102:103], 2, s[6:7]
	global_load_dword v252, v[102:103], off
	v_addc_co_u32_e32 v5, vcc, 0, v3, vcc
	global_load_dwordx4 v[144:147], v[4:5], off nt
	v_add_co_u32_e32 v4, vcc, s88, v2
	v_mov_b32_e32 v241, v103
	v_or_b32_e32 v102, s13, v70
	v_mov_b32_e32 v103, v1
	v_lshl_add_u64 v[102:103], v[102:103], 2, s[6:7]
	global_load_dword v251, v[102:103], off
	v_addc_co_u32_e32 v5, vcc, 0, v3, vcc
	global_load_dwordx4 v[148:151], v[4:5], off nt
	v_add_co_u32_e32 v4, vcc, s19, v2
	v_mov_b32_e32 v240, v103
	v_or_b32_e32 v102, s13, v71
	v_mov_b32_e32 v103, v1
	v_lshl_add_u64 v[102:103], v[102:103], 2, s[6:7]
	global_load_dword v250, v[102:103], off
	v_addc_co_u32_e32 v5, vcc, 0, v3, vcc
	global_load_dwordx4 v[152:155], v[4:5], off nt
	v_add_co_u32_e32 v4, vcc, s20, v2
	v_mov_b32_e32 v217, v103
	v_or_b32_e32 v102, s13, v72
	v_mov_b32_e32 v103, v1
	v_lshl_add_u64 v[102:103], v[102:103], 2, s[6:7]
	global_load_dword v249, v[102:103], off
	v_addc_co_u32_e32 v5, vcc, 0, v3, vcc
	global_load_dwordx4 v[156:159], v[4:5], off nt
	v_add_co_u32_e32 v4, vcc, s21, v2
	v_mov_b32_e32 v216, v103
	v_or_b32_e32 v102, s13, v73
	v_mov_b32_e32 v103, v1
	v_lshl_add_u64 v[102:103], v[102:103], 2, s[6:7]
	global_load_dword v248, v[102:103], off
	v_addc_co_u32_e32 v5, vcc, 0, v3, vcc
	global_load_dwordx4 v[160:163], v[4:5], off nt
	v_add_co_u32_e32 v4, vcc, s89, v2
	v_mov_b32_e32 v209, v103
	v_or_b32_e32 v102, s13, v74
	v_mov_b32_e32 v103, v1
	v_lshl_add_u64 v[102:103], v[102:103], 2, s[6:7]
	global_load_dword v247, v[102:103], off
	v_addc_co_u32_e32 v5, vcc, 0, v3, vcc
	global_load_dwordx4 v[164:167], v[4:5], off nt
	v_add_co_u32_e32 v4, vcc, s22, v2
	v_mov_b32_e32 v208, v103
	s_waitcnt vmcnt(0)
	v_mov_b32_e32 v244, v253
	v_mov_b32_e32 v245, v246
	v_pk_mul_f32 v[242:243], v[132:133], v[244:245] op_sel_hi:[1,0]
	ds_write2_b32 v52, v242, v243 offset1:1
	v_mov_b32_e32 v242, v253
	v_mov_b32_e32 v243, v246
	v_pk_mul_f32 v[132:133], v[134:135], v[242:243] op_sel_hi:[1,0]
	ds_write2_b32 v52, v132, v133 offset0:2 offset1:3
	v_mov_b32_e32 v134, v252
	v_mov_b32_e32 v135, v241
	v_pk_mul_f32 v[132:133], v[136:137], v[134:135] op_sel_hi:[1,0]
	v_mov_b32_e32 v238, v252
	v_mov_b32_e32 v239, v241
	v_pk_mul_f32 v[236:237], v[138:139], v[238:239] op_sel_hi:[1,0]
	ds_write2_b32 v55, v236, v237 offset1:1
	ds_write2_b32 v54, v132, v133 offset1:1
	v_mov_b32_e32 v236, v251
	v_mov_b32_e32 v237, v240
	v_pk_mul_f32 v[132:133], v[140:141], v[236:237] op_sel_hi:[1,0]
	v_mov_b32_e32 v234, v251
	v_mov_b32_e32 v235, v240
	v_pk_mul_f32 v[232:233], v[142:143], v[234:235] op_sel_hi:[1,0]
	ds_write2_b32 v57, v232, v233 offset1:1
	ds_write2_b32 v56, v132, v133 offset1:1
	v_mov_b32_e32 v232, v250
	v_mov_b32_e32 v233, v217
	v_pk_mul_f32 v[132:133], v[144:145], v[232:233] op_sel_hi:[1,0]
	v_mov_b32_e32 v214, v250
	v_mov_b32_e32 v215, v217
	v_pk_mul_f32 v[212:213], v[146:147], v[214:215] op_sel_hi:[1,0]
	ds_write2_b32 v59, v212, v213 offset1:1
	ds_write2_b32 v58, v132, v133 offset1:1
	v_mov_b32_e32 v250, v249
	v_mov_b32_e32 v251, v216
	v_pk_mul_f32 v[212:213], v[148:149], v[250:251] op_sel_hi:[1,0]
	v_mov_b32_e32 v132, v249
	v_mov_b32_e32 v133, v216
	v_pk_mul_f32 v[210:211], v[150:151], v[132:133] op_sel_hi:[1,0]
	ds_write2_b32 v61, v210, v211 offset1:1
	ds_write2_b32 v60, v212, v213 offset1:1
	v_mov_b32_e32 v212, v248
	v_mov_b32_e32 v213, v209
	v_pk_mul_f32 v[210:211], v[152:153], v[212:213] op_sel_hi:[1,0]
	v_mov_b32_e32 v206, v248
	v_mov_b32_e32 v207, v209
	v_pk_mul_f32 v[204:205], v[154:155], v[206:207] op_sel_hi:[1,0]
	ds_write2_b32 v63, v204, v205 offset1:1
	ds_write2_b32 v62, v210, v211 offset1:1
	v_mov_b32_e32 v248, v247
	v_mov_b32_e32 v249, v208
	v_pk_mul_f32 v[210:211], v[156:157], v[248:249] op_sel_hi:[1,0]
	v_mov_b32_e32 v204, v247
	v_mov_b32_e32 v205, v208
	v_pk_mul_f32 v[202:203], v[158:159], v[204:205] op_sel_hi:[1,0]
	ds_write2_b32 v65, v202, v203 offset1:1
	v_mov_b32_e32 v30, v164
	v_mov_b32_e32 v31, v165
	v_mov_b32_e32 v32, v166
	v_mov_b32_e32 v33, v167
	v_mov_b32_e32 v34, v160
	v_mov_b32_e32 v35, v161
	v_mov_b32_e32 v36, v162
	v_mov_b32_e32 v37, v163
	v_mov_b32_e32 v102, v202
	v_mov_b32_e32 v103, v203
	v_mov_b32_e32 v104, v210
	v_mov_b32_e32 v105, v211
	v_mov_b32_e32 v106, v136
	v_mov_b32_e32 v107, v137
	v_mov_b32_e32 v108, v138
	v_mov_b32_e32 v109, v139
	v_mov_b32_e32 v110, v140
	v_mov_b32_e32 v111, v141
	v_mov_b32_e32 v112, v142
	v_mov_b32_e32 v113, v143
	v_mov_b32_e32 v114, v144
	v_mov_b32_e32 v115, v145
	v_mov_b32_e32 v116, v146
; #define LAS __attribute__((address_space(3)))
; __device__ __forceinline__ void tr_item(const float* W, int ldw, bf16* WT, int ldt, const float* gain, int dst_row0, int k0, int n0, LAS float* scr, int lane) {
;     ...
;     for (int i = 0; i < 16; ++i) v[i] = __builtin_nontemporal_load((const f32x4*)(W + (size_t)(k0 + kr + 4 * i) * ldw + n0 + n4));
; #pragma unroll
;     for (int i = 0; i < 16; ++i) { const int k = kr + 4 * i; const float g = gain ? gain[k0 + k] : 1.0f; LAS float* d = scr + k * 65 + n4;
;         d[0] = v[i][0] * g; d[1] = v[i][1] * g; d[2] = v[i][2] * g; d[3] = v[i][3] * g; }
	v_mov_b32_e32 v117, v147
	v_mov_b32_e32 v118, v148
	v_mov_b32_e32 v119, v149
	v_mov_b32_e32 v120, v150
	v_mov_b32_e32 v121, v151
	v_mov_b32_e32 v122, v152
	v_mov_b32_e32 v123, v153
	v_mov_b32_e32 v124, v154
	v_mov_b32_e32 v125, v155
	v_mov_b32_e32 v126, v156
	v_mov_b32_e32 v127, v157
	v_mov_b32_e32 v128, v158
	v_mov_b32_e32 v129, v159
	v_mov_b32_e32 v130, v253
	v_or_b32_e32 v102, s13, v75
	v_mov_b32_e32 v103, v1
	v_lshl_add_u64 v[102:103], v[102:103], 2, s[6:7]
	global_load_dword v253, v[102:103], off
	v_addc_co_u32_e32 v5, vcc, 0, v3, vcc
	global_load_dwordx4 v[132:135], v[4:5], off nt
	v_add_co_u32_e32 v4, vcc, s23, v2
	ds_write2_b32 v64, v104, v105 offset1:1
	s_nop 0
	v_addc_co_u32_e32 v5, vcc, 0, v3, vcc
	global_load_dwordx4 v[136:139], v[4:5], off nt
	v_add_co_u32_e32 v4, vcc, s24, v2
	v_mov_b32_e32 v242, v34
	v_mov_b32_e32 v243, v35
	v_mov_b32_e32 v244, v103
	v_or_b32_e32 v34, s13, v76
	v_mov_b32_e32 v35, v1
	v_lshl_add_u64 v[34:35], v[34:35], 2, s[6:7]
	global_load_dword v252, v[34:35], off
	v_addc_co_u32_e32 v5, vcc, 0, v3, vcc
	global_load_dwordx4 v[140:143], v[4:5], off nt
	v_add_co_u32_e32 v4, vcc, s96, v2
	v_mov_b32_e32 v234, v30
	v_mov_b32_e32 v235, v31
	v_mov_b32_e32 v233, v35
	v_or_b32_e32 v30, s13, v77
	v_mov_b32_e32 v31, v1
	v_lshl_add_u64 v[30:31], v[30:31], 2, s[6:7]
	global_load_dword v251, v[30:31], off
	v_addc_co_u32_e32 v5, vcc, 0, v3, vcc
	global_load_dwordx4 v[144:147], v[4:5], off nt
	v_add_co_u32_e32 v4, vcc, s25, v2
	v_mov_b32_e32 v232, v31
	v_or_b32_e32 v26, s13, v78
	v_mov_b32_e32 v27, v1
	v_lshl_add_u64 v[26:27], v[26:27], 2, s[6:7]
	global_load_dword v250, v[26:27], off
	v_addc_co_u32_e32 v5, vcc, 0, v3, vcc
	global_load_dwordx4 v[148:151], v[4:5], off nt
	v_add_co_u32_e32 v4, vcc, s27, v2
	v_mov_b32_e32 v213, v27
	v_or_b32_e32 v22, s13, v79
	v_mov_b32_e32 v23, v1
	v_lshl_add_u64 v[22:23], v[22:23], 2, s[6:7]
	global_load_dword v249, v[22:23], off
	v_addc_co_u32_e32 v5, vcc, 0, v3, vcc
	global_load_dwordx4 v[152:155], v[4:5], off nt
	v_add_co_u32_e32 v2, vcc, s28, v2
	v_mov_b32_e32 v212, v23
	v_or_b32_e32 v18, s13, v80
	v_mov_b32_e32 v19, v1
	v_lshl_add_u64 v[18:19], v[18:19], 2, s[6:7]
	global_load_dword v248, v[18:19], off
	v_addc_co_u32_e32 v3, vcc, 0, v3, vcc
	global_load_dwordx4 v[156:159], v[2:3], off nt
	v_mov_b32_e32 v211, v19
	v_or_b32_e32 v14, s13, v81
	v_mov_b32_e32 v15, v1
	v_lshl_add_u64 v[14:15], v[14:15], 2, s[6:7]
	global_load_dword v247, v[14:15], off
	v_mov_b32_e32 v210, v15
	v_or_b32_e32 v10, s13, v82
	v_mov_b32_e32 v11, v1
	v_lshl_add_u64 v[10:11], v[10:11], 2, s[6:7]
	global_load_dword v246, v[10:11], off
	v_mov_b32_e32 v209, v11
	v_or_b32_e32 v6, s13, v83
	v_mov_b32_e32 v7, v1
	v_lshl_add_u64 v[6:7], v[6:7], 2, s[6:7]
	global_load_dword v245, v[6:7], off
	v_mov_b32_e32 v208, v7
	s_waitcnt vmcnt(0)
	v_mov_b32_e32 v240, v253
	v_mov_b32_e32 v241, v244
	v_pk_mul_f32 v[238:239], v[242:243], v[240:241] op_sel_hi:[1,0]
	ds_write2_b32 v66, v238, v239 offset1:1
	v_mov_b32_e32 v238, v253
	v_mov_b32_e32 v239, v244
	v_pk_mul_f32 v[236:237], v[36:37], v[238:239] op_sel_hi:[1,0]
	ds_write2_b32 v84, v236, v237 offset1:1
	v_mov_b32_e32 v236, v252
	v_mov_b32_e32 v237, v233
	v_pk_mul_f32 v[216:217], v[234:235], v[236:237] op_sel_hi:[1,0]
	ds_write2_b32 v85, v216, v217 offset1:1
	v_mov_b32_e32 v216, v252
	v_mov_b32_e32 v217, v233
	v_pk_mul_f32 v[214:215], v[32:33], v[216:217] op_sel_hi:[1,0]
	ds_write2_b32 v86, v214, v215 offset1:1
	v_mov_b32_e32 v252, v251
	v_mov_b32_e32 v253, v232
	v_pk_mul_f32 v[214:215], v[132:133], v[252:253] op_sel_hi:[1,0]
	ds_write2_b32 v87, v214, v215 offset1:1
	v_mov_b32_e32 v214, v251
	v_mov_b32_e32 v215, v232
	v_pk_mul_f32 v[132:133], v[134:135], v[214:215] op_sel_hi:[1,0]
	ds_write2_b32 v88, v132, v133 offset1:1
	v_mov_b32_e32 v134, v250
	v_mov_b32_e32 v135, v213
	v_pk_mul_f32 v[132:133], v[136:137], v[134:135] op_sel_hi:[1,0]
	ds_write2_b32 v89, v132, v133 offset1:1
	v_mov_b32_e32 v136, v250
	v_mov_b32_e32 v137, v213
	v_pk_mul_f32 v[132:133], v[138:139], v[136:137] op_sel_hi:[1,0]
	ds_write2_b32 v90, v132, v133 offset1:1
	v_mov_b32_e32 v250, v249
	v_mov_b32_e32 v251, v212
	v_pk_mul_f32 v[138:139], v[140:141], v[250:251] op_sel_hi:[1,0]
	ds_write2_b32 v91, v138, v139 offset1:1
	v_mov_b32_e32 v140, v249
	v_mov_b32_e32 v141, v212
	v_pk_mul_f32 v[138:139], v[142:143], v[140:141] op_sel_hi:[1,0]
	ds_write2_b32 v92, v138, v139 offset1:1
	v_mov_b32_e32 v142, v248
	v_mov_b32_e32 v143, v211
	v_pk_mul_f32 v[138:139], v[144:145], v[142:143] op_sel_hi:[1,0]
	ds_write2_b32 v93, v138, v139 offset1:1
	v_mov_b32_e32 v144, v248
	v_mov_b32_e32 v145, v211
	v_pk_mul_f32 v[138:139], v[146:147], v[144:145] op_sel_hi:[1,0]
	ds_write2_b32 v94, v138, v139 offset1:1
	v_mov_b32_e32 v248, v247
	v_mov_b32_e32 v249, v210
	v_pk_mul_f32 v[146:147], v[148:149], v[248:249] op_sel_hi:[1,0]
	ds_write2_b32 v95, v146, v147 offset1:1
	v_mov_b32_e32 v148, v247
	v_mov_b32_e32 v149, v210
	v_pk_mul_f32 v[146:147], v[150:151], v[148:149] op_sel_hi:[1,0]
	ds_write2_b32 v96, v146, v147 offset1:1
	v_mov_b32_e32 v150, v246
	v_mov_b32_e32 v151, v209
	v_pk_mul_f32 v[146:147], v[152:153], v[150:151] op_sel_hi:[1,0]
	ds_write2_b32 v97, v146, v147 offset1:1
	v_mov_b32_e32 v152, v246
	v_mov_b32_e32 v153, v209
	v_pk_mul_f32 v[146:147], v[154:155], v[152:153] op_sel_hi:[1,0]
	ds_write2_b32 v98, v146, v147 offset1:1
	v_mov_b32_e32 v246, v245
	v_mov_b32_e32 v247, v208
	v_pk_mul_f32 v[154:155], v[156:157], v[246:247] op_sel_hi:[1,0]
	ds_write2_b32 v99, v154, v155 offset1:1
	v_mov_b32_e32 v156, v245
	v_mov_b32_e32 v157, v208
	v_pk_mul_f32 v[154:155], v[158:159], v[156:157] op_sel_hi:[1,0]
	ds_write2_b32 v100, v154, v155 offset1:1
	s_waitcnt lgkmcnt(0)
; #define LAS __attribute__((address_space(3)))
; #define LDS_WAIT() asm volatile("s_waitcnt lgkmcnt(0)" ::: "memory")
; __device__ __forceinline__ unsigned cvtpk(float lo, float hi) { unsigned r; asm volatile("v_cvt_pk_bf16_f32 %0, %1, %2" : "=v"(r) : "v"(lo), "v"(hi)); return r; }
; __device__ __forceinline__ void tr_item(const float* W, int ldw, bf16* WT, int ldt, const float* gain, int dst_row0, int k0, int n0, LAS float* scr, int lane) {
;     ...
;     LDS_WAIT(); asm volatile("" ::: "memory");
;     const int c = lane & 7;
; #pragma unroll
;     for (int j = 0; j < 8; ++j) { const int n = (lane >> 3) + 8 * j; const LAS float* s = scr + (8 * c) * 65 + n;
;         u32x4 o; o.x = cvtpk(s[0 * 65], s[1 * 65]); o.y = cvtpk(s[2 * 65], s[3 * 65]); o.z = cvtpk(s[4 * 65], s[5 * 65]); o.w = cvtpk(s[6 * 65], s[7 * 65]);
;         *(u32x4*)(WT + (size_t)(dst_row0 + n) * ldt + k0 + 8 * c) = o; }
;     LDS_WAIT(); asm volatile("" ::: "memory");
	ds_read2_b32 v[252:253], v39 offset1:65
	ds_read2_b32 v[250:251], v39 offset0:130 offset1:195
	ds_read2_b32 v[248:249], v53 offset0:4 offset1:69
	ds_read2_b32 v[246:247], v53 offset0:134 offset1:199
	v_add_u32_e32 v8, s8, v51
	v_add_u32_e32 v8, 0x25800, v8
	v_ashrrev_i32_e32 v9, 31, v8
	v_lshl_add_u64 v[2:3], v[40:41], 0, s[48:49]
	v_lshlrev_b64 v[8:9], 12, v[8:9]
	v_lshl_add_u64 v[8:9], v[2:3], 0, v[8:9]
	v_mov_b32_e32 v156, v8
	v_mov_b32_e32 v157, v9
	ds_read2_b32 v[244:245], v39 offset0:8 offset1:73
	ds_read2_b32 v[242:243], v39 offset0:138 offset1:203
	ds_read2_b32 v[240:241], v53 offset0:12 offset1:77
	ds_read2_b32 v[238:239], v53 offset0:142 offset1:207
	v_add_u32_e32 v8, s8, v50
	v_add_u32_e32 v8, 0x25800, v8
	v_ashrrev_i32_e32 v9, 31, v8
	v_lshlrev_b64 v[8:9], 12, v[8:9]
	v_lshl_add_u64 v[8:9], v[2:3], 0, v[8:9]
	v_mov_b32_e32 v154, v8
	v_mov_b32_e32 v155, v9
	ds_read2_b32 v[236:237], v39 offset0:16 offset1:81
	ds_read2_b32 v[234:235], v39 offset0:146 offset1:211
	ds_read2_b32 v[232:233], v53 offset0:20 offset1:85
	ds_read2_b32 v[216:217], v53 offset0:150 offset1:215
	v_add_u32_e32 v8, s8, v49
	v_add_u32_e32 v8, 0x25800, v8
	v_ashrrev_i32_e32 v9, 31, v8
	v_lshlrev_b64 v[8:9], 12, v[8:9]
	v_lshl_add_u64 v[8:9], v[2:3], 0, v[8:9]
	v_mov_b32_e32 v152, v8
	v_mov_b32_e32 v153, v9
	ds_read2_b32 v[214:215], v39 offset0:24 offset1:89
	ds_read2_b32 v[212:213], v39 offset0:154 offset1:219
	ds_read2_b32 v[210:211], v53 offset0:28 offset1:93
	ds_read2_b32 v[208:209], v53 offset0:158 offset1:223
	v_add_u32_e32 v8, s8, v48
	v_add_u32_e32 v8, 0x25800, v8
	v_ashrrev_i32_e32 v9, 31, v8
	v_lshlrev_b64 v[8:9], 12, v[8:9]
	v_lshl_add_u64 v[8:9], v[2:3], 0, v[8:9]
	v_mov_b32_e32 v150, v8
	v_mov_b32_e32 v151, v9
	ds_read2_b32 v[206:207], v39 offset0:32 offset1:97
	ds_read2_b32 v[204:205], v39 offset0:162 offset1:227
	ds_read2_b32 v[202:203], v53 offset0:36 offset1:101
	ds_read2_b32 v[200:201], v53 offset0:166 offset1:231
	v_add_u32_e32 v8, s8, v47
	v_add_u32_e32 v8, 0x25800, v8
	v_ashrrev_i32_e32 v9, 31, v8
	v_lshlrev_b64 v[8:9], 12, v[8:9]
	v_lshl_add_u64 v[8:9], v[2:3], 0, v[8:9]
	v_mov_b32_e32 v148, v8
	v_mov_b32_e32 v149, v9
	ds_read2_b32 v[198:199], v39 offset0:40 offset1:105
	ds_read2_b32 v[196:197], v39 offset0:170 offset1:235
	ds_read2_b32 v[194:195], v53 offset0:44 offset1:109
	ds_read2_b32 v[176:177], v53 offset0:174 offset1:239
	v_add_u32_e32 v8, s8, v46
	v_add_u32_e32 v8, 0x25800, v8
	v_ashrrev_i32_e32 v9, 31, v8
	v_lshlrev_b64 v[8:9], 12, v[8:9]
	v_lshl_add_u64 v[8:9], v[2:3], 0, v[8:9]
	v_mov_b32_e32 v146, v8
	v_mov_b32_e32 v147, v9
	ds_read2_b32 v[174:175], v39 offset0:48 offset1:113
	ds_read2_b32 v[172:173], v39 offset0:178 offset1:243
	ds_read2_b32 v[170:171], v53 offset0:52 offset1:117
	ds_read2_b32 v[168:169], v53 offset0:182 offset1:247
	v_add_u32_e32 v8, s8, v45
	v_add_u32_e32 v8, 0x25800, v8
	v_ashrrev_i32_e32 v9, 31, v8
	v_lshlrev_b64 v[8:9], 12, v[8:9]
	v_lshl_add_u64 v[8:9], v[2:3], 0, v[8:9]
	v_mov_b32_e32 v144, v8
	v_mov_b32_e32 v145, v9
	ds_read2_b32 v[166:167], v39 offset0:56 offset1:121
	ds_read2_b32 v[164:165], v39 offset0:186 offset1:251
	ds_read2_b32 v[162:163], v53 offset0:60 offset1:125
	ds_read2_b32 v[160:161], v53 offset0:190 offset1:255
	v_add_u32_e32 v8, s8, v44
	v_add_u32_e32 v8, 0x25800, v8
	v_ashrrev_i32_e32 v9, 31, v8
	v_lshlrev_b64 v[8:9], 12, v[8:9]
	v_lshl_add_u64 v[2:3], v[2:3], 0, v[8:9]
	v_mov_b32_e32 v142, v2
	v_mov_b32_e32 v143, v3
	s_waitcnt lgkmcnt(0)
	v_cvt_pk_bf16_f32 v159, v252, v253
	v_cvt_pk_bf16_f32 v253, v250, v251
	v_cvt_pk_bf16_f32 v252, v248, v249
	v_cvt_pk_bf16_f32 v251, v246, v247
	v_mov_b32_e32 v132, v159
	v_mov_b32_e32 v133, v253
	v_mov_b32_e32 v134, v252
	v_mov_b32_e32 v135, v251
	global_store_dwordx4 v[156:157], v[132:135], off
	v_cvt_pk_bf16_f32 v253, v244, v245
	v_cvt_pk_bf16_f32 v252, v242, v243
	v_cvt_pk_bf16_f32 v251, v240, v241
	v_cvt_pk_bf16_f32 v250, v238, v239
	v_mov_b32_e32 v136, v253
	v_mov_b32_e32 v137, v252
	v_mov_b32_e32 v138, v251
	v_mov_b32_e32 v139, v250
	global_store_dwordx4 v[154:155], v[136:139], off
	v_cvt_pk_bf16_f32 v253, v236, v237
	v_cvt_pk_bf16_f32 v252, v234, v235
	v_cvt_pk_bf16_f32 v251, v232, v233
	v_cvt_pk_bf16_f32 v250, v216, v217
	v_mov_b32_e32 v132, v253
	v_mov_b32_e32 v133, v252
	v_mov_b32_e32 v134, v251
	v_mov_b32_e32 v135, v250
	global_store_dwordx4 v[152:153], v[132:135], off
	v_cvt_pk_bf16_f32 v253, v214, v215
	v_cvt_pk_bf16_f32 v252, v212, v213
	v_cvt_pk_bf16_f32 v251, v210, v211
	v_cvt_pk_bf16_f32 v250, v208, v209
	v_mov_b32_e32 v136, v253
	v_mov_b32_e32 v137, v252
	v_mov_b32_e32 v138, v251
	v_mov_b32_e32 v139, v250
	global_store_dwordx4 v[150:151], v[136:139], off
	v_cvt_pk_bf16_f32 v253, v206, v207
	v_cvt_pk_bf16_f32 v252, v204, v205
	v_cvt_pk_bf16_f32 v251, v202, v203
	v_cvt_pk_bf16_f32 v250, v200, v201
	v_mov_b32_e32 v132, v253
	v_mov_b32_e32 v133, v252
	v_mov_b32_e32 v134, v251
	v_mov_b32_e32 v135, v250
	global_store_dwordx4 v[148:149], v[132:135], off
	v_cvt_pk_bf16_f32 v253, v198, v199
	v_cvt_pk_bf16_f32 v252, v196, v197
	v_cvt_pk_bf16_f32 v251, v194, v195
	v_cvt_pk_bf16_f32 v250, v176, v177
	v_mov_b32_e32 v136, v253
	v_mov_b32_e32 v137, v252
	v_mov_b32_e32 v138, v251
	v_mov_b32_e32 v139, v250
	global_store_dwordx4 v[146:147], v[136:139], off
	v_cvt_pk_bf16_f32 v253, v174, v175
	v_cvt_pk_bf16_f32 v252, v172, v173
	v_cvt_pk_bf16_f32 v251, v170, v171
	v_cvt_pk_bf16_f32 v250, v168, v169
	v_mov_b32_e32 v132, v253
	v_mov_b32_e32 v133, v252
	v_mov_b32_e32 v134, v251
	v_mov_b32_e32 v135, v250
	global_store_dwordx4 v[144:145], v[132:135], off
	v_cvt_pk_bf16_f32 v253, v166, v167
	v_cvt_pk_bf16_f32 v252, v164, v165
	v_cvt_pk_bf16_f32 v251, v162, v163
	v_cvt_pk_bf16_f32 v250, v160, v161
	v_mov_b32_e32 v136, v253
	v_mov_b32_e32 v137, v252
	v_mov_b32_e32 v138, v251
	v_mov_b32_e32 v139, v250
	global_store_dwordx4 v[142:143], v[136:139], off
	s_waitcnt lgkmcnt(0)
	s_cbranch_execnz .LBB0_257
; #define LAS __attribute__((address_space(3)))
; #define LDS_WAIT() asm volatile("s_waitcnt lgkmcnt(0)" ::: "memory")
; __device__ __forceinline__ void tr_item(const float* W, int ldw, bf16* WT, int ldt, const float* gain, int dst_row0, int k0, int n0, LAS float* scr, int lane) {
;     ...
;     for (int i = 0; i < 16; ++i) v[i] = __builtin_nontemporal_load((const f32x4*)(W + (size_t)(k0 + kr + 4 * i) * ldw + n0 + n4));
; #pragma unroll
;     for (int i = 0; i < 16; ++i) { const int k = kr + 4 * i; const float g = gain ? gain[k0 + k] : 1.0f; LAS float* d = scr + k * 65 + n4;
;         d[0] = v[i][0] * g; d[1] = v[i][1] * g; d[2] = v[i][2] * g; d[3] = v[i][3] * g; }
;     LDS_WAIT(); asm volatile("" ::: "memory");
.LBB0_261:
	s_ashr_i32 s8, s11, 31
	s_lshr_b32 s8, s8, 27
	s_add_i32 s8, s11, s8
	s_ashr_i32 s8, s8, 5
	s_load_dwordx2 s[12:13], s[4:5], 0xb8
	s_lshl_b32 s9, s8, 11
	s_sub_i32 s16, s2, s9
	s_add_i32 s14, s16, 0xfffea800
	s_lshl_b32 s8, s8, 6
	s_ashr_i32 s15, s14, 31
	v_or_b32_e32 v126, s8, v67
	s_lshl_b64 s[14:15], s[14:15], 2
	s_waitcnt lgkmcnt(0)
	s_add_u32 s12, s12, s14
	v_or_b32_e32 v4, 4, v126
	v_or_b32_e32 v10, 8, v126
	v_or_b32_e32 v12, 12, v126
	v_or_b32_e32 v18, 16, v126
	v_or_b32_e32 v20, 20, v126
	v_or_b32_e32 v26, 24, v126
	v_or_b32_e32 v28, 28, v126
	v_or_b32_e32 v34, 32, v126
	v_or_b32_e32 v36, 36, v126
	v_or_b32_e32 v106, 40, v126
	v_or_b32_e32 v108, 44, v126
	v_or_b32_e32 v114, 48, v126
	v_or_b32_e32 v116, 52, v126
	s_addc_u32 s13, s13, s15
	v_ashrrev_i32_e32 v127, 31, v126
	v_ashrrev_i32_e32 v5, 31, v4
	v_ashrrev_i32_e32 v11, 31, v10
	v_ashrrev_i32_e32 v13, 31, v12
	v_ashrrev_i32_e32 v19, 31, v18
	v_ashrrev_i32_e32 v21, 31, v20
	v_ashrrev_i32_e32 v27, 31, v26
	v_ashrrev_i32_e32 v29, 31, v28
	v_ashrrev_i32_e32 v35, 31, v34
	v_ashrrev_i32_e32 v37, 31, v36
	v_ashrrev_i32_e32 v107, 31, v106
	v_ashrrev_i32_e32 v109, 31, v108
	v_ashrrev_i32_e32 v115, 31, v114
	v_ashrrev_i32_e32 v117, 31, v116
	v_lshl_add_u64 v[128:129], s[12:13], 0, v[0:1]
	v_lshlrev_b64 v[2:3], 13, v[126:127]
	v_lshlrev_b64 v[4:5], 13, v[4:5]
	v_lshlrev_b64 v[10:11], 13, v[10:11]
	v_lshlrev_b64 v[12:13], 13, v[12:13]
	v_lshlrev_b64 v[18:19], 13, v[18:19]
	v_lshlrev_b64 v[20:21], 13, v[20:21]
	v_lshlrev_b64 v[26:27], 13, v[26:27]
	v_lshlrev_b64 v[28:29], 13, v[28:29]
	v_lshlrev_b64 v[34:35], 13, v[34:35]
	v_lshlrev_b64 v[36:37], 13, v[36:37]
	v_lshlrev_b64 v[106:107], 13, v[106:107]
	v_lshlrev_b64 v[108:109], 13, v[108:109]
	v_lshlrev_b64 v[114:115], 13, v[114:115]
	v_lshlrev_b64 v[116:117], 13, v[116:117]
	v_lshl_add_u64 v[2:3], v[128:129], 0, v[2:3]
	v_lshl_add_u64 v[6:7], v[128:129], 0, v[4:5]
	v_lshl_add_u64 v[10:11], v[128:129], 0, v[10:11]
	v_lshl_add_u64 v[14:15], v[128:129], 0, v[12:13]
	v_lshl_add_u64 v[18:19], v[128:129], 0, v[18:19]
	v_lshl_add_u64 v[22:23], v[128:129], 0, v[20:21]
	v_lshl_add_u64 v[26:27], v[128:129], 0, v[26:27]
	v_lshl_add_u64 v[30:31], v[128:129], 0, v[28:29]
	v_lshl_add_u64 v[34:35], v[128:129], 0, v[34:35]
	v_lshl_add_u64 v[102:103], v[128:129], 0, v[36:37]
	v_lshl_add_u64 v[106:107], v[128:129], 0, v[106:107]
	v_lshl_add_u64 v[110:111], v[128:129], 0, v[108:109]
	v_lshl_add_u64 v[114:115], v[128:129], 0, v[114:115]
	v_lshl_add_u64 v[118:119], v[128:129], 0, v[116:117]
	global_load_dwordx4 v[2:5], v[2:3], off nt
	s_nop 0
	global_load_dwordx4 v[6:9], v[6:7], off nt
	s_nop 0
	global_load_dwordx4 v[10:13], v[10:11], off nt
	s_nop 0
	global_load_dwordx4 v[14:17], v[14:15], off nt
	s_nop 0
	global_load_dwordx4 v[18:21], v[18:19], off nt
	s_nop 0
	global_load_dwordx4 v[22:25], v[22:23], off nt
	s_nop 0
	global_load_dwordx4 v[26:29], v[26:27], off nt
	s_nop 0
	global_load_dwordx4 v[30:33], v[30:31], off nt
	s_nop 0
	global_load_dwordx4 v[34:37], v[34:35], off nt
	s_nop 0
	global_load_dwordx4 v[102:105], v[102:103], off nt
	s_nop 0
	global_load_dwordx4 v[106:109], v[106:107], off nt
	s_nop 0
	global_load_dwordx4 v[110:113], v[110:111], off nt
	s_nop 0
	global_load_dwordx4 v[114:117], v[114:115], off nt
	s_nop 0
	global_load_dwordx4 v[118:121], v[118:119], off nt
	v_or_b32_e32 v122, 56, v126
	v_ashrrev_i32_e32 v123, 31, v122
	v_lshlrev_b64 v[122:123], 13, v[122:123]
	v_or_b32_e32 v126, 60, v126
	v_lshl_add_u64 v[122:123], v[128:129], 0, v[122:123]
	v_ashrrev_i32_e32 v127, 31, v126
	global_load_dwordx4 v[122:125], v[122:123], off nt
	v_lshlrev_b64 v[126:127], 13, v[126:127]
	v_lshl_add_u64 v[126:127], v[128:129], 0, v[126:127]
	global_load_dwordx4 v[126:129], v[126:127], off nt
	v_add_u32_e32 v0, s16, v68
	s_ashr_i32 s9, s8, 31
	s_waitcnt vmcnt(15)
	ds_write2_b32 v52, v2, v3 offset1:1
	ds_write2_b32 v52, v4, v5 offset0:2 offset1:3
	s_waitcnt vmcnt(14)
	ds_write2_b32 v54, v6, v7 offset1:1
	ds_write2_b32 v55, v8, v9 offset1:1
	s_waitcnt vmcnt(13)
	ds_write2_b32 v56, v10, v11 offset1:1
	ds_write2_b32 v57, v12, v13 offset1:1
	s_waitcnt vmcnt(12)
	ds_write2_b32 v58, v14, v15 offset1:1
	ds_write2_b32 v59, v16, v17 offset1:1
	s_waitcnt vmcnt(11)
	ds_write2_b32 v60, v18, v19 offset1:1
	ds_write2_b32 v61, v20, v21 offset1:1
	s_waitcnt vmcnt(10)
	ds_write2_b32 v62, v22, v23 offset1:1
	ds_write2_b32 v63, v24, v25 offset1:1
	s_waitcnt vmcnt(9)
	ds_write2_b32 v64, v26, v27 offset1:1
	ds_write2_b32 v65, v28, v29 offset1:1
	s_waitcnt vmcnt(8)
	ds_write2_b32 v66, v30, v31 offset1:1
	ds_write2_b32 v84, v32, v33 offset1:1
	s_waitcnt vmcnt(7)
	ds_write2_b32 v85, v34, v35 offset1:1
	ds_write2_b32 v86, v36, v37 offset1:1
	s_waitcnt vmcnt(6)
	ds_write2_b32 v87, v102, v103 offset1:1
	ds_write2_b32 v88, v104, v105 offset1:1
	s_waitcnt vmcnt(5)
	ds_write2_b32 v89, v106, v107 offset1:1
	ds_write2_b32 v90, v108, v109 offset1:1
	s_waitcnt vmcnt(4)
	ds_write2_b32 v91, v110, v111 offset1:1
	ds_write2_b32 v92, v112, v113 offset1:1
	s_waitcnt vmcnt(3)
	ds_write2_b32 v93, v114, v115 offset1:1
	ds_write2_b32 v94, v116, v117 offset1:1
	s_waitcnt vmcnt(2)
	ds_write2_b32 v95, v118, v119 offset1:1
	ds_write2_b32 v96, v120, v121 offset1:1
	s_waitcnt vmcnt(1)
	ds_write2_b32 v97, v122, v123 offset1:1
	ds_write2_b32 v98, v124, v125 offset1:1
	s_waitcnt vmcnt(0)
	ds_write2_b32 v99, v126, v127 offset1:1
	ds_write2_b32 v100, v128, v129 offset1:1
	s_waitcnt lgkmcnt(0)
; #define LAS __attribute__((address_space(3)))
; #define LDS_WAIT() asm volatile("s_waitcnt lgkmcnt(0)" ::: "memory")
; __device__ __forceinline__ unsigned cvtpk(float lo, float hi) { unsigned r; asm volatile("v_cvt_pk_bf16_f32 %0, %1, %2" : "=v"(r) : "v"(lo), "v"(hi)); return r; }
; __device__ __forceinline__ void tr_item(const float* W, int ldw, bf16* WT, int ldt, const float* gain, int dst_row0, int k0, int n0, LAS float* scr, int lane) {
;     ...
;     const int c = lane & 7;
; #pragma unroll
;     for (int j = 0; j < 8; ++j) { const int n = (lane >> 3) + 8 * j; const LAS float* s = scr + (8 * c) * 65 + n;
;         u32x4 o; o.x = cvtpk(s[0 * 65], s[1 * 65]); o.y = cvtpk(s[2 * 65], s[3 * 65]); o.z = cvtpk(s[4 * 65], s[5 * 65]); o.w = cvtpk(s[6 * 65], s[7 * 65]);
;         *(u32x4*)(WT + (size_t)(dst_row0 + n) * ldt + k0 + 8 * c) = o; }
;     LDS_WAIT(); asm volatile("" ::: "memory");
	ds_read2_b32 v[252:253], v39 offset1:65
	ds_read2_b32 v[250:251], v39 offset0:130 offset1:195
	ds_read2_b32 v[248:249], v53 offset0:4 offset1:69
	ds_read2_b32 v[246:247], v53 offset0:134 offset1:199
	v_add_u32_e32 v6, 0xfffea800, v0
	v_ashrrev_i32_e32 v7, 31, v6
	v_lshl_add_u64 v[8:9], s[8:9], 1, v[42:43]
	v_lshlrev_b64 v[6:7], 12, v[6:7]
	v_lshl_add_u64 v[6:7], v[8:9], 0, v[6:7]
	ds_read2_b32 v[244:245], v39 offset0:8 offset1:73
	v_mov_b32_e32 v156, v6
	v_mov_b32_e32 v157, v7
	s_nop 0
	ds_read2_b32 v[242:243], v39 offset0:138 offset1:203
	ds_read2_b32 v[240:241], v53 offset0:12 offset1:77
	ds_read2_b32 v[238:239], v53 offset0:142 offset1:207
	v_add_u32_e32 v6, 0xfffea808, v0
	v_ashrrev_i32_e32 v7, 31, v6
	v_lshlrev_b64 v[6:7], 12, v[6:7]
	v_lshl_add_u64 v[6:7], v[8:9], 0, v[6:7]
	ds_read2_b32 v[236:237], v39 offset0:16 offset1:81
	v_mov_b32_e32 v154, v6
	v_mov_b32_e32 v155, v7
	s_nop 0
	ds_read2_b32 v[234:235], v39 offset0:146 offset1:211
	ds_read2_b32 v[232:233], v53 offset0:20 offset1:85
	ds_read2_b32 v[216:217], v53 offset0:150 offset1:215
	v_add_u32_e32 v6, 0xfffea810, v0
	v_ashrrev_i32_e32 v7, 31, v6
	v_lshlrev_b64 v[6:7], 12, v[6:7]
	v_lshl_add_u64 v[6:7], v[8:9], 0, v[6:7]
	ds_read2_b32 v[214:215], v39 offset0:24 offset1:89
	v_mov_b32_e32 v152, v6
	v_mov_b32_e32 v153, v7
	s_nop 0
	ds_read2_b32 v[212:213], v39 offset0:154 offset1:219
	ds_read2_b32 v[210:211], v53 offset0:28 offset1:93
	ds_read2_b32 v[208:209], v53 offset0:158 offset1:223
	v_add_u32_e32 v6, 0xfffea818, v0
	v_ashrrev_i32_e32 v7, 31, v6
	v_lshlrev_b64 v[6:7], 12, v[6:7]
	ds_read2_b32 v[206:207], v39 offset0:32 offset1:97
	v_lshl_add_u64 v[6:7], v[8:9], 0, v[6:7]
	v_mov_b32_e32 v150, v6
	v_mov_b32_e32 v151, v7
	s_nop 0
	v_add_u32_e32 v10, 0xfffea820, v0
	v_ashrrev_i32_e32 v11, 31, v10
	ds_read2_b32 v[204:205], v39 offset0:162 offset1:227
	v_lshlrev_b64 v[10:11], 12, v[10:11]
	ds_read2_b32 v[202:203], v53 offset0:36 offset1:101
	v_lshl_add_u64 v[10:11], v[8:9], 0, v[10:11]
	ds_read2_b32 v[200:201], v53 offset0:166 offset1:231
	v_mov_b32_e32 v148, v10
	v_mov_b32_e32 v149, v11
	v_add_u32_e32 v10, 0xfffea828, v0
	v_ashrrev_i32_e32 v11, 31, v10
	ds_read2_b32 v[198:199], v39 offset0:40 offset1:105
	ds_read2_b32 v[196:197], v39 offset0:170 offset1:235
	v_lshlrev_b64 v[10:11], 12, v[10:11]
	ds_read2_b32 v[194:195], v53 offset0:44 offset1:109
	v_lshl_add_u64 v[10:11], v[8:9], 0, v[10:11]
	ds_read2_b32 v[176:177], v53 offset0:174 offset1:239
	v_mov_b32_e32 v146, v10
	v_mov_b32_e32 v147, v11
	v_add_u32_e32 v10, 0xfffea830, v0
	ds_read2_b32 v[174:175], v39 offset0:48 offset1:113
	ds_read2_b32 v[172:173], v39 offset0:178 offset1:243
	v_ashrrev_i32_e32 v11, 31, v10
	ds_read2_b32 v[170:171], v53 offset0:52 offset1:117
	v_lshlrev_b64 v[10:11], 12, v[10:11]
	ds_read2_b32 v[168:169], v53 offset0:182 offset1:247
	v_lshl_add_u64 v[10:11], v[8:9], 0, v[10:11]
	ds_read2_b32 v[166:167], v39 offset0:56 offset1:121
	v_mov_b32_e32 v144, v10
	v_mov_b32_e32 v145, v11
	v_add_u32_e32 v10, 0xfffea838, v0
	v_ashrrev_i32_e32 v11, 31, v10
	ds_read2_b32 v[164:165], v39 offset0:186 offset1:251
	ds_read2_b32 v[162:163], v53 offset0:60 offset1:125
	ds_read2_b32 v[160:161], v53 offset0:190 offset1:255
	v_lshlrev_b64 v[10:11], 12, v[10:11]
	v_lshl_add_u64 v[6:7], v[8:9], 0, v[10:11]
	v_mov_b32_e32 v142, v6
	v_mov_b32_e32 v143, v7
	s_waitcnt lgkmcnt(0)
	v_cvt_pk_bf16_f32 v159, v252, v253
	v_cvt_pk_bf16_f32 v253, v250, v251
	v_cvt_pk_bf16_f32 v252, v248, v249
	v_cvt_pk_bf16_f32 v251, v246, v247
	v_mov_b32_e32 v132, v159
	v_mov_b32_e32 v133, v253
	v_mov_b32_e32 v134, v252
	v_mov_b32_e32 v135, v251
	global_store_dwordx4 v[156:157], v[132:135], off
	v_cvt_pk_bf16_f32 v250, v244, v245
	v_cvt_pk_bf16_f32 v253, v242, v243
	v_cvt_pk_bf16_f32 v252, v240, v241
	v_cvt_pk_bf16_f32 v251, v238, v239
	v_mov_b32_e32 v136, v250
	v_mov_b32_e32 v137, v253
	v_mov_b32_e32 v138, v252
	v_mov_b32_e32 v139, v251
	global_store_dwordx4 v[154:155], v[136:139], off
	v_cvt_pk_bf16_f32 v249, v236, v237
	v_cvt_pk_bf16_f32 v253, v234, v235
	v_cvt_pk_bf16_f32 v252, v232, v233
	v_cvt_pk_bf16_f32 v251, v216, v217
	v_mov_b32_e32 v132, v249
	v_mov_b32_e32 v133, v253
	v_mov_b32_e32 v134, v252
	v_mov_b32_e32 v135, v251
	global_store_dwordx4 v[152:153], v[132:135], off
	v_cvt_pk_bf16_f32 v250, v214, v215
	v_cvt_pk_bf16_f32 v253, v212, v213
	v_cvt_pk_bf16_f32 v252, v210, v211
	v_cvt_pk_bf16_f32 v251, v208, v209
	v_mov_b32_e32 v136, v250
	v_mov_b32_e32 v137, v253
	v_mov_b32_e32 v138, v252
	v_mov_b32_e32 v139, v251
	global_store_dwordx4 v[150:151], v[136:139], off
	v_cvt_pk_bf16_f32 v249, v206, v207
	v_cvt_pk_bf16_f32 v253, v204, v205
	v_cvt_pk_bf16_f32 v252, v202, v203
	v_cvt_pk_bf16_f32 v251, v200, v201
	v_mov_b32_e32 v132, v249
	v_mov_b32_e32 v133, v253
	v_mov_b32_e32 v134, v252
	v_mov_b32_e32 v135, v251
	global_store_dwordx4 v[148:149], v[132:135], off
	v_cvt_pk_bf16_f32 v250, v198, v199
	v_cvt_pk_bf16_f32 v253, v196, v197
	v_cvt_pk_bf16_f32 v252, v194, v195
	v_cvt_pk_bf16_f32 v251, v176, v177
	v_mov_b32_e32 v136, v250
	v_mov_b32_e32 v137, v253
	v_mov_b32_e32 v138, v252
	v_mov_b32_e32 v139, v251
	global_store_dwordx4 v[146:147], v[136:139], off
	v_cvt_pk_bf16_f32 v249, v174, v175
	v_cvt_pk_bf16_f32 v253, v172, v173
	v_cvt_pk_bf16_f32 v252, v170, v171
	v_cvt_pk_bf16_f32 v251, v168, v169
	v_mov_b32_e32 v132, v249
	v_mov_b32_e32 v133, v253
	v_mov_b32_e32 v134, v252
	v_mov_b32_e32 v135, v251
	global_store_dwordx4 v[144:145], v[132:135], off
	v_cvt_pk_bf16_f32 v250, v166, v167
	v_cvt_pk_bf16_f32 v253, v164, v165
	v_cvt_pk_bf16_f32 v252, v162, v163
	v_cvt_pk_bf16_f32 v251, v160, v161
	v_mov_b32_e32 v136, v250
	v_mov_b32_e32 v137, v253
	v_mov_b32_e32 v138, v252
	v_mov_b32_e32 v139, v251
	global_store_dwordx4 v[142:143], v[136:139], off
	s_waitcnt lgkmcnt(0)
	s_branch .LBB0_257

; #define LAS __attribute__((address_space(3)))
; __device__ __forceinline__ void tr_item(const float* W, int ldw, bf16* WT, int ldt, const float* gain, int dst_row0, int k0, int n0, LAS float* scr, int lane) {
;     ...
;     for (int i = 0; i < 16; ++i) v[i] = __builtin_nontemporal_load((const f32x4*)(W + (size_t)(k0 + kr + 4 * i) * ldw + n0 + n4));
; #pragma unroll
;     for (int i = 0; i < 16; ++i) { const int k = kr + 4 * i; const float g = gain ? gain[k0 + k] : 1.0f; LAS float* d = scr + k * 65 + n4;
;         d[0] = v[i][0] * g; d[1] = v[i][1] * g; d[2] = v[i][2] * g; d[3] = v[i][3] * g; }
; __device__ __forceinline__ void late_up_items(KArgs a, int f, int first, int last, int wi, int nw, LAS float* scr, int lane) {
;     ...
;     for (int idx = first + wi; idx < last; idx += nw) { const int m = idx >= IT_UP ? 1 : 0, item = idx - m * IT_UP;
;         const float* src = (second ? (m ? a->in[I_F2W3] : a->in[I_F2W1]) : (m ? a->in[I_F1W3] : a->in[I_F1W1])) + (size_t)layer * DM * FF;
;         tr_job(src, DM, FF, (bf16*)(a->ws + WS_WUP + (size_t)f * SZ_WUP), (second ? a->in[I_LNF2] : a->in[I_LNF1]) + layer * DM, 1, 128 * m, item, scr, lane); }
.LBB0_760:
	s_cmpk_gt_i32 s13, 0xaff
	s_cselect_b32 s14, 0xfffff500, 0
	s_movk_i32 s8, 0x58
	s_cselect_b32 s8, 0x60, s8
	s_cselect_b32 s15, 0x80, 0
	s_add_i32 s18, s14, s13
	s_add_u32 s8, s4, s8
	s_addc_u32 s9, s5, 0
	s_load_dwordx2 s[16:17], s[8:9], 0x0
	s_mul_hi_i32 s8, s18, 0x2e8ba2e9
	s_lshr_b32 s9, s8, 31
	s_ashr_i32 s8, s8, 4
	s_add_i32 s8, s8, s9
	s_mul_i32 s9, s8, 0x58
	s_sub_i32 s9, s14, s9
	s_add_i32 s9, s13, s9
	s_lshl_b32 s18, s9, 6
	s_lshl_b32 s9, s9, 7
	s_and_b32 s9, s9, 0xffffff00
	s_or_b32 s9, s9, s15
	s_and_b32 s14, s18, 64
	s_ashr_i32 s19, s18, 31
	s_or_b32 s14, s9, s14
	s_lshl_b32 s8, s8, 6
	s_lshl_b64 s[18:19], s[18:19], 2
	s_waitcnt lgkmcnt(0)
	s_add_u32 s16, s16, s18
	s_addc_u32 s17, s17, s19
	v_lshl_add_u64 v[2:3], s[16:17], 0, v[0:1]
	v_or_b32_e32 v100, s8, v67
	v_lshl_add_u64 v[2:3], v[2:3], 0, s[20:21]
	v_mad_i64_i32 v[4:5], s[16:17], v100, s33, v[2:3]
	global_load_dwordx4 v[96:99], v[4:5], off nt
	v_or_b32_e32 v4, 4, v100
	v_mad_i64_i32 v[4:5], s[16:17], v4, s33, v[2:3]
	global_load_dwordx4 v[58:61], v[4:5], off nt
	v_or_b32_e32 v4, 8, v100
	v_mad_i64_i32 v[4:5], s[16:17], v4, s33, v[2:3]
	global_load_dwordx4 v[54:57], v[4:5], off nt
	v_or_b32_e32 v4, 12, v100
	v_mad_i64_i32 v[4:5], s[16:17], v4, s33, v[2:3]
	global_load_dwordx4 v[50:53], v[4:5], off nt
	v_or_b32_e32 v4, 16, v100
	v_mad_i64_i32 v[4:5], s[16:17], v4, s33, v[2:3]
	global_load_dwordx4 v[46:49], v[4:5], off nt
	v_or_b32_e32 v4, 20, v100
	v_mad_i64_i32 v[4:5], s[16:17], v4, s33, v[2:3]
	global_load_dwordx4 v[42:45], v[4:5], off nt
	v_or_b32_e32 v4, 24, v100
	v_mad_i64_i32 v[4:5], s[16:17], v4, s33, v[2:3]
	global_load_dwordx4 v[38:41], v[4:5], off nt
	v_or_b32_e32 v4, 28, v100
	v_mad_i64_i32 v[4:5], s[16:17], v4, s33, v[2:3]
	global_load_dwordx4 v[34:37], v[4:5], off nt
	v_or_b32_e32 v4, 32, v100
	v_mad_i64_i32 v[4:5], s[16:17], v4, s33, v[2:3]
	global_load_dwordx4 v[30:33], v[4:5], off nt
	v_or_b32_e32 v4, 36, v100
	v_mad_i64_i32 v[4:5], s[16:17], v4, s33, v[2:3]
	global_load_dwordx4 v[26:29], v[4:5], off nt
	v_or_b32_e32 v4, 40, v100
	v_mad_i64_i32 v[4:5], s[16:17], v4, s33, v[2:3]
	global_load_dwordx4 v[22:25], v[4:5], off nt
	v_or_b32_e32 v4, 44, v100
	v_mad_i64_i32 v[4:5], s[16:17], v4, s33, v[2:3]
	global_load_dwordx4 v[18:21], v[4:5], off nt
	v_or_b32_e32 v4, 48, v100
	v_mad_i64_i32 v[4:5], s[16:17], v4, s33, v[2:3]
	global_load_dwordx4 v[14:17], v[4:5], off nt
	v_or_b32_e32 v4, 52, v100
	v_mad_i64_i32 v[4:5], s[16:17], v4, s33, v[2:3]
	global_load_dwordx4 v[10:13], v[4:5], off nt
	v_or_b32_e32 v4, 56, v100
	v_ashrrev_i32_e32 v101, 31, v100
	v_mad_i64_i32 v[4:5], s[16:17], v4, s33, v[2:3]
	global_load_dwordx4 v[6:9], v[4:5], off nt
	v_or_b32_e32 v4, 60, v100
	v_lshl_add_u64 v[100:101], v[100:101], 2, s[6:7]
	global_load_dword v64, v[100:101], off
	v_or_b32_e32 v156, s8, v71
	v_ashrrev_i32_e32 v157, 31, v156
	v_lshl_add_u64 v[156:157], v[156:157], 2, s[6:7]
	global_load_dword v141, v[156:157], off
	v_or_b32_e32 v156, s8, v72
	v_ashrrev_i32_e32 v157, 31, v156
	v_lshl_add_u64 v[156:157], v[156:157], 2, s[6:7]
	global_load_dword v142, v[156:157], off
	v_or_b32_e32 v156, s8, v73
	v_ashrrev_i32_e32 v157, 31, v156
	v_lshl_add_u64 v[156:157], v[156:157], 2, s[6:7]
	global_load_dword v143, v[156:157], off
	v_or_b32_e32 v156, s8, v74
	v_ashrrev_i32_e32 v157, 31, v156
	v_lshl_add_u64 v[156:157], v[156:157], 2, s[6:7]
	global_load_dword v144, v[156:157], off
	v_or_b32_e32 v156, s8, v75
	v_ashrrev_i32_e32 v157, 31, v156
	v_lshl_add_u64 v[156:157], v[156:157], 2, s[6:7]
	global_load_dword v145, v[156:157], off
	v_or_b32_e32 v156, s8, v76
	v_ashrrev_i32_e32 v157, 31, v156
	v_lshl_add_u64 v[156:157], v[156:157], 2, s[6:7]
	global_load_dword v146, v[156:157], off
	v_or_b32_e32 v156, s8, v77
	v_ashrrev_i32_e32 v157, 31, v156
	v_lshl_add_u64 v[156:157], v[156:157], 2, s[6:7]
	global_load_dword v147, v[156:157], off
	v_or_b32_e32 v156, s8, v78
	v_ashrrev_i32_e32 v157, 31, v156
	v_lshl_add_u64 v[156:157], v[156:157], 2, s[6:7]
	global_load_dword v148, v[156:157], off
	v_or_b32_e32 v156, s8, v79
	v_ashrrev_i32_e32 v157, 31, v156
	v_lshl_add_u64 v[156:157], v[156:157], 2, s[6:7]
	global_load_dword v149, v[156:157], off
	v_or_b32_e32 v156, s8, v80
	v_ashrrev_i32_e32 v157, 31, v156
	v_lshl_add_u64 v[156:157], v[156:157], 2, s[6:7]
	global_load_dword v150, v[156:157], off
	v_or_b32_e32 v156, s8, v81
	v_ashrrev_i32_e32 v157, 31, v156
	v_lshl_add_u64 v[156:157], v[156:157], 2, s[6:7]
	global_load_dword v151, v[156:157], off
	v_or_b32_e32 v156, s8, v82
	v_ashrrev_i32_e32 v157, 31, v156
	v_lshl_add_u64 v[156:157], v[156:157], 2, s[6:7]
	global_load_dword v152, v[156:157], off
	v_or_b32_e32 v156, s8, v83
	v_ashrrev_i32_e32 v157, 31, v156
	v_lshl_add_u64 v[156:157], v[156:157], 2, s[6:7]
	global_load_dword v153, v[156:157], off
	v_or_b32_e32 v156, s8, v84
	v_ashrrev_i32_e32 v157, 31, v156
	v_lshl_add_u64 v[156:157], v[156:157], 2, s[6:7]
	global_load_dword v154, v[156:157], off
	v_or_b32_e32 v156, s8, v85
	v_ashrrev_i32_e32 v157, 31, v156
	v_lshl_add_u64 v[156:157], v[156:157], 2, s[6:7]
	global_load_dword v155, v[156:157], off
	v_add_u32_e32 v95, 0x410, v94
	v_mad_i64_i32 v[2:3], s[16:17], v4, s33, v[2:3]
	global_load_dwordx4 v[2:5], v[2:3], off nt
	s_ashr_i32 s9, s8, 31
	s_waitcnt vmcnt(1)
	v_pk_mul_f32 v[96:97], v[96:97], v[64:65] op_sel_hi:[1,0]
	ds_write2_b32 v94, v96, v97 offset1:1
	v_pk_mul_f32 v[96:97], v[98:99], v[64:65] op_sel_hi:[1,0]
	ds_write2_b32 v94, v96, v97 offset0:2 offset1:3
	v_or_b32_e32 v96, s8, v71
	v_ashrrev_i32_e32 v97, 31, v96
	v_lshl_add_u64 v[96:97], v[96:97], 2, s[6:7]
	v_mov_b32_e32 v64, v141
	s_waitcnt vmcnt(0)
; #define LAS __attribute__((address_space(3)))
; __device__ __forceinline__ void tr_item(const float* W, int ldw, bf16* WT, int ldt, const float* gain, int dst_row0, int k0, int n0, LAS float* scr, int lane) {
;     ...
;     for (int i = 0; i < 16; ++i) { const int k = kr + 4 * i; const float g = gain ? gain[k0 + k] : 1.0f; LAS float* d = scr + k * 65 + n4;
;         d[0] = v[i][0] * g; d[1] = v[i][1] * g; d[2] = v[i][2] * g; d[3] = v[i][3] * g; }
	v_pk_mul_f32 v[58:59], v[58:59], v[64:65] op_sel_hi:[1,0]
	ds_write2_b32 v95, v58, v59 offset1:1
	v_pk_mul_f32 v[58:59], v[60:61], v[64:65] op_sel_hi:[1,0]
	v_add_u32_e32 v60, 0x418, v94
	ds_write2_b32 v60, v58, v59 offset1:1
	v_or_b32_e32 v58, s8, v72
	v_ashrrev_i32_e32 v59, 31, v58
	v_lshl_add_u64 v[58:59], v[58:59], 2, s[6:7]
	v_mov_b32_e32 v58, v142
	s_waitcnt vmcnt(0)
	v_pk_mul_f32 v[54:55], v[54:55], v[58:59] op_sel_hi:[1,0]
	v_add_u32_e32 v59, 0x820, v94
	ds_write2_b32 v59, v54, v55 offset1:1
	v_pk_mul_f32 v[54:55], v[56:57], v[58:59] op_sel_hi:[1,0]
	v_add_u32_e32 v56, 0x828, v94
	ds_write2_b32 v56, v54, v55 offset1:1
	v_or_b32_e32 v54, s8, v73
	v_ashrrev_i32_e32 v55, 31, v54
	v_lshl_add_u64 v[54:55], v[54:55], 2, s[6:7]
	v_mov_b32_e32 v54, v143
	s_waitcnt vmcnt(0)
	v_pk_mul_f32 v[50:51], v[50:51], v[54:55] op_sel_hi:[1,0]
	v_add_u32_e32 v55, 0xc30, v94
	ds_write2_b32 v55, v50, v51 offset1:1
	v_pk_mul_f32 v[50:51], v[52:53], v[54:55] op_sel_hi:[1,0]
	v_add_u32_e32 v52, 0xc38, v94
	ds_write2_b32 v52, v50, v51 offset1:1
	v_or_b32_e32 v50, s8, v74
	v_ashrrev_i32_e32 v51, 31, v50
	v_lshl_add_u64 v[50:51], v[50:51], 2, s[6:7]
	v_mov_b32_e32 v50, v144
	s_waitcnt vmcnt(0)
	v_pk_mul_f32 v[46:47], v[46:47], v[50:51] op_sel_hi:[1,0]
	v_add_u32_e32 v51, 0x1040, v94
	ds_write2_b32 v51, v46, v47 offset1:1
	v_pk_mul_f32 v[46:47], v[48:49], v[50:51] op_sel_hi:[1,0]
	v_add_u32_e32 v48, 0x1048, v94
	ds_write2_b32 v48, v46, v47 offset1:1
	v_or_b32_e32 v46, s8, v75
	v_ashrrev_i32_e32 v47, 31, v46
	v_lshl_add_u64 v[46:47], v[46:47], 2, s[6:7]
	v_mov_b32_e32 v46, v145
	s_waitcnt vmcnt(0)
	v_pk_mul_f32 v[42:43], v[42:43], v[46:47] op_sel_hi:[1,0]
	v_add_u32_e32 v47, 0x1450, v94
	ds_write2_b32 v47, v42, v43 offset1:1
	v_pk_mul_f32 v[42:43], v[44:45], v[46:47] op_sel_hi:[1,0]
	v_add_u32_e32 v44, 0x1458, v94
	ds_write2_b32 v44, v42, v43 offset1:1
	v_or_b32_e32 v42, s8, v76
	v_ashrrev_i32_e32 v43, 31, v42
	v_lshl_add_u64 v[42:43], v[42:43], 2, s[6:7]
	v_mov_b32_e32 v42, v146
	s_waitcnt vmcnt(0)
	v_pk_mul_f32 v[38:39], v[38:39], v[42:43] op_sel_hi:[1,0]
	v_add_u32_e32 v43, 0x1860, v94
	ds_write2_b32 v43, v38, v39 offset1:1
	v_pk_mul_f32 v[38:39], v[40:41], v[42:43] op_sel_hi:[1,0]
	v_add_u32_e32 v40, 0x1868, v94
	ds_write2_b32 v40, v38, v39 offset1:1
	v_or_b32_e32 v38, s8, v77
	v_ashrrev_i32_e32 v39, 31, v38
	v_lshl_add_u64 v[38:39], v[38:39], 2, s[6:7]
	v_mov_b32_e32 v38, v147
	s_waitcnt vmcnt(0)
	v_pk_mul_f32 v[34:35], v[34:35], v[38:39] op_sel_hi:[1,0]
	v_add_u32_e32 v39, 0x1c70, v94
	ds_write2_b32 v39, v34, v35 offset1:1
	v_pk_mul_f32 v[34:35], v[36:37], v[38:39] op_sel_hi:[1,0]
	v_add_u32_e32 v36, 0x1c78, v94
	ds_write2_b32 v36, v34, v35 offset1:1
	v_or_b32_e32 v34, s8, v78
	v_ashrrev_i32_e32 v35, 31, v34
	v_lshl_add_u64 v[34:35], v[34:35], 2, s[6:7]
	v_mov_b32_e32 v34, v148
	s_waitcnt vmcnt(0)
	v_pk_mul_f32 v[30:31], v[30:31], v[34:35] op_sel_hi:[1,0]
	v_add_u32_e32 v35, 0x2080, v94
	ds_write2_b32 v35, v30, v31 offset1:1
	v_pk_mul_f32 v[30:31], v[32:33], v[34:35] op_sel_hi:[1,0]
	v_add_u32_e32 v32, 0x2088, v94
	ds_write2_b32 v32, v30, v31 offset1:1
	v_or_b32_e32 v30, s8, v79
	v_ashrrev_i32_e32 v31, 31, v30
	v_lshl_add_u64 v[30:31], v[30:31], 2, s[6:7]
	v_mov_b32_e32 v30, v149
	s_waitcnt vmcnt(0)
	v_pk_mul_f32 v[26:27], v[26:27], v[30:31] op_sel_hi:[1,0]
	v_add_u32_e32 v31, 0x2490, v94
	ds_write2_b32 v31, v26, v27 offset1:1
	v_pk_mul_f32 v[26:27], v[28:29], v[30:31] op_sel_hi:[1,0]
	v_add_u32_e32 v28, 0x2498, v94
	ds_write2_b32 v28, v26, v27 offset1:1
	v_or_b32_e32 v26, s8, v80
	v_ashrrev_i32_e32 v27, 31, v26
	v_lshl_add_u64 v[26:27], v[26:27], 2, s[6:7]
	v_mov_b32_e32 v26, v150
	s_waitcnt vmcnt(0)
	v_pk_mul_f32 v[22:23], v[22:23], v[26:27] op_sel_hi:[1,0]
	v_add_u32_e32 v27, 0x28a0, v94
	ds_write2_b32 v27, v22, v23 offset1:1
	v_pk_mul_f32 v[22:23], v[24:25], v[26:27] op_sel_hi:[1,0]
	v_add_u32_e32 v24, 0x28a8, v94
	ds_write2_b32 v24, v22, v23 offset1:1
	v_or_b32_e32 v22, s8, v81
	v_ashrrev_i32_e32 v23, 31, v22
	v_lshl_add_u64 v[22:23], v[22:23], 2, s[6:7]
	v_mov_b32_e32 v22, v151
	s_waitcnt vmcnt(0)
	v_pk_mul_f32 v[18:19], v[18:19], v[22:23] op_sel_hi:[1,0]
	v_add_u32_e32 v23, 0x2cb0, v94
	ds_write2_b32 v23, v18, v19 offset1:1
	v_pk_mul_f32 v[18:19], v[20:21], v[22:23] op_sel_hi:[1,0]
	v_add_u32_e32 v20, 0x2cb8, v94
	ds_write2_b32 v20, v18, v19 offset1:1
	v_or_b32_e32 v18, s8, v82
	v_ashrrev_i32_e32 v19, 31, v18
	v_lshl_add_u64 v[18:19], v[18:19], 2, s[6:7]
	v_mov_b32_e32 v18, v152
	s_waitcnt vmcnt(0)
	v_pk_mul_f32 v[14:15], v[14:15], v[18:19] op_sel_hi:[1,0]
	v_add_u32_e32 v19, 0x30c0, v94
	ds_write2_b32 v19, v14, v15 offset1:1
	v_pk_mul_f32 v[14:15], v[16:17], v[18:19] op_sel_hi:[1,0]
	v_add_u32_e32 v16, 0x30c8, v94
	ds_write2_b32 v16, v14, v15 offset1:1
	v_or_b32_e32 v14, s8, v83
	v_ashrrev_i32_e32 v15, 31, v14
	v_lshl_add_u64 v[14:15], v[14:15], 2, s[6:7]
	v_mov_b32_e32 v14, v153
	s_waitcnt vmcnt(0)
	v_pk_mul_f32 v[10:11], v[10:11], v[14:15] op_sel_hi:[1,0]
	v_add_u32_e32 v15, 0x34d0, v94
	ds_write2_b32 v15, v10, v11 offset1:1
	v_pk_mul_f32 v[10:11], v[12:13], v[14:15] op_sel_hi:[1,0]
	v_add_u32_e32 v12, 0x34d8, v94
	ds_write2_b32 v12, v10, v11 offset1:1
	v_or_b32_e32 v10, s8, v84
	v_ashrrev_i32_e32 v11, 31, v10
	v_lshl_add_u64 v[10:11], v[10:11], 2, s[6:7]
	v_mov_b32_e32 v10, v154
	s_waitcnt vmcnt(0)
	v_pk_mul_f32 v[6:7], v[6:7], v[10:11] op_sel_hi:[1,0]
	v_add_u32_e32 v11, 0x38e0, v94
	ds_write2_b32 v11, v6, v7 offset1:1
	v_pk_mul_f32 v[6:7], v[8:9], v[10:11] op_sel_hi:[1,0]
	v_add_u32_e32 v8, 0x38e8, v94
	ds_write2_b32 v8, v6, v7 offset1:1
	v_or_b32_e32 v6, s8, v85
	v_ashrrev_i32_e32 v7, 31, v6
	v_lshl_add_u64 v[6:7], v[6:7], 2, s[6:7]
	v_mov_b32_e32 v6, v155
	v_add_u32_e32 v8, 0x400, v86
	s_waitcnt vmcnt(0)
; #define LAS __attribute__((address_space(3)))
; #define LDS_WAIT() asm volatile("s_waitcnt lgkmcnt(0)" ::: "memory")
; __device__ __forceinline__ unsigned cvtpk(float lo, float hi) { unsigned r; asm volatile("v_cvt_pk_bf16_f32 %0, %1, %2" : "=v"(r) : "v"(lo), "v"(hi)); return r; }
; __device__ __forceinline__ void tr_item(const float* W, int ldw, bf16* WT, int ldt, const float* gain, int dst_row0, int k0, int n0, LAS float* scr, int lane) {
;     ...
;     for (int i = 0; i < 16; ++i) { const int k = kr + 4 * i; const float g = gain ? gain[k0 + k] : 1.0f; LAS float* d = scr + k * 65 + n4;
;         d[0] = v[i][0] * g; d[1] = v[i][1] * g; d[2] = v[i][2] * g; d[3] = v[i][3] * g; }
;     LDS_WAIT(); asm volatile("" ::: "memory");
;     const int c = lane & 7;
; #pragma unroll
;     for (int j = 0; j < 8; ++j) { const int n = (lane >> 3) + 8 * j; const LAS float* s = scr + (8 * c) * 65 + n;
;         u32x4 o; o.x = cvtpk(s[0 * 65], s[1 * 65]); o.y = cvtpk(s[2 * 65], s[3 * 65]); o.z = cvtpk(s[4 * 65], s[5 * 65]); o.w = cvtpk(s[6 * 65], s[7 * 65]);
;         *(u32x4*)(WT + (size_t)(dst_row0 + n) * ldt + k0 + 8 * c) = o; }
;     LDS_WAIT(); asm volatile("" ::: "memory");
	v_pk_mul_f32 v[2:3], v[2:3], v[6:7] op_sel_hi:[1,0]
	v_add_u32_e32 v7, 0x3cf0, v94
	ds_write2_b32 v7, v2, v3 offset1:1
	v_pk_mul_f32 v[2:3], v[4:5], v[6:7] op_sel_hi:[1,0]
	v_add_u32_e32 v4, 0x3cf8, v94
	ds_write2_b32 v4, v2, v3 offset1:1
	s_waitcnt lgkmcnt(0)
	ds_read2_b32 v[252:253], v86 offset1:65
	ds_read2_b32 v[250:251], v86 offset0:130 offset1:195
	ds_read2_b32 v[248:249], v8 offset0:4 offset1:69
	ds_read2_b32 v[246:247], v8 offset0:134 offset1:199
	v_or_b32_e32 v10, s14, v69
	v_ashrrev_i32_e32 v11, 31, v10
	v_lshl_add_u64 v[6:7], s[8:9], 1, v[62:63]
	v_lshlrev_b64 v[10:11], 12, v[10:11]
	v_lshl_add_u64 v[10:11], v[6:7], 0, v[10:11]
	v_mov_b32_e32 v156, v10
	v_mov_b32_e32 v157, v11
	ds_read2_b32 v[244:245], v86 offset0:8 offset1:73
	s_add_i32 s8, s13, 0x638
	ds_read2_b32 v[242:243], v86 offset0:138 offset1:203
	ds_read2_b32 v[240:241], v8 offset0:12 offset1:77
	ds_read2_b32 v[238:239], v8 offset0:142 offset1:207
	v_or_b32_e32 v10, s14, v87
	v_ashrrev_i32_e32 v11, 31, v10
	v_lshlrev_b64 v[10:11], 12, v[10:11]
	v_lshl_add_u64 v[10:11], v[6:7], 0, v[10:11]
	v_mov_b32_e32 v154, v10
	v_mov_b32_e32 v155, v11
	ds_read2_b32 v[236:237], v86 offset0:16 offset1:81
	s_cmpk_lt_i32 s13, 0xfc8
	ds_read2_b32 v[234:235], v86 offset0:146 offset1:211
	ds_read2_b32 v[232:233], v8 offset0:20 offset1:85
	ds_read2_b32 v[216:217], v8 offset0:150 offset1:215
	v_or_b32_e32 v10, s14, v88
	v_ashrrev_i32_e32 v11, 31, v10
	v_lshlrev_b64 v[10:11], 12, v[10:11]
	v_lshl_add_u64 v[10:11], v[6:7], 0, v[10:11]
	v_mov_b32_e32 v152, v10
	v_mov_b32_e32 v153, v11
	ds_read2_b32 v[214:215], v86 offset0:24 offset1:89
	s_mov_b32 s13, s8
	ds_read2_b32 v[212:213], v86 offset0:154 offset1:219
	ds_read2_b32 v[210:211], v8 offset0:28 offset1:93
	ds_read2_b32 v[208:209], v8 offset0:158 offset1:223
	v_or_b32_e32 v10, s14, v89
	v_ashrrev_i32_e32 v11, 31, v10
	v_lshlrev_b64 v[10:11], 12, v[10:11]
	v_lshl_add_u64 v[10:11], v[6:7], 0, v[10:11]
	v_mov_b32_e32 v150, v10
	v_mov_b32_e32 v151, v11
	ds_read2_b32 v[206:207], v86 offset0:32 offset1:97
	ds_read2_b32 v[204:205], v86 offset0:162 offset1:227
	ds_read2_b32 v[202:203], v8 offset0:36 offset1:101
	ds_read2_b32 v[200:201], v8 offset0:166 offset1:231
	v_or_b32_e32 v10, s14, v90
	v_ashrrev_i32_e32 v11, 31, v10
	v_lshlrev_b64 v[10:11], 12, v[10:11]
	v_lshl_add_u64 v[10:11], v[6:7], 0, v[10:11]
	v_mov_b32_e32 v148, v10
	v_mov_b32_e32 v149, v11
	ds_read2_b32 v[198:199], v86 offset0:40 offset1:105
	ds_read2_b32 v[196:197], v86 offset0:170 offset1:235
	ds_read2_b32 v[194:195], v8 offset0:44 offset1:109
	ds_read2_b32 v[176:177], v8 offset0:174 offset1:239
	v_or_b32_e32 v10, s14, v91
	v_ashrrev_i32_e32 v11, 31, v10
	v_lshlrev_b64 v[10:11], 12, v[10:11]
	v_lshl_add_u64 v[10:11], v[6:7], 0, v[10:11]
	v_mov_b32_e32 v146, v10
	v_mov_b32_e32 v147, v11
	ds_read2_b32 v[174:175], v86 offset0:48 offset1:113
	ds_read2_b32 v[172:173], v86 offset0:178 offset1:243
	ds_read2_b32 v[170:171], v8 offset0:52 offset1:117
	ds_read2_b32 v[168:169], v8 offset0:182 offset1:247
	v_or_b32_e32 v10, s14, v92
	v_ashrrev_i32_e32 v11, 31, v10
	v_lshlrev_b64 v[10:11], 12, v[10:11]
	v_lshl_add_u64 v[10:11], v[6:7], 0, v[10:11]
	v_mov_b32_e32 v144, v10
	v_mov_b32_e32 v145, v11
	ds_read2_b32 v[166:167], v86 offset0:56 offset1:121
	ds_read2_b32 v[164:165], v86 offset0:186 offset1:251
	ds_read2_b32 v[162:163], v8 offset0:60 offset1:125
	ds_read2_b32 v[160:161], v8 offset0:190 offset1:255
	v_or_b32_e32 v8, s14, v93
	v_ashrrev_i32_e32 v9, 31, v8
	v_lshlrev_b64 v[8:9], 12, v[8:9]
	v_lshl_add_u64 v[6:7], v[6:7], 0, v[8:9]
	v_mov_b32_e32 v142, v6
	v_mov_b32_e32 v143, v7
	s_waitcnt lgkmcnt(0)
	v_cvt_pk_bf16_f32 v159, v252, v253
	v_cvt_pk_bf16_f32 v253, v250, v251
	v_cvt_pk_bf16_f32 v252, v248, v249
	v_cvt_pk_bf16_f32 v251, v246, v247
	v_mov_b32_e32 v132, v159
	v_mov_b32_e32 v133, v253
	v_mov_b32_e32 v134, v252
	v_mov_b32_e32 v135, v251
	global_store_dwordx4 v[156:157], v[132:135], off
	v_cvt_pk_bf16_f32 v253, v244, v245
	v_cvt_pk_bf16_f32 v252, v242, v243
	v_cvt_pk_bf16_f32 v251, v240, v241
	v_cvt_pk_bf16_f32 v250, v238, v239
	v_mov_b32_e32 v136, v253
	v_mov_b32_e32 v137, v252
	v_mov_b32_e32 v138, v251
	v_mov_b32_e32 v139, v250
	global_store_dwordx4 v[154:155], v[136:139], off
	v_cvt_pk_bf16_f32 v253, v236, v237
	v_cvt_pk_bf16_f32 v252, v234, v235
	v_cvt_pk_bf16_f32 v251, v232, v233
	v_cvt_pk_bf16_f32 v250, v216, v217
	v_mov_b32_e32 v132, v253
	v_mov_b32_e32 v133, v252
	v_mov_b32_e32 v134, v251
	v_mov_b32_e32 v135, v250
	global_store_dwordx4 v[152:153], v[132:135], off
	v_cvt_pk_bf16_f32 v253, v214, v215
	v_cvt_pk_bf16_f32 v252, v212, v213
	v_cvt_pk_bf16_f32 v251, v210, v211
	v_cvt_pk_bf16_f32 v250, v208, v209
	v_mov_b32_e32 v136, v253
	v_mov_b32_e32 v137, v252
	v_mov_b32_e32 v138, v251
	v_mov_b32_e32 v139, v250
	global_store_dwordx4 v[150:151], v[136:139], off
	v_cvt_pk_bf16_f32 v253, v206, v207
	v_cvt_pk_bf16_f32 v252, v204, v205
	v_cvt_pk_bf16_f32 v251, v202, v203
	v_cvt_pk_bf16_f32 v250, v200, v201
	v_mov_b32_e32 v132, v253
	v_mov_b32_e32 v133, v252
	v_mov_b32_e32 v134, v251
	v_mov_b32_e32 v135, v250
	global_store_dwordx4 v[148:149], v[132:135], off
	v_cvt_pk_bf16_f32 v253, v198, v199
	v_cvt_pk_bf16_f32 v252, v196, v197
	v_cvt_pk_bf16_f32 v251, v194, v195
	v_cvt_pk_bf16_f32 v250, v176, v177
	v_mov_b32_e32 v136, v253
	v_mov_b32_e32 v137, v252
	v_mov_b32_e32 v138, v251
	v_mov_b32_e32 v139, v250
	global_store_dwordx4 v[146:147], v[136:139], off
	v_cvt_pk_bf16_f32 v253, v174, v175
	v_cvt_pk_bf16_f32 v252, v172, v173
	v_cvt_pk_bf16_f32 v251, v170, v171
	v_cvt_pk_bf16_f32 v250, v168, v169
	v_mov_b32_e32 v132, v253
	v_mov_b32_e32 v133, v252
	v_mov_b32_e32 v134, v251
	v_mov_b32_e32 v135, v250
	global_store_dwordx4 v[144:145], v[132:135], off
	v_cvt_pk_bf16_f32 v253, v166, v167
	v_cvt_pk_bf16_f32 v252, v164, v165
	v_cvt_pk_bf16_f32 v251, v162, v163
	v_cvt_pk_bf16_f32 v250, v160, v161
	v_mov_b32_e32 v136, v253
	v_mov_b32_e32 v137, v252
	v_mov_b32_e32 v138, v251
	v_mov_b32_e32 v139, v250
	global_store_dwordx4 v[142:143], v[136:139], off
	s_waitcnt lgkmcnt(0)
	s_cbranch_scc1 .LBB0_760

; #define LAS __attribute__((address_space(3)))
; #define LDS_WAIT() asm volatile("s_waitcnt lgkmcnt(0)" ::: "memory")
; __device__ __forceinline__ void tr_item(const float* W, int ldw, bf16* WT, int ldt, const float* gain, int dst_row0, int k0, int n0, LAS float* scr, int lane) {
;     ...
;     for (int i = 0; i < 16; ++i) v[i] = __builtin_nontemporal_load((const f32x4*)(W + (size_t)(k0 + kr + 4 * i) * ldw + n0 + n4));
; #pragma unroll
;     for (int i = 0; i < 16; ++i) { const int k = kr + 4 * i; const float g = gain ? gain[k0 + k] : 1.0f; LAS float* d = scr + k * 65 + n4;
;         d[0] = v[i][0] * g; d[1] = v[i][1] * g; d[2] = v[i][2] * g; d[3] = v[i][3] * g; }
;     LDS_WAIT(); asm volatile("" ::: "memory");
.LBB0_766:
	s_lshr_b32 s9, s10, 5
	s_load_dwordx2 s[6:7], s[4:5], 0x100
	s_lshl_b32 s8, s9, 11
	s_sub_i32 s8, s2, s8
	s_add_i32 s12, s8, 0xfffcce00
	s_ashr_i32 s13, s12, 31
	s_lshl_b64 s[12:13], s[12:13], 2
	s_waitcnt lgkmcnt(0)
	s_add_u32 s6, s6, s12
	v_lshl_or_b32 v4, s9, 6, v67
	s_addc_u32 s7, s7, s13
	v_lshl_add_u64 v[2:3], s[6:7], 0, v[0:1]
	v_lshlrev_b32_e32 v4, 11, v4
	v_mov_b32_e32 v5, v1
	v_lshl_add_u64 v[62:63], v[4:5], 2, v[2:3]
	s_mov_b32 s6, 0x8000
	v_add_co_u32_e32 v2, vcc, s6, v62
	s_mov_b32 s6, 0x10000
	s_nop 0
	v_addc_co_u32_e32 v3, vcc, 0, v63, vcc
	v_add_co_u32_e32 v10, vcc, s6, v62
	global_load_dwordx4 v[6:9], v[62:63], off nt
	s_nop 0
	global_load_dwordx4 v[2:5], v[2:3], off nt
	v_addc_co_u32_e32 v11, vcc, 0, v63, vcc
	v_add_co_u32_e32 v12, vcc, s16, v62
	s_lshl_b32 s9, s9, 7
	s_nop 0
	v_addc_co_u32_e32 v13, vcc, 0, v63, vcc
	v_add_co_u32_e32 v18, vcc, s88, v62
	global_load_dwordx4 v[14:17], v[10:11], off nt
	s_nop 0
	global_load_dwordx4 v[10:13], v[12:13], off nt
	v_addc_co_u32_e32 v19, vcc, 0, v63, vcc
	v_add_co_u32_e32 v20, vcc, s17, v62
	v_mov_b32_e32 v71, v1
	s_nop 0
	v_addc_co_u32_e32 v21, vcc, 0, v63, vcc
	v_add_co_u32_e32 v26, vcc, s18, v62
	global_load_dwordx4 v[22:25], v[18:19], off nt
	s_nop 0
	global_load_dwordx4 v[18:21], v[20:21], off nt
	v_addc_co_u32_e32 v27, vcc, 0, v63, vcc
	v_add_co_u32_e32 v28, vcc, s19, v62
	s_nop 1
	v_addc_co_u32_e32 v29, vcc, 0, v63, vcc
	v_add_co_u32_e32 v34, vcc, s89, v62
	global_load_dwordx4 v[30:33], v[26:27], off nt
	s_nop 0
	global_load_dwordx4 v[26:29], v[28:29], off nt
	v_addc_co_u32_e32 v35, vcc, 0, v63, vcc
	v_add_co_u32_e32 v36, vcc, s20, v62
	s_nop 1
	v_addc_co_u32_e32 v37, vcc, 0, v63, vcc
	v_add_co_u32_e32 v42, vcc, s21, v62
	global_load_dwordx4 v[38:41], v[34:35], off nt
	s_nop 0
	global_load_dwordx4 v[34:37], v[36:37], off nt
	v_addc_co_u32_e32 v43, vcc, 0, v63, vcc
	v_add_co_u32_e32 v44, vcc, s22, v62
	s_nop 1
	v_addc_co_u32_e32 v45, vcc, 0, v63, vcc
	v_add_co_u32_e32 v50, vcc, s96, v62
	global_load_dwordx4 v[46:49], v[42:43], off nt
	s_nop 0
	global_load_dwordx4 v[42:45], v[44:45], off nt
	v_addc_co_u32_e32 v51, vcc, 0, v63, vcc
	v_add_co_u32_e32 v52, vcc, s23, v62
	s_nop 1
	v_addc_co_u32_e32 v53, vcc, 0, v63, vcc
	global_load_dwordx4 v[54:57], v[50:51], off nt
	s_nop 0
	global_load_dwordx4 v[50:53], v[52:53], off nt
	v_add_co_u32_e32 v58, vcc, s24, v62
	s_load_dwordx2 s[6:7], s[4:5], 0x118
	s_nop 0
	v_addc_co_u32_e32 v59, vcc, 0, v63, vcc
	global_load_dwordx4 v[58:61], v[58:59], off nt
	v_add_co_u32_e32 v62, vcc, s25, v62
	s_waitcnt lgkmcnt(0)
	s_add_u32 s6, s6, s9
	v_addc_co_u32_e32 v63, vcc, 0, v63, vcc
	global_load_dwordx4 v[62:65], v[62:63], off nt
	s_addc_u32 s7, s7, 0
	s_waitcnt vmcnt(15)
	ds_write2_b32 v81, v6, v7 offset1:1
	ds_write2_b32 v81, v8, v9 offset0:2 offset1:3
	s_waitcnt vmcnt(14)
	ds_write2_b32 v83, v2, v3 offset1:1
	ds_write2_b32 v84, v4, v5 offset1:1
	s_waitcnt vmcnt(13)
	ds_write2_b32 v85, v14, v15 offset1:1
	ds_write2_b32 v86, v16, v17 offset1:1
	s_waitcnt vmcnt(12)
	ds_write2_b32 v87, v10, v11 offset1:1
	ds_write2_b32 v88, v12, v13 offset1:1
	s_waitcnt vmcnt(11)
	ds_write2_b32 v89, v22, v23 offset1:1
	ds_write2_b32 v90, v24, v25 offset1:1
	s_waitcnt vmcnt(10)
	ds_write2_b32 v91, v18, v19 offset1:1
	ds_write2_b32 v92, v20, v21 offset1:1
	s_waitcnt vmcnt(9)
	ds_write2_b32 v93, v30, v31 offset1:1
	ds_write2_b32 v94, v32, v33 offset1:1
	s_waitcnt vmcnt(8)
	ds_write2_b32 v95, v26, v27 offset1:1
	ds_write2_b32 v96, v28, v29 offset1:1
	s_waitcnt vmcnt(7)
	ds_write2_b32 v97, v38, v39 offset1:1
	ds_write2_b32 v98, v40, v41 offset1:1
	s_waitcnt vmcnt(6)
	ds_write2_b32 v99, v34, v35 offset1:1
	ds_write2_b32 v100, v36, v37 offset1:1
	s_waitcnt vmcnt(5)
	ds_write2_b32 v101, v46, v47 offset1:1
	ds_write2_b32 v102, v48, v49 offset1:1
	s_waitcnt vmcnt(4)
	ds_write2_b32 v103, v42, v43 offset1:1
	ds_write2_b32 v104, v44, v45 offset1:1
	s_waitcnt vmcnt(3)
	ds_write2_b32 v105, v54, v55 offset1:1
	ds_write2_b32 v106, v56, v57 offset1:1
	s_waitcnt vmcnt(2)
	ds_write2_b32 v107, v50, v51 offset1:1
	ds_write2_b32 v108, v52, v53 offset1:1
	s_waitcnt vmcnt(1)
	ds_write2_b32 v109, v58, v59 offset1:1
	ds_write2_b32 v110, v60, v61 offset1:1
	s_waitcnt vmcnt(0)
	ds_write2_b32 v111, v62, v63 offset1:1
	ds_write2_b32 v112, v64, v65 offset1:1
	s_waitcnt lgkmcnt(0)
; #define LAS __attribute__((address_space(3)))
; #define LDS_WAIT() asm volatile("s_waitcnt lgkmcnt(0)" ::: "memory")
; __device__ __forceinline__ unsigned cvtpk(float lo, float hi) { unsigned r; asm volatile("v_cvt_pk_bf16_f32 %0, %1, %2" : "=v"(r) : "v"(lo), "v"(hi)); return r; }
; __device__ __forceinline__ void tr_item(const float* W, int ldw, bf16* WT, int ldt, const float* gain, int dst_row0, int k0, int n0, LAS float* scr, int lane) {
;     ...
;     const int c = lane & 7;
; #pragma unroll
;     for (int j = 0; j < 8; ++j) { const int n = (lane >> 3) + 8 * j; const LAS float* s = scr + (8 * c) * 65 + n;
;         u32x4 o; o.x = cvtpk(s[0 * 65], s[1 * 65]); o.y = cvtpk(s[2 * 65], s[3 * 65]); o.z = cvtpk(s[4 * 65], s[5 * 65]); o.w = cvtpk(s[6 * 65], s[7 * 65]);
;         *(u32x4*)(WT + (size_t)(dst_row0 + n) * ldt + k0 + 8 * c) = o; }
;     LDS_WAIT(); asm volatile("" ::: "memory");
	ds_read2_b32 v[252:253], v72 offset1:65
	ds_read2_b32 v[250:251], v72 offset0:130 offset1:195
	ds_read2_b32 v[248:249], v82 offset0:4 offset1:69
	ds_read2_b32 v[246:247], v82 offset0:134 offset1:199
	v_add_u32_e32 v6, s8, v80
	v_lshl_add_u64 v[8:9], s[6:7], 0, v[70:71]
	s_mov_b64 s[6:7], 0x13b00000
	v_ashrrev_i32_e32 v7, 31, v6
	v_lshl_add_u64 v[8:9], v[8:9], 0, s[6:7]
	v_lshlrev_b64 v[6:7], 12, v[6:7]
	v_lshl_add_u64 v[6:7], v[8:9], 0, v[6:7]
	ds_read2_b32 v[244:245], v72 offset0:8 offset1:73
	v_mov_b32_e32 v156, v6
	v_mov_b32_e32 v157, v7
	s_nop 0
	ds_read2_b32 v[242:243], v72 offset0:138 offset1:203
	ds_read2_b32 v[240:241], v82 offset0:12 offset1:77
	ds_read2_b32 v[238:239], v82 offset0:142 offset1:207
	v_add_u32_e32 v6, s8, v79
	v_ashrrev_i32_e32 v7, 31, v6
	v_lshlrev_b64 v[6:7], 12, v[6:7]
	v_lshl_add_u64 v[6:7], v[8:9], 0, v[6:7]
	ds_read2_b32 v[236:237], v72 offset0:16 offset1:81
	v_mov_b32_e32 v154, v6
	v_mov_b32_e32 v155, v7
	s_nop 0
	ds_read2_b32 v[234:235], v72 offset0:146 offset1:211
	ds_read2_b32 v[232:233], v82 offset0:20 offset1:85
	ds_read2_b32 v[216:217], v82 offset0:150 offset1:215
	v_add_u32_e32 v6, s8, v78
	v_ashrrev_i32_e32 v7, 31, v6
	v_lshlrev_b64 v[6:7], 12, v[6:7]
	v_lshl_add_u64 v[6:7], v[8:9], 0, v[6:7]
	ds_read2_b32 v[214:215], v72 offset0:24 offset1:89
	v_mov_b32_e32 v152, v6
	v_mov_b32_e32 v153, v7
	s_nop 0
	ds_read2_b32 v[212:213], v72 offset0:154 offset1:219
	ds_read2_b32 v[210:211], v82 offset0:28 offset1:93
	ds_read2_b32 v[208:209], v82 offset0:158 offset1:223
	v_add_u32_e32 v6, s8, v77
	v_ashrrev_i32_e32 v7, 31, v6
	v_lshlrev_b64 v[6:7], 12, v[6:7]
	ds_read2_b32 v[206:207], v72 offset0:32 offset1:97
	v_lshl_add_u64 v[6:7], v[8:9], 0, v[6:7]
	v_mov_b32_e32 v150, v6
	v_mov_b32_e32 v151, v7
	s_nop 0
	v_add_u32_e32 v10, s8, v76
	v_ashrrev_i32_e32 v11, 31, v10
	ds_read2_b32 v[204:205], v72 offset0:162 offset1:227
	v_lshlrev_b64 v[10:11], 12, v[10:11]
	ds_read2_b32 v[202:203], v82 offset0:36 offset1:101
	v_lshl_add_u64 v[10:11], v[8:9], 0, v[10:11]
	ds_read2_b32 v[200:201], v82 offset0:166 offset1:231
	v_mov_b32_e32 v148, v10
	v_mov_b32_e32 v149, v11
	v_add_u32_e32 v10, s8, v75
	v_ashrrev_i32_e32 v11, 31, v10
	ds_read2_b32 v[198:199], v72 offset0:40 offset1:105
	ds_read2_b32 v[196:197], v72 offset0:170 offset1:235
	v_lshlrev_b64 v[10:11], 12, v[10:11]
	ds_read2_b32 v[194:195], v82 offset0:44 offset1:109
	v_lshl_add_u64 v[10:11], v[8:9], 0, v[10:11]
	ds_read2_b32 v[176:177], v82 offset0:174 offset1:239
	v_mov_b32_e32 v146, v10
	v_mov_b32_e32 v147, v11
	v_add_u32_e32 v10, s8, v74
	ds_read2_b32 v[174:175], v72 offset0:48 offset1:113
	ds_read2_b32 v[172:173], v72 offset0:178 offset1:243
	v_ashrrev_i32_e32 v11, 31, v10
	ds_read2_b32 v[170:171], v82 offset0:52 offset1:117
	v_lshlrev_b64 v[10:11], 12, v[10:11]
	ds_read2_b32 v[168:169], v82 offset0:182 offset1:247
	v_lshl_add_u64 v[10:11], v[8:9], 0, v[10:11]
	ds_read2_b32 v[166:167], v72 offset0:56 offset1:121
	v_mov_b32_e32 v144, v10
	v_mov_b32_e32 v145, v11
	v_add_u32_e32 v10, s8, v73
	v_ashrrev_i32_e32 v11, 31, v10
	ds_read2_b32 v[164:165], v72 offset0:186 offset1:251
	ds_read2_b32 v[162:163], v82 offset0:60 offset1:125
	ds_read2_b32 v[160:161], v82 offset0:190 offset1:255
	v_lshlrev_b64 v[10:11], 12, v[10:11]
	v_lshl_add_u64 v[6:7], v[8:9], 0, v[10:11]
	v_mov_b32_e32 v142, v6
	v_mov_b32_e32 v143, v7
	s_waitcnt lgkmcnt(0)
	v_cvt_pk_bf16_f32 v159, v252, v253
	v_cvt_pk_bf16_f32 v253, v250, v251
	v_cvt_pk_bf16_f32 v252, v248, v249
	v_cvt_pk_bf16_f32 v251, v246, v247
	v_mov_b32_e32 v132, v159
	v_mov_b32_e32 v133, v253
	v_mov_b32_e32 v134, v252
	v_mov_b32_e32 v135, v251
	global_store_dwordx4 v[156:157], v[132:135], off
	v_cvt_pk_bf16_f32 v250, v244, v245
	v_cvt_pk_bf16_f32 v253, v242, v243
	v_cvt_pk_bf16_f32 v252, v240, v241
	v_cvt_pk_bf16_f32 v251, v238, v239
	v_mov_b32_e32 v136, v250
	v_mov_b32_e32 v137, v253
	v_mov_b32_e32 v138, v252
	v_mov_b32_e32 v139, v251
	global_store_dwordx4 v[154:155], v[136:139], off
	v_cvt_pk_bf16_f32 v249, v236, v237
	v_cvt_pk_bf16_f32 v253, v234, v235
	v_cvt_pk_bf16_f32 v252, v232, v233
	v_cvt_pk_bf16_f32 v251, v216, v217
	v_mov_b32_e32 v132, v249
	v_mov_b32_e32 v133, v253
	v_mov_b32_e32 v134, v252
	v_mov_b32_e32 v135, v251
	global_store_dwordx4 v[152:153], v[132:135], off
	v_cvt_pk_bf16_f32 v250, v214, v215
	v_cvt_pk_bf16_f32 v253, v212, v213
	v_cvt_pk_bf16_f32 v252, v210, v211
	v_cvt_pk_bf16_f32 v251, v208, v209
	v_mov_b32_e32 v136, v250
	v_mov_b32_e32 v137, v253
	v_mov_b32_e32 v138, v252
	v_mov_b32_e32 v139, v251
	global_store_dwordx4 v[150:151], v[136:139], off
	v_cvt_pk_bf16_f32 v249, v206, v207
	v_cvt_pk_bf16_f32 v253, v204, v205
	v_cvt_pk_bf16_f32 v252, v202, v203
	v_cvt_pk_bf16_f32 v251, v200, v201
	v_mov_b32_e32 v132, v249
	v_mov_b32_e32 v133, v253
	v_mov_b32_e32 v134, v252
	v_mov_b32_e32 v135, v251
	global_store_dwordx4 v[148:149], v[132:135], off
	v_cvt_pk_bf16_f32 v250, v198, v199
	v_cvt_pk_bf16_f32 v253, v196, v197
	v_cvt_pk_bf16_f32 v252, v194, v195
	v_cvt_pk_bf16_f32 v251, v176, v177
	v_mov_b32_e32 v136, v250
	v_mov_b32_e32 v137, v253
	v_mov_b32_e32 v138, v252
	v_mov_b32_e32 v139, v251
	global_store_dwordx4 v[146:147], v[136:139], off
	v_cvt_pk_bf16_f32 v249, v174, v175
	v_cvt_pk_bf16_f32 v253, v172, v173
	v_cvt_pk_bf16_f32 v252, v170, v171
	v_cvt_pk_bf16_f32 v251, v168, v169
	v_mov_b32_e32 v132, v249
	v_mov_b32_e32 v133, v253
	v_mov_b32_e32 v134, v252
	v_mov_b32_e32 v135, v251
	global_store_dwordx4 v[144:145], v[132:135], off
	v_cvt_pk_bf16_f32 v250, v166, v167
	v_cvt_pk_bf16_f32 v253, v164, v165
	v_cvt_pk_bf16_f32 v252, v162, v163
	v_cvt_pk_bf16_f32 v251, v160, v161
	v_mov_b32_e32 v136, v250
	v_mov_b32_e32 v137, v253
	v_mov_b32_e32 v138, v252
	v_mov_b32_e32 v139, v251
	global_store_dwordx4 v[142:143], v[136:139], off
	s_waitcnt lgkmcnt(0)
	s_cbranch_execnz .LBB0_763
; #define LAS __attribute__((address_space(3)))
; #define LDS_WAIT() asm volatile("s_waitcnt lgkmcnt(0)" ::: "memory")
; __device__ __forceinline__ void tr_item(const float* W, int ldw, bf16* WT, int ldt, const float* gain, int dst_row0, int k0, int n0, LAS float* scr, int lane) {
;     ...
;     for (int i = 0; i < 16; ++i) v[i] = __builtin_nontemporal_load((const f32x4*)(W + (size_t)(k0 + kr + 4 * i) * ldw + n0 + n4));
; #pragma unroll
;     for (int i = 0; i < 16; ++i) { const int k = kr + 4 * i; const float g = gain ? gain[k0 + k] : 1.0f; LAS float* d = scr + k * 65 + n4;
;         d[0] = v[i][0] * g; d[1] = v[i][1] * g; d[2] = v[i][2] * g; d[3] = v[i][3] * g; }
;     LDS_WAIT(); asm volatile("" ::: "memory");
.LBB0_767:
	s_ashr_i32 s6, s11, 31
	s_lshr_b32 s6, s6, 27
	s_add_i32 s6, s11, s6
	s_ashr_i32 s6, s6, 5
	s_load_dwordx2 s[8:9], s[4:5], 0x68
	s_lshl_b32 s7, s6, 11
	s_sub_i32 s12, s2, s7
	s_add_i32 s14, s12, 0xffff8e00
	s_ashr_i32 s15, s14, 31
	s_lshl_b32 s6, s6, 6
	s_lshl_b64 s[14:15], s[14:15], 2
	v_or_b32_e32 v62, s6, v67
	s_waitcnt lgkmcnt(0)
	s_add_u32 s8, s8, s14
	s_addc_u32 s9, s9, s15
	v_or_b32_e32 v4, 4, v62
	v_or_b32_e32 v10, 8, v62
	v_or_b32_e32 v12, 12, v62
	v_or_b32_e32 v18, 16, v62
	v_or_b32_e32 v20, 20, v62
	v_or_b32_e32 v26, 24, v62
	v_or_b32_e32 v28, 28, v62
	v_or_b32_e32 v34, 32, v62
	v_or_b32_e32 v36, 36, v62
	v_or_b32_e32 v42, 40, v62
	v_or_b32_e32 v44, 44, v62
	v_or_b32_e32 v50, 48, v62
	v_or_b32_e32 v52, 52, v62
	v_lshl_add_u64 v[2:3], s[8:9], 0, v[0:1]
	s_mov_b64 s[8:9], 0x2c00000
	v_ashrrev_i32_e32 v63, 31, v62
	v_ashrrev_i32_e32 v5, 31, v4
	v_ashrrev_i32_e32 v11, 31, v10
	v_ashrrev_i32_e32 v13, 31, v12
	v_ashrrev_i32_e32 v19, 31, v18
	v_ashrrev_i32_e32 v21, 31, v20
	v_ashrrev_i32_e32 v27, 31, v26
	v_ashrrev_i32_e32 v29, 31, v28
	v_ashrrev_i32_e32 v35, 31, v34
	v_ashrrev_i32_e32 v37, 31, v36
	v_ashrrev_i32_e32 v43, 31, v42
	v_ashrrev_i32_e32 v45, 31, v44
	v_ashrrev_i32_e32 v51, 31, v50
	v_ashrrev_i32_e32 v53, 31, v52
	v_lshl_add_u64 v[64:65], v[2:3], 0, s[8:9]
	v_lshlrev_b64 v[2:3], 13, v[62:63]
	v_lshlrev_b64 v[4:5], 13, v[4:5]
	v_lshlrev_b64 v[10:11], 13, v[10:11]
	v_lshlrev_b64 v[12:13], 13, v[12:13]
	v_lshlrev_b64 v[18:19], 13, v[18:19]
	v_lshlrev_b64 v[20:21], 13, v[20:21]
	v_lshlrev_b64 v[26:27], 13, v[26:27]
	v_lshlrev_b64 v[28:29], 13, v[28:29]
	v_lshlrev_b64 v[34:35], 13, v[34:35]
	v_lshlrev_b64 v[36:37], 13, v[36:37]
	v_lshlrev_b64 v[42:43], 13, v[42:43]
	v_lshlrev_b64 v[44:45], 13, v[44:45]
	v_lshlrev_b64 v[50:51], 13, v[50:51]
	v_lshlrev_b64 v[52:53], 13, v[52:53]
	v_lshl_add_u64 v[2:3], v[64:65], 0, v[2:3]
	v_lshl_add_u64 v[4:5], v[64:65], 0, v[4:5]
	v_lshl_add_u64 v[10:11], v[64:65], 0, v[10:11]
	v_lshl_add_u64 v[12:13], v[64:65], 0, v[12:13]
	v_lshl_add_u64 v[18:19], v[64:65], 0, v[18:19]
	v_lshl_add_u64 v[20:21], v[64:65], 0, v[20:21]
	v_lshl_add_u64 v[26:27], v[64:65], 0, v[26:27]
	v_lshl_add_u64 v[28:29], v[64:65], 0, v[28:29]
	v_lshl_add_u64 v[34:35], v[64:65], 0, v[34:35]
	v_lshl_add_u64 v[36:37], v[64:65], 0, v[36:37]
	v_lshl_add_u64 v[42:43], v[64:65], 0, v[42:43]
	v_lshl_add_u64 v[44:45], v[64:65], 0, v[44:45]
	v_lshl_add_u64 v[50:51], v[64:65], 0, v[50:51]
	v_lshl_add_u64 v[52:53], v[64:65], 0, v[52:53]
	global_load_dwordx4 v[6:9], v[2:3], off nt
	s_nop 0
	global_load_dwordx4 v[2:5], v[4:5], off nt
	s_nop 0
	global_load_dwordx4 v[14:17], v[10:11], off nt
	s_nop 0
	global_load_dwordx4 v[10:13], v[12:13], off nt
	s_nop 0
	global_load_dwordx4 v[22:25], v[18:19], off nt
	s_nop 0
	global_load_dwordx4 v[18:21], v[20:21], off nt
	s_nop 0
	global_load_dwordx4 v[30:33], v[26:27], off nt
	s_nop 0
	global_load_dwordx4 v[26:29], v[28:29], off nt
	s_nop 0
	global_load_dwordx4 v[38:41], v[34:35], off nt
	s_nop 0
	global_load_dwordx4 v[34:37], v[36:37], off nt
	s_nop 0
	global_load_dwordx4 v[46:49], v[42:43], off nt
	s_nop 0
	global_load_dwordx4 v[42:45], v[44:45], off nt
	s_nop 0
	global_load_dwordx4 v[54:57], v[50:51], off nt
	s_nop 0
	global_load_dwordx4 v[50:53], v[52:53], off nt
	v_or_b32_e32 v58, 56, v62
	v_ashrrev_i32_e32 v59, 31, v58
	v_lshlrev_b64 v[58:59], 13, v[58:59]
	v_or_b32_e32 v62, 60, v62
	v_lshl_add_u64 v[58:59], v[64:65], 0, v[58:59]
	v_ashrrev_i32_e32 v63, 31, v62
	global_load_dwordx4 v[58:61], v[58:59], off nt
	v_lshlrev_b64 v[62:63], 13, v[62:63]
	v_lshl_add_u64 v[62:63], v[64:65], 0, v[62:63]
	global_load_dwordx4 v[62:65], v[62:63], off nt
	s_load_dwordx2 s[8:9], s[4:5], 0x118
	s_ashr_i32 s7, s6, 31
	s_lshl_b64 s[6:7], s[6:7], 1
	v_mov_b32_e32 v71, v1
	v_add_u32_e32 v0, s12, v69
	s_waitcnt vmcnt(15)
	ds_write2_b32 v81, v6, v7 offset1:1
	ds_write2_b32 v81, v8, v9 offset0:2 offset1:3
	s_waitcnt vmcnt(14)
	ds_write2_b32 v83, v2, v3 offset1:1
	ds_write2_b32 v84, v4, v5 offset1:1
	s_waitcnt vmcnt(13)
	ds_write2_b32 v85, v14, v15 offset1:1
	ds_write2_b32 v86, v16, v17 offset1:1
	s_waitcnt vmcnt(12)
	ds_write2_b32 v87, v10, v11 offset1:1
	ds_write2_b32 v88, v12, v13 offset1:1
	s_waitcnt vmcnt(11)
	ds_write2_b32 v89, v22, v23 offset1:1
	ds_write2_b32 v90, v24, v25 offset1:1
	s_waitcnt vmcnt(10)
	ds_write2_b32 v91, v18, v19 offset1:1
	ds_write2_b32 v92, v20, v21 offset1:1
	s_waitcnt vmcnt(9)
	ds_write2_b32 v93, v30, v31 offset1:1
	ds_write2_b32 v94, v32, v33 offset1:1
	s_waitcnt vmcnt(8)
	ds_write2_b32 v95, v26, v27 offset1:1
	ds_write2_b32 v96, v28, v29 offset1:1
	s_waitcnt vmcnt(7)
	ds_write2_b32 v97, v38, v39 offset1:1
	ds_write2_b32 v98, v40, v41 offset1:1
	s_waitcnt vmcnt(6)
	ds_write2_b32 v99, v34, v35 offset1:1
	ds_write2_b32 v100, v36, v37 offset1:1
	s_waitcnt vmcnt(5)
	ds_write2_b32 v101, v46, v47 offset1:1
	ds_write2_b32 v102, v48, v49 offset1:1
	s_waitcnt vmcnt(4)
	ds_write2_b32 v103, v42, v43 offset1:1
	ds_write2_b32 v104, v44, v45 offset1:1
	s_waitcnt vmcnt(3)
	ds_write2_b32 v105, v54, v55 offset1:1
	ds_write2_b32 v106, v56, v57 offset1:1
	s_waitcnt vmcnt(2)
	ds_write2_b32 v107, v50, v51 offset1:1
	ds_write2_b32 v108, v52, v53 offset1:1
	s_waitcnt vmcnt(1)
	ds_write2_b32 v109, v58, v59 offset1:1
	ds_write2_b32 v110, v60, v61 offset1:1
	s_waitcnt vmcnt(0)
	ds_write2_b32 v111, v62, v63 offset1:1
	ds_write2_b32 v112, v64, v65 offset1:1
	s_waitcnt lgkmcnt(0)
; #define LAS __attribute__((address_space(3)))
; #define LDS_WAIT() asm volatile("s_waitcnt lgkmcnt(0)" ::: "memory")
; __device__ __forceinline__ unsigned cvtpk(float lo, float hi) { unsigned r; asm volatile("v_cvt_pk_bf16_f32 %0, %1, %2" : "=v"(r) : "v"(lo), "v"(hi)); return r; }
; __device__ __forceinline__ void tr_item(const float* W, int ldw, bf16* WT, int ldt, const float* gain, int dst_row0, int k0, int n0, LAS float* scr, int lane) {
;     ...
;     const int c = lane & 7;
; #pragma unroll
;     for (int j = 0; j < 8; ++j) { const int n = (lane >> 3) + 8 * j; const LAS float* s = scr + (8 * c) * 65 + n;
;         u32x4 o; o.x = cvtpk(s[0 * 65], s[1 * 65]); o.y = cvtpk(s[2 * 65], s[3 * 65]); o.z = cvtpk(s[4 * 65], s[5 * 65]); o.w = cvtpk(s[6 * 65], s[7 * 65]);
;         *(u32x4*)(WT + (size_t)(dst_row0 + n) * ldt + k0 + 8 * c) = o; }
;     LDS_WAIT(); asm volatile("" ::: "memory");
	s_waitcnt lgkmcnt(0)
	s_add_u32 s6, s8, s6
	ds_read2_b32 v[252:253], v72 offset1:65
	s_addc_u32 s7, s9, s7
	ds_read2_b32 v[250:251], v72 offset0:130 offset1:195
	v_lshl_add_u64 v[8:9], s[6:7], 0, v[70:71]
	s_mov_b64 s[6:7], 0xf200000
	ds_read2_b32 v[248:249], v82 offset0:4 offset1:69
	v_lshl_add_u64 v[8:9], v[8:9], 0, s[6:7]
	v_add_u32_e32 v10, 0xffff8e00, v0
	ds_read2_b32 v[246:247], v82 offset0:134 offset1:199
	v_mad_i64_i32 v[10:11], s[6:7], v10, s61, v[8:9]
	ds_read2_b32 v[244:245], v72 offset0:8 offset1:73
	v_mov_b32_e32 v156, v10
	v_mov_b32_e32 v157, v11
	v_add_u32_e32 v10, 0xffff8e08, v0
	v_mad_i64_i32 v[10:11], s[6:7], v10, s61, v[8:9]
	ds_read2_b32 v[242:243], v72 offset0:138 offset1:203
	ds_read2_b32 v[240:241], v82 offset0:12 offset1:77
	ds_read2_b32 v[238:239], v82 offset0:142 offset1:207
	ds_read2_b32 v[236:237], v72 offset0:16 offset1:81
	v_mov_b32_e32 v154, v10
	v_mov_b32_e32 v155, v11
	v_add_u32_e32 v10, 0xffff8e10, v0
	v_mad_i64_i32 v[10:11], s[6:7], v10, s61, v[8:9]
	ds_read2_b32 v[234:235], v72 offset0:146 offset1:211
	ds_read2_b32 v[232:233], v82 offset0:20 offset1:85
	ds_read2_b32 v[216:217], v82 offset0:150 offset1:215
	ds_read2_b32 v[214:215], v72 offset0:24 offset1:89
	v_mov_b32_e32 v152, v10
	v_mov_b32_e32 v153, v11
	v_add_u32_e32 v10, 0xffff8e18, v0
	v_mad_i64_i32 v[10:11], s[6:7], v10, s61, v[8:9]
	ds_read2_b32 v[212:213], v72 offset0:154 offset1:219
	ds_read2_b32 v[210:211], v82 offset0:28 offset1:93
	ds_read2_b32 v[208:209], v82 offset0:158 offset1:223
	ds_read2_b32 v[206:207], v72 offset0:32 offset1:97
	v_mov_b32_e32 v150, v10
	v_mov_b32_e32 v151, v11
	v_add_u32_e32 v10, 0xffff8e20, v0
	v_mad_i64_i32 v[10:11], s[6:7], v10, s61, v[8:9]
	ds_read2_b32 v[204:205], v72 offset0:162 offset1:227
	ds_read2_b32 v[202:203], v82 offset0:36 offset1:101
	ds_read2_b32 v[200:201], v82 offset0:166 offset1:231
	ds_read2_b32 v[198:199], v72 offset0:40 offset1:105
	v_mov_b32_e32 v148, v10
	v_mov_b32_e32 v149, v11
	v_add_u32_e32 v10, 0xffff8e28, v0
	v_mad_i64_i32 v[10:11], s[6:7], v10, s61, v[8:9]
	ds_read2_b32 v[196:197], v72 offset0:170 offset1:235
	ds_read2_b32 v[194:195], v82 offset0:44 offset1:109
	ds_read2_b32 v[176:177], v82 offset0:174 offset1:239
	ds_read2_b32 v[174:175], v72 offset0:48 offset1:113
	v_mov_b32_e32 v146, v10
	v_mov_b32_e32 v147, v11
	v_add_u32_e32 v10, 0xffff8e30, v0
	v_mad_i64_i32 v[10:11], s[6:7], v10, s61, v[8:9]
	ds_read2_b32 v[172:173], v72 offset0:178 offset1:243
	ds_read2_b32 v[170:171], v82 offset0:52 offset1:117
	ds_read2_b32 v[168:169], v82 offset0:182 offset1:247
	ds_read2_b32 v[166:167], v72 offset0:56 offset1:121
	v_mov_b32_e32 v144, v10
	v_mov_b32_e32 v145, v11
	v_add_u32_e32 v0, 0xffff8e38, v0
	ds_read2_b32 v[164:165], v72 offset0:186 offset1:251
	ds_read2_b32 v[162:163], v82 offset0:60 offset1:125
	ds_read2_b32 v[160:161], v82 offset0:190 offset1:255
	v_mad_i64_i32 v[6:7], s[6:7], v0, s61, v[8:9]
	v_mov_b32_e32 v142, v6
	v_mov_b32_e32 v143, v7
	s_waitcnt lgkmcnt(0)
	v_cvt_pk_bf16_f32 v159, v252, v253
	v_cvt_pk_bf16_f32 v253, v250, v251
	v_cvt_pk_bf16_f32 v252, v248, v249
	v_cvt_pk_bf16_f32 v251, v246, v247
	v_mov_b32_e32 v132, v159
	v_mov_b32_e32 v133, v253
	v_mov_b32_e32 v134, v252
	v_mov_b32_e32 v135, v251
	global_store_dwordx4 v[156:157], v[132:135], off
	v_cvt_pk_bf16_f32 v250, v244, v245
	v_cvt_pk_bf16_f32 v253, v242, v243
	v_cvt_pk_bf16_f32 v252, v240, v241
	v_cvt_pk_bf16_f32 v251, v238, v239
	v_mov_b32_e32 v136, v250
	v_mov_b32_e32 v137, v253
	v_mov_b32_e32 v138, v252
	v_mov_b32_e32 v139, v251
	global_store_dwordx4 v[154:155], v[136:139], off
	v_cvt_pk_bf16_f32 v249, v236, v237
	v_cvt_pk_bf16_f32 v253, v234, v235
	v_cvt_pk_bf16_f32 v252, v232, v233
	v_cvt_pk_bf16_f32 v251, v216, v217
	v_mov_b32_e32 v132, v249
	v_mov_b32_e32 v133, v253
	v_mov_b32_e32 v134, v252
	v_mov_b32_e32 v135, v251
	global_store_dwordx4 v[152:153], v[132:135], off
	v_cvt_pk_bf16_f32 v250, v214, v215
	v_cvt_pk_bf16_f32 v253, v212, v213
	v_cvt_pk_bf16_f32 v252, v210, v211
	v_cvt_pk_bf16_f32 v251, v208, v209
	v_mov_b32_e32 v136, v250
	v_mov_b32_e32 v137, v253
	v_mov_b32_e32 v138, v252
	v_mov_b32_e32 v139, v251
	global_store_dwordx4 v[150:151], v[136:139], off
	v_cvt_pk_bf16_f32 v249, v206, v207
	v_cvt_pk_bf16_f32 v253, v204, v205
	v_cvt_pk_bf16_f32 v252, v202, v203
	v_cvt_pk_bf16_f32 v251, v200, v201
	v_mov_b32_e32 v132, v249
	v_mov_b32_e32 v133, v253
	v_mov_b32_e32 v134, v252
	v_mov_b32_e32 v135, v251
	global_store_dwordx4 v[148:149], v[132:135], off
	v_cvt_pk_bf16_f32 v250, v198, v199
	v_cvt_pk_bf16_f32 v253, v196, v197
	v_cvt_pk_bf16_f32 v252, v194, v195
	v_cvt_pk_bf16_f32 v251, v176, v177
	v_mov_b32_e32 v136, v250
	v_mov_b32_e32 v137, v253
	v_mov_b32_e32 v138, v252
	v_mov_b32_e32 v139, v251
	global_store_dwordx4 v[146:147], v[136:139], off
	v_cvt_pk_bf16_f32 v249, v174, v175
	v_cvt_pk_bf16_f32 v253, v172, v173
	v_cvt_pk_bf16_f32 v252, v170, v171
	v_cvt_pk_bf16_f32 v251, v168, v169
	v_mov_b32_e32 v132, v249
	v_mov_b32_e32 v133, v253
	v_mov_b32_e32 v134, v252
	v_mov_b32_e32 v135, v251
	global_store_dwordx4 v[144:145], v[132:135], off
	v_cvt_pk_bf16_f32 v250, v166, v167
	v_cvt_pk_bf16_f32 v253, v164, v165
	v_cvt_pk_bf16_f32 v252, v162, v163
	v_cvt_pk_bf16_f32 v251, v160, v161
	v_mov_b32_e32 v136, v250
	v_mov_b32_e32 v137, v253
	v_mov_b32_e32 v138, v252
	v_mov_b32_e32 v139, v251
	global_store_dwordx4 v[142:143], v[136:139], off
	s_waitcnt lgkmcnt(0)
	s_branch .LBB0_763

; __device__ __forceinline__ void phase_gla_norm(KArgs a, int gw, int NGW, int lane) {
;     ...
;         else { const int s = row - MPROMPT; const u32x2 qw = *(const u32x2*)(Q + (size_t)row * 1024 + h * 256 + lane * 4), kw = *(const u32x2*)(Kf + (size_t)row * 1024 + h * 256 + lane * 4); const f32x4 q = (f32x4){bflo(qw.x), bfhi(qw.x), bflo(qw.y), bfhi(qw.y)}, k = (f32x4){bflo(kw.x), bfhi(kw.x), bflo(kw.y), bfhi(kw.y)};
;             const float qk = wave_sum((q[0] * k[0] + q[1] * k[1]) + (q[2] * k[2] + q[3] * k[3]));
;             const u32x2 va = *(const u32x2*)(V + off), vb = *(const u32x2*)(V + off + 256);
;             o0 = (f32x4){bflo(va.x), bfhi(va.x), bflo(va.y), bfhi(va.y)} * qk; o1 = (f32x4){bflo(vb.x), bfhi(vb.x), bflo(vb.y), bfhi(vb.y)} * qk;
; #pragma unroll
;             for (int p = 0; p < 8; ++p) { const float* op = OP + ((size_t)p * MSAMP + s) * DM + h * 512 + lane * 4; o0 = o0 + *(const f32x4*)op; o1 = o1 + *(const f32x4*)(op + 256); } }
.LBB0_971:
	s_ashr_i32 s14, s2, 2
	s_ashr_i32 s15, s14, 31
	s_lshl_b64 s[4:5], s[14:15], 11
	v_mov_b32_e32 v25, s5
	v_or_b32_e32 v24, s4, v0
	s_cmpk_gt_i32 s14, 0x1fff
	s_mov_b64 s[16:17], -1
	s_cbranch_scc0 .LBB0_973
	v_lshl_add_u64 v[10:11], v[18:19], 0, s[4:5]
	v_lshl_add_u64 v[12:13], v[20:21], 0, s[4:5]
	global_load_dwordx2 v[10:11], v[10:11], off
	s_add_i32 s48, s14, 0xffffe000
	global_load_dwordx2 v[12:13], v[12:13], off
	s_lshl_b64 s[4:5], s[48:49], 13
	s_mov_b64 s[16:17], 0
	s_waitcnt vmcnt(1)
	v_lshlrev_b32_e32 v15, 16, v11
	v_lshlrev_b32_e32 v14, 16, v10
	v_and_b32_e32 v11, 0xffff0000, v11
	v_and_b32_e32 v10, 0xffff0000, v10
	s_waitcnt vmcnt(0)
	v_lshlrev_b32_e32 v17, 16, v13
	v_lshlrev_b32_e32 v16, 16, v12
	v_and_b32_e32 v13, 0xffff0000, v13
	v_and_b32_e32 v12, 0xffff0000, v12
	v_pk_mul_f32 v[10:11], v[10:11], v[12:13]
	s_nop 0
	v_pk_fma_f32 v[10:11], v[14:15], v[16:17], v[10:11]
	s_nop 0
	v_add_f32_e32 v10, v10, v11
	ds_bpermute_b32 v11, v28, v10
	s_waitcnt lgkmcnt(0)
	v_add_f32_e32 v10, v10, v11
	ds_bpermute_b32 v11, v29, v10
	s_waitcnt lgkmcnt(0)
	v_add_f32_e32 v10, v10, v11
	ds_bpermute_b32 v11, v30, v10
	s_waitcnt lgkmcnt(0)
	v_add_f32_e32 v10, v10, v11
	ds_bpermute_b32 v11, v31, v10
	s_waitcnt lgkmcnt(0)
	v_add_f32_e32 v10, v10, v11
	ds_bpermute_b32 v11, v32, v10
	s_waitcnt lgkmcnt(0)
	v_add_f32_e32 v10, v10, v11
	ds_bpermute_b32 v11, v33, v10
	s_waitcnt lgkmcnt(0)
	v_add_f32_e32 v16, v10, v11
	v_lshl_add_u64 v[10:11], v[24:25], 1, s[12:13]
	global_load_dwordx2 v[176:177], v[10:11], off
	s_nop 0
	global_load_dwordx2 v[174:175], v[10:11], off offset:512
	v_lshl_add_u64 v[10:11], v[22:23], 0, s[4:5]
	global_load_dwordx4 v[96:99], v[10:11], off
	global_load_dwordx4 v[100:103], v[10:11], off offset:1024
	v_add_co_u32_e32 v38, vcc, s45, v10
	s_nop 1
	v_addc_co_u32_e32 v39, vcc, 0, v11, vcc
	global_load_dwordx4 v[104:107], v[38:39], off
	global_load_dwordx4 v[108:111], v[38:39], off offset:1024
	v_add_co_u32_e32 v38, vcc, s39, v10
	s_nop 1
	v_addc_co_u32_e32 v39, vcc, 0, v11, vcc
	global_load_dwordx4 v[112:115], v[38:39], off
	global_load_dwordx4 v[116:119], v[38:39], off offset:1024
	v_add_co_u32_e32 v38, vcc, s47, v10
	s_nop 1
	v_addc_co_u32_e32 v39, vcc, 0, v11, vcc
	global_load_dwordx4 v[120:123], v[38:39], off
	global_load_dwordx4 v[124:127], v[38:39], off offset:1024
	v_add_co_u32_e32 v38, vcc, s77, v10
	s_nop 1
	v_addc_co_u32_e32 v39, vcc, 0, v11, vcc
	global_load_dwordx4 v[128:131], v[38:39], off
	global_load_dwordx4 v[132:135], v[38:39], off offset:1024
	v_add_co_u32_e32 v38, vcc, s35, v10
	s_nop 1
	v_addc_co_u32_e32 v39, vcc, 0, v11, vcc
	global_load_dwordx4 v[136:139], v[38:39], off
	global_load_dwordx4 v[140:143], v[38:39], off offset:1024
	s_waitcnt vmcnt(0)
	v_lshlrev_b32_e32 v173, 16, v176
	v_lshlrev_b32_e32 v172, 16, v174
	v_and_b32_e32 v171, 0xffff0000, v174
	v_lshlrev_b32_e32 v174, 16, v175
	v_and_b32_e32 v170, 0xffff0000, v175
	v_and_b32_e32 v175, 0xffff0000, v176
	v_lshlrev_b32_e32 v176, 16, v177
	v_and_b32_e32 v169, 0xffff0000, v177
	v_mov_b32_e32 v166, v173
	v_mov_b32_e32 v167, v175
	v_pk_fma_f32 v[164:165], v[16:17], v[166:167], v[96:97] op_sel_hi:[0,1,1]
	v_mov_b32_e32 v96, v176
	v_mov_b32_e32 v97, v169
	v_pk_fma_f32 v[162:163], v[16:17], v[96:97], v[98:99] op_sel_hi:[0,1,1]
	v_mov_b32_e32 v176, v172
	v_mov_b32_e32 v177, v171
	v_pk_fma_f32 v[98:99], v[16:17], v[176:177], v[100:101] op_sel_hi:[0,1,1]
	v_mov_b32_e32 v172, v174
	v_mov_b32_e32 v173, v170
	v_pk_fma_f32 v[100:101], v[16:17], v[172:173], v[102:103] op_sel_hi:[0,1,1]
	v_pk_add_f32 v[174:175], v[106:107], v[162:163]
	v_pk_add_f32 v[170:171], v[104:105], v[164:165]
	v_pk_add_f32 v[164:165], v[110:111], v[100:101]
	v_pk_add_f32 v[162:163], v[108:109], v[98:99]
	v_pk_add_f32 v[110:111], v[112:113], v[170:171]
	v_pk_add_f32 v[170:171], v[114:115], v[174:175]
	v_pk_add_f32 v[174:175], v[116:117], v[162:163]
	v_pk_add_f32 v[162:163], v[118:119], v[164:165]
	v_pk_add_f32 v[164:165], v[122:123], v[170:171]
	v_pk_add_f32 v[170:171], v[120:121], v[110:111]
	v_pk_add_f32 v[122:123], v[126:127], v[162:163]
	v_pk_add_f32 v[162:163], v[124:125], v[174:175]
	v_pk_add_f32 v[174:175], v[128:129], v[170:171]
	v_pk_add_f32 v[170:171], v[130:131], v[164:165]
	v_pk_add_f32 v[164:165], v[132:133], v[162:163]
	v_pk_add_f32 v[162:163], v[134:135], v[122:123]
	v_pk_add_f32 v[134:135], v[138:139], v[170:171]
	v_pk_add_f32 v[170:171], v[136:137], v[174:175]
	v_pk_add_f32 v[174:175], v[142:143], v[162:163]
	v_mov_b32_e32 v12, v140
	v_mov_b32_e32 v13, v141
	v_mov_b32_e32 v14, v142
	v_mov_b32_e32 v15, v143
	v_mov_b32_e32 v16, v162
	v_mov_b32_e32 v17, v163
	v_mov_b32_e32 v26, v170
	v_mov_b32_e32 v27, v171
	v_mov_b32_e32 v34, v134
	v_mov_b32_e32 v35, v135
	v_mov_b32_e32 v36, v164
	v_mov_b32_e32 v37, v165
	v_mov_b32_e32 v38, v174
	v_mov_b32_e32 v39, v175
	v_add_co_u32_e32 v16, vcc, s74, v10
	v_pk_add_f32 v[36:37], v[12:13], v[36:37]
	s_nop 0
	v_addc_co_u32_e32 v17, vcc, 0, v11, vcc
	global_load_dwordx4 v[96:99], v[16:17], off
	global_load_dwordx4 v[100:103], v[16:17], off offset:1024
	v_mov_b32_e32 v174, v36
	v_mov_b32_e32 v175, v37
	v_add_co_u32_e32 v36, vcc, s66, v10
	s_nop 0
	s_nop 1
	v_addc_co_u32_e32 v37, vcc, 0, v11, vcc
	global_load_dwordx4 v[104:107], v[36:37], off
	global_load_dwordx4 v[108:111], v[36:37], off offset:1024
	s_waitcnt vmcnt(0)
	v_pk_add_f32 v[176:177], v[34:35], v[98:99]
	v_pk_add_f32 v[98:99], v[26:27], v[96:97]
	v_pk_add_f32 v[96:97], v[174:175], v[100:101]
	v_pk_add_f32 v[100:101], v[38:39], v[102:103]
	v_pk_add_f32 v[102:103], v[176:177], v[106:107]
	v_pk_add_f32 v[176:177], v[98:99], v[104:105]
	v_pk_add_f32 v[106:107], v[100:101], v[110:111]
	v_pk_add_f32 v[104:105], v[96:97], v[108:109]
	v_mov_b32_e32 v10, v176
	v_mov_b32_e32 v11, v177
	v_mov_b32_e32 v12, v102
	v_mov_b32_e32 v13, v103
	v_mov_b32_e32 v14, v104
	v_mov_b32_e32 v15, v105
	v_mov_b32_e32 v16, v106
	v_mov_b32_e32 v17, v107
	v_mov_b32_e32 v26, v98
	v_mov_b32_e32 v27, v99
	v_mov_b32_e32 v34, v108
	v_mov_b32_e32 v35, v109
	v_mov_b32_e32 v36, v110
	v_mov_b32_e32 v37, v111

; #define LAS __attribute__((address_space(3)))
; __device__ __forceinline__ void tr_item(const float* W, int ldw, bf16* WT, int ldt, const float* gain, int dst_row0, int k0, int n0, LAS float* scr, int lane) {
;     ...
;     for (int i = 0; i < 16; ++i) v[i] = __builtin_nontemporal_load((const f32x4*)(W + (size_t)(k0 + kr + 4 * i) * ldw + n0 + n4));
; #pragma unroll
;     for (int i = 0; i < 16; ++i) { const int k = kr + 4 * i; const float g = gain ? gain[k0 + k] : 1.0f; LAS float* d = scr + k * 65 + n4;
;         d[0] = v[i][0] * g; d[1] = v[i][1] * g; d[2] = v[i][2] * g; d[3] = v[i][3] * g; }
; __device__ __forceinline__ void late_up_items(KArgs a, int f, int first, int last, int wi, int nw, LAS float* scr, int lane) {
;     ...
;     for (int idx = first + wi; idx < last; idx += nw) { const int m = idx >= IT_UP ? 1 : 0, item = idx - m * IT_UP;
;         const float* src = (second ? (m ? a->in[I_F2W3] : a->in[I_F2W1]) : (m ? a->in[I_F1W3] : a->in[I_F1W1])) + (size_t)layer * DM * FF;
;         tr_job(src, DM, FF, (bf16*)(a->ws + WS_WUP + (size_t)f * SZ_WUP), (second ? a->in[I_LNF2] : a->in[I_LNF1]) + layer * DM, 1, 128 * m, item, scr, lane); }
.LBB0_1863:
	s_cmpk_gt_i32 s15, 0xaff
	s_cselect_b32 s16, 0xfffff500, 0
	s_cselect_b32 s10, 56, 48
	s_cselect_b32 s17, 0x80, 0
	s_add_i32 s20, s16, s15
	s_add_u32 s10, s4, s10
	s_addc_u32 s11, s5, 0
	s_load_dwordx2 s[18:19], s[10:11], 0x0
	s_mul_hi_i32 s10, s20, 0x2e8ba2e9
	s_lshr_b32 s11, s10, 31
	s_ashr_i32 s10, s10, 4
	s_add_i32 s10, s10, s11
	s_mul_i32 s11, s10, 0x58
	s_sub_i32 s11, s16, s11
	s_add_i32 s11, s15, s11
	s_lshl_b32 s20, s11, 6
	s_lshl_b32 s11, s11, 7
	s_and_b32 s11, s11, 0xffffff00
	s_or_b32 s11, s11, s17
	s_and_b32 s16, s20, 64
	s_ashr_i32 s21, s20, 31
	s_or_b32 s16, s11, s16
	s_lshl_b32 s10, s10, 6
	s_lshl_b64 s[20:21], s[20:21], 2
	s_waitcnt lgkmcnt(0)
	s_add_u32 s18, s18, s20
	s_addc_u32 s19, s19, s21
	v_lshl_add_u64 v[2:3], s[18:19], 0, v[0:1]
	v_or_b32_e32 v100, s10, v67
	v_lshl_add_u64 v[2:3], v[2:3], 0, s[22:23]
	v_mad_i64_i32 v[4:5], s[18:19], v100, s33, v[2:3]
	global_load_dwordx4 v[96:99], v[4:5], off nt
	v_or_b32_e32 v4, 4, v100
	v_mad_i64_i32 v[4:5], s[18:19], v4, s33, v[2:3]
	global_load_dwordx4 v[58:61], v[4:5], off nt
	v_or_b32_e32 v4, 8, v100
	v_mad_i64_i32 v[4:5], s[18:19], v4, s33, v[2:3]
	global_load_dwordx4 v[54:57], v[4:5], off nt
	v_or_b32_e32 v4, 12, v100
	v_mad_i64_i32 v[4:5], s[18:19], v4, s33, v[2:3]
	global_load_dwordx4 v[50:53], v[4:5], off nt
	v_or_b32_e32 v4, 16, v100
	v_mad_i64_i32 v[4:5], s[18:19], v4, s33, v[2:3]
	global_load_dwordx4 v[46:49], v[4:5], off nt
	v_or_b32_e32 v4, 20, v100
	v_mad_i64_i32 v[4:5], s[18:19], v4, s33, v[2:3]
	global_load_dwordx4 v[42:45], v[4:5], off nt
	v_or_b32_e32 v4, 24, v100
	v_mad_i64_i32 v[4:5], s[18:19], v4, s33, v[2:3]
	global_load_dwordx4 v[38:41], v[4:5], off nt
	v_or_b32_e32 v4, 28, v100
	v_mad_i64_i32 v[4:5], s[18:19], v4, s33, v[2:3]
	global_load_dwordx4 v[34:37], v[4:5], off nt
	v_or_b32_e32 v4, 32, v100
	v_mad_i64_i32 v[4:5], s[18:19], v4, s33, v[2:3]
	global_load_dwordx4 v[30:33], v[4:5], off nt
	v_or_b32_e32 v4, 36, v100
	v_mad_i64_i32 v[4:5], s[18:19], v4, s33, v[2:3]
	global_load_dwordx4 v[26:29], v[4:5], off nt
	v_or_b32_e32 v4, 40, v100
	v_mad_i64_i32 v[4:5], s[18:19], v4, s33, v[2:3]
	global_load_dwordx4 v[22:25], v[4:5], off nt
	v_or_b32_e32 v4, 44, v100
	v_mad_i64_i32 v[4:5], s[18:19], v4, s33, v[2:3]
	global_load_dwordx4 v[18:21], v[4:5], off nt
	v_or_b32_e32 v4, 48, v100
	v_mad_i64_i32 v[4:5], s[18:19], v4, s33, v[2:3]
	global_load_dwordx4 v[14:17], v[4:5], off nt
	v_or_b32_e32 v4, 52, v100
	v_mad_i64_i32 v[4:5], s[18:19], v4, s33, v[2:3]
	global_load_dwordx4 v[10:13], v[4:5], off nt
	v_or_b32_e32 v4, 56, v100
	v_ashrrev_i32_e32 v101, 31, v100
	v_mad_i64_i32 v[4:5], s[18:19], v4, s33, v[2:3]
	global_load_dwordx4 v[6:9], v[4:5], off nt
	v_or_b32_e32 v4, 60, v100
	v_lshl_add_u64 v[100:101], v[100:101], 2, s[8:9]
	global_load_dword v64, v[100:101], off
	v_or_b32_e32 v156, s10, v79
	v_ashrrev_i32_e32 v157, 31, v156
	v_lshl_add_u64 v[156:157], v[156:157], 2, s[8:9]
	global_load_dword v141, v[156:157], off
	v_or_b32_e32 v156, s10, v80
	v_ashrrev_i32_e32 v157, 31, v156
	v_lshl_add_u64 v[156:157], v[156:157], 2, s[8:9]
	global_load_dword v142, v[156:157], off
	v_or_b32_e32 v156, s10, v81
	v_ashrrev_i32_e32 v157, 31, v156
	v_lshl_add_u64 v[156:157], v[156:157], 2, s[8:9]
	global_load_dword v143, v[156:157], off
	v_or_b32_e32 v156, s10, v82
	v_ashrrev_i32_e32 v157, 31, v156
	v_lshl_add_u64 v[156:157], v[156:157], 2, s[8:9]
	global_load_dword v144, v[156:157], off
	v_or_b32_e32 v156, s10, v83
	v_ashrrev_i32_e32 v157, 31, v156
	v_lshl_add_u64 v[156:157], v[156:157], 2, s[8:9]
	global_load_dword v145, v[156:157], off
	v_or_b32_e32 v156, s10, v84
	v_ashrrev_i32_e32 v157, 31, v156
	v_lshl_add_u64 v[156:157], v[156:157], 2, s[8:9]
	global_load_dword v146, v[156:157], off
	v_or_b32_e32 v156, s10, v85
	v_ashrrev_i32_e32 v157, 31, v156
	v_lshl_add_u64 v[156:157], v[156:157], 2, s[8:9]
	global_load_dword v147, v[156:157], off
	v_or_b32_e32 v156, s10, v86
	v_ashrrev_i32_e32 v157, 31, v156
	v_lshl_add_u64 v[156:157], v[156:157], 2, s[8:9]
	global_load_dword v148, v[156:157], off
	v_or_b32_e32 v156, s10, v87
	v_ashrrev_i32_e32 v157, 31, v156
	v_lshl_add_u64 v[156:157], v[156:157], 2, s[8:9]
	global_load_dword v149, v[156:157], off
	v_or_b32_e32 v156, s10, v88
	v_ashrrev_i32_e32 v157, 31, v156
	v_lshl_add_u64 v[156:157], v[156:157], 2, s[8:9]
	global_load_dword v150, v[156:157], off
	v_or_b32_e32 v156, s10, v89
	v_ashrrev_i32_e32 v157, 31, v156
	v_lshl_add_u64 v[156:157], v[156:157], 2, s[8:9]
	global_load_dword v151, v[156:157], off
	v_or_b32_e32 v156, s10, v90
	v_ashrrev_i32_e32 v157, 31, v156
	v_lshl_add_u64 v[156:157], v[156:157], 2, s[8:9]
	global_load_dword v152, v[156:157], off
	v_or_b32_e32 v156, s10, v91
	v_ashrrev_i32_e32 v157, 31, v156
	v_lshl_add_u64 v[156:157], v[156:157], 2, s[8:9]
	global_load_dword v153, v[156:157], off
	v_or_b32_e32 v156, s10, v92
	v_ashrrev_i32_e32 v157, 31, v156
	v_lshl_add_u64 v[156:157], v[156:157], 2, s[8:9]
	global_load_dword v154, v[156:157], off
	v_or_b32_e32 v156, s10, v93
	v_ashrrev_i32_e32 v157, 31, v156
	v_lshl_add_u64 v[156:157], v[156:157], 2, s[8:9]
	global_load_dword v155, v[156:157], off
	v_mad_i64_i32 v[2:3], s[18:19], v4, s33, v[2:3]
	global_load_dwordx4 v[2:5], v[2:3], off nt
	s_ashr_i32 s11, s10, 31
	s_waitcnt vmcnt(1)
	v_pk_mul_f32 v[96:97], v[96:97], v[64:65] op_sel_hi:[1,0]
	ds_write2_b32 v95, v96, v97 offset1:1
	v_pk_mul_f32 v[96:97], v[98:99], v[64:65] op_sel_hi:[1,0]
	ds_write2_b32 v95, v96, v97 offset0:2 offset1:3
	v_or_b32_e32 v96, s10, v79
	v_ashrrev_i32_e32 v97, 31, v96
	v_lshl_add_u64 v[96:97], v[96:97], 2, s[8:9]
	v_mov_b32_e32 v64, v141
	v_add_u32_e32 v96, 0x410, v95
	s_waitcnt vmcnt(0)
; #define LAS __attribute__((address_space(3)))
; __device__ __forceinline__ void tr_item(const float* W, int ldw, bf16* WT, int ldt, const float* gain, int dst_row0, int k0, int n0, LAS float* scr, int lane) {
;     ...
;     for (int i = 0; i < 16; ++i) { const int k = kr + 4 * i; const float g = gain ? gain[k0 + k] : 1.0f; LAS float* d = scr + k * 65 + n4;
;         d[0] = v[i][0] * g; d[1] = v[i][1] * g; d[2] = v[i][2] * g; d[3] = v[i][3] * g; }
	v_pk_mul_f32 v[58:59], v[58:59], v[64:65] op_sel_hi:[1,0]
	ds_write2_b32 v96, v58, v59 offset1:1
	v_pk_mul_f32 v[58:59], v[60:61], v[64:65] op_sel_hi:[1,0]
	v_add_u32_e32 v60, 0x418, v95
	ds_write2_b32 v60, v58, v59 offset1:1
	v_or_b32_e32 v58, s10, v80
	v_ashrrev_i32_e32 v59, 31, v58
	v_lshl_add_u64 v[58:59], v[58:59], 2, s[8:9]
	v_mov_b32_e32 v58, v142
	s_waitcnt vmcnt(0)
	v_pk_mul_f32 v[54:55], v[54:55], v[58:59] op_sel_hi:[1,0]
	v_add_u32_e32 v59, 0x820, v95
	ds_write2_b32 v59, v54, v55 offset1:1
	v_pk_mul_f32 v[54:55], v[56:57], v[58:59] op_sel_hi:[1,0]
	v_add_u32_e32 v56, 0x828, v95
	ds_write2_b32 v56, v54, v55 offset1:1
	v_or_b32_e32 v54, s10, v81
	v_ashrrev_i32_e32 v55, 31, v54
	v_lshl_add_u64 v[54:55], v[54:55], 2, s[8:9]
	v_mov_b32_e32 v54, v143
	s_waitcnt vmcnt(0)
	v_pk_mul_f32 v[50:51], v[50:51], v[54:55] op_sel_hi:[1,0]
	v_add_u32_e32 v55, 0xc30, v95
	ds_write2_b32 v55, v50, v51 offset1:1
	v_pk_mul_f32 v[50:51], v[52:53], v[54:55] op_sel_hi:[1,0]
	v_add_u32_e32 v52, 0xc38, v95
	ds_write2_b32 v52, v50, v51 offset1:1
	v_or_b32_e32 v50, s10, v82
	v_ashrrev_i32_e32 v51, 31, v50
	v_lshl_add_u64 v[50:51], v[50:51], 2, s[8:9]
	v_mov_b32_e32 v50, v144
	s_waitcnt vmcnt(0)
	v_pk_mul_f32 v[46:47], v[46:47], v[50:51] op_sel_hi:[1,0]
	v_add_u32_e32 v51, 0x1040, v95
	ds_write2_b32 v51, v46, v47 offset1:1
	v_pk_mul_f32 v[46:47], v[48:49], v[50:51] op_sel_hi:[1,0]
	v_add_u32_e32 v48, 0x1048, v95
	ds_write2_b32 v48, v46, v47 offset1:1
	v_or_b32_e32 v46, s10, v83
	v_ashrrev_i32_e32 v47, 31, v46
	v_lshl_add_u64 v[46:47], v[46:47], 2, s[8:9]
	v_mov_b32_e32 v46, v145
	s_waitcnt vmcnt(0)
	v_pk_mul_f32 v[42:43], v[42:43], v[46:47] op_sel_hi:[1,0]
	v_add_u32_e32 v47, 0x1450, v95
	ds_write2_b32 v47, v42, v43 offset1:1
	v_pk_mul_f32 v[42:43], v[44:45], v[46:47] op_sel_hi:[1,0]
	v_add_u32_e32 v44, 0x1458, v95
	ds_write2_b32 v44, v42, v43 offset1:1
	v_or_b32_e32 v42, s10, v84
	v_ashrrev_i32_e32 v43, 31, v42
	v_lshl_add_u64 v[42:43], v[42:43], 2, s[8:9]
	v_mov_b32_e32 v42, v146
	s_waitcnt vmcnt(0)
	v_pk_mul_f32 v[38:39], v[38:39], v[42:43] op_sel_hi:[1,0]
	v_add_u32_e32 v43, 0x1860, v95
	ds_write2_b32 v43, v38, v39 offset1:1
	v_pk_mul_f32 v[38:39], v[40:41], v[42:43] op_sel_hi:[1,0]
	v_add_u32_e32 v40, 0x1868, v95
	ds_write2_b32 v40, v38, v39 offset1:1
	v_or_b32_e32 v38, s10, v85
	v_ashrrev_i32_e32 v39, 31, v38
	v_lshl_add_u64 v[38:39], v[38:39], 2, s[8:9]
	v_mov_b32_e32 v38, v147
	s_waitcnt vmcnt(0)
	v_pk_mul_f32 v[34:35], v[34:35], v[38:39] op_sel_hi:[1,0]
	v_add_u32_e32 v39, 0x1c70, v95
	ds_write2_b32 v39, v34, v35 offset1:1
	v_pk_mul_f32 v[34:35], v[36:37], v[38:39] op_sel_hi:[1,0]
	v_add_u32_e32 v36, 0x1c78, v95
	ds_write2_b32 v36, v34, v35 offset1:1
	v_or_b32_e32 v34, s10, v86
	v_ashrrev_i32_e32 v35, 31, v34
	v_lshl_add_u64 v[34:35], v[34:35], 2, s[8:9]
	v_mov_b32_e32 v34, v148
	s_waitcnt vmcnt(0)
	v_pk_mul_f32 v[30:31], v[30:31], v[34:35] op_sel_hi:[1,0]
	v_add_u32_e32 v35, 0x2080, v95
	ds_write2_b32 v35, v30, v31 offset1:1
	v_pk_mul_f32 v[30:31], v[32:33], v[34:35] op_sel_hi:[1,0]
	v_add_u32_e32 v32, 0x2088, v95
	ds_write2_b32 v32, v30, v31 offset1:1
	v_or_b32_e32 v30, s10, v87
	v_ashrrev_i32_e32 v31, 31, v30
	v_lshl_add_u64 v[30:31], v[30:31], 2, s[8:9]
	v_mov_b32_e32 v30, v149
	s_waitcnt vmcnt(0)
	v_pk_mul_f32 v[26:27], v[26:27], v[30:31] op_sel_hi:[1,0]
	v_add_u32_e32 v31, 0x2490, v95
	ds_write2_b32 v31, v26, v27 offset1:1
	v_pk_mul_f32 v[26:27], v[28:29], v[30:31] op_sel_hi:[1,0]
	v_add_u32_e32 v28, 0x2498, v95
	ds_write2_b32 v28, v26, v27 offset1:1
	v_or_b32_e32 v26, s10, v88
	v_ashrrev_i32_e32 v27, 31, v26
	v_lshl_add_u64 v[26:27], v[26:27], 2, s[8:9]
	v_mov_b32_e32 v26, v150
	s_waitcnt vmcnt(0)
	v_pk_mul_f32 v[22:23], v[22:23], v[26:27] op_sel_hi:[1,0]
	v_add_u32_e32 v27, 0x28a0, v95
	ds_write2_b32 v27, v22, v23 offset1:1
	v_pk_mul_f32 v[22:23], v[24:25], v[26:27] op_sel_hi:[1,0]
	v_add_u32_e32 v24, 0x28a8, v95
	ds_write2_b32 v24, v22, v23 offset1:1
	v_or_b32_e32 v22, s10, v89
	v_ashrrev_i32_e32 v23, 31, v22
	v_lshl_add_u64 v[22:23], v[22:23], 2, s[8:9]
	v_mov_b32_e32 v22, v151
	s_waitcnt vmcnt(0)
	v_pk_mul_f32 v[18:19], v[18:19], v[22:23] op_sel_hi:[1,0]
	v_add_u32_e32 v23, 0x2cb0, v95
	ds_write2_b32 v23, v18, v19 offset1:1
	v_pk_mul_f32 v[18:19], v[20:21], v[22:23] op_sel_hi:[1,0]
	v_add_u32_e32 v20, 0x2cb8, v95
	ds_write2_b32 v20, v18, v19 offset1:1
	v_or_b32_e32 v18, s10, v90
	v_ashrrev_i32_e32 v19, 31, v18
	v_lshl_add_u64 v[18:19], v[18:19], 2, s[8:9]
	v_mov_b32_e32 v18, v152
	s_waitcnt vmcnt(0)
	v_pk_mul_f32 v[14:15], v[14:15], v[18:19] op_sel_hi:[1,0]
	v_add_u32_e32 v19, 0x30c0, v95
	ds_write2_b32 v19, v14, v15 offset1:1
	v_pk_mul_f32 v[14:15], v[16:17], v[18:19] op_sel_hi:[1,0]
	v_add_u32_e32 v16, 0x30c8, v95
	ds_write2_b32 v16, v14, v15 offset1:1
	v_or_b32_e32 v14, s10, v91
	v_ashrrev_i32_e32 v15, 31, v14
	v_lshl_add_u64 v[14:15], v[14:15], 2, s[8:9]
	v_mov_b32_e32 v14, v153
	s_waitcnt vmcnt(0)
	v_pk_mul_f32 v[10:11], v[10:11], v[14:15] op_sel_hi:[1,0]
	v_add_u32_e32 v15, 0x34d0, v95
	ds_write2_b32 v15, v10, v11 offset1:1
	v_pk_mul_f32 v[10:11], v[12:13], v[14:15] op_sel_hi:[1,0]
	v_add_u32_e32 v12, 0x34d8, v95
	ds_write2_b32 v12, v10, v11 offset1:1
	v_or_b32_e32 v10, s10, v92
	v_ashrrev_i32_e32 v11, 31, v10
	v_lshl_add_u64 v[10:11], v[10:11], 2, s[8:9]
	v_mov_b32_e32 v10, v154
	s_waitcnt vmcnt(0)
	v_pk_mul_f32 v[6:7], v[6:7], v[10:11] op_sel_hi:[1,0]
	v_add_u32_e32 v11, 0x38e0, v95
	ds_write2_b32 v11, v6, v7 offset1:1
	v_pk_mul_f32 v[6:7], v[8:9], v[10:11] op_sel_hi:[1,0]
	v_add_u32_e32 v8, 0x38e8, v95
	ds_write2_b32 v8, v6, v7 offset1:1
	v_or_b32_e32 v6, s10, v93
	v_ashrrev_i32_e32 v7, 31, v6
	v_lshl_add_u64 v[6:7], v[6:7], 2, s[8:9]
	v_mov_b32_e32 v6, v155
	v_add_u32_e32 v8, 0x400, v71
	s_waitcnt vmcnt(0)
; #define LAS __attribute__((address_space(3)))
; #define LDS_WAIT() asm volatile("s_waitcnt lgkmcnt(0)" ::: "memory")
; __device__ __forceinline__ unsigned cvtpk(float lo, float hi) { unsigned r; asm volatile("v_cvt_pk_bf16_f32 %0, %1, %2" : "=v"(r) : "v"(lo), "v"(hi)); return r; }
; __device__ __forceinline__ void tr_item(const float* W, int ldw, bf16* WT, int ldt, const float* gain, int dst_row0, int k0, int n0, LAS float* scr, int lane) {
;     ...
;     for (int i = 0; i < 16; ++i) { const int k = kr + 4 * i; const float g = gain ? gain[k0 + k] : 1.0f; LAS float* d = scr + k * 65 + n4;
;         d[0] = v[i][0] * g; d[1] = v[i][1] * g; d[2] = v[i][2] * g; d[3] = v[i][3] * g; }
;     LDS_WAIT(); asm volatile("" ::: "memory");
;     const int c = lane & 7;
; #pragma unroll
;     for (int j = 0; j < 8; ++j) { const int n = (lane >> 3) + 8 * j; const LAS float* s = scr + (8 * c) * 65 + n;
;         u32x4 o; o.x = cvtpk(s[0 * 65], s[1 * 65]); o.y = cvtpk(s[2 * 65], s[3 * 65]); o.z = cvtpk(s[4 * 65], s[5 * 65]); o.w = cvtpk(s[6 * 65], s[7 * 65]);
;         *(u32x4*)(WT + (size_t)(dst_row0 + n) * ldt + k0 + 8 * c) = o; }
;     LDS_WAIT(); asm volatile("" ::: "memory");
	v_pk_mul_f32 v[2:3], v[2:3], v[6:7] op_sel_hi:[1,0]
	v_add_u32_e32 v7, 0x3cf0, v95
	ds_write2_b32 v7, v2, v3 offset1:1
	v_pk_mul_f32 v[2:3], v[4:5], v[6:7] op_sel_hi:[1,0]
	v_add_u32_e32 v4, 0x3cf8, v95
	ds_write2_b32 v4, v2, v3 offset1:1
	s_waitcnt lgkmcnt(0)
	ds_read2_b32 v[252:253], v71 offset1:65
	ds_read2_b32 v[250:251], v71 offset0:130 offset1:195
	ds_read2_b32 v[248:249], v8 offset0:4 offset1:69
	ds_read2_b32 v[246:247], v8 offset0:134 offset1:199
	v_or_b32_e32 v10, s16, v69
	v_ashrrev_i32_e32 v11, 31, v10
	v_lshl_add_u64 v[6:7], s[10:11], 1, v[62:63]
	v_lshlrev_b64 v[10:11], 12, v[10:11]
	v_lshl_add_u64 v[10:11], v[6:7], 0, v[10:11]
	v_mov_b32_e32 v156, v10
	v_mov_b32_e32 v157, v11
	ds_read2_b32 v[244:245], v71 offset0:8 offset1:73
	s_add_i32 s10, s15, 0x2a0
	ds_read2_b32 v[242:243], v71 offset0:138 offset1:203
	ds_read2_b32 v[240:241], v8 offset0:12 offset1:77
	ds_read2_b32 v[238:239], v8 offset0:142 offset1:207
	v_or_b32_e32 v10, s16, v72
	v_ashrrev_i32_e32 v11, 31, v10
	v_lshlrev_b64 v[10:11], 12, v[10:11]
	v_lshl_add_u64 v[10:11], v[6:7], 0, v[10:11]
	v_mov_b32_e32 v154, v10
	v_mov_b32_e32 v155, v11
	ds_read2_b32 v[236:237], v71 offset0:16 offset1:81
	s_cmpk_lt_i32 s15, 0x1360
	ds_read2_b32 v[234:235], v71 offset0:146 offset1:211
	ds_read2_b32 v[232:233], v8 offset0:20 offset1:85
	ds_read2_b32 v[216:217], v8 offset0:150 offset1:215
	v_or_b32_e32 v10, s16, v73
	v_ashrrev_i32_e32 v11, 31, v10
	v_lshlrev_b64 v[10:11], 12, v[10:11]
	v_lshl_add_u64 v[10:11], v[6:7], 0, v[10:11]
	v_mov_b32_e32 v152, v10
	v_mov_b32_e32 v153, v11
	ds_read2_b32 v[214:215], v71 offset0:24 offset1:89
	s_mov_b32 s15, s10
	ds_read2_b32 v[212:213], v71 offset0:154 offset1:219
	ds_read2_b32 v[210:211], v8 offset0:28 offset1:93
	ds_read2_b32 v[208:209], v8 offset0:158 offset1:223
	v_or_b32_e32 v10, s16, v74
	v_ashrrev_i32_e32 v11, 31, v10
	v_lshlrev_b64 v[10:11], 12, v[10:11]
	v_lshl_add_u64 v[10:11], v[6:7], 0, v[10:11]
	v_mov_b32_e32 v150, v10
	v_mov_b32_e32 v151, v11
	ds_read2_b32 v[206:207], v71 offset0:32 offset1:97
	ds_read2_b32 v[204:205], v71 offset0:162 offset1:227
	ds_read2_b32 v[202:203], v8 offset0:36 offset1:101
	ds_read2_b32 v[200:201], v8 offset0:166 offset1:231
	v_or_b32_e32 v10, s16, v75
	v_ashrrev_i32_e32 v11, 31, v10
	v_lshlrev_b64 v[10:11], 12, v[10:11]
	v_lshl_add_u64 v[10:11], v[6:7], 0, v[10:11]
	v_mov_b32_e32 v148, v10
	v_mov_b32_e32 v149, v11
	ds_read2_b32 v[198:199], v71 offset0:40 offset1:105
	ds_read2_b32 v[196:197], v71 offset0:170 offset1:235
	ds_read2_b32 v[194:195], v8 offset0:44 offset1:109
	ds_read2_b32 v[176:177], v8 offset0:174 offset1:239
	v_or_b32_e32 v10, s16, v76
	v_ashrrev_i32_e32 v11, 31, v10
	v_lshlrev_b64 v[10:11], 12, v[10:11]
	v_lshl_add_u64 v[10:11], v[6:7], 0, v[10:11]
	v_mov_b32_e32 v146, v10
	v_mov_b32_e32 v147, v11
	ds_read2_b32 v[174:175], v71 offset0:48 offset1:113
	ds_read2_b32 v[172:173], v71 offset0:178 offset1:243
	ds_read2_b32 v[170:171], v8 offset0:52 offset1:117
	ds_read2_b32 v[168:169], v8 offset0:182 offset1:247
	v_or_b32_e32 v10, s16, v77
	v_ashrrev_i32_e32 v11, 31, v10
	v_lshlrev_b64 v[10:11], 12, v[10:11]
	v_lshl_add_u64 v[10:11], v[6:7], 0, v[10:11]
	v_mov_b32_e32 v144, v10
	v_mov_b32_e32 v145, v11
	ds_read2_b32 v[166:167], v71 offset0:56 offset1:121
	ds_read2_b32 v[164:165], v71 offset0:186 offset1:251
	ds_read2_b32 v[162:163], v8 offset0:60 offset1:125
	ds_read2_b32 v[160:161], v8 offset0:190 offset1:255
	v_or_b32_e32 v8, s16, v94
	v_ashrrev_i32_e32 v9, 31, v8
	v_lshlrev_b64 v[8:9], 12, v[8:9]
	v_lshl_add_u64 v[6:7], v[6:7], 0, v[8:9]
	v_mov_b32_e32 v142, v6
	v_mov_b32_e32 v143, v7
	s_waitcnt lgkmcnt(0)
	v_cvt_pk_bf16_f32 v159, v252, v253
	v_cvt_pk_bf16_f32 v253, v250, v251
	v_cvt_pk_bf16_f32 v252, v248, v249
	v_cvt_pk_bf16_f32 v251, v246, v247
	v_mov_b32_e32 v132, v159
	v_mov_b32_e32 v133, v253
	v_mov_b32_e32 v134, v252
	v_mov_b32_e32 v135, v251
	global_store_dwordx4 v[156:157], v[132:135], off
	v_cvt_pk_bf16_f32 v253, v244, v245
	v_cvt_pk_bf16_f32 v252, v242, v243
	v_cvt_pk_bf16_f32 v251, v240, v241
	v_cvt_pk_bf16_f32 v250, v238, v239
	v_mov_b32_e32 v136, v253
	v_mov_b32_e32 v137, v252
	v_mov_b32_e32 v138, v251
	v_mov_b32_e32 v139, v250
	global_store_dwordx4 v[154:155], v[136:139], off
	v_cvt_pk_bf16_f32 v253, v236, v237
	v_cvt_pk_bf16_f32 v252, v234, v235
	v_cvt_pk_bf16_f32 v251, v232, v233
	v_cvt_pk_bf16_f32 v250, v216, v217
	v_mov_b32_e32 v132, v253
	v_mov_b32_e32 v133, v252
	v_mov_b32_e32 v134, v251
	v_mov_b32_e32 v135, v250
	global_store_dwordx4 v[152:153], v[132:135], off
	v_cvt_pk_bf16_f32 v253, v214, v215
	v_cvt_pk_bf16_f32 v252, v212, v213
	v_cvt_pk_bf16_f32 v251, v210, v211
	v_cvt_pk_bf16_f32 v250, v208, v209
	v_mov_b32_e32 v136, v253
	v_mov_b32_e32 v137, v252
	v_mov_b32_e32 v138, v251
	v_mov_b32_e32 v139, v250
	global_store_dwordx4 v[150:151], v[136:139], off
	v_cvt_pk_bf16_f32 v253, v206, v207
	v_cvt_pk_bf16_f32 v252, v204, v205
	v_cvt_pk_bf16_f32 v251, v202, v203
	v_cvt_pk_bf16_f32 v250, v200, v201
	v_mov_b32_e32 v132, v253
	v_mov_b32_e32 v133, v252
	v_mov_b32_e32 v134, v251
	v_mov_b32_e32 v135, v250
	global_store_dwordx4 v[148:149], v[132:135], off
	v_cvt_pk_bf16_f32 v253, v198, v199
	v_cvt_pk_bf16_f32 v252, v196, v197
	v_cvt_pk_bf16_f32 v251, v194, v195
	v_cvt_pk_bf16_f32 v250, v176, v177
	v_mov_b32_e32 v136, v253
	v_mov_b32_e32 v137, v252
	v_mov_b32_e32 v138, v251
	v_mov_b32_e32 v139, v250
	global_store_dwordx4 v[146:147], v[136:139], off
	v_cvt_pk_bf16_f32 v253, v174, v175
	v_cvt_pk_bf16_f32 v252, v172, v173
	v_cvt_pk_bf16_f32 v251, v170, v171
	v_cvt_pk_bf16_f32 v250, v168, v169
	v_mov_b32_e32 v132, v253
	v_mov_b32_e32 v133, v252
	v_mov_b32_e32 v134, v251
	v_mov_b32_e32 v135, v250
	global_store_dwordx4 v[144:145], v[132:135], off
	v_cvt_pk_bf16_f32 v253, v166, v167
	v_cvt_pk_bf16_f32 v252, v164, v165
	v_cvt_pk_bf16_f32 v251, v162, v163
	v_cvt_pk_bf16_f32 v250, v160, v161
	v_mov_b32_e32 v136, v253
	v_mov_b32_e32 v137, v252
	v_mov_b32_e32 v138, v251
	v_mov_b32_e32 v139, v250
	global_store_dwordx4 v[142:143], v[136:139], off
	s_waitcnt lgkmcnt(0)
	s_cbranch_scc1 .LBB0_1863

; #define LAS __attribute__((address_space(3)))
; __device__ __forceinline__ void tr_item(const float* W, int ldw, bf16* WT, int ldt, const float* gain, int dst_row0, int k0, int n0, LAS float* scr, int lane) {
;     ...
;     for (int i = 0; i < 16; ++i) v[i] = __builtin_nontemporal_load((const f32x4*)(W + (size_t)(k0 + kr + 4 * i) * ldw + n0 + n4));
; #pragma unroll
;     for (int i = 0; i < 16; ++i) { const int k = kr + 4 * i; const float g = gain ? gain[k0 + k] : 1.0f; LAS float* d = scr + k * 65 + n4;
;         d[0] = v[i][0] * g; d[1] = v[i][1] * g; d[2] = v[i][2] * g; d[3] = v[i][3] * g; }
; __device__ __forceinline__ void late_convert(KArgs a, LAS unsigned char* lds, int set, int wi, int nw, int wave, int lane) {
;     ...
;         for (int idx = wi; idx < IT_SQ + 2 * IT_QK + 64; idx += nw) {
;             if (idx < IT_SQ) tr_job(a->in[I_GR], DM, DM, (bf16*)(a->ws + WS_WQKVR), gm, 0, 4096, idx, scr, lane);
;             else if (idx < IT_SQ + IT_QK) tr_job(a->in[I_GQ], DM, 1024, (bf16*)(a->ws + WS_WQKVR), gm, 0, 0, idx - IT_SQ, scr, lane);
;             else if (idx < IT_SQ + 2 * IT_QK) tr_job(a->in[I_GK], DM, 1024, (bf16*)(a->ws + WS_WQKVR), gm, 0, 1024, idx - IT_SQ - IT_QK, scr, lane);
.LBB0_1871:
	s_andn2_b64 vcc, exec, s[8:9]
	s_cbranch_vccnz .LBB0_1873
	s_lshr_b32 s15, s12, 4
	s_lshl_b32 s8, s15, 10
	s_load_dwordx2 s[18:19], s[4:5], 0xc8
	s_load_dwordx2 s[10:11], s[4:5], 0x118
	s_sub_i32 s8, s2, s8
	s_add_i32 s8, s8, 0xfffd2800
	s_ashr_i32 s9, s8, 31
	s_lshl_b32 s16, s15, 6
	s_lshl_b64 s[20:21], s[8:9], 2
	s_waitcnt lgkmcnt(0)
	s_add_u32 s18, s18, s20
	v_or_b32_e32 v76, s16, v67
	s_addc_u32 s19, s19, s21
	v_lshlrev_b32_e32 v0, 2, v66
	v_mov_b32_e32 v77, v1
	v_lshl_add_u64 v[2:3], s[18:19], 0, v[0:1]
	v_lshlrev_b64 v[4:5], 12, v[76:77]
	v_lshl_add_u64 v[4:5], v[2:3], 0, v[4:5]
	v_lshlrev_b32_e32 v0, 10, v76
	v_lshl_add_u64 v[76:77], v[76:77], 2, s[6:7]
	global_load_dwordx4 v[116:119], v[4:5], off nt
	v_lshl_add_u64 v[2:3], v[0:1], 2, v[2:3]
	global_load_dword v253, v[76:77], off
	v_add_u32_e32 v71, v94, v78
	v_add_co_u32_e32 v4, vcc, s41, v2
	s_mov_b32 s9, 0x8000
	s_nop 0
	v_addc_co_u32_e32 v5, vcc, 0, v3, vcc
	global_load_dwordx4 v[120:123], v[4:5], off nt
	v_add_co_u32_e32 v4, vcc, s9, v2
	s_mov_b32 s9, 0xc000
	s_nop 0
	v_addc_co_u32_e32 v5, vcc, 0, v3, vcc
	global_load_dwordx4 v[124:127], v[4:5], off nt
	v_add_co_u32_e32 v4, vcc, s9, v2
	s_mov_b32 s9, 0x10000
	s_nop 0
	v_addc_co_u32_e32 v5, vcc, 0, v3, vcc
	global_load_dwordx4 v[128:131], v[4:5], off nt
	v_add_co_u32_e32 v4, vcc, s9, v2
	s_mov_b32 s9, 0x14000
	s_nop 0
	v_addc_co_u32_e32 v5, vcc, 0, v3, vcc
	global_load_dwordx4 v[132:135], v[4:5], off nt
	v_add_co_u32_e32 v4, vcc, s9, v2
	s_mov_b32 s9, 0x18000
	s_nop 0
	v_addc_co_u32_e32 v5, vcc, 0, v3, vcc
	global_load_dwordx4 v[136:139], v[4:5], off nt
	v_add_co_u32_e32 v4, vcc, s9, v2
	s_mov_b32 s9, 0x1c000
	s_nop 0
	v_addc_co_u32_e32 v5, vcc, 0, v3, vcc
	global_load_dwordx4 v[140:143], v[4:5], off nt
	v_add_co_u32_e32 v4, vcc, s9, v2
	s_mov_b32 s9, 0x24000
	s_nop 0
	v_addc_co_u32_e32 v5, vcc, 0, v3, vcc
	global_load_dwordx4 v[144:147], v[4:5], off nt
	v_add_co_u32_e32 v4, vcc, s88, v2
	v_mov_b32_e32 v252, v1
	v_or_b32_e32 v0, s16, v79
	s_waitcnt vmcnt(0)
	v_mov_b32_e32 v250, v253
	v_mov_b32_e32 v251, v252
	v_pk_mul_f32 v[248:249], v[116:117], v[250:251] op_sel_hi:[1,0]
	ds_write2_b32 v71, v248, v249 offset1:1
	v_mov_b32_e32 v248, v253
	v_mov_b32_e32 v249, v252
	v_pk_mul_f32 v[116:117], v[118:119], v[248:249] op_sel_hi:[1,0]
	ds_write2_b32 v71, v116, v117 offset0:2 offset1:3
	v_mov_b32_e32 v34, v144
	v_mov_b32_e32 v35, v145
	v_mov_b32_e32 v36, v146
	v_mov_b32_e32 v37, v147
	v_mov_b32_e32 v38, v140
	v_mov_b32_e32 v39, v141
	v_mov_b32_e32 v40, v142
	v_mov_b32_e32 v41, v143
	v_mov_b32_e32 v42, v136
	v_mov_b32_e32 v43, v137
	v_mov_b32_e32 v44, v138
	v_mov_b32_e32 v45, v139
	v_mov_b32_e32 v46, v132
	v_mov_b32_e32 v47, v133
	v_mov_b32_e32 v48, v134
	v_mov_b32_e32 v49, v135
	v_mov_b32_e32 v50, v128
	v_mov_b32_e32 v51, v129
	v_mov_b32_e32 v52, v130
	v_mov_b32_e32 v53, v131
	v_mov_b32_e32 v54, v124
	v_mov_b32_e32 v55, v125
	v_mov_b32_e32 v56, v126
	v_mov_b32_e32 v57, v127
	v_mov_b32_e32 v58, v120
	v_mov_b32_e32 v59, v121
	v_mov_b32_e32 v60, v122
	v_mov_b32_e32 v61, v123
	v_mov_b32_e32 v62, v116
	v_mov_b32_e32 v63, v117
	v_mov_b32_e32 v64, v118
	v_mov_b32_e32 v65, v119
	v_lshl_add_u64 v[62:63], v[0:1], 2, s[6:7]
	global_load_dword v253, v[62:63], off
	v_add_u32_e32 v62, 0x410, v71
	v_addc_co_u32_e32 v5, vcc, 0, v3, vcc
	global_load_dwordx4 v[116:119], v[4:5], off nt
	v_add_co_u32_e32 v4, vcc, s9, v2
	s_mov_b32 s9, 0x28000
	s_nop 0
	v_addc_co_u32_e32 v5, vcc, 0, v3, vcc
	global_load_dwordx4 v[120:123], v[4:5], off nt
	v_add_co_u32_e32 v4, vcc, s9, v2
	s_mov_b32 s9, 0x2c000
	s_nop 0
	v_addc_co_u32_e32 v5, vcc, 0, v3, vcc
	global_load_dwordx4 v[124:127], v[4:5], off nt
	v_add_co_u32_e32 v4, vcc, s9, v2
	s_mov_b32 s9, 0x30000
	s_nop 0
	v_addc_co_u32_e32 v5, vcc, 0, v3, vcc
	global_load_dwordx4 v[128:131], v[4:5], off nt
	v_add_co_u32_e32 v4, vcc, s9, v2
	s_mov_b32 s9, 0x34000
	s_nop 0
	v_addc_co_u32_e32 v5, vcc, 0, v3, vcc
	global_load_dwordx4 v[132:135], v[4:5], off nt
	v_add_co_u32_e32 v4, vcc, s9, v2
	s_mov_b32 s9, 0x38000
	s_nop 0
	v_addc_co_u32_e32 v5, vcc, 0, v3, vcc
	global_load_dwordx4 v[136:139], v[4:5], off nt
	v_add_co_u32_e32 v4, vcc, s9, v2
	s_mov_b32 s9, 0x3c000
	s_nop 0
	v_addc_co_u32_e32 v5, vcc, 0, v3, vcc
	global_load_dwordx4 v[140:143], v[4:5], off nt
	v_add_co_u32_e32 v2, vcc, s9, v2
	s_lshl_b32 s9, s15, 7
	s_nop 0
	v_addc_co_u32_e32 v3, vcc, 0, v3, vcc
	global_load_dwordx4 v[144:147], v[2:3], off nt
	s_add_u32 s10, s10, s9
	s_addc_u32 s11, s11, 0
	v_mov_b32_e32 v236, v58
	v_mov_b32_e32 v237, v59
	v_mov_b32_e32 v238, v1
	v_add_u32_e32 v0, 0x418, v71
	v_mov_b32_e32 v215, v0
	v_or_b32_e32 v0, s16, v80
	v_lshl_add_u64 v[58:59], v[0:1], 2, s[6:7]
	global_load_dword v252, v[58:59], off
	v_add_u32_e32 v58, 0x820, v71
	v_mov_b32_e32 v212, v54
	v_mov_b32_e32 v213, v55
	v_add_u32_e32 v0, 0x828, v71
	v_mov_b32_e32 v214, v0
	v_or_b32_e32 v0, s16, v81
	v_lshl_add_u64 v[54:55], v[0:1], 2, s[6:7]
	global_load_dword v251, v[54:55], off
	v_add_u32_e32 v54, 0xc30, v71
	v_mov_b32_e32 v206, v50
	v_mov_b32_e32 v207, v51
	v_add_u32_e32 v0, 0xc38, v71
	v_mov_b32_e32 v203, v0
	v_or_b32_e32 v0, s16, v82
	v_lshl_add_u64 v[50:51], v[0:1], 2, s[6:7]
	global_load_dword v250, v[50:51], off
	v_add_u32_e32 v50, 0x1040, v71
	v_mov_b32_e32 v200, v46
	v_mov_b32_e32 v201, v47
	v_add_u32_e32 v0, 0x1048, v71
	v_mov_b32_e32 v202, v0
	v_or_b32_e32 v0, s16, v83
	v_lshl_add_u64 v[46:47], v[0:1], 2, s[6:7]
	global_load_dword v249, v[46:47], off
	v_add_u32_e32 v46, 0x1450, v71
	v_mov_b32_e32 v194, v42
	v_mov_b32_e32 v195, v43
	v_mov_b32_e32 v176, v44
	v_mov_b32_e32 v177, v45
	v_add_u32_e32 v42, v94, v95
	v_or_b32_e32 v0, s16, v84
; #define LAS __attribute__((address_space(3)))
; __device__ __forceinline__ void tr_item(const float* W, int ldw, bf16* WT, int ldt, const float* gain, int dst_row0, int k0, int n0, LAS float* scr, int lane) {
;     ...
;     for (int i = 0; i < 16; ++i) v[i] = __builtin_nontemporal_load((const f32x4*)(W + (size_t)(k0 + kr + 4 * i) * ldw + n0 + n4));
; #pragma unroll
;     for (int i = 0; i < 16; ++i) { const int k = kr + 4 * i; const float g = gain ? gain[k0 + k] : 1.0f; LAS float* d = scr + k * 65 + n4;
;         d[0] = v[i][0] * g; d[1] = v[i][1] * g; d[2] = v[i][2] * g; d[3] = v[i][3] * g; }
	v_lshl_add_u64 v[44:45], v[0:1], 2, s[6:7]
	global_load_dword v248, v[44:45], off
	v_add_u32_e32 v43, 0x410, v42
	v_mov_b32_e32 v172, v38
	v_mov_b32_e32 v173, v39
	v_add_u32_e32 v0, 0x418, v42
	v_mov_b32_e32 v167, v0
	v_or_b32_e32 v0, s16, v85
	v_lshl_add_u64 v[38:39], v[0:1], 2, s[6:7]
	global_load_dword v247, v[38:39], off
	v_add_u32_e32 v38, 0x820, v42
	v_mov_b32_e32 v164, v34
	v_mov_b32_e32 v165, v35
	v_add_u32_e32 v0, 0x828, v42
	v_mov_b32_e32 v166, v0
	v_or_b32_e32 v0, s16, v86
	v_lshl_add_u64 v[34:35], v[0:1], 2, s[6:7]
	global_load_dword v246, v[34:35], off
	v_add_u32_e32 v34, 0xc30, v42
	v_add_u32_e32 v0, 0xc38, v42
	v_mov_b32_e32 v159, v0
	v_or_b32_e32 v0, s16, v87
	v_lshl_add_u64 v[30:31], v[0:1], 2, s[6:7]
	global_load_dword v245, v[30:31], off
	v_add_u32_e32 v30, 0x1040, v42
	v_add_u32_e32 v0, 0x1048, v42
	v_mov_b32_e32 v158, v0
	v_or_b32_e32 v0, s16, v88
	v_lshl_add_u64 v[26:27], v[0:1], 2, s[6:7]
	global_load_dword v244, v[26:27], off
	v_add_u32_e32 v26, 0x1450, v42
	v_add_u32_e32 v0, 0x1458, v42
	v_mov_b32_e32 v157, v0
	v_or_b32_e32 v0, s16, v89
	v_lshl_add_u64 v[22:23], v[0:1], 2, s[6:7]
	global_load_dword v243, v[22:23], off
	v_add_u32_e32 v22, 0x1860, v42
	v_add_u32_e32 v0, 0x1868, v42
	v_mov_b32_e32 v156, v0
	v_or_b32_e32 v0, s16, v90
	v_lshl_add_u64 v[18:19], v[0:1], 2, s[6:7]
	global_load_dword v242, v[18:19], off
	v_add_u32_e32 v18, 0x1c70, v42
	v_add_u32_e32 v0, 0x1c78, v42
	v_mov_b32_e32 v155, v0
	v_or_b32_e32 v0, s16, v91
	v_lshl_add_u64 v[14:15], v[0:1], 2, s[6:7]
	global_load_dword v241, v[14:15], off
	v_add_u32_e32 v14, 0x2080, v42
	v_add_u32_e32 v0, 0x2088, v42
	v_mov_b32_e32 v154, v0
	v_or_b32_e32 v0, s16, v92
	v_lshl_add_u64 v[10:11], v[0:1], 2, s[6:7]
	global_load_dword v240, v[10:11], off
	v_add_u32_e32 v10, 0x2490, v42
	v_add_u32_e32 v0, 0x2498, v42
	v_mov_b32_e32 v153, v0
	v_or_b32_e32 v0, s16, v93
	v_lshl_add_u64 v[6:7], v[0:1], 2, s[6:7]
	global_load_dword v239, v[6:7], off
	v_add_u32_e32 v6, 0x28a0, v42
	v_add_u32_e32 v0, 0x28a8, v42
	s_waitcnt vmcnt(0)
	v_mov_b32_e32 v234, v253
	v_mov_b32_e32 v235, v238
	v_pk_mul_f32 v[232:233], v[236:237], v[234:235] op_sel_hi:[1,0]
	ds_write2_b32 v62, v232, v233 offset1:1
	v_mov_b32_e32 v232, v253
	v_mov_b32_e32 v233, v238
	v_pk_mul_f32 v[216:217], v[60:61], v[232:233] op_sel_hi:[1,0]
	ds_write2_b32 v215, v216, v217 offset1:1
	v_mov_b32_e32 v216, v252
	v_mov_b32_e32 v217, v238
	v_pk_mul_f32 v[210:211], v[212:213], v[216:217] op_sel_hi:[1,0]
	ds_write2_b32 v58, v210, v211 offset1:1
	v_mov_b32_e32 v210, v252
	v_mov_b32_e32 v211, v238
	v_pk_mul_f32 v[208:209], v[56:57], v[210:211] op_sel_hi:[1,0]
	ds_write2_b32 v214, v208, v209 offset1:1
	v_mov_b32_e32 v252, v251
	v_mov_b32_e32 v253, v238
	v_pk_mul_f32 v[208:209], v[206:207], v[252:253] op_sel_hi:[1,0]
	ds_write2_b32 v54, v208, v209 offset1:1
	v_mov_b32_e32 v208, v251
	v_mov_b32_e32 v209, v238
	v_pk_mul_f32 v[204:205], v[52:53], v[208:209] op_sel_hi:[1,0]
	ds_write2_b32 v203, v204, v205 offset1:1
	v_mov_b32_e32 v204, v250
	v_mov_b32_e32 v205, v238
	v_pk_mul_f32 v[198:199], v[200:201], v[204:205] op_sel_hi:[1,0]
	ds_write2_b32 v50, v198, v199 offset1:1
	v_mov_b32_e32 v198, v250
	v_mov_b32_e32 v199, v238
	v_pk_mul_f32 v[196:197], v[48:49], v[198:199] op_sel_hi:[1,0]
	ds_write2_b32 v202, v196, v197 offset1:1
	v_mov_b32_e32 v250, v249
	v_mov_b32_e32 v251, v238
	v_pk_mul_f32 v[196:197], v[194:195], v[250:251] op_sel_hi:[1,0]
	ds_write2_b32 v46, v196, v197 offset1:1
	v_mov_b32_e32 v196, v249
	v_mov_b32_e32 v197, v238
	v_pk_mul_f32 v[174:175], v[176:177], v[196:197] op_sel_hi:[1,0]
	ds_write2_b32 v42, v174, v175 offset0:2 offset1:3
	v_mov_b32_e32 v174, v248
	v_mov_b32_e32 v175, v238
	v_pk_mul_f32 v[170:171], v[172:173], v[174:175] op_sel_hi:[1,0]
	ds_write2_b32 v43, v170, v171 offset1:1
	v_mov_b32_e32 v170, v248
	v_mov_b32_e32 v171, v238
	v_pk_mul_f32 v[168:169], v[40:41], v[170:171] op_sel_hi:[1,0]
	ds_write2_b32 v167, v168, v169 offset1:1
	v_mov_b32_e32 v248, v247
	v_mov_b32_e32 v249, v238
	v_pk_mul_f32 v[168:169], v[164:165], v[248:249] op_sel_hi:[1,0]
	ds_write2_b32 v38, v168, v169 offset1:1
	v_mov_b32_e32 v168, v247
	v_mov_b32_e32 v169, v238
	v_pk_mul_f32 v[162:163], v[36:37], v[168:169] op_sel_hi:[1,0]
	ds_write2_b32 v166, v162, v163 offset1:1
	v_mov_b32_e32 v162, v246
	v_mov_b32_e32 v163, v238
	v_pk_mul_f32 v[160:161], v[116:117], v[162:163] op_sel_hi:[1,0]
	ds_write2_b32 v34, v160, v161 offset1:1
	v_mov_b32_e32 v160, v246
	v_mov_b32_e32 v161, v238
	v_pk_mul_f32 v[116:117], v[118:119], v[160:161] op_sel_hi:[1,0]
	ds_write2_b32 v159, v116, v117 offset1:1
	v_mov_b32_e32 v246, v245
	v_mov_b32_e32 v247, v238
	v_pk_mul_f32 v[118:119], v[120:121], v[246:247] op_sel_hi:[1,0]
	ds_write2_b32 v30, v118, v119 offset1:1
	v_mov_b32_e32 v120, v245
	v_mov_b32_e32 v121, v238
	v_pk_mul_f32 v[118:119], v[122:123], v[120:121] op_sel_hi:[1,0]
	ds_write2_b32 v158, v118, v119 offset1:1
	v_mov_b32_e32 v122, v244
	v_mov_b32_e32 v123, v238
	v_pk_mul_f32 v[118:119], v[124:125], v[122:123] op_sel_hi:[1,0]
	ds_write2_b32 v26, v118, v119 offset1:1
	v_mov_b32_e32 v124, v244
	v_mov_b32_e32 v125, v238
	v_pk_mul_f32 v[118:119], v[126:127], v[124:125] op_sel_hi:[1,0]
	ds_write2_b32 v157, v118, v119 offset1:1
	v_mov_b32_e32 v244, v243
	v_mov_b32_e32 v245, v238
	v_pk_mul_f32 v[126:127], v[128:129], v[244:245] op_sel_hi:[1,0]
	ds_write2_b32 v22, v126, v127 offset1:1
	v_mov_b32_e32 v128, v243
	v_mov_b32_e32 v129, v238
	v_pk_mul_f32 v[126:127], v[130:131], v[128:129] op_sel_hi:[1,0]
	ds_write2_b32 v156, v126, v127 offset1:1
	v_mov_b32_e32 v130, v242
	v_mov_b32_e32 v131, v238
	v_pk_mul_f32 v[126:127], v[132:133], v[130:131] op_sel_hi:[1,0]
	ds_write2_b32 v18, v126, v127 offset1:1
	v_mov_b32_e32 v132, v242
	v_mov_b32_e32 v133, v238
	v_pk_mul_f32 v[126:127], v[134:135], v[132:133] op_sel_hi:[1,0]
	ds_write2_b32 v155, v126, v127 offset1:1
	v_mov_b32_e32 v242, v241
	v_mov_b32_e32 v243, v238
	v_pk_mul_f32 v[134:135], v[136:137], v[242:243] op_sel_hi:[1,0]
	ds_write2_b32 v14, v134, v135 offset1:1
	v_mov_b32_e32 v136, v241
	v_mov_b32_e32 v137, v238
	v_pk_mul_f32 v[134:135], v[138:139], v[136:137] op_sel_hi:[1,0]
	ds_write2_b32 v154, v134, v135 offset1:1
	v_mov_b32_e32 v138, v240
	v_mov_b32_e32 v139, v238
	v_pk_mul_f32 v[134:135], v[140:141], v[138:139] op_sel_hi:[1,0]
	ds_write2_b32 v10, v134, v135 offset1:1
	v_mov_b32_e32 v140, v240
	v_mov_b32_e32 v141, v238
	v_pk_mul_f32 v[134:135], v[142:143], v[140:141] op_sel_hi:[1,0]
	ds_write2_b32 v153, v134, v135 offset1:1
	v_mov_b32_e32 v240, v239
	v_mov_b32_e32 v241, v238
	v_pk_mul_f32 v[142:143], v[144:145], v[240:241] op_sel_hi:[1,0]
	ds_write2_b32 v6, v142, v143 offset1:1
	v_mov_b32_e32 v144, v239
	v_mov_b32_e32 v145, v238
	v_pk_mul_f32 v[142:143], v[146:147], v[144:145] op_sel_hi:[1,0]
	ds_write2_b32 v0, v142, v143 offset1:1
	s_waitcnt lgkmcnt(0)
; #define LAS __attribute__((address_space(3)))
; #define LDS_WAIT() asm volatile("s_waitcnt lgkmcnt(0)" ::: "memory")
; __device__ __forceinline__ unsigned cvtpk(float lo, float hi) { unsigned r; asm volatile("v_cvt_pk_bf16_f32 %0, %1, %2" : "=v"(r) : "v"(lo), "v"(hi)); return r; }
; __device__ __forceinline__ void tr_item(const float* W, int ldw, bf16* WT, int ldt, const float* gain, int dst_row0, int k0, int n0, LAS float* scr, int lane) {
;     ...
;     const int c = lane & 7;
; #pragma unroll
;     for (int j = 0; j < 8; ++j) { const int n = (lane >> 3) + 8 * j; const LAS float* s = scr + (8 * c) * 65 + n;
;         u32x4 o; o.x = cvtpk(s[0 * 65], s[1 * 65]); o.y = cvtpk(s[2 * 65], s[3 * 65]); o.z = cvtpk(s[4 * 65], s[5 * 65]); o.w = cvtpk(s[6 * 65], s[7 * 65]);
;         *(u32x4*)(WT + (size_t)(dst_row0 + n) * ldt + k0 + 8 * c) = o; }
;     LDS_WAIT(); asm volatile("" ::: "memory");
	v_lshlrev_b32_e32 v0, 1, v68
	ds_read2_b32 v[252:253], v96 offset1:65
	v_lshl_add_u64 v[2:3], s[10:11], 0, v[0:1]
	ds_read2_b32 v[250:251], v96 offset0:130 offset1:195
	v_add_u32_e32 v0, 0x400, v96
	ds_read2_b32 v[248:249], v0 offset0:4 offset1:69
	ds_read2_b32 v[246:247], v0 offset0:134 offset1:199
	v_add_u32_e32 v8, s8, v104
	v_add_u32_e32 v8, 0x2d800, v8
	s_mov_b64 s[10:11], 0x12200000
	v_ashrrev_i32_e32 v9, 31, v8
	v_lshl_add_u64 v[2:3], v[2:3], 0, s[10:11]
	v_lshlrev_b64 v[8:9], 12, v[8:9]
	v_lshl_add_u64 v[8:9], v[2:3], 0, v[8:9]
	v_mov_b32_e32 v156, v8
	v_mov_b32_e32 v157, v9
	ds_read2_b32 v[244:245], v96 offset0:8 offset1:73
	ds_read2_b32 v[242:243], v96 offset0:138 offset1:203
	ds_read2_b32 v[240:241], v0 offset0:12 offset1:77
	ds_read2_b32 v[238:239], v0 offset0:142 offset1:207
	v_add_u32_e32 v8, s8, v103
	v_add_u32_e32 v8, 0x2d800, v8
	v_ashrrev_i32_e32 v9, 31, v8
	v_lshlrev_b64 v[8:9], 12, v[8:9]
	v_lshl_add_u64 v[8:9], v[2:3], 0, v[8:9]
	v_mov_b32_e32 v154, v8
	v_mov_b32_e32 v155, v9
	ds_read2_b32 v[236:237], v96 offset0:16 offset1:81
	ds_read2_b32 v[234:235], v96 offset0:146 offset1:211
	ds_read2_b32 v[232:233], v0 offset0:20 offset1:85
	ds_read2_b32 v[216:217], v0 offset0:150 offset1:215
	v_add_u32_e32 v8, s8, v102
	v_add_u32_e32 v8, 0x2d800, v8
	v_ashrrev_i32_e32 v9, 31, v8
	v_lshlrev_b64 v[8:9], 12, v[8:9]
	v_lshl_add_u64 v[8:9], v[2:3], 0, v[8:9]
	v_mov_b32_e32 v152, v8
	v_mov_b32_e32 v153, v9
	ds_read2_b32 v[214:215], v96 offset0:24 offset1:89
	ds_read2_b32 v[212:213], v96 offset0:154 offset1:219
	ds_read2_b32 v[210:211], v0 offset0:28 offset1:93
	ds_read2_b32 v[208:209], v0 offset0:158 offset1:223
	v_add_u32_e32 v8, s8, v101
	v_add_u32_e32 v8, 0x2d800, v8
	v_ashrrev_i32_e32 v9, 31, v8
	v_lshlrev_b64 v[8:9], 12, v[8:9]
	v_lshl_add_u64 v[8:9], v[2:3], 0, v[8:9]
	v_mov_b32_e32 v150, v8
	v_mov_b32_e32 v151, v9
	ds_read2_b32 v[206:207], v96 offset0:32 offset1:97
	ds_read2_b32 v[204:205], v96 offset0:162 offset1:227
	ds_read2_b32 v[202:203], v0 offset0:36 offset1:101
	ds_read2_b32 v[200:201], v0 offset0:166 offset1:231
	v_add_u32_e32 v8, s8, v100
	v_add_u32_e32 v8, 0x2d800, v8
	v_ashrrev_i32_e32 v9, 31, v8
	v_lshlrev_b64 v[8:9], 12, v[8:9]
	v_lshl_add_u64 v[8:9], v[2:3], 0, v[8:9]
	v_mov_b32_e32 v148, v8
	v_mov_b32_e32 v149, v9
	ds_read2_b32 v[198:199], v96 offset0:40 offset1:105
	ds_read2_b32 v[196:197], v96 offset0:170 offset1:235
	ds_read2_b32 v[194:195], v0 offset0:44 offset1:109
	ds_read2_b32 v[176:177], v0 offset0:174 offset1:239
	v_add_u32_e32 v8, s8, v99
	v_add_u32_e32 v8, 0x2d800, v8
	v_ashrrev_i32_e32 v9, 31, v8
	v_lshlrev_b64 v[8:9], 12, v[8:9]
	v_lshl_add_u64 v[8:9], v[2:3], 0, v[8:9]
	v_mov_b32_e32 v146, v8
	v_mov_b32_e32 v147, v9
	ds_read2_b32 v[174:175], v96 offset0:48 offset1:113
	ds_read2_b32 v[172:173], v96 offset0:178 offset1:243
	ds_read2_b32 v[170:171], v0 offset0:52 offset1:117
	ds_read2_b32 v[168:169], v0 offset0:182 offset1:247
	v_add_u32_e32 v8, s8, v98
	v_add_u32_e32 v8, 0x2d800, v8
	v_ashrrev_i32_e32 v9, 31, v8
	v_lshlrev_b64 v[8:9], 12, v[8:9]
	v_lshl_add_u64 v[8:9], v[2:3], 0, v[8:9]
	v_mov_b32_e32 v144, v8
	v_mov_b32_e32 v145, v9
	ds_read2_b32 v[166:167], v96 offset0:56 offset1:121
	ds_read2_b32 v[164:165], v96 offset0:186 offset1:251
	ds_read2_b32 v[162:163], v0 offset0:60 offset1:125
	ds_read2_b32 v[160:161], v0 offset0:190 offset1:255
	v_add_u32_e32 v0, s8, v97
	v_add_u32_e32 v8, 0x2d800, v0
	v_ashrrev_i32_e32 v9, 31, v8
	v_lshlrev_b64 v[8:9], 12, v[8:9]
	v_lshl_add_u64 v[2:3], v[2:3], 0, v[8:9]
	v_mov_b32_e32 v142, v2
	v_mov_b32_e32 v143, v3
	s_waitcnt lgkmcnt(0)
	v_cvt_pk_bf16_f32 v159, v252, v253
	v_cvt_pk_bf16_f32 v253, v250, v251
	v_cvt_pk_bf16_f32 v252, v248, v249
	v_cvt_pk_bf16_f32 v251, v246, v247
	v_mov_b32_e32 v132, v159
	v_mov_b32_e32 v133, v253
	v_mov_b32_e32 v134, v252
	v_mov_b32_e32 v135, v251
	global_store_dwordx4 v[156:157], v[132:135], off
	v_cvt_pk_bf16_f32 v253, v244, v245
	v_cvt_pk_bf16_f32 v252, v242, v243
	v_cvt_pk_bf16_f32 v251, v240, v241
	v_cvt_pk_bf16_f32 v250, v238, v239
	v_mov_b32_e32 v136, v253
	v_mov_b32_e32 v137, v252
	v_mov_b32_e32 v138, v251
	v_mov_b32_e32 v139, v250
	global_store_dwordx4 v[154:155], v[136:139], off
	v_cvt_pk_bf16_f32 v253, v236, v237
	v_cvt_pk_bf16_f32 v252, v234, v235
	v_cvt_pk_bf16_f32 v251, v232, v233
	v_cvt_pk_bf16_f32 v250, v216, v217
	v_mov_b32_e32 v132, v253
	v_mov_b32_e32 v133, v252
	v_mov_b32_e32 v134, v251
	v_mov_b32_e32 v135, v250
	global_store_dwordx4 v[152:153], v[132:135], off
	v_cvt_pk_bf16_f32 v253, v214, v215
	v_cvt_pk_bf16_f32 v252, v212, v213
	v_cvt_pk_bf16_f32 v251, v210, v211
	v_cvt_pk_bf16_f32 v250, v208, v209
	v_mov_b32_e32 v136, v253
	v_mov_b32_e32 v137, v252
	v_mov_b32_e32 v138, v251
	v_mov_b32_e32 v139, v250
	global_store_dwordx4 v[150:151], v[136:139], off
	v_cvt_pk_bf16_f32 v253, v206, v207
	v_cvt_pk_bf16_f32 v252, v204, v205
	v_cvt_pk_bf16_f32 v251, v202, v203
	v_cvt_pk_bf16_f32 v250, v200, v201
	v_mov_b32_e32 v132, v253
	v_mov_b32_e32 v133, v252
	v_mov_b32_e32 v134, v251
	v_mov_b32_e32 v135, v250
	global_store_dwordx4 v[148:149], v[132:135], off
	v_cvt_pk_bf16_f32 v253, v198, v199
	v_cvt_pk_bf16_f32 v252, v196, v197
	v_cvt_pk_bf16_f32 v251, v194, v195
	v_cvt_pk_bf16_f32 v250, v176, v177
	v_mov_b32_e32 v136, v253
	v_mov_b32_e32 v137, v252
	v_mov_b32_e32 v138, v251
	v_mov_b32_e32 v139, v250
	global_store_dwordx4 v[146:147], v[136:139], off
	v_cvt_pk_bf16_f32 v253, v174, v175
	v_cvt_pk_bf16_f32 v252, v172, v173
	v_cvt_pk_bf16_f32 v251, v170, v171
	v_cvt_pk_bf16_f32 v250, v168, v169
	v_mov_b32_e32 v132, v253
	v_mov_b32_e32 v133, v252
	v_mov_b32_e32 v134, v251
	v_mov_b32_e32 v135, v250
	global_store_dwordx4 v[144:145], v[132:135], off
	v_cvt_pk_bf16_f32 v253, v166, v167
	v_cvt_pk_bf16_f32 v252, v164, v165
	v_cvt_pk_bf16_f32 v251, v162, v163
	v_cvt_pk_bf16_f32 v250, v160, v161
	v_mov_b32_e32 v136, v253
	v_mov_b32_e32 v137, v252
	v_mov_b32_e32 v138, v251
	v_mov_b32_e32 v139, v250
	global_store_dwordx4 v[142:143], v[136:139], off
	s_waitcnt lgkmcnt(0)

; #define LAS __attribute__((address_space(3)))
; __device__ __forceinline__ void tr_item(const float* W, int ldw, bf16* WT, int ldt, const float* gain, int dst_row0, int k0, int n0, LAS float* scr, int lane) {
;     ...
;     for (int i = 0; i < 16; ++i) v[i] = __builtin_nontemporal_load((const f32x4*)(W + (size_t)(k0 + kr + 4 * i) * ldw + n0 + n4));
; #pragma unroll
;     for (int i = 0; i < 16; ++i) { const int k = kr + 4 * i; const float g = gain ? gain[k0 + k] : 1.0f; LAS float* d = scr + k * 65 + n4;
;         d[0] = v[i][0] * g; d[1] = v[i][1] * g; d[2] = v[i][2] * g; d[3] = v[i][3] * g; }
.LBB0_1874:
	s_andn2_b64 vcc, exec, s[8:9]
	s_cbranch_vccnz .LBB0_1876
	s_lshl_b32 s8, s13, 6
	s_and_b32 s8, s8, 0xfffffc00
	s_load_dwordx2 s[16:17], s[4:5], 0xc0
	s_load_dwordx2 s[10:11], s[4:5], 0x118
	s_lshl_b32 s9, s12, 2
	s_sub_i32 s8, s2, s8
	s_add_i32 s8, s8, 0xfffda800
	s_addk_i32 s9, 0x800
	s_and_b32 s48, s9, 0xffffffc0
	s_ashr_i32 s9, s8, 31
	s_lshl_b64 s[18:19], s[8:9], 2
	s_waitcnt lgkmcnt(0)
	s_add_u32 s16, s16, s18
	v_or_b32_e32 v76, s48, v67
	s_addc_u32 s17, s17, s19
	v_lshlrev_b32_e32 v0, 2, v66
	v_mov_b32_e32 v77, v1
	v_lshl_add_u64 v[2:3], s[16:17], 0, v[0:1]
	v_lshlrev_b64 v[4:5], 12, v[76:77]
	v_lshl_add_u64 v[4:5], v[2:3], 0, v[4:5]
	v_lshlrev_b32_e32 v0, 10, v76
	v_lshl_add_u64 v[76:77], v[76:77], 2, s[6:7]
	global_load_dwordx4 v[116:119], v[4:5], off nt
	v_lshl_add_u64 v[2:3], v[0:1], 2, v[2:3]
	global_load_dword v253, v[76:77], off
	v_add_u32_e32 v71, v94, v78
	v_add_co_u32_e32 v4, vcc, s41, v2
	s_mov_b32 s9, 0x8000
	s_nop 0
	v_addc_co_u32_e32 v5, vcc, 0, v3, vcc
	global_load_dwordx4 v[120:123], v[4:5], off nt
	v_add_co_u32_e32 v4, vcc, s9, v2
	s_mov_b32 s9, 0xc000
	s_nop 0
	v_addc_co_u32_e32 v5, vcc, 0, v3, vcc
	global_load_dwordx4 v[124:127], v[4:5], off nt
	v_add_co_u32_e32 v4, vcc, s9, v2
	s_mov_b32 s9, 0x10000
	s_nop 0
	v_addc_co_u32_e32 v5, vcc, 0, v3, vcc
	global_load_dwordx4 v[128:131], v[4:5], off nt
	v_add_co_u32_e32 v4, vcc, s9, v2
	s_mov_b32 s9, 0x14000
	s_nop 0
	v_addc_co_u32_e32 v5, vcc, 0, v3, vcc
	global_load_dwordx4 v[132:135], v[4:5], off nt
	v_add_co_u32_e32 v4, vcc, s9, v2
	s_mov_b32 s9, 0x18000
	s_nop 0
	v_addc_co_u32_e32 v5, vcc, 0, v3, vcc
	global_load_dwordx4 v[136:139], v[4:5], off nt
	v_add_co_u32_e32 v4, vcc, s9, v2
	s_mov_b32 s9, 0x1c000
	s_nop 0
	v_addc_co_u32_e32 v5, vcc, 0, v3, vcc
	global_load_dwordx4 v[140:143], v[4:5], off nt
	v_add_co_u32_e32 v4, vcc, s9, v2
	s_mov_b32 s9, 0x24000
	s_nop 0
	v_addc_co_u32_e32 v5, vcc, 0, v3, vcc
	global_load_dwordx4 v[144:147], v[4:5], off nt
	v_add_co_u32_e32 v4, vcc, s88, v2
	s_lshl_b64 s[16:17], s[48:49], 1
	s_nop 0
	v_addc_co_u32_e32 v5, vcc, 0, v3, vcc
	global_load_dwordx4 v[148:151], v[4:5], off nt
	v_add_co_u32_e32 v4, vcc, s9, v2
	s_mov_b32 s9, 0x28000
	s_nop 0
	v_addc_co_u32_e32 v5, vcc, 0, v3, vcc
	global_load_dwordx4 v[152:155], v[4:5], off nt
	v_add_co_u32_e32 v4, vcc, s9, v2
	s_mov_b32 s9, 0x2c000
	s_nop 0
	v_addc_co_u32_e32 v5, vcc, 0, v3, vcc
	global_load_dwordx4 v[156:159], v[4:5], off nt
	v_add_co_u32_e32 v4, vcc, s9, v2
	s_mov_b32 s9, 0x30000
	s_nop 0
	v_addc_co_u32_e32 v5, vcc, 0, v3, vcc
	global_load_dwordx4 v[160:163], v[4:5], off nt
	v_add_co_u32_e32 v4, vcc, s9, v2
	s_mov_b32 s9, 0x34000
	s_nop 0
	v_addc_co_u32_e32 v5, vcc, 0, v3, vcc
	global_load_dwordx4 v[164:167], v[4:5], off nt
	v_add_co_u32_e32 v4, vcc, s9, v2
	s_mov_b32 s9, 0x38000
	s_nop 0
	v_addc_co_u32_e32 v5, vcc, 0, v3, vcc
	global_load_dwordx4 v[168:171], v[4:5], off nt
	v_mov_b32_e32 v252, v1
	v_or_b32_e32 v0, s48, v79
	s_waitcnt vmcnt(0)
	v_mov_b32_e32 v250, v253
	v_mov_b32_e32 v251, v252
	v_pk_mul_f32 v[248:249], v[116:117], v[250:251] op_sel_hi:[1,0]
	ds_write2_b32 v71, v248, v249 offset1:1
	v_mov_b32_e32 v248, v253
	v_mov_b32_e32 v249, v252
	v_pk_mul_f32 v[116:117], v[118:119], v[248:249] op_sel_hi:[1,0]
	ds_write2_b32 v71, v116, v117 offset0:2 offset1:3
	v_mov_b32_e32 v10, v168
	v_mov_b32_e32 v11, v169
	v_mov_b32_e32 v12, v170
	v_mov_b32_e32 v13, v171
	v_mov_b32_e32 v14, v164
	v_mov_b32_e32 v15, v165
	v_mov_b32_e32 v16, v166
	v_mov_b32_e32 v17, v167
	v_mov_b32_e32 v18, v160
	v_mov_b32_e32 v19, v161
	v_mov_b32_e32 v20, v162
	v_mov_b32_e32 v21, v163
	v_mov_b32_e32 v22, v156
	v_mov_b32_e32 v23, v157
	v_mov_b32_e32 v24, v158
	v_mov_b32_e32 v25, v159
	v_mov_b32_e32 v26, v152
	v_mov_b32_e32 v27, v153
	v_mov_b32_e32 v28, v154
	v_mov_b32_e32 v29, v155
	v_mov_b32_e32 v30, v148
	v_mov_b32_e32 v31, v149
	v_mov_b32_e32 v32, v150
	v_mov_b32_e32 v33, v151
	v_mov_b32_e32 v34, v144
	v_mov_b32_e32 v35, v145
	v_mov_b32_e32 v36, v146
	v_mov_b32_e32 v37, v147
	v_mov_b32_e32 v38, v140
	v_mov_b32_e32 v39, v141
	v_mov_b32_e32 v40, v142
	v_mov_b32_e32 v41, v143
	v_mov_b32_e32 v42, v136
	v_mov_b32_e32 v43, v137
	v_mov_b32_e32 v44, v138
	v_mov_b32_e32 v45, v139
	v_mov_b32_e32 v46, v132
	v_mov_b32_e32 v47, v133
	v_mov_b32_e32 v48, v134
	v_mov_b32_e32 v49, v135
	v_mov_b32_e32 v50, v128
	v_mov_b32_e32 v51, v129
	v_mov_b32_e32 v52, v130
	v_mov_b32_e32 v53, v131
	v_mov_b32_e32 v54, v124
	v_mov_b32_e32 v55, v125
	v_mov_b32_e32 v56, v126
	v_mov_b32_e32 v57, v127
	v_mov_b32_e32 v58, v120
	v_mov_b32_e32 v59, v121
	v_mov_b32_e32 v60, v122
	v_mov_b32_e32 v61, v123
	v_mov_b32_e32 v62, v116
	v_mov_b32_e32 v63, v117
	v_mov_b32_e32 v64, v118
	v_mov_b32_e32 v65, v119
	v_lshl_add_u64 v[62:63], v[0:1], 2, s[6:7]
	global_load_dword v253, v[62:63], off
	v_add_u32_e32 v62, 0x410, v71
	v_add_co_u32_e32 v4, vcc, s9, v2
	s_mov_b32 s9, 0x3c000
	s_nop 0
	v_addc_co_u32_e32 v5, vcc, 0, v3, vcc
	global_load_dwordx4 v[116:119], v[4:5], off nt
	v_add_co_u32_e32 v2, vcc, s9, v2
	s_add_u32 s10, s10, s16
	s_nop 0
	v_addc_co_u32_e32 v3, vcc, 0, v3, vcc
	global_load_dwordx4 v[120:123], v[2:3], off nt
	s_addc_u32 s11, s11, s17
	v_mov_b32_e32 v236, v58
	v_mov_b32_e32 v237, v59
	v_mov_b32_e32 v238, v1
	v_add_u32_e32 v0, 0x418, v71
	v_mov_b32_e32 v215, v0
	v_or_b32_e32 v0, s48, v80
	v_lshl_add_u64 v[58:59], v[0:1], 2, s[6:7]
	global_load_dword v252, v[58:59], off
	v_add_u32_e32 v58, 0x820, v71
	v_mov_b32_e32 v212, v54
	v_mov_b32_e32 v213, v55
	v_add_u32_e32 v0, 0x828, v71
	v_mov_b32_e32 v214, v0
	v_or_b32_e32 v0, s48, v81
	v_lshl_add_u64 v[54:55], v[0:1], 2, s[6:7]
	global_load_dword v251, v[54:55], off
; #define LAS __attribute__((address_space(3)))
; __device__ __forceinline__ void tr_item(const float* W, int ldw, bf16* WT, int ldt, const float* gain, int dst_row0, int k0, int n0, LAS float* scr, int lane) {
;     ...
;     for (int i = 0; i < 16; ++i) { const int k = kr + 4 * i; const float g = gain ? gain[k0 + k] : 1.0f; LAS float* d = scr + k * 65 + n4;
;         d[0] = v[i][0] * g; d[1] = v[i][1] * g; d[2] = v[i][2] * g; d[3] = v[i][3] * g; }
	v_add_u32_e32 v54, 0xc30, v71
	v_mov_b32_e32 v206, v50
	v_mov_b32_e32 v207, v51
	v_add_u32_e32 v0, 0xc38, v71
	v_mov_b32_e32 v203, v0
	v_or_b32_e32 v0, s48, v82
	v_lshl_add_u64 v[50:51], v[0:1], 2, s[6:7]
	global_load_dword v250, v[50:51], off
	v_add_u32_e32 v50, 0x1040, v71
	v_mov_b32_e32 v200, v46
	v_mov_b32_e32 v201, v47
	v_add_u32_e32 v0, 0x1048, v71
	v_mov_b32_e32 v202, v0
	v_or_b32_e32 v0, s48, v83
	v_lshl_add_u64 v[46:47], v[0:1], 2, s[6:7]
	global_load_dword v249, v[46:47], off
	v_add_u32_e32 v46, 0x1450, v71
	v_mov_b32_e32 v194, v42
	v_mov_b32_e32 v195, v43
	v_mov_b32_e32 v176, v44
	v_mov_b32_e32 v177, v45
	v_add_u32_e32 v42, v94, v95
	v_or_b32_e32 v0, s48, v84
	v_lshl_add_u64 v[44:45], v[0:1], 2, s[6:7]
	global_load_dword v248, v[44:45], off
	v_add_u32_e32 v43, 0x410, v42
	v_mov_b32_e32 v172, v38
	v_mov_b32_e32 v173, v39
	v_add_u32_e32 v0, 0x418, v42
	v_mov_b32_e32 v167, v0
	v_or_b32_e32 v0, s48, v85
	v_lshl_add_u64 v[38:39], v[0:1], 2, s[6:7]
	global_load_dword v247, v[38:39], off
	v_add_u32_e32 v38, 0x820, v42
	v_mov_b32_e32 v164, v34
	v_mov_b32_e32 v165, v35
	v_add_u32_e32 v0, 0x828, v42
	v_mov_b32_e32 v166, v0
	v_or_b32_e32 v0, s48, v86
	v_lshl_add_u64 v[34:35], v[0:1], 2, s[6:7]
	global_load_dword v246, v[34:35], off
	v_add_u32_e32 v34, 0xc30, v42
	v_mov_b32_e32 v160, v30
	v_mov_b32_e32 v161, v31
	v_add_u32_e32 v0, 0xc38, v42
	v_mov_b32_e32 v155, v0
	v_or_b32_e32 v0, s48, v87
	v_lshl_add_u64 v[30:31], v[0:1], 2, s[6:7]
	global_load_dword v245, v[30:31], off
	v_add_u32_e32 v30, 0x1040, v42
	v_mov_b32_e32 v152, v26
	v_mov_b32_e32 v153, v27
	v_add_u32_e32 v0, 0x1048, v42
	v_mov_b32_e32 v154, v0
	v_or_b32_e32 v0, s48, v88
	v_lshl_add_u64 v[26:27], v[0:1], 2, s[6:7]
	global_load_dword v244, v[26:27], off
	v_add_u32_e32 v26, 0x1450, v42
	v_mov_b32_e32 v148, v22
	v_mov_b32_e32 v149, v23
	v_add_u32_e32 v0, 0x1458, v42
	v_mov_b32_e32 v143, v0
	v_or_b32_e32 v0, s48, v89
	v_lshl_add_u64 v[22:23], v[0:1], 2, s[6:7]
	global_load_dword v243, v[22:23], off
	v_add_u32_e32 v22, 0x1860, v42
	v_mov_b32_e32 v140, v18
	v_mov_b32_e32 v141, v19
	v_add_u32_e32 v0, 0x1868, v42
	v_mov_b32_e32 v142, v0
	v_or_b32_e32 v0, s48, v90
	v_lshl_add_u64 v[18:19], v[0:1], 2, s[6:7]
	global_load_dword v242, v[18:19], off
	v_add_u32_e32 v18, 0x1c70, v42
	v_mov_b32_e32 v136, v14
	v_mov_b32_e32 v137, v15
	v_add_u32_e32 v0, 0x1c78, v42
	v_mov_b32_e32 v131, v0
	v_or_b32_e32 v0, s48, v91
	v_lshl_add_u64 v[14:15], v[0:1], 2, s[6:7]
	global_load_dword v241, v[14:15], off
	v_add_u32_e32 v14, 0x2080, v42
	v_mov_b32_e32 v128, v10
	v_mov_b32_e32 v129, v11
	v_add_u32_e32 v0, 0x2088, v42
	v_mov_b32_e32 v130, v0
	v_or_b32_e32 v0, s48, v92
	v_lshl_add_u64 v[10:11], v[0:1], 2, s[6:7]
	global_load_dword v240, v[10:11], off
	v_add_u32_e32 v10, 0x2490, v42
	v_add_u32_e32 v0, 0x2498, v42
	v_mov_b32_e32 v115, v0
	v_or_b32_e32 v0, s48, v93
	v_lshl_add_u64 v[6:7], v[0:1], 2, s[6:7]
	global_load_dword v239, v[6:7], off
	v_add_u32_e32 v6, 0x28a0, v42
	v_add_u32_e32 v0, 0x28a8, v42
	s_waitcnt vmcnt(0)
	v_mov_b32_e32 v234, v253
	v_mov_b32_e32 v235, v238
	v_pk_mul_f32 v[232:233], v[236:237], v[234:235] op_sel_hi:[1,0]
	ds_write2_b32 v62, v232, v233 offset1:1
	v_mov_b32_e32 v232, v253
	v_mov_b32_e32 v233, v238
	v_pk_mul_f32 v[216:217], v[60:61], v[232:233] op_sel_hi:[1,0]
	ds_write2_b32 v215, v216, v217 offset1:1
	v_mov_b32_e32 v216, v252
	v_mov_b32_e32 v217, v238
	v_pk_mul_f32 v[210:211], v[212:213], v[216:217] op_sel_hi:[1,0]
	ds_write2_b32 v58, v210, v211 offset1:1
	v_mov_b32_e32 v210, v252
	v_mov_b32_e32 v211, v238
	v_pk_mul_f32 v[208:209], v[56:57], v[210:211] op_sel_hi:[1,0]
	ds_write2_b32 v214, v208, v209 offset1:1
	v_mov_b32_e32 v252, v251
	v_mov_b32_e32 v253, v238
	v_pk_mul_f32 v[208:209], v[206:207], v[252:253] op_sel_hi:[1,0]
	ds_write2_b32 v54, v208, v209 offset1:1
	v_mov_b32_e32 v208, v251
	v_mov_b32_e32 v209, v238
	v_pk_mul_f32 v[204:205], v[52:53], v[208:209] op_sel_hi:[1,0]
	ds_write2_b32 v203, v204, v205 offset1:1
	v_mov_b32_e32 v204, v250
	v_mov_b32_e32 v205, v238
	v_pk_mul_f32 v[198:199], v[200:201], v[204:205] op_sel_hi:[1,0]
	ds_write2_b32 v50, v198, v199 offset1:1
	v_mov_b32_e32 v198, v250
	v_mov_b32_e32 v199, v238
	v_pk_mul_f32 v[196:197], v[48:49], v[198:199] op_sel_hi:[1,0]
	ds_write2_b32 v202, v196, v197 offset1:1
	v_mov_b32_e32 v250, v249
	v_mov_b32_e32 v251, v238
	v_pk_mul_f32 v[196:197], v[194:195], v[250:251] op_sel_hi:[1,0]
	ds_write2_b32 v46, v196, v197 offset1:1
	v_mov_b32_e32 v196, v249
	v_mov_b32_e32 v197, v238
	v_pk_mul_f32 v[174:175], v[176:177], v[196:197] op_sel_hi:[1,0]
	ds_write2_b32 v42, v174, v175 offset0:2 offset1:3
	v_mov_b32_e32 v174, v248
	v_mov_b32_e32 v175, v238
	v_pk_mul_f32 v[170:171], v[172:173], v[174:175] op_sel_hi:[1,0]
	ds_write2_b32 v43, v170, v171 offset1:1
	v_mov_b32_e32 v170, v248
	v_mov_b32_e32 v171, v238
	v_pk_mul_f32 v[168:169], v[40:41], v[170:171] op_sel_hi:[1,0]
	ds_write2_b32 v167, v168, v169 offset1:1
	v_mov_b32_e32 v248, v247
	v_mov_b32_e32 v249, v238
	v_pk_mul_f32 v[168:169], v[164:165], v[248:249] op_sel_hi:[1,0]
	ds_write2_b32 v38, v168, v169 offset1:1
	v_mov_b32_e32 v168, v247
	v_mov_b32_e32 v169, v238
	v_pk_mul_f32 v[162:163], v[36:37], v[168:169] op_sel_hi:[1,0]
	ds_write2_b32 v166, v162, v163 offset1:1
	v_mov_b32_e32 v162, v246
	v_mov_b32_e32 v163, v238
	v_pk_mul_f32 v[158:159], v[160:161], v[162:163] op_sel_hi:[1,0]
	ds_write2_b32 v34, v158, v159 offset1:1
	v_mov_b32_e32 v158, v246
	v_mov_b32_e32 v159, v238
	v_pk_mul_f32 v[156:157], v[32:33], v[158:159] op_sel_hi:[1,0]
	ds_write2_b32 v155, v156, v157 offset1:1
	v_mov_b32_e32 v246, v245
	v_mov_b32_e32 v247, v238
	v_pk_mul_f32 v[156:157], v[152:153], v[246:247] op_sel_hi:[1,0]
; #define LAS __attribute__((address_space(3)))
; #define LDS_WAIT() asm volatile("s_waitcnt lgkmcnt(0)" ::: "memory")
; __device__ __forceinline__ unsigned cvtpk(float lo, float hi) { unsigned r; asm volatile("v_cvt_pk_bf16_f32 %0, %1, %2" : "=v"(r) : "v"(lo), "v"(hi)); return r; }
; __device__ __forceinline__ void tr_item(const float* W, int ldw, bf16* WT, int ldt, const float* gain, int dst_row0, int k0, int n0, LAS float* scr, int lane) {
;     ...
;     for (int i = 0; i < 16; ++i) { const int k = kr + 4 * i; const float g = gain ? gain[k0 + k] : 1.0f; LAS float* d = scr + k * 65 + n4;
;         d[0] = v[i][0] * g; d[1] = v[i][1] * g; d[2] = v[i][2] * g; d[3] = v[i][3] * g; }
;     LDS_WAIT(); asm volatile("" ::: "memory");
;     const int c = lane & 7;
; #pragma unroll
;     for (int j = 0; j < 8; ++j) { const int n = (lane >> 3) + 8 * j; const LAS float* s = scr + (8 * c) * 65 + n;
;         u32x4 o; o.x = cvtpk(s[0 * 65], s[1 * 65]); o.y = cvtpk(s[2 * 65], s[3 * 65]); o.z = cvtpk(s[4 * 65], s[5 * 65]); o.w = cvtpk(s[6 * 65], s[7 * 65]);
;         *(u32x4*)(WT + (size_t)(dst_row0 + n) * ldt + k0 + 8 * c) = o; }
	ds_write2_b32 v30, v156, v157 offset1:1
	v_mov_b32_e32 v156, v245
	v_mov_b32_e32 v157, v238
	v_pk_mul_f32 v[150:151], v[28:29], v[156:157] op_sel_hi:[1,0]
	ds_write2_b32 v154, v150, v151 offset1:1
	v_mov_b32_e32 v150, v244
	v_mov_b32_e32 v151, v238
	v_pk_mul_f32 v[146:147], v[148:149], v[150:151] op_sel_hi:[1,0]
	ds_write2_b32 v26, v146, v147 offset1:1
	v_mov_b32_e32 v146, v244
	v_mov_b32_e32 v147, v238
	v_pk_mul_f32 v[144:145], v[24:25], v[146:147] op_sel_hi:[1,0]
	ds_write2_b32 v143, v144, v145 offset1:1
	v_mov_b32_e32 v244, v243
	v_mov_b32_e32 v245, v238
	v_pk_mul_f32 v[144:145], v[140:141], v[244:245] op_sel_hi:[1,0]
	ds_write2_b32 v22, v144, v145 offset1:1
	v_mov_b32_e32 v144, v243
	v_mov_b32_e32 v145, v238
	v_pk_mul_f32 v[138:139], v[20:21], v[144:145] op_sel_hi:[1,0]
	ds_write2_b32 v142, v138, v139 offset1:1
	v_mov_b32_e32 v138, v242
	v_mov_b32_e32 v139, v238
	v_pk_mul_f32 v[134:135], v[136:137], v[138:139] op_sel_hi:[1,0]
	ds_write2_b32 v18, v134, v135 offset1:1
	v_mov_b32_e32 v134, v242
	v_mov_b32_e32 v135, v238
	v_pk_mul_f32 v[132:133], v[16:17], v[134:135] op_sel_hi:[1,0]
	ds_write2_b32 v131, v132, v133 offset1:1
	v_mov_b32_e32 v242, v241
	v_mov_b32_e32 v243, v238
	v_pk_mul_f32 v[132:133], v[128:129], v[242:243] op_sel_hi:[1,0]
	ds_write2_b32 v14, v132, v133 offset1:1
	v_mov_b32_e32 v132, v241
	v_mov_b32_e32 v133, v238
	v_pk_mul_f32 v[126:127], v[12:13], v[132:133] op_sel_hi:[1,0]
	ds_write2_b32 v130, v126, v127 offset1:1
	v_mov_b32_e32 v126, v240
	v_mov_b32_e32 v127, v238
	v_pk_mul_f32 v[124:125], v[116:117], v[126:127] op_sel_hi:[1,0]
	ds_write2_b32 v10, v124, v125 offset1:1
	v_mov_b32_e32 v124, v240
	v_mov_b32_e32 v125, v238
	v_pk_mul_f32 v[116:117], v[118:119], v[124:125] op_sel_hi:[1,0]
	ds_write2_b32 v115, v116, v117 offset1:1
	v_mov_b32_e32 v240, v239
	v_mov_b32_e32 v241, v238
	v_pk_mul_f32 v[118:119], v[120:121], v[240:241] op_sel_hi:[1,0]
	ds_write2_b32 v6, v118, v119 offset1:1
	v_mov_b32_e32 v120, v239
	v_mov_b32_e32 v121, v238
	v_pk_mul_f32 v[118:119], v[122:123], v[120:121] op_sel_hi:[1,0]
	ds_write2_b32 v0, v118, v119 offset1:1
	s_waitcnt lgkmcnt(0)
	v_lshlrev_b32_e32 v0, 1, v68
	ds_read2_b32 v[252:253], v96 offset1:65
	v_lshl_add_u64 v[2:3], s[10:11], 0, v[0:1]
	ds_read2_b32 v[250:251], v96 offset0:130 offset1:195
	v_add_u32_e32 v0, 0x400, v96
	ds_read2_b32 v[248:249], v0 offset0:4 offset1:69
	ds_read2_b32 v[246:247], v0 offset0:134 offset1:199
	v_add_u32_e32 v8, s8, v112
	v_add_u32_e32 v8, 0x25800, v8
	s_mov_b64 s[10:11], 0x12200000
	v_ashrrev_i32_e32 v9, 31, v8
	v_lshl_add_u64 v[2:3], v[2:3], 0, s[10:11]
	v_lshlrev_b64 v[8:9], 12, v[8:9]
	v_lshl_add_u64 v[8:9], v[2:3], 0, v[8:9]
	v_mov_b32_e32 v156, v8
	v_mov_b32_e32 v157, v9
	ds_read2_b32 v[244:245], v96 offset0:8 offset1:73
	ds_read2_b32 v[242:243], v96 offset0:138 offset1:203
	ds_read2_b32 v[240:241], v0 offset0:12 offset1:77
	ds_read2_b32 v[238:239], v0 offset0:142 offset1:207
	v_add_u32_e32 v8, s8, v111
	v_add_u32_e32 v8, 0x25800, v8
	v_ashrrev_i32_e32 v9, 31, v8
	v_lshlrev_b64 v[8:9], 12, v[8:9]
	v_lshl_add_u64 v[8:9], v[2:3], 0, v[8:9]
	v_mov_b32_e32 v154, v8
	v_mov_b32_e32 v155, v9
	ds_read2_b32 v[236:237], v96 offset0:16 offset1:81
	ds_read2_b32 v[234:235], v96 offset0:146 offset1:211
	ds_read2_b32 v[232:233], v0 offset0:20 offset1:85
	ds_read2_b32 v[216:217], v0 offset0:150 offset1:215
	v_add_u32_e32 v8, s8, v110
	v_add_u32_e32 v8, 0x25800, v8
	v_ashrrev_i32_e32 v9, 31, v8
	v_lshlrev_b64 v[8:9], 12, v[8:9]
	v_lshl_add_u64 v[8:9], v[2:3], 0, v[8:9]
	v_mov_b32_e32 v152, v8
	v_mov_b32_e32 v153, v9
	ds_read2_b32 v[214:215], v96 offset0:24 offset1:89
	ds_read2_b32 v[212:213], v96 offset0:154 offset1:219
	ds_read2_b32 v[210:211], v0 offset0:28 offset1:93
	ds_read2_b32 v[208:209], v0 offset0:158 offset1:223
	v_add_u32_e32 v8, s8, v109
	v_add_u32_e32 v8, 0x25800, v8
	v_ashrrev_i32_e32 v9, 31, v8
	v_lshlrev_b64 v[8:9], 12, v[8:9]
	v_lshl_add_u64 v[8:9], v[2:3], 0, v[8:9]
	v_mov_b32_e32 v150, v8
	v_mov_b32_e32 v151, v9
	ds_read2_b32 v[206:207], v96 offset0:32 offset1:97
	ds_read2_b32 v[204:205], v96 offset0:162 offset1:227
	ds_read2_b32 v[202:203], v0 offset0:36 offset1:101
	ds_read2_b32 v[200:201], v0 offset0:166 offset1:231
	v_add_u32_e32 v8, s8, v108
	v_add_u32_e32 v8, 0x25800, v8
	v_ashrrev_i32_e32 v9, 31, v8
	v_lshlrev_b64 v[8:9], 12, v[8:9]
	v_lshl_add_u64 v[8:9], v[2:3], 0, v[8:9]
	v_mov_b32_e32 v148, v8
	v_mov_b32_e32 v149, v9
	ds_read2_b32 v[198:199], v96 offset0:40 offset1:105
	ds_read2_b32 v[196:197], v96 offset0:170 offset1:235
	ds_read2_b32 v[194:195], v0 offset0:44 offset1:109
	ds_read2_b32 v[176:177], v0 offset0:174 offset1:239
	v_add_u32_e32 v8, s8, v107
	v_add_u32_e32 v8, 0x25800, v8
	v_ashrrev_i32_e32 v9, 31, v8
	v_lshlrev_b64 v[8:9], 12, v[8:9]
	v_lshl_add_u64 v[8:9], v[2:3], 0, v[8:9]
	v_mov_b32_e32 v146, v8
	v_mov_b32_e32 v147, v9
	ds_read2_b32 v[174:175], v96 offset0:48 offset1:113
	ds_read2_b32 v[172:173], v96 offset0:178 offset1:243
	ds_read2_b32 v[170:171], v0 offset0:52 offset1:117
	ds_read2_b32 v[168:169], v0 offset0:182 offset1:247
	v_add_u32_e32 v8, s8, v106
	v_add_u32_e32 v8, 0x25800, v8
	v_ashrrev_i32_e32 v9, 31, v8
	v_lshlrev_b64 v[8:9], 12, v[8:9]
	v_lshl_add_u64 v[8:9], v[2:3], 0, v[8:9]
	v_mov_b32_e32 v144, v8
	v_mov_b32_e32 v145, v9
	ds_read2_b32 v[166:167], v96 offset0:56 offset1:121
	ds_read2_b32 v[164:165], v96 offset0:186 offset1:251
	ds_read2_b32 v[162:163], v0 offset0:60 offset1:125
	ds_read2_b32 v[160:161], v0 offset0:190 offset1:255
	v_add_u32_e32 v0, s8, v105
	v_add_u32_e32 v8, 0x25800, v0
	v_ashrrev_i32_e32 v9, 31, v8
	v_lshlrev_b64 v[8:9], 12, v[8:9]
	v_lshl_add_u64 v[2:3], v[2:3], 0, v[8:9]
	v_mov_b32_e32 v142, v2
	v_mov_b32_e32 v143, v3
	s_waitcnt lgkmcnt(0)
; #define LAS __attribute__((address_space(3)))
; __device__ __forceinline__ unsigned cvtpk(float lo, float hi) { unsigned r; asm volatile("v_cvt_pk_bf16_f32 %0, %1, %2" : "=v"(r) : "v"(lo), "v"(hi)); return r; }
; __device__ __forceinline__ void tr_item(const float* W, int ldw, bf16* WT, int ldt, const float* gain, int dst_row0, int k0, int n0, LAS float* scr, int lane) {
;     ...
;     for (int j = 0; j < 8; ++j) { const int n = (lane >> 3) + 8 * j; const LAS float* s = scr + (8 * c) * 65 + n;
;         u32x4 o; o.x = cvtpk(s[0 * 65], s[1 * 65]); o.y = cvtpk(s[2 * 65], s[3 * 65]); o.z = cvtpk(s[4 * 65], s[5 * 65]); o.w = cvtpk(s[6 * 65], s[7 * 65]);
;         *(u32x4*)(WT + (size_t)(dst_row0 + n) * ldt + k0 + 8 * c) = o; }
	v_cvt_pk_bf16_f32 v159, v252, v253
	v_cvt_pk_bf16_f32 v253, v250, v251
	v_cvt_pk_bf16_f32 v252, v248, v249
	v_cvt_pk_bf16_f32 v251, v246, v247
	v_mov_b32_e32 v132, v159
	v_mov_b32_e32 v133, v253
	v_mov_b32_e32 v134, v252
	v_mov_b32_e32 v135, v251
	global_store_dwordx4 v[156:157], v[132:135], off
	v_cvt_pk_bf16_f32 v253, v244, v245
	v_cvt_pk_bf16_f32 v252, v242, v243
	v_cvt_pk_bf16_f32 v251, v240, v241
	v_cvt_pk_bf16_f32 v250, v238, v239
	v_mov_b32_e32 v136, v253
	v_mov_b32_e32 v137, v252
	v_mov_b32_e32 v138, v251
	v_mov_b32_e32 v139, v250
	global_store_dwordx4 v[154:155], v[136:139], off
	v_cvt_pk_bf16_f32 v253, v236, v237
	v_cvt_pk_bf16_f32 v252, v234, v235
	v_cvt_pk_bf16_f32 v251, v232, v233
	v_cvt_pk_bf16_f32 v250, v216, v217
	v_mov_b32_e32 v132, v253
	v_mov_b32_e32 v133, v252
	v_mov_b32_e32 v134, v251
	v_mov_b32_e32 v135, v250
	global_store_dwordx4 v[152:153], v[132:135], off
	v_cvt_pk_bf16_f32 v253, v214, v215
	v_cvt_pk_bf16_f32 v252, v212, v213
	v_cvt_pk_bf16_f32 v251, v210, v211
	v_cvt_pk_bf16_f32 v250, v208, v209
	v_mov_b32_e32 v136, v253
	v_mov_b32_e32 v137, v252
	v_mov_b32_e32 v138, v251
	v_mov_b32_e32 v139, v250
	global_store_dwordx4 v[150:151], v[136:139], off
	v_cvt_pk_bf16_f32 v253, v206, v207
	v_cvt_pk_bf16_f32 v252, v204, v205
	v_cvt_pk_bf16_f32 v251, v202, v203
	v_cvt_pk_bf16_f32 v250, v200, v201
	v_mov_b32_e32 v132, v253
	v_mov_b32_e32 v133, v252
	v_mov_b32_e32 v134, v251
	v_mov_b32_e32 v135, v250
	global_store_dwordx4 v[148:149], v[132:135], off
	v_cvt_pk_bf16_f32 v253, v198, v199
	v_cvt_pk_bf16_f32 v252, v196, v197
	v_cvt_pk_bf16_f32 v251, v194, v195
	v_cvt_pk_bf16_f32 v250, v176, v177
	v_mov_b32_e32 v136, v253
	v_mov_b32_e32 v137, v252
	v_mov_b32_e32 v138, v251
	v_mov_b32_e32 v139, v250
	global_store_dwordx4 v[146:147], v[136:139], off
	v_cvt_pk_bf16_f32 v253, v174, v175
	v_cvt_pk_bf16_f32 v252, v172, v173
	v_cvt_pk_bf16_f32 v251, v170, v171
	v_cvt_pk_bf16_f32 v250, v168, v169
	v_mov_b32_e32 v132, v253
	v_mov_b32_e32 v133, v252
	v_mov_b32_e32 v134, v251
	v_mov_b32_e32 v135, v250
	global_store_dwordx4 v[144:145], v[132:135], off
	v_cvt_pk_bf16_f32 v253, v166, v167
	v_cvt_pk_bf16_f32 v252, v164, v165
	v_cvt_pk_bf16_f32 v251, v162, v163
	v_cvt_pk_bf16_f32 v250, v160, v161
	v_mov_b32_e32 v136, v253
	v_mov_b32_e32 v137, v252
	v_mov_b32_e32 v138, v251
	v_mov_b32_e32 v139, v250
	global_store_dwordx4 v[142:143], v[136:139], off
	s_waitcnt lgkmcnt(0)

; #define LAS __attribute__((address_space(3)))
; __device__ __forceinline__ void tr_item(const float* W, int ldw, bf16* WT, int ldt, const float* gain, int dst_row0, int k0, int n0, LAS float* scr, int lane) {
;     ...
;     for (int i = 0; i < 16; ++i) v[i] = __builtin_nontemporal_load((const f32x4*)(W + (size_t)(k0 + kr + 4 * i) * ldw + n0 + n4));
; #pragma unroll
;     for (int i = 0; i < 16; ++i) { const int k = kr + 4 * i; const float g = gain ? gain[k0 + k] : 1.0f; LAS float* d = scr + k * 65 + n4;
.LBB0_1877:
	s_andn2_b64 vcc, exec, s[8:9]
	s_cbranch_vccnz .LBB0_1866
	s_ashr_i32 s10, s14, 31
	s_lshr_b32 s10, s10, 27
	s_add_i32 s10, s14, s10
	s_ashr_i32 s10, s10, 5
	s_lshl_b32 s11, s10, 11
	s_load_dwordx2 s[16:17], s[4:5], 0xf0
	s_load_dwordx2 s[8:9], s[4:5], 0x118
	s_sub_i32 s15, s2, s11
	s_add_i32 s18, s15, 0xfffea800
	s_ashr_i32 s19, s18, 31
	s_lshl_b32 s10, s10, 6
	s_lshl_b64 s[18:19], s[18:19], 2
	v_or_b32_e32 v76, s10, v67
	s_waitcnt lgkmcnt(0)
	s_add_u32 s16, s16, s18
	s_addc_u32 s17, s17, s19
	v_lshlrev_b32_e32 v0, 2, v66
	v_ashrrev_i32_e32 v77, 31, v76
	v_lshl_add_u64 v[2:3], s[16:17], 0, v[0:1]
	v_lshlrev_b64 v[4:5], 13, v[76:77]
	v_lshl_add_u64 v[4:5], v[2:3], 0, v[4:5]
	global_load_dwordx4 v[62:65], v[4:5], off nt
	v_or_b32_e32 v4, 4, v76
	v_ashrrev_i32_e32 v5, 31, v4
	v_lshlrev_b64 v[4:5], 13, v[4:5]
	v_lshl_add_u64 v[4:5], v[2:3], 0, v[4:5]
	global_load_dwordx4 v[58:61], v[4:5], off nt
	v_or_b32_e32 v4, 8, v76
	v_ashrrev_i32_e32 v5, 31, v4
	v_lshlrev_b64 v[4:5], 13, v[4:5]
	v_lshl_add_u64 v[4:5], v[2:3], 0, v[4:5]
	global_load_dwordx4 v[54:57], v[4:5], off nt
	v_or_b32_e32 v4, 12, v76
	v_ashrrev_i32_e32 v5, 31, v4
	v_lshlrev_b64 v[4:5], 13, v[4:5]
	v_lshl_add_u64 v[4:5], v[2:3], 0, v[4:5]
	global_load_dwordx4 v[50:53], v[4:5], off nt
	v_or_b32_e32 v4, 16, v76
	v_ashrrev_i32_e32 v5, 31, v4
	v_lshlrev_b64 v[4:5], 13, v[4:5]
	v_lshl_add_u64 v[4:5], v[2:3], 0, v[4:5]
	global_load_dwordx4 v[46:49], v[4:5], off nt
	v_or_b32_e32 v4, 20, v76
	v_ashrrev_i32_e32 v5, 31, v4
	v_lshlrev_b64 v[4:5], 13, v[4:5]
	v_lshl_add_u64 v[4:5], v[2:3], 0, v[4:5]
	global_load_dwordx4 v[42:45], v[4:5], off nt
	v_or_b32_e32 v4, 24, v76
	v_ashrrev_i32_e32 v5, 31, v4
	v_lshlrev_b64 v[4:5], 13, v[4:5]
	v_lshl_add_u64 v[4:5], v[2:3], 0, v[4:5]
	global_load_dwordx4 v[38:41], v[4:5], off nt
	v_or_b32_e32 v4, 28, v76
	v_ashrrev_i32_e32 v5, 31, v4
	v_lshlrev_b64 v[4:5], 13, v[4:5]
	v_lshl_add_u64 v[4:5], v[2:3], 0, v[4:5]
	global_load_dwordx4 v[34:37], v[4:5], off nt
	v_or_b32_e32 v4, 32, v76
	v_ashrrev_i32_e32 v5, 31, v4
	v_lshlrev_b64 v[4:5], 13, v[4:5]
	v_lshl_add_u64 v[4:5], v[2:3], 0, v[4:5]
	global_load_dwordx4 v[30:33], v[4:5], off nt
	v_or_b32_e32 v4, 36, v76
	v_ashrrev_i32_e32 v5, 31, v4
	v_lshlrev_b64 v[4:5], 13, v[4:5]
	v_lshl_add_u64 v[4:5], v[2:3], 0, v[4:5]
	global_load_dwordx4 v[26:29], v[4:5], off nt
	v_or_b32_e32 v4, 40, v76
	v_ashrrev_i32_e32 v5, 31, v4
	v_lshlrev_b64 v[4:5], 13, v[4:5]
	v_lshl_add_u64 v[4:5], v[2:3], 0, v[4:5]
	global_load_dwordx4 v[22:25], v[4:5], off nt
	v_or_b32_e32 v4, 44, v76
	v_ashrrev_i32_e32 v5, 31, v4
	v_lshlrev_b64 v[4:5], 13, v[4:5]
	v_lshl_add_u64 v[4:5], v[2:3], 0, v[4:5]
	global_load_dwordx4 v[18:21], v[4:5], off nt
	v_or_b32_e32 v4, 48, v76
	v_ashrrev_i32_e32 v5, 31, v4
	v_lshlrev_b64 v[4:5], 13, v[4:5]
	v_lshl_add_u64 v[4:5], v[2:3], 0, v[4:5]
	global_load_dwordx4 v[14:17], v[4:5], off nt
	v_or_b32_e32 v4, 52, v76
	v_ashrrev_i32_e32 v5, 31, v4
	v_lshlrev_b64 v[4:5], 13, v[4:5]
	v_lshl_add_u64 v[4:5], v[2:3], 0, v[4:5]
	global_load_dwordx4 v[10:13], v[4:5], off nt
	v_or_b32_e32 v4, 56, v76
	v_ashrrev_i32_e32 v5, 31, v4
	v_lshlrev_b64 v[4:5], 13, v[4:5]
	v_lshl_add_u64 v[4:5], v[2:3], 0, v[4:5]
	global_load_dwordx4 v[6:9], v[4:5], off nt
	v_or_b32_e32 v4, 60, v76
	v_lshl_add_u64 v[76:77], v[76:77], 2, s[6:7]
	global_load_dword v0, v[76:77], off
	v_or_b32_e32 v156, s10, v79
	v_ashrrev_i32_e32 v157, 31, v156
	v_lshl_add_u64 v[156:157], v[156:157], 2, s[6:7]
	global_load_dword v141, v[156:157], off
	v_or_b32_e32 v156, s10, v80
	v_ashrrev_i32_e32 v157, 31, v156
	v_lshl_add_u64 v[156:157], v[156:157], 2, s[6:7]
	global_load_dword v142, v[156:157], off
	v_or_b32_e32 v156, s10, v81
	v_ashrrev_i32_e32 v157, 31, v156
	v_lshl_add_u64 v[156:157], v[156:157], 2, s[6:7]
	global_load_dword v143, v[156:157], off
	v_or_b32_e32 v156, s10, v82
	v_ashrrev_i32_e32 v157, 31, v156
	v_lshl_add_u64 v[156:157], v[156:157], 2, s[6:7]
	global_load_dword v144, v[156:157], off
	v_or_b32_e32 v156, s10, v83
	v_ashrrev_i32_e32 v157, 31, v156
	v_lshl_add_u64 v[156:157], v[156:157], 2, s[6:7]
	global_load_dword v145, v[156:157], off
	v_or_b32_e32 v156, s10, v84
	v_ashrrev_i32_e32 v157, 31, v156
	v_lshl_add_u64 v[156:157], v[156:157], 2, s[6:7]
	global_load_dword v146, v[156:157], off
	v_or_b32_e32 v156, s10, v85
	v_ashrrev_i32_e32 v157, 31, v156
	v_lshl_add_u64 v[156:157], v[156:157], 2, s[6:7]
	global_load_dword v147, v[156:157], off
	v_or_b32_e32 v156, s10, v86
	v_ashrrev_i32_e32 v157, 31, v156
	v_lshl_add_u64 v[156:157], v[156:157], 2, s[6:7]
	global_load_dword v148, v[156:157], off
	v_or_b32_e32 v156, s10, v87
	v_ashrrev_i32_e32 v157, 31, v156
	v_lshl_add_u64 v[156:157], v[156:157], 2, s[6:7]
	global_load_dword v149, v[156:157], off
	v_or_b32_e32 v156, s10, v88
	v_ashrrev_i32_e32 v157, 31, v156
	v_lshl_add_u64 v[156:157], v[156:157], 2, s[6:7]
	global_load_dword v150, v[156:157], off
	v_or_b32_e32 v156, s10, v89
	v_ashrrev_i32_e32 v157, 31, v156
	v_lshl_add_u64 v[156:157], v[156:157], 2, s[6:7]
	global_load_dword v151, v[156:157], off
	v_or_b32_e32 v156, s10, v90
	v_ashrrev_i32_e32 v157, 31, v156
	v_lshl_add_u64 v[156:157], v[156:157], 2, s[6:7]
	global_load_dword v152, v[156:157], off
	v_or_b32_e32 v156, s10, v91
	v_ashrrev_i32_e32 v157, 31, v156
	v_lshl_add_u64 v[156:157], v[156:157], 2, s[6:7]
	global_load_dword v153, v[156:157], off
	v_or_b32_e32 v156, s10, v92
	v_ashrrev_i32_e32 v157, 31, v156
	v_lshl_add_u64 v[156:157], v[156:157], 2, s[6:7]
	global_load_dword v154, v[156:157], off
	v_or_b32_e32 v156, s10, v93
	v_ashrrev_i32_e32 v157, 31, v156
	v_lshl_add_u64 v[156:157], v[156:157], 2, s[6:7]
	global_load_dword v155, v[156:157], off
	v_add_u32_e32 v71, v94, v78
	v_ashrrev_i32_e32 v5, 31, v4
	v_lshlrev_b64 v[4:5], 13, v[4:5]
	v_lshl_add_u64 v[2:3], v[2:3], 0, v[4:5]
	global_load_dwordx4 v[2:5], v[2:3], off nt
	s_ashr_i32 s11, s10, 31
	s_waitcnt vmcnt(1)
; #define LAS __attribute__((address_space(3)))
; __device__ __forceinline__ void tr_item(const float* W, int ldw, bf16* WT, int ldt, const float* gain, int dst_row0, int k0, int n0, LAS float* scr, int lane) {
;     ...
;     for (int i = 0; i < 16; ++i) { const int k = kr + 4 * i; const float g = gain ? gain[k0 + k] : 1.0f; LAS float* d = scr + k * 65 + n4;
;         d[0] = v[i][0] * g; d[1] = v[i][1] * g; d[2] = v[i][2] * g; d[3] = v[i][3] * g; }
	v_pk_mul_f32 v[62:63], v[62:63], v[0:1] op_sel_hi:[1,0]
	ds_write2_b32 v71, v62, v63 offset1:1
	v_pk_mul_f32 v[62:63], v[64:65], v[0:1] op_sel_hi:[1,0]
	ds_write2_b32 v71, v62, v63 offset0:2 offset1:3
	v_or_b32_e32 v62, s10, v79
	v_ashrrev_i32_e32 v63, 31, v62
	v_lshl_add_u64 v[62:63], v[62:63], 2, s[6:7]
	v_mov_b32_e32 v0, v141
	v_add_u32_e32 v62, 0x410, v71
	s_waitcnt vmcnt(0)
	v_pk_mul_f32 v[58:59], v[58:59], v[0:1] op_sel_hi:[1,0]
	ds_write2_b32 v62, v58, v59 offset1:1
	v_pk_mul_f32 v[58:59], v[60:61], v[0:1] op_sel_hi:[1,0]
	v_add_u32_e32 v0, 0x418, v71
	ds_write2_b32 v0, v58, v59 offset1:1
	v_or_b32_e32 v58, s10, v80
	v_ashrrev_i32_e32 v59, 31, v58
	v_lshl_add_u64 v[58:59], v[58:59], 2, s[6:7]
	v_mov_b32_e32 v0, v142
	v_add_u32_e32 v58, 0x820, v71
	s_waitcnt vmcnt(0)
	v_pk_mul_f32 v[54:55], v[54:55], v[0:1] op_sel_hi:[1,0]
	ds_write2_b32 v58, v54, v55 offset1:1
	v_pk_mul_f32 v[54:55], v[56:57], v[0:1] op_sel_hi:[1,0]
	v_add_u32_e32 v0, 0x828, v71
	ds_write2_b32 v0, v54, v55 offset1:1
	v_or_b32_e32 v54, s10, v81
	v_ashrrev_i32_e32 v55, 31, v54
	v_lshl_add_u64 v[54:55], v[54:55], 2, s[6:7]
	v_mov_b32_e32 v0, v143
	v_add_u32_e32 v54, 0xc30, v71
	s_waitcnt vmcnt(0)
	v_pk_mul_f32 v[50:51], v[50:51], v[0:1] op_sel_hi:[1,0]
	ds_write2_b32 v54, v50, v51 offset1:1
	v_pk_mul_f32 v[50:51], v[52:53], v[0:1] op_sel_hi:[1,0]
	v_add_u32_e32 v0, 0xc38, v71
	ds_write2_b32 v0, v50, v51 offset1:1
	v_or_b32_e32 v50, s10, v82
	v_ashrrev_i32_e32 v51, 31, v50
	v_lshl_add_u64 v[50:51], v[50:51], 2, s[6:7]
	v_mov_b32_e32 v0, v144
	v_add_u32_e32 v50, 0x1040, v71
	s_waitcnt vmcnt(0)
	v_pk_mul_f32 v[46:47], v[46:47], v[0:1] op_sel_hi:[1,0]
	ds_write2_b32 v50, v46, v47 offset1:1
	v_pk_mul_f32 v[46:47], v[48:49], v[0:1] op_sel_hi:[1,0]
	v_add_u32_e32 v0, 0x1048, v71
	ds_write2_b32 v0, v46, v47 offset1:1
	v_or_b32_e32 v46, s10, v83
	v_ashrrev_i32_e32 v47, 31, v46
	v_lshl_add_u64 v[46:47], v[46:47], 2, s[6:7]
	v_mov_b32_e32 v0, v145
	v_add_u32_e32 v46, 0x1450, v71
	s_waitcnt vmcnt(0)
	v_pk_mul_f32 v[42:43], v[42:43], v[0:1] op_sel_hi:[1,0]
	ds_write2_b32 v46, v42, v43 offset1:1
	v_pk_mul_f32 v[44:45], v[44:45], v[0:1] op_sel_hi:[1,0]
	v_add_u32_e32 v42, v94, v95
	ds_write2_b32 v42, v44, v45 offset0:2 offset1:3
	v_or_b32_e32 v44, s10, v84
	v_ashrrev_i32_e32 v45, 31, v44
	v_lshl_add_u64 v[44:45], v[44:45], 2, s[6:7]
	v_mov_b32_e32 v0, v146
	v_add_u32_e32 v43, 0x410, v42
	s_waitcnt vmcnt(0)
	v_pk_mul_f32 v[38:39], v[38:39], v[0:1] op_sel_hi:[1,0]
	ds_write2_b32 v43, v38, v39 offset1:1
	v_pk_mul_f32 v[38:39], v[40:41], v[0:1] op_sel_hi:[1,0]
	v_add_u32_e32 v0, 0x418, v42
	ds_write2_b32 v0, v38, v39 offset1:1
	v_or_b32_e32 v38, s10, v85
	v_ashrrev_i32_e32 v39, 31, v38
	v_lshl_add_u64 v[38:39], v[38:39], 2, s[6:7]
	v_mov_b32_e32 v0, v147
	v_add_u32_e32 v38, 0x820, v42
	s_waitcnt vmcnt(0)
	v_pk_mul_f32 v[34:35], v[34:35], v[0:1] op_sel_hi:[1,0]
	ds_write2_b32 v38, v34, v35 offset1:1
	v_pk_mul_f32 v[34:35], v[36:37], v[0:1] op_sel_hi:[1,0]
	v_add_u32_e32 v0, 0x828, v42
	ds_write2_b32 v0, v34, v35 offset1:1
	v_or_b32_e32 v34, s10, v86
	v_ashrrev_i32_e32 v35, 31, v34
	v_lshl_add_u64 v[34:35], v[34:35], 2, s[6:7]
	v_mov_b32_e32 v0, v148
	v_add_u32_e32 v34, 0xc30, v42
	s_waitcnt vmcnt(0)
	v_pk_mul_f32 v[30:31], v[30:31], v[0:1] op_sel_hi:[1,0]
	ds_write2_b32 v34, v30, v31 offset1:1
	v_pk_mul_f32 v[30:31], v[32:33], v[0:1] op_sel_hi:[1,0]
	v_add_u32_e32 v0, 0xc38, v42
	ds_write2_b32 v0, v30, v31 offset1:1
	v_or_b32_e32 v30, s10, v87
	v_ashrrev_i32_e32 v31, 31, v30
	v_lshl_add_u64 v[30:31], v[30:31], 2, s[6:7]
	v_mov_b32_e32 v0, v149
	v_add_u32_e32 v30, 0x1040, v42
	s_waitcnt vmcnt(0)
	v_pk_mul_f32 v[26:27], v[26:27], v[0:1] op_sel_hi:[1,0]
	ds_write2_b32 v30, v26, v27 offset1:1
	v_pk_mul_f32 v[26:27], v[28:29], v[0:1] op_sel_hi:[1,0]
	v_add_u32_e32 v0, 0x1048, v42
	ds_write2_b32 v0, v26, v27 offset1:1
	v_or_b32_e32 v26, s10, v88
	v_ashrrev_i32_e32 v27, 31, v26
	v_lshl_add_u64 v[26:27], v[26:27], 2, s[6:7]
	v_mov_b32_e32 v0, v150
	v_add_u32_e32 v26, 0x1450, v42
	s_waitcnt vmcnt(0)
	v_pk_mul_f32 v[22:23], v[22:23], v[0:1] op_sel_hi:[1,0]
	ds_write2_b32 v26, v22, v23 offset1:1
	v_pk_mul_f32 v[22:23], v[24:25], v[0:1] op_sel_hi:[1,0]
	v_add_u32_e32 v0, 0x1458, v42
	ds_write2_b32 v0, v22, v23 offset1:1
	v_or_b32_e32 v22, s10, v89
	v_ashrrev_i32_e32 v23, 31, v22
	v_lshl_add_u64 v[22:23], v[22:23], 2, s[6:7]
	v_mov_b32_e32 v0, v151
	v_add_u32_e32 v22, 0x1860, v42
	s_waitcnt vmcnt(0)
	v_pk_mul_f32 v[18:19], v[18:19], v[0:1] op_sel_hi:[1,0]
	ds_write2_b32 v22, v18, v19 offset1:1
	v_pk_mul_f32 v[18:19], v[20:21], v[0:1] op_sel_hi:[1,0]
	v_add_u32_e32 v0, 0x1868, v42
	ds_write2_b32 v0, v18, v19 offset1:1
	v_or_b32_e32 v18, s10, v90
	v_ashrrev_i32_e32 v19, 31, v18
	v_lshl_add_u64 v[18:19], v[18:19], 2, s[6:7]
	v_mov_b32_e32 v0, v152
	v_add_u32_e32 v18, 0x1c70, v42
	s_waitcnt vmcnt(0)
	v_pk_mul_f32 v[14:15], v[14:15], v[0:1] op_sel_hi:[1,0]
	ds_write2_b32 v18, v14, v15 offset1:1
	v_pk_mul_f32 v[14:15], v[16:17], v[0:1] op_sel_hi:[1,0]
	v_add_u32_e32 v0, 0x1c78, v42
	ds_write2_b32 v0, v14, v15 offset1:1
	v_or_b32_e32 v14, s10, v91
	v_ashrrev_i32_e32 v15, 31, v14
	v_lshl_add_u64 v[14:15], v[14:15], 2, s[6:7]
	v_mov_b32_e32 v0, v153
	v_add_u32_e32 v14, 0x2080, v42
	s_waitcnt vmcnt(0)
	v_pk_mul_f32 v[10:11], v[10:11], v[0:1] op_sel_hi:[1,0]
	ds_write2_b32 v14, v10, v11 offset1:1
	v_pk_mul_f32 v[10:11], v[12:13], v[0:1] op_sel_hi:[1,0]
	v_add_u32_e32 v0, 0x2088, v42
	ds_write2_b32 v0, v10, v11 offset1:1
	v_or_b32_e32 v10, s10, v92
	v_ashrrev_i32_e32 v11, 31, v10
	v_lshl_add_u64 v[10:11], v[10:11], 2, s[6:7]
	v_mov_b32_e32 v0, v154
	v_add_u32_e32 v10, 0x2490, v42
	s_waitcnt vmcnt(0)
; #define LAS __attribute__((address_space(3)))
; #define LDS_WAIT() asm volatile("s_waitcnt lgkmcnt(0)" ::: "memory")
; __device__ __forceinline__ unsigned cvtpk(float lo, float hi) { unsigned r; asm volatile("v_cvt_pk_bf16_f32 %0, %1, %2" : "=v"(r) : "v"(lo), "v"(hi)); return r; }
; __device__ __forceinline__ void tr_item(const float* W, int ldw, bf16* WT, int ldt, const float* gain, int dst_row0, int k0, int n0, LAS float* scr, int lane) {
;     ...
;     for (int i = 0; i < 16; ++i) { const int k = kr + 4 * i; const float g = gain ? gain[k0 + k] : 1.0f; LAS float* d = scr + k * 65 + n4;
;         d[0] = v[i][0] * g; d[1] = v[i][1] * g; d[2] = v[i][2] * g; d[3] = v[i][3] * g; }
;     LDS_WAIT(); asm volatile("" ::: "memory");
;     const int c = lane & 7;
; #pragma unroll
;     for (int j = 0; j < 8; ++j) { const int n = (lane >> 3) + 8 * j; const LAS float* s = scr + (8 * c) * 65 + n;
;         u32x4 o; o.x = cvtpk(s[0 * 65], s[1 * 65]); o.y = cvtpk(s[2 * 65], s[3 * 65]); o.z = cvtpk(s[4 * 65], s[5 * 65]); o.w = cvtpk(s[6 * 65], s[7 * 65]);
;         *(u32x4*)(WT + (size_t)(dst_row0 + n) * ldt + k0 + 8 * c) = o; }
	v_pk_mul_f32 v[6:7], v[6:7], v[0:1] op_sel_hi:[1,0]
	ds_write2_b32 v10, v6, v7 offset1:1
	v_pk_mul_f32 v[6:7], v[8:9], v[0:1] op_sel_hi:[1,0]
	v_add_u32_e32 v0, 0x2498, v42
	ds_write2_b32 v0, v6, v7 offset1:1
	v_or_b32_e32 v6, s10, v93
	v_ashrrev_i32_e32 v7, 31, v6
	v_lshl_add_u64 v[6:7], v[6:7], 2, s[6:7]
	v_mov_b32_e32 v0, v155
	v_add_u32_e32 v6, 0x28a0, v42
	s_lshl_b64 s[10:11], s[10:11], 1
	s_add_u32 s8, s8, s10
	s_addc_u32 s9, s9, s11
	v_add_u32_e32 v10, s15, v69
	s_waitcnt vmcnt(0)
	v_pk_mul_f32 v[2:3], v[2:3], v[0:1] op_sel_hi:[1,0]
	ds_write2_b32 v6, v2, v3 offset1:1
	v_pk_mul_f32 v[2:3], v[4:5], v[0:1] op_sel_hi:[1,0]
	v_add_u32_e32 v0, 0x28a8, v42
	ds_write2_b32 v0, v2, v3 offset1:1
	s_waitcnt lgkmcnt(0)
	v_lshlrev_b32_e32 v0, 1, v68
	ds_read2_b32 v[252:253], v96 offset1:65
	v_lshl_add_u64 v[2:3], s[8:9], 0, v[0:1]
	ds_read2_b32 v[250:251], v96 offset0:130 offset1:195
	v_add_u32_e32 v0, 0x400, v96
	ds_read2_b32 v[248:249], v0 offset0:4 offset1:69
	ds_read2_b32 v[246:247], v0 offset0:134 offset1:199
	v_add_u32_e32 v8, 0xfffeb800, v10
	s_mov_b64 s[8:9], 0x12200000
	v_ashrrev_i32_e32 v9, 31, v8
	v_lshl_add_u64 v[2:3], v[2:3], 0, s[8:9]
	v_lshlrev_b64 v[8:9], 12, v[8:9]
	v_lshl_add_u64 v[8:9], v[2:3], 0, v[8:9]
	v_mov_b32_e32 v156, v8
	v_mov_b32_e32 v157, v9
	ds_read2_b32 v[244:245], v96 offset0:8 offset1:73
	ds_read2_b32 v[242:243], v96 offset0:138 offset1:203
	ds_read2_b32 v[240:241], v0 offset0:12 offset1:77
	ds_read2_b32 v[238:239], v0 offset0:142 offset1:207
	v_add_u32_e32 v8, 0xfffeb808, v10
	v_ashrrev_i32_e32 v9, 31, v8
	v_lshlrev_b64 v[8:9], 12, v[8:9]
	v_lshl_add_u64 v[8:9], v[2:3], 0, v[8:9]
	v_mov_b32_e32 v154, v8
	v_mov_b32_e32 v155, v9
	ds_read2_b32 v[236:237], v96 offset0:16 offset1:81
	ds_read2_b32 v[234:235], v96 offset0:146 offset1:211
	ds_read2_b32 v[232:233], v0 offset0:20 offset1:85
	ds_read2_b32 v[216:217], v0 offset0:150 offset1:215
	v_add_u32_e32 v8, 0xfffeb810, v10
	v_ashrrev_i32_e32 v9, 31, v8
	v_lshlrev_b64 v[8:9], 12, v[8:9]
	v_lshl_add_u64 v[8:9], v[2:3], 0, v[8:9]
	v_mov_b32_e32 v152, v8
	v_mov_b32_e32 v153, v9
	ds_read2_b32 v[214:215], v96 offset0:24 offset1:89
	ds_read2_b32 v[212:213], v96 offset0:154 offset1:219
	ds_read2_b32 v[210:211], v0 offset0:28 offset1:93
	ds_read2_b32 v[208:209], v0 offset0:158 offset1:223
	v_add_u32_e32 v8, 0xfffeb818, v10
	v_ashrrev_i32_e32 v9, 31, v8
	v_lshlrev_b64 v[8:9], 12, v[8:9]
	v_lshl_add_u64 v[8:9], v[2:3], 0, v[8:9]
	v_mov_b32_e32 v150, v8
	v_mov_b32_e32 v151, v9
	ds_read2_b32 v[206:207], v96 offset0:32 offset1:97
	ds_read2_b32 v[204:205], v96 offset0:162 offset1:227
	ds_read2_b32 v[202:203], v0 offset0:36 offset1:101
	ds_read2_b32 v[200:201], v0 offset0:166 offset1:231
	v_add_u32_e32 v8, 0xfffeb820, v10
	v_ashrrev_i32_e32 v9, 31, v8
	v_lshlrev_b64 v[8:9], 12, v[8:9]
	v_lshl_add_u64 v[8:9], v[2:3], 0, v[8:9]
	v_mov_b32_e32 v148, v8
	v_mov_b32_e32 v149, v9
	ds_read2_b32 v[198:199], v96 offset0:40 offset1:105
	ds_read2_b32 v[196:197], v96 offset0:170 offset1:235
	ds_read2_b32 v[194:195], v0 offset0:44 offset1:109
	ds_read2_b32 v[176:177], v0 offset0:174 offset1:239
	v_add_u32_e32 v8, 0xfffeb828, v10
	v_ashrrev_i32_e32 v9, 31, v8
	v_lshlrev_b64 v[8:9], 12, v[8:9]
	v_lshl_add_u64 v[8:9], v[2:3], 0, v[8:9]
	v_mov_b32_e32 v146, v8
	v_mov_b32_e32 v147, v9
	ds_read2_b32 v[174:175], v96 offset0:48 offset1:113
	ds_read2_b32 v[172:173], v96 offset0:178 offset1:243
	ds_read2_b32 v[170:171], v0 offset0:52 offset1:117
	ds_read2_b32 v[168:169], v0 offset0:182 offset1:247
	v_add_u32_e32 v8, 0xfffeb830, v10
	v_ashrrev_i32_e32 v9, 31, v8
	v_lshlrev_b64 v[8:9], 12, v[8:9]
	v_lshl_add_u64 v[8:9], v[2:3], 0, v[8:9]
	v_mov_b32_e32 v144, v8
	v_mov_b32_e32 v145, v9
	ds_read2_b32 v[166:167], v96 offset0:56 offset1:121
	ds_read2_b32 v[164:165], v96 offset0:186 offset1:251
	ds_read2_b32 v[162:163], v0 offset0:60 offset1:125
	ds_read2_b32 v[160:161], v0 offset0:190 offset1:255
	v_add_u32_e32 v8, 0xfffeb838, v10
	v_ashrrev_i32_e32 v9, 31, v8
	v_lshlrev_b64 v[8:9], 12, v[8:9]
	v_lshl_add_u64 v[2:3], v[2:3], 0, v[8:9]
	v_mov_b32_e32 v142, v2
	v_mov_b32_e32 v143, v3
	s_waitcnt lgkmcnt(0)
	v_cvt_pk_bf16_f32 v159, v252, v253
	v_cvt_pk_bf16_f32 v253, v250, v251
	v_cvt_pk_bf16_f32 v252, v248, v249
	v_cvt_pk_bf16_f32 v251, v246, v247
	v_mov_b32_e32 v132, v159
	v_mov_b32_e32 v133, v253
	v_mov_b32_e32 v134, v252
	v_mov_b32_e32 v135, v251
	global_store_dwordx4 v[156:157], v[132:135], off
	v_cvt_pk_bf16_f32 v253, v244, v245
	v_cvt_pk_bf16_f32 v252, v242, v243
	v_cvt_pk_bf16_f32 v251, v240, v241
	v_cvt_pk_bf16_f32 v250, v238, v239
	v_mov_b32_e32 v136, v253
	v_mov_b32_e32 v137, v252
	v_mov_b32_e32 v138, v251
	v_mov_b32_e32 v139, v250
	global_store_dwordx4 v[154:155], v[136:139], off
	v_cvt_pk_bf16_f32 v253, v236, v237
	v_cvt_pk_bf16_f32 v252, v234, v235
	v_cvt_pk_bf16_f32 v251, v232, v233
	v_cvt_pk_bf16_f32 v250, v216, v217
	v_mov_b32_e32 v132, v253
	v_mov_b32_e32 v133, v252
	v_mov_b32_e32 v134, v251
	v_mov_b32_e32 v135, v250
	global_store_dwordx4 v[152:153], v[132:135], off
	v_cvt_pk_bf16_f32 v253, v214, v215
	v_cvt_pk_bf16_f32 v252, v212, v213
	v_cvt_pk_bf16_f32 v251, v210, v211
	v_cvt_pk_bf16_f32 v250, v208, v209
	v_mov_b32_e32 v136, v253
	v_mov_b32_e32 v137, v252
	v_mov_b32_e32 v138, v251
	v_mov_b32_e32 v139, v250
	global_store_dwordx4 v[150:151], v[136:139], off
	v_cvt_pk_bf16_f32 v253, v206, v207
	v_cvt_pk_bf16_f32 v252, v204, v205
	v_cvt_pk_bf16_f32 v251, v202, v203
	v_cvt_pk_bf16_f32 v250, v200, v201
	v_mov_b32_e32 v132, v253
	v_mov_b32_e32 v133, v252
	v_mov_b32_e32 v134, v251
	v_mov_b32_e32 v135, v250
	global_store_dwordx4 v[148:149], v[132:135], off
	v_cvt_pk_bf16_f32 v253, v198, v199
	v_cvt_pk_bf16_f32 v252, v196, v197
	v_cvt_pk_bf16_f32 v251, v194, v195
	v_cvt_pk_bf16_f32 v250, v176, v177
	v_mov_b32_e32 v136, v253
	v_mov_b32_e32 v137, v252
	v_mov_b32_e32 v138, v251
	v_mov_b32_e32 v139, v250
	global_store_dwordx4 v[146:147], v[136:139], off
	v_cvt_pk_bf16_f32 v253, v174, v175
	v_cvt_pk_bf16_f32 v252, v172, v173
	v_cvt_pk_bf16_f32 v251, v170, v171
	v_cvt_pk_bf16_f32 v250, v168, v169
	v_mov_b32_e32 v132, v253
	v_mov_b32_e32 v133, v252
	v_mov_b32_e32 v134, v251
	v_mov_b32_e32 v135, v250
	global_store_dwordx4 v[144:145], v[132:135], off
	v_cvt_pk_bf16_f32 v253, v166, v167
	v_cvt_pk_bf16_f32 v252, v164, v165
	v_cvt_pk_bf16_f32 v251, v162, v163
	v_cvt_pk_bf16_f32 v250, v160, v161
	v_mov_b32_e32 v136, v253
	v_mov_b32_e32 v137, v252
	v_mov_b32_e32 v138, v251
	v_mov_b32_e32 v139, v250
	global_store_dwordx4 v[142:143], v[136:139], off
	s_waitcnt lgkmcnt(0)
	s_branch .LBB0_1866
